# v13: GEMM K-loops: per-phase s_setprio flips removed, one static s_setprio 1 for waves 4-7 per GEMM phase
# speedup vs baseline: 1.0040x; 1.0040x over previous
; #define PG8_STAGE(bufoff, gbase, voff) do { _Pragma("unroll") for (int _i = 0; _i < 2; ++_i) \
;         __builtin_amdgcn_global_load_lds((const unsigned*)((const char*)(gbase) + (voff)[_i]), (LAS unsigned*)(lds + (bufoff) + ldsw + _i * 8192), 16, 0, 0); } while (0)
; #define PG8_BAR __builtin_amdgcn_s_barrier()
; template <class Epi>
; DI void gemm_phase(LAS unsigned char* lds, const Gemm g, const StaticOrder& S, const Epi& E) {
;     ...
;     for (int i = 0; i < 2; ++i) { int R, C; stage_rc(tid * 16 + i * 8192, R, C); const int Rb = (R & ~31) + perm32(R & 31);
;         voffA[i] = (unsigned)(R * K + C) * 2u; voffB[i] = (unsigned)(Rb * K + C) * 2u; }
;     const size_t kstep = (size_t)(BK * 2);
;     const size_t hstep = (size_t)HALF * K * 2;
;     const size_t tstep = 2 * hstep;
;     const unsigned ldsw = (unsigned)wid * 1024u;
;     const int aoff = lds_byte(wr * 64 + fr, fq * 8), boff = lds_byte(wc * 32 + fr, fq * 8);
;     ...
;     const char* cA = (const char*)g.A + (size_t)cur.pm * tstep; const char* cB = (const char*)g.Bt + (size_t)cur.pn * tstep;
;     PG8_STAGE(PG8_SB(0, 0), cB, voffB); PG8_STAGE(PG8_SA(0, 0), cA, voffA); PG8_STAGE(PG8_SB(0, 1), cB + hstep, voffB); PG8_STAGE(PG8_SA(0, 1), cA + hstep, voffA);
;     if (wr == 1) PG8_BAR;
.LBB0_385:
	s_bitcmp0_b32 s94, 0
	s_cselect_b64 s[10:11], -1, 0
	v_writelane_b32 v236, s10, 29
	v_readlane_b32 s48, v238, 1
	v_readlane_b32 s54, v238, 7
	v_writelane_b32 v236, s11, 30
	s_and_b64 s[10:11], s[10:11], exec
	v_readlane_b32 s55, v238, 8
	v_readlane_b32 s63, v238, 16
	v_readlane_b32 s5, v238, 26
	v_readlane_b32 s62, v238, 15
	s_cselect_b32 s85, s63, s5
	v_readlane_b32 s5, v238, 25
	v_readlane_b32 s54, v237, 32
	s_cselect_b32 s86, s62, s5
	s_andn2_b64 vcc, exec, s[2:3]
	v_readlane_b32 s55, v237, 33
	v_readlane_b32 s49, v238, 2
	v_readlane_b32 s50, v238, 3
	v_readlane_b32 s51, v238, 4
	v_readlane_b32 s52, v238, 5
	v_readlane_b32 s53, v238, 6
	v_readlane_b32 s56, v238, 9
	v_readlane_b32 s57, v238, 10
	v_readlane_b32 s58, v238, 11
	v_readlane_b32 s59, v238, 12
	v_readlane_b32 s60, v238, 13
	v_readlane_b32 s61, v238, 14
	s_cbranch_vccnz .LBB0_578
	v_bfe_i32 v2, v12, 27, 1
	v_lshlrev_b32_e32 v0, 4, v12
	v_lshrrev_b32_e32 v2, 22, v2
	v_add_u32_e32 v2, v0, v2
	v_and_b32_e32 v2, 0xfffffc00, v2
	v_ashrrev_i32_e32 v1, 31, v12
	v_sub_u32_e32 v2, v0, v2
	v_lshrrev_b32_e32 v1, 26, v1
	v_lshrrev_b32_e32 v3, 4, v2
	v_add_u32_e32 v1, v12, v1
	v_bitop3_b32 v3, v3, v2, 32 bitop3:0x6c
	v_ashrrev_i32_e32 v2, 31, v2
	v_ashrrev_i32_e32 v1, 6, v1
	v_lshrrev_b32_e32 v2, 26, v2
	v_lshlrev_b32_e32 v4, 3, v1
	v_add_u32_e32 v2, v3, v2
	v_and_b32_e32 v4, -16, v4
	v_ashrrev_i32_e32 v2, 6, v2
	v_lshlrev_b32_e32 v1, 5, v1
	v_add_u32_e32 v4, v2, v4
	v_and_b32_e32 v13, 32, v1
	v_mul_i32_i24_e32 v1, 64, v2
	v_sub_u32_e32 v1, v3, v1
	v_lshlrev_b32_e32 v3, 1, v4
	v_lshrrev_b32_e32 v5, 2, v4
	v_and_b32_e32 v2, 3, v2
	s_mov_b32 s2, 0x7fffffe0
	v_ashrrev_i16_sdwa v1, v169, sext(v1) dst_sel:DWORD dst_unused:UNUSED_PAD src0_sel:DWORD src1_sel:BYTE_0
	v_and_b32_e32 v3, 24, v3
	v_and_b32_e32 v5, 4, v5
	v_and_or_b32 v2, v4, s2, v2
	v_bfe_i32 v14, v1, 0, 16
	v_or3_b32 v2, v2, v5, v3
	v_add_u32_e32 v1, v13, v14
	v_mul_lo_u32 v15, v4, s12
	v_mul_lo_u32 v2, v2, s12
	v_add_u32_e32 v0, 0x2000, v0
	v_add_lshl_u32 v144, v1, v15, 1
	v_add_lshl_u32 v166, v2, v1, 1
	v_ashrrev_i32_e32 v1, 31, v0
	v_lshrrev_b32_e32 v1, 22, v1
	v_add_u32_e32 v1, v0, v1
	v_ashrrev_i32_e32 v1, 10, v1
	v_mul_i32_i24_e32 v2, 0x400, v1
	v_sub_u32_e32 v0, v0, v2
	v_lshrrev_b32_e32 v2, 4, v0
	v_bitop3_b32 v0, v2, v0, 32 bitop3:0x6c
	v_ashrrev_i32_e32 v3, 31, v0
	v_lshrrev_b32_e32 v3, 26, v3
	v_lshlrev_b32_e32 v2, 3, v1
	v_add_u32_e32 v3, v0, v3
	v_and_b32_e32 v2, -16, v2
	v_ashrrev_i32_e32 v4, 6, v3
	v_add_u32_e32 v2, v4, v2
	v_and_b32_e32 v4, 3, v4
	s_ashr_i32 s13, s12, 31
	v_and_or_b32 v4, v2, s2, v4
	s_lshl_b64 s[50:51], s[12:13], 9
	s_ashr_i32 s2, s0, 31
	s_mul_i32 s2, s50, s2
	s_mul_hi_u32 s3, s50, s0
	s_add_i32 s10, s3, s2
	s_lshr_b64 s[2:3], s[12:13], 23
	s_mul_i32 s3, s2, s0
	s_add_i32 s3, s10, s3
	s_ashr_i32 s10, s16, 31
	s_mul_i32 s10, s50, s10
	s_mul_hi_u32 s11, s50, s16
	s_ashr_i32 s5, s19, 6
	v_lshlrev_b32_e32 v1, 5, v1
	s_add_i32 s10, s11, s10
	s_mul_i32 s2, s2, s16
	v_and_b32_e32 v16, 32, v1
	v_and_b32_e32 v1, 0xc0, v3
	s_ashr_i32 s14, s19, 8
	s_lshl_b64 s[48:49], s[12:13], 8
	s_lshl_b32 s37, s5, 10
	s_add_i32 s2, s10, s2
	s_mul_i32 s10, s50, s16
	v_sub_u32_e32 v0, v0, v1
	v_lshlrev_b32_e32 v1, 1, v2
	v_lshrrev_b32_e32 v3, 2, v2
	s_add_u32 s10, s86, s10
	v_ashrrev_i16_sdwa v0, v169, sext(v0) dst_sel:DWORD dst_unused:UNUSED_PAD src0_sel:DWORD src1_sel:BYTE_0
	v_and_b32_e32 v1, 24, v1
	v_and_b32_e32 v3, 4, v3
	s_addc_u32 s11, s85, s2
	s_add_i32 s87, s37, 0x100
	v_bfe_i32 v17, v0, 0, 16
	v_or3_b32 v1, v4, v3, v1
	s_add_i32 m0, s87, 0x10000
	v_readlane_b32 s68, v238, 1
	v_add_u32_e32 v0, v16, v17
	v_mul_lo_u32 v1, v1, s12
	s_mul_i32 s15, s50, s0
	global_load_lds_dwordx4 v166, s[10:11]
	s_add_i32 m0, s87, 0x12000
	v_readlane_b32 s80, v238, 13
	v_add_lshl_u32 v148, v1, v0, 1
	v_readlane_b32 s77, v238, 10
	v_readlane_b32 s81, v238, 14
	s_add_u32 s2, s80, s15
	v_mul_lo_u32 v18, v2, s12
	global_load_lds_dwordx4 v148, s[10:11]
	s_addc_u32 s3, s81, s3
	s_mov_b32 m0, s87
	s_add_i32 s77, s87, 0x2000
	v_add_lshl_u32 v146, v0, v18, 1
	global_load_lds_dwordx4 v144, s[2:3]
	s_mov_b32 m0, s77
	s_add_u32 s38, s10, s48
	global_load_lds_dwordx4 v146, s[2:3]
	s_addc_u32 s39, s11, s49
	s_add_i32 m0, s87, 0x14000
	v_mov_b32_e32 v149, v167
	global_load_lds_dwordx4 v166, s[38:39]
	s_add_i32 m0, s87, 0x16000
	s_add_u32 s40, s2, s48
	s_addc_u32 s41, s3, s49
	s_add_i32 s80, s87, 0x4000
	global_load_lds_dwordx4 v148, s[38:39]
	s_mov_b32 m0, s80
	s_add_i32 s81, s87, 0x6000
	global_load_lds_dwordx4 v144, s[40:41]
	s_mov_b32 m0, s81
	v_mov_b32_e32 v145, v167
	global_load_lds_dwordx4 v146, s[40:41]
	v_mov_b32_e32 v147, v167
	v_lshl_add_u64 v[10:11], s[10:11], 0, v[166:167]
	v_lshl_add_u64 v[8:9], s[10:11], 0, v[148:149]
	v_lshl_add_u64 v[6:7], s[2:3], 0, v[144:145]
	v_lshl_add_u64 v[4:5], s[2:3], 0, v[146:147]
	v_lshl_add_u64 v[2:3], s[38:39], 0, v[166:167]
	s_cmp_lg_u32 s14, 1
	v_lshl_add_u64 v[0:1], s[38:39], 0, v[148:149]
	s_movk_i32 s60, 0x300
	v_readlane_b32 s69, v238, 2
	v_readlane_b32 s70, v238, 3
	v_readlane_b32 s71, v238, 4
	v_readlane_b32 s72, v238, 5
	v_readlane_b32 s73, v238, 6
	v_readlane_b32 s74, v238, 7
	v_readlane_b32 s75, v238, 8
	v_readlane_b32 s76, v238, 9
	v_readlane_b32 s78, v238, 11
	v_readlane_b32 s79, v238, 12
	v_readlane_b32 s82, v238, 15
	v_readlane_b32 s83, v238, 16
	s_cbranch_scc1 .LBB0_388
	s_setprio 1
	s_barrier

; #define PG8_STAGE(bufoff, gbase, voff) do { _Pragma("unroll") for (int _i = 0; _i < 2; ++_i) \
;         __builtin_amdgcn_global_load_lds((const unsigned*)((const char*)(gbase) + (voff)[_i]), (LAS unsigned*)(lds + (bufoff) + ldsw + _i * 8192), 16, 0, 0); } while (0)
; #define PG8_LDA(dst, b, h) do { _Pragma("unroll") for (int m = 0; m < 4; ++m) _Pragma("unroll") for (int k = 0; k < 2; ++k) dst[m][k] = *(const LAS bf16x8*)(lds + PG8_SA(b, h) + aoff + m * 2048 + k * 1024); } while (0)
; #define PG8_LDB(dst, b, h) do { _Pragma("unroll") for (int n = 0; n < 2; ++n) _Pragma("unroll") for (int k = 0; k < 2; ++k) dst[n][k] = *(const LAS bf16x8*)(lds + PG8_SB(b, h) + boff + n * 2048 + k * 1024); } while (0)
; #define PG8_MMA(ai, bj, At, Bt) do { __builtin_amdgcn_s_setprio(1); _Pragma("unroll") for (int m = 0; m < 4; ++m) _Pragma("unroll") for (int n = 0; n < 2; ++n) _Pragma("unroll") for (int k = 0; k < 2; ++k) \
;         acc[ai][bj][m][n] = __builtin_amdgcn_mfma_f32_16x16x32_bf16(Bt[n][k], At[m][k], acc[ai][bj][m][n], 0, 0, 0); __builtin_amdgcn_s_setprio(0); } while (0)
; #define PG8_WAIT_L(n) asm volatile("s_waitcnt lgkmcnt(" #n ")" ::: "memory")
; #define PG8_BAR __builtin_amdgcn_s_barrier()
; #define PG8_SCHED __builtin_amdgcn_sched_barrier(0)
; template <class Epi>
; DI void gemm_phase(LAS unsigned char* lds, const Gemm g, const StaticOrder& S, const Epi& E) {
;     ...
;             const bool last = (t == nt - 2);
;             const char* a1 = cA + (size_t)(t + 1) * kstep;
;             const char* a2 = last ? nA : cA + (size_t)(t + 2) * kstep; const char* b2 = last ? nB : cB + (size_t)(t + 2) * kstep;
;             const char* a3 = a2 + kstep; const char* b3 = b2 + kstep;
;             PG8_LDB(B0, 0, 0); PG8_SCHED; PG8_LDA(At, 0, 0); PG8_STAGE(PG8_SA(1, 1), a1 + hstep, voffA);
;             PG8_WAIT_L(8); PG8_BAR; PG8_WAIT_L(0); PG8_MMA(0, 0, At, B0); PG8_BAR; PG8_SCHED;
;             PG8_LDB(B1, 0, 1); PG8_STAGE(PG8_SB(0, 0), b2, voffB);
;             PG8_BAR; PG8_WAIT_L(0); PG8_MMA(0, 1, At, B1); PG8_BAR;
;             PG8_LDA(At, 0, 1); PG8_STAGE(PG8_SA(0, 0), a2, voffA);
;             PG8_BAR; PG8_WAIT_L(0); PG8_MMA(1, 0, At, B0); PG8_BAR; PG8_SCHED;
.LBB0_397:
	s_andn2_b64 vcc, exec, s[72:73]
	s_waitcnt lgkmcnt(0)
	s_cbranch_vccnz .LBB0_400
	s_add_u32 s2, s2, 0x80
	s_addc_u32 s3, s3, 0
	s_add_u32 s14, s10, 0x100
	s_addc_u32 s15, s11, 0
	s_mov_b32 s4, 0
	s_mov_b32 s33, 0x1c000
	s_add_i32 s5, s4, 2
	s_add_u32 s10, s2, 0x80
	s_addc_u32 s11, s3, 0
	s_add_i32 s17, s56, 0x100
	v_add_u32_e32 v140, s17, v190
	ds_read_b128 v[128:131], v140
	ds_read_b128 v[132:135], v140 offset:1024
	ds_read_b128 v[136:139], v140 offset:2048
	ds_read_b128 v[140:143], v140 offset:3072
	s_cmp_eq_u32 s70, s4
	s_cselect_b32 s11, s53, s11
	s_cselect_b32 s10, s52, s10
	s_cselect_b32 s13, s59, s15
	s_cselect_b32 s12, s58, s14
	v_lshl_add_u64 v[162:163], s[2:3], 0, v[150:151]
	s_add_i32 m0, s87, 0xc000
	ds_read_b128 v[154:157], v191
	ds_read_b128 v[158:161], v191 offset:1024
	ds_read_b128 v[170:173], v191 offset:2048
	ds_read_b128 v[174:177], v191 offset:3072
	ds_read_b128 v[178:181], v191 offset:4096
	ds_read_b128 v[192:195], v191 offset:5120
	ds_read_b128 v[196:199], v191 offset:6144
	ds_read_b128 v[200:203], v191 offset:7168
	global_load_lds_dwordx4 v[162:163], off
	v_lshl_add_u64 v[162:163], s[2:3], 0, v[152:153]
	s_add_i32 m0, s87, 0xe000
	s_nop 0
	global_load_lds_dwordx4 v[162:163], off
	s_waitcnt lgkmcnt(8)
	s_barrier
	s_waitcnt lgkmcnt(0)
	s_waitcnt lgkmcnt(0)
	v_mfma_f32_16x16x32_bf16 v[124:127], v[128:131], v[154:157], 0
	v_mfma_f32_16x16x32_bf16 v[120:123], v[136:139], v[154:157], 0
	v_mfma_f32_16x16x32_bf16 v[108:111], v[128:131], v[170:173], 0
	v_mfma_f32_16x16x32_bf16 v[104:107], v[136:139], v[170:173], 0
	v_mfma_f32_16x16x32_bf16 v[92:95], v[128:131], v[178:181], 0
	v_mfma_f32_16x16x32_bf16 v[88:91], v[136:139], v[178:181], 0
	v_mfma_f32_16x16x32_bf16 v[76:79], v[128:131], v[196:199], 0
	v_mfma_f32_16x16x32_bf16 v[72:75], v[136:139], v[196:199], 0
	v_mfma_f32_16x16x32_bf16 v[124:127], v[132:135], v[158:161], v[124:127]
	v_mfma_f32_16x16x32_bf16 v[120:123], v[140:143], v[158:161], v[120:123]
	v_mfma_f32_16x16x32_bf16 v[108:111], v[132:135], v[174:177], v[108:111]
	v_mfma_f32_16x16x32_bf16 v[104:107], v[140:143], v[174:177], v[104:107]
	v_mfma_f32_16x16x32_bf16 v[92:95], v[132:135], v[192:195], v[92:95]
	v_mfma_f32_16x16x32_bf16 v[88:91], v[140:143], v[192:195], v[88:91]
	v_mfma_f32_16x16x32_bf16 v[76:79], v[132:135], v[200:203], v[76:79]
	v_mfma_f32_16x16x32_bf16 v[72:75], v[140:143], v[200:203], v[72:75]
	s_barrier
	s_add_i32 s4, s57, 0x100
	v_add_u32_e32 v162, s4, v190
	s_add_i32 s17, s17, s37
	ds_read_b128 v[204:207], v162
	ds_read_b128 v[208:211], v162 offset:1024
	ds_read_b128 v[212:215], v162 offset:2048
	ds_read_b128 v[216:219], v162 offset:3072
	v_lshl_add_u64 v[162:163], s[12:13], 0, v[166:167]
	s_mov_b32 m0, s17
	v_lshl_add_u64 v[182:183], s[12:13], 0, v[148:149]
	global_load_lds_dwordx4 v[162:163], off
	s_add_i32 m0, s17, 0x2000
	s_nop 0
	global_load_lds_dwordx4 v[182:183], off
	s_barrier
	s_waitcnt lgkmcnt(0)
	s_waitcnt lgkmcnt(0)
	v_mfma_f32_16x16x32_bf16 v[116:119], v[204:207], v[154:157], 0
	v_mfma_f32_16x16x32_bf16 v[112:115], v[212:215], v[154:157], 0
	v_mfma_f32_16x16x32_bf16 v[100:103], v[204:207], v[170:173], 0
	v_mfma_f32_16x16x32_bf16 v[96:99], v[212:215], v[170:173], 0
	v_mfma_f32_16x16x32_bf16 v[84:87], v[204:207], v[178:181], 0
	v_mfma_f32_16x16x32_bf16 v[80:83], v[212:215], v[178:181], 0
	v_mfma_f32_16x16x32_bf16 v[68:71], v[204:207], v[196:199], 0
	v_mfma_f32_16x16x32_bf16 v[64:67], v[212:215], v[196:199], 0
	v_mfma_f32_16x16x32_bf16 v[116:119], v[208:211], v[158:161], v[116:119]
	v_mfma_f32_16x16x32_bf16 v[112:115], v[216:219], v[158:161], v[112:115]
	v_mfma_f32_16x16x32_bf16 v[100:103], v[208:211], v[174:177], v[100:103]
	v_mfma_f32_16x16x32_bf16 v[96:99], v[216:219], v[174:177], v[96:99]
	v_mfma_f32_16x16x32_bf16 v[84:87], v[208:211], v[192:195], v[84:87]
	v_mfma_f32_16x16x32_bf16 v[80:83], v[216:219], v[192:195], v[80:83]
	v_mfma_f32_16x16x32_bf16 v[68:71], v[208:211], v[200:203], v[68:71]
	v_mfma_f32_16x16x32_bf16 v[64:67], v[216:219], v[200:203], v[64:67]
	s_mov_b32 m0, s87
	v_lshl_add_u64 v[220:221], s[10:11], 0, v[144:145]
	s_barrier
	ds_read_b128 v[154:157], v191 offset:16384
	ds_read_b128 v[158:161], v191 offset:17408
	ds_read_b128 v[170:173], v191 offset:18432
	ds_read_b128 v[174:177], v191 offset:19456
	ds_read_b128 v[178:181], v191 offset:20480
	ds_read_b128 v[192:195], v191 offset:21504
	ds_read_b128 v[196:199], v191 offset:22528
	ds_read_b128 v[200:203], v191 offset:23552
	global_load_lds_dwordx4 v[220:221], off
	v_lshl_add_u64 v[222:223], s[10:11], 0, v[146:147]
	s_mov_b32 m0, s77
	s_nop 0
	global_load_lds_dwordx4 v[222:223], off
	s_barrier
	s_waitcnt lgkmcnt(0)
	s_waitcnt lgkmcnt(0)
	v_mfma_f32_16x16x32_bf16 v[60:63], v[128:131], v[154:157], 0
	v_mfma_f32_16x16x32_bf16 v[56:59], v[136:139], v[154:157], 0
	v_mfma_f32_16x16x32_bf16 v[44:47], v[128:131], v[170:173], 0
	v_mfma_f32_16x16x32_bf16 v[40:43], v[136:139], v[170:173], 0
	v_mfma_f32_16x16x32_bf16 v[28:31], v[128:131], v[178:181], 0
	v_mfma_f32_16x16x32_bf16 v[24:27], v[136:139], v[178:181], 0
	v_mfma_f32_16x16x32_bf16 v[12:15], v[128:131], v[196:199], 0
	v_mfma_f32_16x16x32_bf16 v[8:11], v[136:139], v[196:199], 0
	v_mfma_f32_16x16x32_bf16 v[60:63], v[132:135], v[158:161], v[60:63]
	v_mfma_f32_16x16x32_bf16 v[56:59], v[140:143], v[158:161], v[56:59]
	v_mfma_f32_16x16x32_bf16 v[44:47], v[132:135], v[174:177], v[44:47]
	v_mfma_f32_16x16x32_bf16 v[40:43], v[140:143], v[174:177], v[40:43]
	v_mfma_f32_16x16x32_bf16 v[28:31], v[132:135], v[192:195], v[28:31]
	v_mfma_f32_16x16x32_bf16 v[24:27], v[140:143], v[192:195], v[24:27]
	v_mfma_f32_16x16x32_bf16 v[12:15], v[132:135], v[200:203], v[12:15]
	v_mfma_f32_16x16x32_bf16 v[8:11], v[140:143], v[200:203], v[8:11]
	s_barrier
; #define PG8_STAGE(bufoff, gbase, voff) do { _Pragma("unroll") for (int _i = 0; _i < 2; ++_i) \
;         __builtin_amdgcn_global_load_lds((const unsigned*)((const char*)(gbase) + (voff)[_i]), (LAS unsigned*)(lds + (bufoff) + ldsw + _i * 8192), 16, 0, 0); } while (0)
; #define PG8_LDA(dst, b, h) do { _Pragma("unroll") for (int m = 0; m < 4; ++m) _Pragma("unroll") for (int k = 0; k < 2; ++k) dst[m][k] = *(const LAS bf16x8*)(lds + PG8_SA(b, h) + aoff + m * 2048 + k * 1024); } while (0)
; #define PG8_LDB(dst, b, h) do { _Pragma("unroll") for (int n = 0; n < 2; ++n) _Pragma("unroll") for (int k = 0; k < 2; ++k) dst[n][k] = *(const LAS bf16x8*)(lds + PG8_SB(b, h) + boff + n * 2048 + k * 1024); } while (0)
; #define PG8_MMA(ai, bj, At, Bt) do { __builtin_amdgcn_s_setprio(1); _Pragma("unroll") for (int m = 0; m < 4; ++m) _Pragma("unroll") for (int n = 0; n < 2; ++n) _Pragma("unroll") for (int k = 0; k < 2; ++k) \
;         acc[ai][bj][m][n] = __builtin_amdgcn_mfma_f32_16x16x32_bf16(Bt[n][k], At[m][k], acc[ai][bj][m][n], 0, 0, 0); __builtin_amdgcn_s_setprio(0); } while (0)
; #define PG8_WAIT_V(n) asm volatile("s_waitcnt vmcnt(" #n ")" ::: "memory")
; #define PG8_WAIT_L(n) asm volatile("s_waitcnt lgkmcnt(" #n ")" ::: "memory")
; #define PG8_BAR __builtin_amdgcn_s_barrier()
; #define PG8_SCHED __builtin_amdgcn_sched_barrier(0)
; template <class Epi>
; DI void gemm_phase(LAS unsigned char* lds, const Gemm g, const StaticOrder& S, const Epi& E) {
;     ...
;             PG8_STAGE(PG8_SB(0, 1), b2 + hstep, voffB);
;             PG8_WAIT_V(6); PG8_BAR; PG8_MMA(1, 1, At, B1); PG8_BAR;
;             PG8_LDB(B0, 1, 0); PG8_SCHED; PG8_LDA(At, 1, 0); PG8_STAGE(PG8_SA(0, 1), a2 + hstep, voffA);
;             PG8_WAIT_L(8); PG8_BAR; PG8_WAIT_L(0); PG8_MMA(0, 0, At, B0); PG8_BAR; PG8_SCHED;
;             PG8_LDB(B1, 1, 1); PG8_STAGE(PG8_SB(1, 0), b3, voffB);
;             PG8_BAR; PG8_WAIT_L(0); PG8_MMA(0, 1, At, B1); PG8_BAR;
;             PG8_LDA(At, 1, 1); PG8_STAGE(PG8_SA(1, 0), a3, voffA);
	s_add_u32 s12, s12, s48
	s_addc_u32 s13, s13, s49
	s_add_i32 s4, s4, s37
	v_lshl_add_u64 v[224:225], s[12:13], 0, v[166:167]
	s_mov_b32 m0, s4
	v_lshl_add_u64 v[226:227], s[12:13], 0, v[148:149]
	global_load_lds_dwordx4 v[224:225], off
	s_add_i32 m0, s4, 0x2000
	s_nop 0
	global_load_lds_dwordx4 v[226:227], off
	s_waitcnt vmcnt(6)
	s_barrier
	v_mfma_f32_16x16x32_bf16 v[52:55], v[204:207], v[154:157], 0
	v_mfma_f32_16x16x32_bf16 v[48:51], v[212:215], v[154:157], 0
	v_mfma_f32_16x16x32_bf16 v[36:39], v[204:207], v[170:173], 0
	v_mfma_f32_16x16x32_bf16 v[32:35], v[212:215], v[170:173], 0
	v_mfma_f32_16x16x32_bf16 v[20:23], v[204:207], v[178:181], 0
	v_mfma_f32_16x16x32_bf16 v[16:19], v[212:215], v[178:181], 0
	v_mfma_f32_16x16x32_bf16 v[4:7], v[204:207], v[196:199], 0
	v_mfma_f32_16x16x32_bf16 v[0:3], v[212:215], v[196:199], 0
	v_mfma_f32_16x16x32_bf16 v[52:55], v[208:211], v[158:161], v[52:55]
	v_mfma_f32_16x16x32_bf16 v[48:51], v[216:219], v[158:161], v[48:51]
	v_mfma_f32_16x16x32_bf16 v[36:39], v[208:211], v[174:177], v[36:39]
	v_mfma_f32_16x16x32_bf16 v[32:35], v[216:219], v[174:177], v[32:35]
	v_mfma_f32_16x16x32_bf16 v[20:23], v[208:211], v[192:195], v[20:23]
	v_mfma_f32_16x16x32_bf16 v[16:19], v[216:219], v[192:195], v[16:19]
	v_mfma_f32_16x16x32_bf16 v[4:7], v[208:211], v[200:203], v[4:7]
	v_mfma_f32_16x16x32_bf16 v[0:3], v[216:219], v[200:203], v[0:3]
	s_add_i32 s4, s64, 0x100
	v_add_u32_e32 v140, s4, v190
	s_barrier
	ds_read_b128 v[128:131], v140
	ds_read_b128 v[132:135], v140 offset:1024
	ds_read_b128 v[136:139], v140 offset:2048
	ds_read_b128 v[140:143], v140 offset:3072
	s_add_u32 s10, s10, s48
	s_addc_u32 s11, s11, s49
	s_mov_b32 m0, s80
	v_lshl_add_u64 v[204:205], s[10:11], 0, v[144:145]
	ds_read_b128 v[154:157], v191 offset:32768
	ds_read_b128 v[158:161], v191 offset:33792
	ds_read_b128 v[170:173], v191 offset:34816
	ds_read_b128 v[174:177], v191 offset:35840
	ds_read_b128 v[178:181], v191 offset:36864
	ds_read_b128 v[192:195], v191 offset:37888
	ds_read_b128 v[196:199], v191 offset:38912
	ds_read_b128 v[200:203], v191 offset:39936
	global_load_lds_dwordx4 v[204:205], off
	v_lshl_add_u64 v[204:205], s[10:11], 0, v[146:147]
	s_mov_b32 m0, s81
	s_nop 0
	global_load_lds_dwordx4 v[204:205], off
	s_waitcnt lgkmcnt(8)
	s_barrier
	s_waitcnt lgkmcnt(0)
	s_waitcnt lgkmcnt(0)
	v_mfma_f32_16x16x32_bf16 v[124:127], v[128:131], v[154:157], v[124:127]
	v_mfma_f32_16x16x32_bf16 v[120:123], v[136:139], v[154:157], v[120:123]
	v_mfma_f32_16x16x32_bf16 v[108:111], v[128:131], v[170:173], v[108:111]
	v_mfma_f32_16x16x32_bf16 v[104:107], v[136:139], v[170:173], v[104:107]
	v_mfma_f32_16x16x32_bf16 v[92:95], v[128:131], v[178:181], v[92:95]
	v_mfma_f32_16x16x32_bf16 v[88:91], v[136:139], v[178:181], v[88:91]
	v_mfma_f32_16x16x32_bf16 v[76:79], v[128:131], v[196:199], v[76:79]
	v_mfma_f32_16x16x32_bf16 v[72:75], v[136:139], v[196:199], v[72:75]
	v_mfma_f32_16x16x32_bf16 v[124:127], v[132:135], v[158:161], v[124:127]
	v_mfma_f32_16x16x32_bf16 v[120:123], v[140:143], v[158:161], v[120:123]
	v_mfma_f32_16x16x32_bf16 v[108:111], v[132:135], v[174:177], v[108:111]
	v_mfma_f32_16x16x32_bf16 v[104:107], v[140:143], v[174:177], v[104:107]
	v_mfma_f32_16x16x32_bf16 v[92:95], v[132:135], v[192:195], v[92:95]
	v_mfma_f32_16x16x32_bf16 v[88:91], v[140:143], v[192:195], v[88:91]
	v_mfma_f32_16x16x32_bf16 v[76:79], v[132:135], v[200:203], v[76:79]
	v_mfma_f32_16x16x32_bf16 v[72:75], v[140:143], v[200:203], v[72:75]
	s_barrier
	s_add_i32 s10, s33, 0x100
	s_add_i32 s4, s4, s37
	v_add_u32_e32 v216, s10, v190
	v_lshl_add_u64 v[162:163], v[162:163], 0, s[66:67]
	s_mov_b32 m0, s4
	ds_read_b128 v[204:207], v216
	ds_read_b128 v[208:211], v216 offset:1024
	ds_read_b128 v[212:215], v216 offset:2048
	ds_read_b128 v[216:219], v216 offset:3072
	global_load_lds_dwordx4 v[162:163], off
	v_lshl_add_u64 v[162:163], v[182:183], 0, s[66:67]
	s_add_i32 m0, s4, 0x2000
	s_nop 0
	global_load_lds_dwordx4 v[162:163], off
	s_barrier
	s_waitcnt lgkmcnt(0)
	s_waitcnt lgkmcnt(0)
	v_mfma_f32_16x16x32_bf16 v[116:119], v[204:207], v[154:157], v[116:119]
	v_mfma_f32_16x16x32_bf16 v[112:115], v[212:215], v[154:157], v[112:115]
	v_mfma_f32_16x16x32_bf16 v[100:103], v[204:207], v[170:173], v[100:103]
	v_mfma_f32_16x16x32_bf16 v[96:99], v[212:215], v[170:173], v[96:99]
	v_mfma_f32_16x16x32_bf16 v[84:87], v[204:207], v[178:181], v[84:87]
	v_mfma_f32_16x16x32_bf16 v[80:83], v[212:215], v[178:181], v[80:83]
	v_mfma_f32_16x16x32_bf16 v[68:71], v[204:207], v[196:199], v[68:71]
	v_mfma_f32_16x16x32_bf16 v[64:67], v[212:215], v[196:199], v[64:67]
	v_mfma_f32_16x16x32_bf16 v[116:119], v[208:211], v[158:161], v[116:119]
	v_mfma_f32_16x16x32_bf16 v[112:115], v[216:219], v[158:161], v[112:115]
	v_mfma_f32_16x16x32_bf16 v[100:103], v[208:211], v[174:177], v[100:103]
	v_mfma_f32_16x16x32_bf16 v[96:99], v[216:219], v[174:177], v[96:99]
	v_mfma_f32_16x16x32_bf16 v[84:87], v[208:211], v[192:195], v[84:87]
	v_mfma_f32_16x16x32_bf16 v[80:83], v[216:219], v[192:195], v[80:83]
	v_mfma_f32_16x16x32_bf16 v[68:71], v[208:211], v[200:203], v[68:71]
	v_mfma_f32_16x16x32_bf16 v[64:67], v[216:219], v[200:203], v[64:67]
	s_mov_b32 m0, s82
	v_lshl_add_u64 v[162:163], v[220:221], 0, s[66:67]
	s_barrier
	ds_read_b128 v[154:157], v191 offset:49152
	ds_read_b128 v[158:161], v191 offset:50176
	ds_read_b128 v[170:173], v191 offset:51200
	ds_read_b128 v[174:177], v191 offset:52224
	ds_read_b128 v[178:181], v191 offset:53248
	ds_read_b128 v[192:195], v191 offset:54272
	ds_read_b128 v[196:199], v191 offset:55296
	ds_read_b128 v[200:203], v191 offset:56320
	global_load_lds_dwordx4 v[162:163], off
	v_lshl_add_u64 v[162:163], v[222:223], 0, s[66:67]
	s_mov_b32 m0, s83
	s_nop 0
	global_load_lds_dwordx4 v[162:163], off
	s_barrier
; #define PG8_STAGE(bufoff, gbase, voff) do { _Pragma("unroll") for (int _i = 0; _i < 2; ++_i) \
;         __builtin_amdgcn_global_load_lds((const unsigned*)((const char*)(gbase) + (voff)[_i]), (LAS unsigned*)(lds + (bufoff) + ldsw + _i * 8192), 16, 0, 0); } while (0)
; #define PG8_LDA(dst, b, h) do { _Pragma("unroll") for (int m = 0; m < 4; ++m) _Pragma("unroll") for (int k = 0; k < 2; ++k) dst[m][k] = *(const LAS bf16x8*)(lds + PG8_SA(b, h) + aoff + m * 2048 + k * 1024); } while (0)
; #define PG8_LDB(dst, b, h) do { _Pragma("unroll") for (int n = 0; n < 2; ++n) _Pragma("unroll") for (int k = 0; k < 2; ++k) dst[n][k] = *(const LAS bf16x8*)(lds + PG8_SB(b, h) + boff + n * 2048 + k * 1024); } while (0)
; #define PG8_MMA(ai, bj, At, Bt) do { __builtin_amdgcn_s_setprio(1); _Pragma("unroll") for (int m = 0; m < 4; ++m) _Pragma("unroll") for (int n = 0; n < 2; ++n) _Pragma("unroll") for (int k = 0; k < 2; ++k) \
;         acc[ai][bj][m][n] = __builtin_amdgcn_mfma_f32_16x16x32_bf16(Bt[n][k], At[m][k], acc[ai][bj][m][n], 0, 0, 0); __builtin_amdgcn_s_setprio(0); } while (0)
; #define PG8_WAIT_V(n) asm volatile("s_waitcnt vmcnt(" #n ")" ::: "memory")
; #define PG8_WAIT_L(n) asm volatile("s_waitcnt lgkmcnt(" #n ")" ::: "memory")
; #define PG8_BAR __builtin_amdgcn_s_barrier()
; #define PG8_SCHED __builtin_amdgcn_sched_barrier(0)
; template <class Epi>
; DI void gemm_phase(LAS unsigned char* lds, const Gemm g, const StaticOrder& S, const Epi& E) {
;     ...
;         for (int t = 0; t < nt; t += 2) {
;             const bool last = (t == nt - 2);
;             const char* a1 = cA + (size_t)(t + 1) * kstep;
;             const char* a2 = last ? nA : cA + (size_t)(t + 2) * kstep; const char* b2 = last ? nB : cB + (size_t)(t + 2) * kstep;
;             const char* a3 = a2 + kstep; const char* b3 = b2 + kstep;
;             PG8_LDB(B0, 0, 0); PG8_SCHED; PG8_LDA(At, 0, 0); PG8_STAGE(PG8_SA(1, 1), a1 + hstep, voffA);
;             PG8_WAIT_L(8); PG8_BAR; PG8_WAIT_L(0); PG8_MMA(0, 0, At, B0); PG8_BAR; PG8_SCHED;
;             PG8_LDB(B1, 0, 1); PG8_STAGE(PG8_SB(0, 0), b2, voffB);
;     ...
;             PG8_LDA(At, 1, 1); PG8_STAGE(PG8_SA(1, 0), a3, voffA);
;             PG8_BAR; PG8_WAIT_L(0); PG8_MMA(1, 0, At, B0); PG8_BAR; PG8_SCHED;
;             PG8_STAGE(PG8_SB(1, 1), b3 + hstep, voffB);
;             PG8_WAIT_V(6); PG8_BAR; PG8_MMA(1, 1, At, B1); PG8_BAR;
	s_waitcnt lgkmcnt(0)
	s_waitcnt lgkmcnt(0)
	v_mfma_f32_16x16x32_bf16 v[60:63], v[128:131], v[154:157], v[60:63]
	v_mfma_f32_16x16x32_bf16 v[56:59], v[136:139], v[154:157], v[56:59]
	v_mfma_f32_16x16x32_bf16 v[44:47], v[128:131], v[170:173], v[44:47]
	v_mfma_f32_16x16x32_bf16 v[40:43], v[136:139], v[170:173], v[40:43]
	v_mfma_f32_16x16x32_bf16 v[28:31], v[128:131], v[178:181], v[28:31]
	v_mfma_f32_16x16x32_bf16 v[24:27], v[136:139], v[178:181], v[24:27]
	v_mfma_f32_16x16x32_bf16 v[12:15], v[128:131], v[196:199], v[12:15]
	v_mfma_f32_16x16x32_bf16 v[8:11], v[136:139], v[196:199], v[8:11]
	v_mfma_f32_16x16x32_bf16 v[60:63], v[132:135], v[158:161], v[60:63]
	v_mfma_f32_16x16x32_bf16 v[56:59], v[140:143], v[158:161], v[56:59]
	v_mfma_f32_16x16x32_bf16 v[44:47], v[132:135], v[174:177], v[44:47]
	v_mfma_f32_16x16x32_bf16 v[40:43], v[140:143], v[174:177], v[40:43]
	v_mfma_f32_16x16x32_bf16 v[28:31], v[132:135], v[192:195], v[28:31]
	v_mfma_f32_16x16x32_bf16 v[24:27], v[140:143], v[192:195], v[24:27]
	v_mfma_f32_16x16x32_bf16 v[12:15], v[132:135], v[200:203], v[12:15]
	v_mfma_f32_16x16x32_bf16 v[8:11], v[140:143], v[200:203], v[8:11]
	s_barrier
	s_add_i32 s4, s10, s37
	v_lshl_add_u64 v[128:129], v[224:225], 0, s[66:67]
	s_mov_b32 m0, s4
	s_nop 0
	global_load_lds_dwordx4 v[128:129], off
	v_lshl_add_u64 v[128:129], v[226:227], 0, s[66:67]
	s_add_i32 m0, s4, 0x2000
	s_nop 0
	global_load_lds_dwordx4 v[128:129], off
	s_waitcnt vmcnt(6)
	s_barrier
	v_mfma_f32_16x16x32_bf16 v[52:55], v[204:207], v[154:157], v[52:55]
	v_mfma_f32_16x16x32_bf16 v[48:51], v[212:215], v[154:157], v[48:51]
	v_mfma_f32_16x16x32_bf16 v[36:39], v[204:207], v[170:173], v[36:39]
	v_mfma_f32_16x16x32_bf16 v[32:35], v[212:215], v[170:173], v[32:35]
	v_mfma_f32_16x16x32_bf16 v[20:23], v[204:207], v[178:181], v[20:23]
	v_mfma_f32_16x16x32_bf16 v[16:19], v[212:215], v[178:181], v[16:19]
	v_mfma_f32_16x16x32_bf16 v[4:7], v[204:207], v[196:199], v[4:7]
	v_mfma_f32_16x16x32_bf16 v[0:3], v[212:215], v[196:199], v[0:3]
	v_mfma_f32_16x16x32_bf16 v[52:55], v[208:211], v[158:161], v[52:55]
	v_mfma_f32_16x16x32_bf16 v[48:51], v[216:219], v[158:161], v[48:51]
	v_mfma_f32_16x16x32_bf16 v[36:39], v[208:211], v[174:177], v[36:39]
	v_mfma_f32_16x16x32_bf16 v[32:35], v[216:219], v[174:177], v[32:35]
	v_mfma_f32_16x16x32_bf16 v[20:23], v[208:211], v[192:195], v[20:23]
	v_mfma_f32_16x16x32_bf16 v[16:19], v[216:219], v[192:195], v[16:19]
	v_mfma_f32_16x16x32_bf16 v[4:7], v[208:211], v[200:203], v[4:7]
	v_mfma_f32_16x16x32_bf16 v[0:3], v[216:219], v[200:203], v[0:3]
	s_add_u32 s2, s2, 0x100
	s_addc_u32 s3, s3, 0
	s_add_u32 s14, s14, 0x100
	s_addc_u32 s15, s15, 0
	s_cmp_ge_i32 s5, s95
	s_mov_b32 s4, s5
	s_barrier
	s_cbranch_scc0 .LBB0_399
	s_branch .Lpeel_exit_0
.LBB0_399:
	s_add_i32 s5, s4, 2
	s_add_u32 s10, s2, 0x80
	s_addc_u32 s11, s3, 0
	s_add_i32 s17, s56, 0x100
	v_add_u32_e32 v140, s17, v190
	ds_read_b128 v[128:131], v140
	ds_read_b128 v[132:135], v140 offset:1024
	ds_read_b128 v[136:139], v140 offset:2048
	ds_read_b128 v[140:143], v140 offset:3072
	s_cmp_eq_u32 s70, s4
	s_cselect_b32 s11, s53, s11
	s_cselect_b32 s10, s52, s10
	s_cselect_b32 s13, s59, s15
	s_cselect_b32 s12, s58, s14
	v_lshl_add_u64 v[162:163], s[2:3], 0, v[150:151]
	s_add_i32 m0, s87, 0xc000
	ds_read_b128 v[154:157], v191
	ds_read_b128 v[158:161], v191 offset:1024
	ds_read_b128 v[170:173], v191 offset:2048
	ds_read_b128 v[174:177], v191 offset:3072
	ds_read_b128 v[178:181], v191 offset:4096
	ds_read_b128 v[192:195], v191 offset:5120
	ds_read_b128 v[196:199], v191 offset:6144
	ds_read_b128 v[200:203], v191 offset:7168
	global_load_lds_dwordx4 v[162:163], off
	v_lshl_add_u64 v[162:163], s[2:3], 0, v[152:153]
	s_add_i32 m0, s87, 0xe000
	s_nop 0
	global_load_lds_dwordx4 v[162:163], off
	s_waitcnt lgkmcnt(8)
	s_barrier
	s_waitcnt lgkmcnt(0)
	s_waitcnt lgkmcnt(0)
	v_mfma_f32_16x16x32_bf16 v[124:127], v[128:131], v[154:157], v[124:127]
	v_mfma_f32_16x16x32_bf16 v[120:123], v[136:139], v[154:157], v[120:123]
	v_mfma_f32_16x16x32_bf16 v[108:111], v[128:131], v[170:173], v[108:111]
	v_mfma_f32_16x16x32_bf16 v[104:107], v[136:139], v[170:173], v[104:107]
	v_mfma_f32_16x16x32_bf16 v[92:95], v[128:131], v[178:181], v[92:95]
	v_mfma_f32_16x16x32_bf16 v[88:91], v[136:139], v[178:181], v[88:91]
	v_mfma_f32_16x16x32_bf16 v[76:79], v[128:131], v[196:199], v[76:79]
	v_mfma_f32_16x16x32_bf16 v[72:75], v[136:139], v[196:199], v[72:75]
	v_mfma_f32_16x16x32_bf16 v[124:127], v[132:135], v[158:161], v[124:127]
	v_mfma_f32_16x16x32_bf16 v[120:123], v[140:143], v[158:161], v[120:123]
	v_mfma_f32_16x16x32_bf16 v[108:111], v[132:135], v[174:177], v[108:111]
	v_mfma_f32_16x16x32_bf16 v[104:107], v[140:143], v[174:177], v[104:107]
	v_mfma_f32_16x16x32_bf16 v[92:95], v[132:135], v[192:195], v[92:95]
	v_mfma_f32_16x16x32_bf16 v[88:91], v[140:143], v[192:195], v[88:91]
	v_mfma_f32_16x16x32_bf16 v[76:79], v[132:135], v[200:203], v[76:79]
	v_mfma_f32_16x16x32_bf16 v[72:75], v[140:143], v[200:203], v[72:75]
	s_barrier
	s_add_i32 s4, s57, 0x100
	v_add_u32_e32 v162, s4, v190
	s_add_i32 s17, s17, s37
	ds_read_b128 v[204:207], v162
	ds_read_b128 v[208:211], v162 offset:1024
	ds_read_b128 v[212:215], v162 offset:2048
	ds_read_b128 v[216:219], v162 offset:3072
	v_lshl_add_u64 v[162:163], s[12:13], 0, v[166:167]
	s_mov_b32 m0, s17
	v_lshl_add_u64 v[182:183], s[12:13], 0, v[148:149]
	global_load_lds_dwordx4 v[162:163], off
	s_add_i32 m0, s17, 0x2000
	s_nop 0
	global_load_lds_dwordx4 v[182:183], off
	s_barrier
; #define PG8_STAGE(bufoff, gbase, voff) do { _Pragma("unroll") for (int _i = 0; _i < 2; ++_i) \
;         __builtin_amdgcn_global_load_lds((const unsigned*)((const char*)(gbase) + (voff)[_i]), (LAS unsigned*)(lds + (bufoff) + ldsw + _i * 8192), 16, 0, 0); } while (0)
; #define PG8_LDA(dst, b, h) do { _Pragma("unroll") for (int m = 0; m < 4; ++m) _Pragma("unroll") for (int k = 0; k < 2; ++k) dst[m][k] = *(const LAS bf16x8*)(lds + PG8_SA(b, h) + aoff + m * 2048 + k * 1024); } while (0)
; #define PG8_LDB(dst, b, h) do { _Pragma("unroll") for (int n = 0; n < 2; ++n) _Pragma("unroll") for (int k = 0; k < 2; ++k) dst[n][k] = *(const LAS bf16x8*)(lds + PG8_SB(b, h) + boff + n * 2048 + k * 1024); } while (0)
; #define PG8_MMA(ai, bj, At, Bt) do { __builtin_amdgcn_s_setprio(1); _Pragma("unroll") for (int m = 0; m < 4; ++m) _Pragma("unroll") for (int n = 0; n < 2; ++n) _Pragma("unroll") for (int k = 0; k < 2; ++k) \
;         acc[ai][bj][m][n] = __builtin_amdgcn_mfma_f32_16x16x32_bf16(Bt[n][k], At[m][k], acc[ai][bj][m][n], 0, 0, 0); __builtin_amdgcn_s_setprio(0); } while (0)
; #define PG8_WAIT_V(n) asm volatile("s_waitcnt vmcnt(" #n ")" ::: "memory")
; #define PG8_WAIT_L(n) asm volatile("s_waitcnt lgkmcnt(" #n ")" ::: "memory")
; #define PG8_BAR __builtin_amdgcn_s_barrier()
; #define PG8_SCHED __builtin_amdgcn_sched_barrier(0)
; template <class Epi>
; DI void gemm_phase(LAS unsigned char* lds, const Gemm g, const StaticOrder& S, const Epi& E) {
;     ...
;             PG8_BAR; PG8_WAIT_L(0); PG8_MMA(0, 1, At, B1); PG8_BAR;
;             PG8_LDA(At, 0, 1); PG8_STAGE(PG8_SA(0, 0), a2, voffA);
;             PG8_BAR; PG8_WAIT_L(0); PG8_MMA(1, 0, At, B0); PG8_BAR; PG8_SCHED;
;             PG8_STAGE(PG8_SB(0, 1), b2 + hstep, voffB);
;             PG8_WAIT_V(6); PG8_BAR; PG8_MMA(1, 1, At, B1); PG8_BAR;
;             PG8_LDB(B0, 1, 0); PG8_SCHED; PG8_LDA(At, 1, 0); PG8_STAGE(PG8_SA(0, 1), a2 + hstep, voffA);
;             PG8_WAIT_L(8); PG8_BAR; PG8_WAIT_L(0); PG8_MMA(0, 0, At, B0); PG8_BAR; PG8_SCHED;
	s_waitcnt lgkmcnt(0)
	s_waitcnt lgkmcnt(0)
	v_mfma_f32_16x16x32_bf16 v[116:119], v[204:207], v[154:157], v[116:119]
	v_mfma_f32_16x16x32_bf16 v[112:115], v[212:215], v[154:157], v[112:115]
	v_mfma_f32_16x16x32_bf16 v[100:103], v[204:207], v[170:173], v[100:103]
	v_mfma_f32_16x16x32_bf16 v[96:99], v[212:215], v[170:173], v[96:99]
	v_mfma_f32_16x16x32_bf16 v[84:87], v[204:207], v[178:181], v[84:87]
	v_mfma_f32_16x16x32_bf16 v[80:83], v[212:215], v[178:181], v[80:83]
	v_mfma_f32_16x16x32_bf16 v[68:71], v[204:207], v[196:199], v[68:71]
	v_mfma_f32_16x16x32_bf16 v[64:67], v[212:215], v[196:199], v[64:67]
	v_mfma_f32_16x16x32_bf16 v[116:119], v[208:211], v[158:161], v[116:119]
	v_mfma_f32_16x16x32_bf16 v[112:115], v[216:219], v[158:161], v[112:115]
	v_mfma_f32_16x16x32_bf16 v[100:103], v[208:211], v[174:177], v[100:103]
	v_mfma_f32_16x16x32_bf16 v[96:99], v[216:219], v[174:177], v[96:99]
	v_mfma_f32_16x16x32_bf16 v[84:87], v[208:211], v[192:195], v[84:87]
	v_mfma_f32_16x16x32_bf16 v[80:83], v[216:219], v[192:195], v[80:83]
	v_mfma_f32_16x16x32_bf16 v[68:71], v[208:211], v[200:203], v[68:71]
	v_mfma_f32_16x16x32_bf16 v[64:67], v[216:219], v[200:203], v[64:67]
	s_mov_b32 m0, s87
	v_lshl_add_u64 v[220:221], s[10:11], 0, v[144:145]
	s_barrier
	ds_read_b128 v[154:157], v191 offset:16384
	ds_read_b128 v[158:161], v191 offset:17408
	ds_read_b128 v[170:173], v191 offset:18432
	ds_read_b128 v[174:177], v191 offset:19456
	ds_read_b128 v[178:181], v191 offset:20480
	ds_read_b128 v[192:195], v191 offset:21504
	ds_read_b128 v[196:199], v191 offset:22528
	ds_read_b128 v[200:203], v191 offset:23552
	global_load_lds_dwordx4 v[220:221], off
	v_lshl_add_u64 v[222:223], s[10:11], 0, v[146:147]
	s_mov_b32 m0, s77
	s_nop 0
	global_load_lds_dwordx4 v[222:223], off
	s_barrier
	s_waitcnt lgkmcnt(0)
	s_waitcnt lgkmcnt(0)
	v_mfma_f32_16x16x32_bf16 v[60:63], v[128:131], v[154:157], v[60:63]
	v_mfma_f32_16x16x32_bf16 v[56:59], v[136:139], v[154:157], v[56:59]
	v_mfma_f32_16x16x32_bf16 v[44:47], v[128:131], v[170:173], v[44:47]
	v_mfma_f32_16x16x32_bf16 v[40:43], v[136:139], v[170:173], v[40:43]
	v_mfma_f32_16x16x32_bf16 v[28:31], v[128:131], v[178:181], v[28:31]
	v_mfma_f32_16x16x32_bf16 v[24:27], v[136:139], v[178:181], v[24:27]
	v_mfma_f32_16x16x32_bf16 v[12:15], v[128:131], v[196:199], v[12:15]
	v_mfma_f32_16x16x32_bf16 v[8:11], v[136:139], v[196:199], v[8:11]
	v_mfma_f32_16x16x32_bf16 v[60:63], v[132:135], v[158:161], v[60:63]
	v_mfma_f32_16x16x32_bf16 v[56:59], v[140:143], v[158:161], v[56:59]
	v_mfma_f32_16x16x32_bf16 v[44:47], v[132:135], v[174:177], v[44:47]
	v_mfma_f32_16x16x32_bf16 v[40:43], v[140:143], v[174:177], v[40:43]
	v_mfma_f32_16x16x32_bf16 v[28:31], v[132:135], v[192:195], v[28:31]
	v_mfma_f32_16x16x32_bf16 v[24:27], v[140:143], v[192:195], v[24:27]
	v_mfma_f32_16x16x32_bf16 v[12:15], v[132:135], v[200:203], v[12:15]
	v_mfma_f32_16x16x32_bf16 v[8:11], v[140:143], v[200:203], v[8:11]
	s_barrier
	s_add_u32 s12, s12, s48
	s_addc_u32 s13, s13, s49
	s_add_i32 s4, s4, s37
	v_lshl_add_u64 v[224:225], s[12:13], 0, v[166:167]
	s_mov_b32 m0, s4
	v_lshl_add_u64 v[226:227], s[12:13], 0, v[148:149]
	global_load_lds_dwordx4 v[224:225], off
	s_add_i32 m0, s4, 0x2000
	s_nop 0
	global_load_lds_dwordx4 v[226:227], off
	s_waitcnt vmcnt(6)
	s_barrier
	v_mfma_f32_16x16x32_bf16 v[52:55], v[204:207], v[154:157], v[52:55]
	v_mfma_f32_16x16x32_bf16 v[48:51], v[212:215], v[154:157], v[48:51]
	v_mfma_f32_16x16x32_bf16 v[36:39], v[204:207], v[170:173], v[36:39]
	v_mfma_f32_16x16x32_bf16 v[32:35], v[212:215], v[170:173], v[32:35]
	v_mfma_f32_16x16x32_bf16 v[20:23], v[204:207], v[178:181], v[20:23]
	v_mfma_f32_16x16x32_bf16 v[16:19], v[212:215], v[178:181], v[16:19]
	v_mfma_f32_16x16x32_bf16 v[4:7], v[204:207], v[196:199], v[4:7]
	v_mfma_f32_16x16x32_bf16 v[0:3], v[212:215], v[196:199], v[0:3]
	v_mfma_f32_16x16x32_bf16 v[52:55], v[208:211], v[158:161], v[52:55]
	v_mfma_f32_16x16x32_bf16 v[48:51], v[216:219], v[158:161], v[48:51]
	v_mfma_f32_16x16x32_bf16 v[36:39], v[208:211], v[174:177], v[36:39]
	v_mfma_f32_16x16x32_bf16 v[32:35], v[216:219], v[174:177], v[32:35]
	v_mfma_f32_16x16x32_bf16 v[20:23], v[208:211], v[192:195], v[20:23]
	v_mfma_f32_16x16x32_bf16 v[16:19], v[216:219], v[192:195], v[16:19]
	v_mfma_f32_16x16x32_bf16 v[4:7], v[208:211], v[200:203], v[4:7]
	v_mfma_f32_16x16x32_bf16 v[0:3], v[216:219], v[200:203], v[0:3]
	s_add_i32 s4, s64, 0x100
	v_add_u32_e32 v140, s4, v190
	s_barrier
	ds_read_b128 v[128:131], v140
	ds_read_b128 v[132:135], v140 offset:1024
	ds_read_b128 v[136:139], v140 offset:2048
	ds_read_b128 v[140:143], v140 offset:3072
	s_add_u32 s10, s10, s48
	s_addc_u32 s11, s11, s49
	s_mov_b32 m0, s80
	v_lshl_add_u64 v[204:205], s[10:11], 0, v[144:145]
	ds_read_b128 v[154:157], v191 offset:32768
	ds_read_b128 v[158:161], v191 offset:33792
	ds_read_b128 v[170:173], v191 offset:34816
	ds_read_b128 v[174:177], v191 offset:35840
	ds_read_b128 v[178:181], v191 offset:36864
	ds_read_b128 v[192:195], v191 offset:37888
	ds_read_b128 v[196:199], v191 offset:38912
	ds_read_b128 v[200:203], v191 offset:39936
	global_load_lds_dwordx4 v[204:205], off
	v_lshl_add_u64 v[204:205], s[10:11], 0, v[146:147]
	s_mov_b32 m0, s81
	s_nop 0
	global_load_lds_dwordx4 v[204:205], off
	s_waitcnt lgkmcnt(8)
	s_barrier
; #define PG8_STAGE(bufoff, gbase, voff) do { _Pragma("unroll") for (int _i = 0; _i < 2; ++_i) \
;         __builtin_amdgcn_global_load_lds((const unsigned*)((const char*)(gbase) + (voff)[_i]), (LAS unsigned*)(lds + (bufoff) + ldsw + _i * 8192), 16, 0, 0); } while (0)
; #define PG8_LDA(dst, b, h) do { _Pragma("unroll") for (int m = 0; m < 4; ++m) _Pragma("unroll") for (int k = 0; k < 2; ++k) dst[m][k] = *(const LAS bf16x8*)(lds + PG8_SA(b, h) + aoff + m * 2048 + k * 1024); } while (0)
; #define PG8_LDB(dst, b, h) do { _Pragma("unroll") for (int n = 0; n < 2; ++n) _Pragma("unroll") for (int k = 0; k < 2; ++k) dst[n][k] = *(const LAS bf16x8*)(lds + PG8_SB(b, h) + boff + n * 2048 + k * 1024); } while (0)
; #define PG8_MMA(ai, bj, At, Bt) do { __builtin_amdgcn_s_setprio(1); _Pragma("unroll") for (int m = 0; m < 4; ++m) _Pragma("unroll") for (int n = 0; n < 2; ++n) _Pragma("unroll") for (int k = 0; k < 2; ++k) \
;         acc[ai][bj][m][n] = __builtin_amdgcn_mfma_f32_16x16x32_bf16(Bt[n][k], At[m][k], acc[ai][bj][m][n], 0, 0, 0); __builtin_amdgcn_s_setprio(0); } while (0)
; #define PG8_WAIT_V(n) asm volatile("s_waitcnt vmcnt(" #n ")" ::: "memory")
; #define PG8_WAIT_L(n) asm volatile("s_waitcnt lgkmcnt(" #n ")" ::: "memory")
; #define PG8_BAR __builtin_amdgcn_s_barrier()
; #define PG8_SCHED __builtin_amdgcn_sched_barrier(0)
; template <class Epi>
; DI void gemm_phase(LAS unsigned char* lds, const Gemm g, const StaticOrder& S, const Epi& E) {
;     ...
;             PG8_WAIT_L(8); PG8_BAR; PG8_WAIT_L(0); PG8_MMA(0, 0, At, B0); PG8_BAR; PG8_SCHED;
;             PG8_LDB(B1, 1, 1); PG8_STAGE(PG8_SB(1, 0), b3, voffB);
;             PG8_BAR; PG8_WAIT_L(0); PG8_MMA(0, 1, At, B1); PG8_BAR;
;             PG8_LDA(At, 1, 1); PG8_STAGE(PG8_SA(1, 0), a3, voffA);
;             PG8_BAR; PG8_WAIT_L(0); PG8_MMA(1, 0, At, B0); PG8_BAR; PG8_SCHED;
;             PG8_STAGE(PG8_SB(1, 1), b3 + hstep, voffB);
;             PG8_WAIT_V(6); PG8_BAR; PG8_MMA(1, 1, At, B1); PG8_BAR;
;         }
	s_waitcnt lgkmcnt(0)
	s_waitcnt lgkmcnt(0)
	v_mfma_f32_16x16x32_bf16 v[124:127], v[128:131], v[154:157], v[124:127]
	v_mfma_f32_16x16x32_bf16 v[120:123], v[136:139], v[154:157], v[120:123]
	v_mfma_f32_16x16x32_bf16 v[108:111], v[128:131], v[170:173], v[108:111]
	v_mfma_f32_16x16x32_bf16 v[104:107], v[136:139], v[170:173], v[104:107]
	v_mfma_f32_16x16x32_bf16 v[92:95], v[128:131], v[178:181], v[92:95]
	v_mfma_f32_16x16x32_bf16 v[88:91], v[136:139], v[178:181], v[88:91]
	v_mfma_f32_16x16x32_bf16 v[76:79], v[128:131], v[196:199], v[76:79]
	v_mfma_f32_16x16x32_bf16 v[72:75], v[136:139], v[196:199], v[72:75]
	v_mfma_f32_16x16x32_bf16 v[124:127], v[132:135], v[158:161], v[124:127]
	v_mfma_f32_16x16x32_bf16 v[120:123], v[140:143], v[158:161], v[120:123]
	v_mfma_f32_16x16x32_bf16 v[108:111], v[132:135], v[174:177], v[108:111]
	v_mfma_f32_16x16x32_bf16 v[104:107], v[140:143], v[174:177], v[104:107]
	v_mfma_f32_16x16x32_bf16 v[92:95], v[132:135], v[192:195], v[92:95]
	v_mfma_f32_16x16x32_bf16 v[88:91], v[140:143], v[192:195], v[88:91]
	v_mfma_f32_16x16x32_bf16 v[76:79], v[132:135], v[200:203], v[76:79]
	v_mfma_f32_16x16x32_bf16 v[72:75], v[140:143], v[200:203], v[72:75]
	s_barrier
	s_add_i32 s10, s33, 0x100
	s_add_i32 s4, s4, s37
	v_add_u32_e32 v216, s10, v190
	v_lshl_add_u64 v[162:163], v[162:163], 0, s[66:67]
	s_mov_b32 m0, s4
	ds_read_b128 v[204:207], v216
	ds_read_b128 v[208:211], v216 offset:1024
	ds_read_b128 v[212:215], v216 offset:2048
	ds_read_b128 v[216:219], v216 offset:3072
	global_load_lds_dwordx4 v[162:163], off
	v_lshl_add_u64 v[162:163], v[182:183], 0, s[66:67]
	s_add_i32 m0, s4, 0x2000
	s_nop 0
	global_load_lds_dwordx4 v[162:163], off
	s_barrier
	s_waitcnt lgkmcnt(0)
	s_waitcnt lgkmcnt(0)
	v_mfma_f32_16x16x32_bf16 v[116:119], v[204:207], v[154:157], v[116:119]
	v_mfma_f32_16x16x32_bf16 v[112:115], v[212:215], v[154:157], v[112:115]
	v_mfma_f32_16x16x32_bf16 v[100:103], v[204:207], v[170:173], v[100:103]
	v_mfma_f32_16x16x32_bf16 v[96:99], v[212:215], v[170:173], v[96:99]
	v_mfma_f32_16x16x32_bf16 v[84:87], v[204:207], v[178:181], v[84:87]
	v_mfma_f32_16x16x32_bf16 v[80:83], v[212:215], v[178:181], v[80:83]
	v_mfma_f32_16x16x32_bf16 v[68:71], v[204:207], v[196:199], v[68:71]
	v_mfma_f32_16x16x32_bf16 v[64:67], v[212:215], v[196:199], v[64:67]
	v_mfma_f32_16x16x32_bf16 v[116:119], v[208:211], v[158:161], v[116:119]
	v_mfma_f32_16x16x32_bf16 v[112:115], v[216:219], v[158:161], v[112:115]
	v_mfma_f32_16x16x32_bf16 v[100:103], v[208:211], v[174:177], v[100:103]
	v_mfma_f32_16x16x32_bf16 v[96:99], v[216:219], v[174:177], v[96:99]
	v_mfma_f32_16x16x32_bf16 v[84:87], v[208:211], v[192:195], v[84:87]
	v_mfma_f32_16x16x32_bf16 v[80:83], v[216:219], v[192:195], v[80:83]
	v_mfma_f32_16x16x32_bf16 v[68:71], v[208:211], v[200:203], v[68:71]
	v_mfma_f32_16x16x32_bf16 v[64:67], v[216:219], v[200:203], v[64:67]
	s_mov_b32 m0, s82
	v_lshl_add_u64 v[162:163], v[220:221], 0, s[66:67]
	s_barrier
	ds_read_b128 v[154:157], v191 offset:49152
	ds_read_b128 v[158:161], v191 offset:50176
	ds_read_b128 v[170:173], v191 offset:51200
	ds_read_b128 v[174:177], v191 offset:52224
	ds_read_b128 v[178:181], v191 offset:53248
	ds_read_b128 v[192:195], v191 offset:54272
	ds_read_b128 v[196:199], v191 offset:55296
	ds_read_b128 v[200:203], v191 offset:56320
	global_load_lds_dwordx4 v[162:163], off
	v_lshl_add_u64 v[162:163], v[222:223], 0, s[66:67]
	s_mov_b32 m0, s83
	s_nop 0
	global_load_lds_dwordx4 v[162:163], off
	s_barrier
	s_waitcnt lgkmcnt(0)
	s_waitcnt lgkmcnt(0)
	v_mfma_f32_16x16x32_bf16 v[60:63], v[128:131], v[154:157], v[60:63]
	v_mfma_f32_16x16x32_bf16 v[56:59], v[136:139], v[154:157], v[56:59]
	v_mfma_f32_16x16x32_bf16 v[44:47], v[128:131], v[170:173], v[44:47]
	v_mfma_f32_16x16x32_bf16 v[40:43], v[136:139], v[170:173], v[40:43]
	v_mfma_f32_16x16x32_bf16 v[28:31], v[128:131], v[178:181], v[28:31]
	v_mfma_f32_16x16x32_bf16 v[24:27], v[136:139], v[178:181], v[24:27]
	v_mfma_f32_16x16x32_bf16 v[12:15], v[128:131], v[196:199], v[12:15]
	v_mfma_f32_16x16x32_bf16 v[8:11], v[136:139], v[196:199], v[8:11]
	v_mfma_f32_16x16x32_bf16 v[60:63], v[132:135], v[158:161], v[60:63]
	v_mfma_f32_16x16x32_bf16 v[56:59], v[140:143], v[158:161], v[56:59]
	v_mfma_f32_16x16x32_bf16 v[44:47], v[132:135], v[174:177], v[44:47]
	v_mfma_f32_16x16x32_bf16 v[40:43], v[140:143], v[174:177], v[40:43]
	v_mfma_f32_16x16x32_bf16 v[28:31], v[132:135], v[192:195], v[28:31]
	v_mfma_f32_16x16x32_bf16 v[24:27], v[140:143], v[192:195], v[24:27]
	v_mfma_f32_16x16x32_bf16 v[12:15], v[132:135], v[200:203], v[12:15]
	v_mfma_f32_16x16x32_bf16 v[8:11], v[140:143], v[200:203], v[8:11]
	s_barrier
	s_add_i32 s4, s10, s37
	v_lshl_add_u64 v[128:129], v[224:225], 0, s[66:67]
	s_mov_b32 m0, s4
	s_nop 0
	global_load_lds_dwordx4 v[128:129], off
	v_lshl_add_u64 v[128:129], v[226:227], 0, s[66:67]
	s_add_i32 m0, s4, 0x2000
	s_nop 0
	global_load_lds_dwordx4 v[128:129], off
	s_waitcnt vmcnt(6)
	s_barrier
	v_mfma_f32_16x16x32_bf16 v[52:55], v[204:207], v[154:157], v[52:55]
	v_mfma_f32_16x16x32_bf16 v[48:51], v[212:215], v[154:157], v[48:51]
	v_mfma_f32_16x16x32_bf16 v[36:39], v[204:207], v[170:173], v[36:39]
	v_mfma_f32_16x16x32_bf16 v[32:35], v[212:215], v[170:173], v[32:35]
	v_mfma_f32_16x16x32_bf16 v[20:23], v[204:207], v[178:181], v[20:23]
	v_mfma_f32_16x16x32_bf16 v[16:19], v[212:215], v[178:181], v[16:19]
	v_mfma_f32_16x16x32_bf16 v[4:7], v[204:207], v[196:199], v[4:7]
	v_mfma_f32_16x16x32_bf16 v[0:3], v[212:215], v[196:199], v[0:3]
	v_mfma_f32_16x16x32_bf16 v[52:55], v[208:211], v[158:161], v[52:55]
	v_mfma_f32_16x16x32_bf16 v[48:51], v[216:219], v[158:161], v[48:51]
	v_mfma_f32_16x16x32_bf16 v[36:39], v[208:211], v[174:177], v[36:39]
	v_mfma_f32_16x16x32_bf16 v[32:35], v[216:219], v[174:177], v[32:35]
	v_mfma_f32_16x16x32_bf16 v[20:23], v[208:211], v[192:195], v[20:23]
	v_mfma_f32_16x16x32_bf16 v[16:19], v[216:219], v[192:195], v[16:19]
	v_mfma_f32_16x16x32_bf16 v[4:7], v[208:211], v[200:203], v[4:7]
	v_mfma_f32_16x16x32_bf16 v[0:3], v[216:219], v[200:203], v[0:3]
	s_add_u32 s2, s2, 0x100
	s_addc_u32 s3, s3, 0
	s_add_u32 s14, s14, 0x100
	s_addc_u32 s15, s15, 0
	s_cmp_ge_i32 s5, s95
	s_mov_b32 s4, s5
	s_barrier
	s_cbranch_scc0 .LBB0_399

; #define PG8_WAIT_V(n) asm volatile("s_waitcnt vmcnt(" #n ")" ::: "memory")
; #define PG8_BAR __builtin_amdgcn_s_barrier()
; template <class Epi>
; DI void gemm_phase(LAS unsigned char* lds, const Gemm g, const StaticOrder& S, const Epi& E) {
;     ...
;     PG8_WAIT_V(0);
;     if (wr == 0) PG8_BAR;
;     PG8_BAR;
.LBB0_577:
	v_readlane_b32 s36, v237, 62
	v_readlane_b32 s33, v236, 20
	s_barrier
	s_setprio 0
	v_readlane_b32 s37, v237, 63
	v_readlane_b32 s38, v236, 0
	v_readlane_b32 s39, v236, 1
	v_readlane_b32 s40, v236, 2
	v_readlane_b32 s41, v236, 3
	v_readlane_b32 s42, v236, 4
	v_readlane_b32 s43, v236, 5
	v_readlane_b32 s44, v236, 6
	v_readlane_b32 s45, v236, 7
	v_readlane_b32 s46, v236, 8
	v_readlane_b32 s47, v236, 9
	v_readlane_b32 s48, v236, 10
	v_readlane_b32 s49, v236, 11
	v_readlane_b32 s50, v236, 12
	v_readlane_b32 s51, v236, 13

; #define PG8_STAGE(bufoff, gbase, voff) do { _Pragma("unroll") for (int _i = 0; _i < 2; ++_i) \
;         __builtin_amdgcn_global_load_lds((const unsigned*)((const char*)(gbase) + (voff)[_i]), (LAS unsigned*)(lds + (bufoff) + ldsw + _i * 8192), 16, 0, 0); } while (0)
; #define PG8_BAR __builtin_amdgcn_s_barrier()
; template <class Epi>
; DI void gemm_phase(LAS unsigned char* lds, const Gemm g, const StaticOrder& S, const Epi& E) {
;     ...
;     for (int i = 0; i < 2; ++i) { int R, C; stage_rc(tid * 16 + i * 8192, R, C); const int Rb = (R & ~31) + perm32(R & 31);
;         voffA[i] = (unsigned)(R * K + C) * 2u; voffB[i] = (unsigned)(Rb * K + C) * 2u; }
;     const size_t kstep = (size_t)(BK * 2);
;     const size_t hstep = (size_t)HALF * K * 2;
;     const size_t tstep = 2 * hstep;
;     const unsigned ldsw = (unsigned)wid * 1024u;
;     const int aoff = lds_byte(wr * 64 + fr, fq * 8), boff = lds_byte(wc * 32 + fr, fq * 8);
;     ...
;     Unit cur, nxt; int ui = 0;
;     if (!S.next(0, cur)) return;
;     f32x4 acc[2][2][4][2];
; #pragma unroll
;     for (int a = 0; a < 2; ++a)
; #pragma unroll
;         for (int b = 0; b < 2; ++b)
; #pragma unroll
;             for (int m = 0; m < 4; ++m)
; #pragma unroll
;                 for (int n = 0; n < 2; ++n) acc[a][b][m][n] = (f32x4){0.f, 0.f, 0.f, 0.f};
;     bf16x8 At[4][2], B0[2][2], B1[2][2];
;     const char* cA = (const char*)g.A + (size_t)cur.pm * tstep; const char* cB = (const char*)g.Bt + (size_t)cur.pn * tstep;
;     PG8_STAGE(PG8_SB(0, 0), cB, voffB); PG8_STAGE(PG8_SA(0, 0), cA, voffA); PG8_STAGE(PG8_SB(0, 1), cB + hstep, voffB); PG8_STAGE(PG8_SA(0, 1), cA + hstep, voffA);
;     if (wr == 1) PG8_BAR;
.LBB0_632:
	v_readlane_b32 s68, v238, 23
	s_andn2_b64 vcc, exec, s[10:11]
	v_readlane_b32 s69, v238, 24
	s_cbranch_vccnz .LBB0_705
	v_bfe_i32 v2, v18, 27, 1
	v_lshlrev_b32_e32 v0, 4, v18
	v_lshrrev_b32_e32 v2, 22, v2
	v_add_u32_e32 v2, v0, v2
	v_and_b32_e32 v2, 0xfffffc00, v2
	v_ashrrev_i32_e32 v1, 31, v18
	v_sub_u32_e32 v2, v0, v2
	v_lshrrev_b32_e32 v1, 26, v1
	v_lshrrev_b32_e32 v3, 4, v2
	v_add_u32_e32 v1, v18, v1
	v_bitop3_b32 v3, v3, v2, 32 bitop3:0x6c
	v_ashrrev_i32_e32 v2, 31, v2
	v_ashrrev_i32_e32 v1, 6, v1
	v_lshrrev_b32_e32 v2, 26, v2
	v_lshlrev_b32_e32 v4, 3, v1
	v_add_u32_e32 v2, v3, v2
	v_and_b32_e32 v4, -16, v4
	v_ashrrev_i32_e32 v2, 6, v2
	v_lshlrev_b32_e32 v1, 5, v1
	v_add_u32_e32 v4, v2, v4
	v_and_b32_e32 v12, 32, v1
	v_mul_i32_i24_e32 v1, 64, v2
	v_sub_u32_e32 v1, v3, v1
	v_lshlrev_b32_e32 v3, 1, v4
	v_lshrrev_b32_e32 v5, 2, v4
	v_and_b32_e32 v2, 3, v2
	s_mov_b32 s4, 0x7fffffe0
	v_ashrrev_i16_sdwa v1, v169, sext(v1) dst_sel:DWORD dst_unused:UNUSED_PAD src0_sel:DWORD src1_sel:BYTE_0
	v_and_b32_e32 v3, 24, v3
	v_and_b32_e32 v5, 4, v5
	v_and_or_b32 v2, v4, s4, v2
	v_bfe_i32 v13, v1, 0, 16
	v_or3_b32 v2, v2, v5, v3
	v_add_u32_e32 v1, v12, v13
	v_mul_lo_u32 v14, v4, s14
	v_mul_lo_u32 v2, v2, s14
	v_add_u32_e32 v0, 0x2000, v0
	v_add_lshl_u32 v128, v1, v14, 1
	v_add_lshl_u32 v130, v2, v1, 1
	v_ashrrev_i32_e32 v1, 31, v0
	v_lshrrev_b32_e32 v1, 22, v1
	v_add_u32_e32 v1, v0, v1
	v_ashrrev_i32_e32 v1, 10, v1
	v_mul_i32_i24_e32 v2, 0x400, v1
	v_sub_u32_e32 v0, v0, v2
	v_lshrrev_b32_e32 v2, 4, v0
	s_add_u32 s52, s86, 0x600000
	v_bitop3_b32 v0, v2, v0, 32 bitop3:0x6c
	s_addc_u32 s53, s85, 0
	v_ashrrev_i32_e32 v3, 31, v0
	s_ashr_i32 s15, s14, 31
	v_lshrrev_b32_e32 v3, 26, v3
	s_lshl_b64 s[12:13], s[14:15], 9
	s_ashr_i32 s5, s79, 31
	v_lshlrev_b32_e32 v2, 3, v1
	v_add_u32_e32 v3, v0, v3
	s_mul_i32 s5, s12, s5
	s_mul_hi_u32 s16, s12, s79
	s_ashr_i32 s18, s8, 31
	v_and_b32_e32 v2, -16, v2
	v_ashrrev_i32_e32 v4, 6, v3
	s_add_i32 s5, s16, s5
	s_lshr_b64 s[16:17], s[14:15], 23
	s_mul_i32 s18, s12, s18
	s_mul_hi_u32 s19, s12, s8
	s_ashr_i32 s3, s50, 6
	v_add_u32_e32 v2, v4, v2
	v_lshlrev_b32_e32 v1, 5, v1
	v_and_b32_e32 v4, 3, v4
	s_mul_i32 s17, s16, s79
	s_add_i32 s18, s19, s18
	s_mul_i32 s16, s16, s8
	v_and_b32_e32 v15, 32, v1
	v_and_b32_e32 v1, 0xc0, v3
	v_and_or_b32 v4, v2, s4, v4
	s_ashr_i32 s4, s50, 8
	s_lshl_b64 s[10:11], s[14:15], 8
	s_mov_b64 s[36:37], s[54:55]
	s_lshl_b32 s54, s3, 10
	s_add_i32 s5, s5, s17
	s_add_i32 s18, s18, s16
	s_mul_i32 s16, s12, s8
	v_sub_u32_e32 v0, v0, v1
	v_lshlrev_b32_e32 v1, 1, v2
	v_lshrrev_b32_e32 v3, 2, v2
	s_add_u32 s44, s52, s16
	v_ashrrev_i16_sdwa v0, v169, sext(v0) dst_sel:DWORD dst_unused:UNUSED_PAD src0_sel:DWORD src1_sel:BYTE_0
	v_and_b32_e32 v1, 24, v1
	v_and_b32_e32 v3, 4, v3
	s_addc_u32 s45, s53, s18
	s_add_i32 s55, s54, 0x100
	v_bfe_i32 v16, v0, 0, 16
	v_or3_b32 v1, v4, v3, v1
	s_add_i32 m0, s55, 0x10000
	v_add_u32_e32 v0, v15, v16
	v_mul_lo_u32 v1, v1, s14
	s_mul_i32 s17, s12, s79
	global_load_lds_dwordx4 v130, s[44:45]
	s_add_i32 m0, s55, 0x12000
	v_add_lshl_u32 v134, v1, v0, 1
	s_add_u32 s46, s36, s17
	v_mul_lo_u32 v17, v2, s14
	global_load_lds_dwordx4 v134, s[44:45]
	s_addc_u32 s47, s37, s5
	s_mov_b32 m0, s55
	s_add_i32 s56, s55, 0x2000
	v_add_lshl_u32 v132, v0, v17, 1
	global_load_lds_dwordx4 v128, s[46:47]
	s_mov_b32 m0, s56
	s_add_u32 s16, s44, s10
	global_load_lds_dwordx4 v132, s[46:47]
	s_addc_u32 s17, s45, s11
	s_add_i32 m0, s55, 0x14000
	v_mov_b32_e32 v131, v167
	v_mov_b32_e32 v135, v167
	global_load_lds_dwordx4 v130, s[16:17]
	s_add_i32 m0, s55, 0x16000
	v_lshl_add_u64 v[8:9], s[16:17], 0, v[130:131]
	v_lshl_add_u64 v[10:11], s[16:17], 0, v[134:135]
	global_load_lds_dwordx4 v134, s[16:17]
	s_add_u32 s16, s46, s10
	s_addc_u32 s17, s47, s11
	s_add_i32 s57, s55, 0x4000
	s_mov_b32 m0, s57
	s_add_i32 s58, s55, 0x6000
	global_load_lds_dwordx4 v128, s[16:17]
	s_mov_b32 m0, s58
	v_mov_b32_e32 v129, v167
	global_load_lds_dwordx4 v132, s[16:17]
	v_mov_b32_e32 v133, v167
	v_lshl_add_u64 v[0:1], s[44:45], 0, v[130:131]
	v_lshl_add_u64 v[2:3], s[44:45], 0, v[134:135]
	v_lshl_add_u64 v[4:5], s[46:47], 0, v[128:129]
	v_lshl_add_u64 v[6:7], s[46:47], 0, v[132:133]
	s_cmp_lg_u32 s4, 1
	s_mov_b64 s[16:17], 0x80
	s_cbranch_scc1 .LBB0_635
	s_setprio 1
	s_barrier

; #define PG8_STAGE(bufoff, gbase, voff) do { _Pragma("unroll") for (int _i = 0; _i < 2; ++_i) \
;         __builtin_amdgcn_global_load_lds((const unsigned*)((const char*)(gbase) + (voff)[_i]), (LAS unsigned*)(lds + (bufoff) + ldsw + _i * 8192), 16, 0, 0); } while (0)
; #define PG8_LDA(dst, b, h) do { _Pragma("unroll") for (int m = 0; m < 4; ++m) _Pragma("unroll") for (int k = 0; k < 2; ++k) dst[m][k] = *(const LAS bf16x8*)(lds + PG8_SA(b, h) + aoff + m * 2048 + k * 1024); } while (0)
; #define PG8_LDB(dst, b, h) do { _Pragma("unroll") for (int n = 0; n < 2; ++n) _Pragma("unroll") for (int k = 0; k < 2; ++k) dst[n][k] = *(const LAS bf16x8*)(lds + PG8_SB(b, h) + boff + n * 2048 + k * 1024); } while (0)
; #define PG8_MMA(ai, bj, At, Bt) do { __builtin_amdgcn_s_setprio(1); _Pragma("unroll") for (int m = 0; m < 4; ++m) _Pragma("unroll") for (int n = 0; n < 2; ++n) _Pragma("unroll") for (int k = 0; k < 2; ++k) \
;         acc[ai][bj][m][n] = __builtin_amdgcn_mfma_f32_16x16x32_bf16(Bt[n][k], At[m][k], acc[ai][bj][m][n], 0, 0, 0); __builtin_amdgcn_s_setprio(0); } while (0)
; #define PG8_WAIT_L(n) asm volatile("s_waitcnt lgkmcnt(" #n ")" ::: "memory")
; #define PG8_BAR __builtin_amdgcn_s_barrier()
; #define PG8_SCHED __builtin_amdgcn_sched_barrier(0)
; template <class Epi>
; DI void gemm_phase(LAS unsigned char* lds, const Gemm g, const StaticOrder& S, const Epi& E) {
;     ...
;             const bool last = (t == nt - 2);
;             const char* a1 = cA + (size_t)(t + 1) * kstep;
;             const char* a2 = last ? nA : cA + (size_t)(t + 2) * kstep; const char* b2 = last ? nB : cB + (size_t)(t + 2) * kstep;
;             const char* a3 = a2 + kstep; const char* b3 = b2 + kstep;
;             PG8_LDB(B0, 0, 0); PG8_SCHED; PG8_LDA(At, 0, 0); PG8_STAGE(PG8_SA(1, 1), a1 + hstep, voffA);
;             PG8_WAIT_L(8); PG8_BAR; PG8_WAIT_L(0); PG8_MMA(0, 0, At, B0); PG8_BAR; PG8_SCHED;
;             PG8_LDB(B1, 0, 1); PG8_STAGE(PG8_SB(0, 0), b2, voffB);
;             PG8_BAR; PG8_WAIT_L(0); PG8_MMA(0, 1, At, B1); PG8_BAR;
;             PG8_LDA(At, 0, 1); PG8_STAGE(PG8_SA(0, 0), a2, voffA);
;             PG8_BAR; PG8_WAIT_L(0); PG8_MMA(1, 0, At, B0); PG8_BAR; PG8_SCHED;
.LBB0_643:
	s_andn2_b64 vcc, exec, s[14:15]
	s_cbranch_vccnz .LBB0_646
	s_add_u32 s40, s46, 0x80
	s_addc_u32 s41, s47, 0
	s_add_u32 s0, s44, 0x100
	s_addc_u32 s46, s45, 0
	s_mov_b32 s4, 0
	s_mov_b32 s72, 0x10000
	s_mov_b32 s73, 0x14000
	s_mov_b32 s74, 0x18000
	s_mov_b32 s75, 0x1c000
	s_mov_b64 s[76:77], 0x80
	s_add_i32 s5, s4, 2
	s_add_u32 s42, s40, 0x80
	s_addc_u32 s43, s41, 0
	s_add_i32 s47, s72, 0x100
	v_add_u32_e32 v156, s47, v150
	ds_read_b128 v[140:143], v156
	ds_read_b128 v[144:147], v156 offset:1024
	ds_read_b128 v[152:155], v156 offset:2048
	ds_read_b128 v[156:159], v156 offset:3072
	s_cmp_eq_u32 s63, s4
	s_cselect_b32 s43, s19, s43
	s_cselect_b32 s42, s18, s42
	s_cselect_b32 s45, s37, s46
	s_cselect_b32 s44, s36, s0
	v_lshl_add_u64 v[182:183], s[40:41], 0, v[136:137]
	s_add_i32 m0, s55, 0xc000
	ds_read_b128 v[160:163], v151
	ds_read_b128 v[170:173], v151 offset:1024
	ds_read_b128 v[174:177], v151 offset:2048
	ds_read_b128 v[178:181], v151 offset:3072
	ds_read_b128 v[188:191], v151 offset:4096
	ds_read_b128 v[192:195], v151 offset:5120
	ds_read_b128 v[196:199], v151 offset:6144
	ds_read_b128 v[200:203], v151 offset:7168
	global_load_lds_dwordx4 v[182:183], off
	v_lshl_add_u64 v[182:183], s[40:41], 0, v[138:139]
	s_add_i32 m0, s55, 0xe000
	s_nop 0
	global_load_lds_dwordx4 v[182:183], off
	s_waitcnt lgkmcnt(8)
	s_barrier
	s_waitcnt lgkmcnt(0)
	s_waitcnt lgkmcnt(0)
	v_mfma_f32_16x16x32_bf16 v[120:123], v[140:143], v[160:163], 0
	v_mfma_f32_16x16x32_bf16 v[124:127], v[152:155], v[160:163], 0
	v_mfma_f32_16x16x32_bf16 v[108:111], v[140:143], v[174:177], 0
	v_mfma_f32_16x16x32_bf16 v[104:107], v[152:155], v[174:177], 0
	v_mfma_f32_16x16x32_bf16 v[92:95], v[140:143], v[188:191], 0
	v_mfma_f32_16x16x32_bf16 v[88:91], v[152:155], v[188:191], 0
	v_mfma_f32_16x16x32_bf16 v[76:79], v[140:143], v[196:199], 0
	v_mfma_f32_16x16x32_bf16 v[72:75], v[152:155], v[196:199], 0
	v_mfma_f32_16x16x32_bf16 v[120:123], v[144:147], v[170:173], v[120:123]
	v_mfma_f32_16x16x32_bf16 v[124:127], v[156:159], v[170:173], v[124:127]
	v_mfma_f32_16x16x32_bf16 v[108:111], v[144:147], v[178:181], v[108:111]
	v_mfma_f32_16x16x32_bf16 v[104:107], v[156:159], v[178:181], v[104:107]
	v_mfma_f32_16x16x32_bf16 v[92:95], v[144:147], v[192:195], v[92:95]
	v_mfma_f32_16x16x32_bf16 v[88:91], v[156:159], v[192:195], v[88:91]
	v_mfma_f32_16x16x32_bf16 v[76:79], v[144:147], v[200:203], v[76:79]
	v_mfma_f32_16x16x32_bf16 v[72:75], v[156:159], v[200:203], v[72:75]
	s_barrier
	s_add_i32 s4, s73, 0x100
	s_add_i32 s47, s47, s54
	v_add_u32_e32 v166, s4, v150
	v_lshl_add_u64 v[182:183], s[44:45], 0, v[130:131]
	s_mov_b32 m0, s47
	ds_read_b128 v[204:207], v166
	ds_read_b128 v[208:211], v166 offset:1024
	ds_read_b128 v[212:215], v166 offset:2048
	ds_read_b128 v[216:219], v166 offset:3072
	global_load_lds_dwordx4 v[182:183], off
	v_lshl_add_u64 v[220:221], s[44:45], 0, v[134:135]
	s_add_i32 m0, s47, 0x2000
	s_nop 0
	global_load_lds_dwordx4 v[220:221], off
	s_barrier
	s_waitcnt lgkmcnt(0)
	s_waitcnt lgkmcnt(0)
	v_mfma_f32_16x16x32_bf16 v[116:119], v[204:207], v[160:163], 0
	v_mfma_f32_16x16x32_bf16 v[112:115], v[212:215], v[160:163], 0
	v_mfma_f32_16x16x32_bf16 v[100:103], v[204:207], v[174:177], 0
	v_mfma_f32_16x16x32_bf16 v[96:99], v[212:215], v[174:177], 0
	v_mfma_f32_16x16x32_bf16 v[84:87], v[204:207], v[188:191], 0
	v_mfma_f32_16x16x32_bf16 v[80:83], v[212:215], v[188:191], 0
	v_mfma_f32_16x16x32_bf16 v[68:71], v[204:207], v[196:199], 0
	v_mfma_f32_16x16x32_bf16 v[64:67], v[212:215], v[196:199], 0
	v_mfma_f32_16x16x32_bf16 v[116:119], v[208:211], v[170:173], v[116:119]
	v_mfma_f32_16x16x32_bf16 v[112:115], v[216:219], v[170:173], v[112:115]
	v_mfma_f32_16x16x32_bf16 v[100:103], v[208:211], v[178:181], v[100:103]
	v_mfma_f32_16x16x32_bf16 v[96:99], v[216:219], v[178:181], v[96:99]
	v_mfma_f32_16x16x32_bf16 v[84:87], v[208:211], v[192:195], v[84:87]
	v_mfma_f32_16x16x32_bf16 v[80:83], v[216:219], v[192:195], v[80:83]
	v_mfma_f32_16x16x32_bf16 v[68:71], v[208:211], v[200:203], v[68:71]
	v_mfma_f32_16x16x32_bf16 v[64:67], v[216:219], v[200:203], v[64:67]
	s_mov_b32 m0, s55
	v_lshl_add_u64 v[222:223], s[42:43], 0, v[128:129]
	s_barrier
	ds_read_b128 v[160:163], v151 offset:16384
	ds_read_b128 v[170:173], v151 offset:17408
	ds_read_b128 v[174:177], v151 offset:18432
	ds_read_b128 v[178:181], v151 offset:19456
	ds_read_b128 v[188:191], v151 offset:20480
	ds_read_b128 v[192:195], v151 offset:21504
	ds_read_b128 v[196:199], v151 offset:22528
	ds_read_b128 v[200:203], v151 offset:23552
	global_load_lds_dwordx4 v[222:223], off
	v_lshl_add_u64 v[224:225], s[42:43], 0, v[132:133]
	s_mov_b32 m0, s56
	s_nop 0
	global_load_lds_dwordx4 v[224:225], off
	s_barrier
	s_waitcnt lgkmcnt(0)
	s_waitcnt lgkmcnt(0)
	v_mfma_f32_16x16x32_bf16 v[60:63], v[140:143], v[160:163], 0
	v_mfma_f32_16x16x32_bf16 v[56:59], v[152:155], v[160:163], 0
	v_mfma_f32_16x16x32_bf16 v[44:47], v[140:143], v[174:177], 0
	v_mfma_f32_16x16x32_bf16 v[40:43], v[152:155], v[174:177], 0
	v_mfma_f32_16x16x32_bf16 v[28:31], v[140:143], v[188:191], 0
	v_mfma_f32_16x16x32_bf16 v[24:27], v[152:155], v[188:191], 0
	v_mfma_f32_16x16x32_bf16 v[12:15], v[140:143], v[196:199], 0
	v_mfma_f32_16x16x32_bf16 v[8:11], v[152:155], v[196:199], 0
	v_mfma_f32_16x16x32_bf16 v[60:63], v[144:147], v[170:173], v[60:63]
	v_mfma_f32_16x16x32_bf16 v[56:59], v[156:159], v[170:173], v[56:59]
	v_mfma_f32_16x16x32_bf16 v[44:47], v[144:147], v[178:181], v[44:47]
	v_mfma_f32_16x16x32_bf16 v[40:43], v[156:159], v[178:181], v[40:43]
	v_mfma_f32_16x16x32_bf16 v[28:31], v[144:147], v[192:195], v[28:31]
	v_mfma_f32_16x16x32_bf16 v[24:27], v[156:159], v[192:195], v[24:27]
	v_mfma_f32_16x16x32_bf16 v[12:15], v[144:147], v[200:203], v[12:15]
	v_mfma_f32_16x16x32_bf16 v[8:11], v[156:159], v[200:203], v[8:11]
	s_barrier
; #define PG8_STAGE(bufoff, gbase, voff) do { _Pragma("unroll") for (int _i = 0; _i < 2; ++_i) \
;         __builtin_amdgcn_global_load_lds((const unsigned*)((const char*)(gbase) + (voff)[_i]), (LAS unsigned*)(lds + (bufoff) + ldsw + _i * 8192), 16, 0, 0); } while (0)
; #define PG8_LDA(dst, b, h) do { _Pragma("unroll") for (int m = 0; m < 4; ++m) _Pragma("unroll") for (int k = 0; k < 2; ++k) dst[m][k] = *(const LAS bf16x8*)(lds + PG8_SA(b, h) + aoff + m * 2048 + k * 1024); } while (0)
; #define PG8_LDB(dst, b, h) do { _Pragma("unroll") for (int n = 0; n < 2; ++n) _Pragma("unroll") for (int k = 0; k < 2; ++k) dst[n][k] = *(const LAS bf16x8*)(lds + PG8_SB(b, h) + boff + n * 2048 + k * 1024); } while (0)
; #define PG8_MMA(ai, bj, At, Bt) do { __builtin_amdgcn_s_setprio(1); _Pragma("unroll") for (int m = 0; m < 4; ++m) _Pragma("unroll") for (int n = 0; n < 2; ++n) _Pragma("unroll") for (int k = 0; k < 2; ++k) \
;         acc[ai][bj][m][n] = __builtin_amdgcn_mfma_f32_16x16x32_bf16(Bt[n][k], At[m][k], acc[ai][bj][m][n], 0, 0, 0); __builtin_amdgcn_s_setprio(0); } while (0)
; #define PG8_WAIT_V(n) asm volatile("s_waitcnt vmcnt(" #n ")" ::: "memory")
; #define PG8_WAIT_L(n) asm volatile("s_waitcnt lgkmcnt(" #n ")" ::: "memory")
; #define PG8_BAR __builtin_amdgcn_s_barrier()
; #define PG8_SCHED __builtin_amdgcn_sched_barrier(0)
; template <class Epi>
; DI void gemm_phase(LAS unsigned char* lds, const Gemm g, const StaticOrder& S, const Epi& E) {
;     ...
;             PG8_STAGE(PG8_SB(0, 1), b2 + hstep, voffB);
;             PG8_WAIT_V(6); PG8_BAR; PG8_MMA(1, 1, At, B1); PG8_BAR;
;             PG8_LDB(B0, 1, 0); PG8_SCHED; PG8_LDA(At, 1, 0); PG8_STAGE(PG8_SA(0, 1), a2 + hstep, voffA);
;             PG8_WAIT_L(8); PG8_BAR; PG8_WAIT_L(0); PG8_MMA(0, 0, At, B0); PG8_BAR; PG8_SCHED;
;             PG8_LDB(B1, 1, 1); PG8_STAGE(PG8_SB(1, 0), b3, voffB);
;             PG8_BAR; PG8_WAIT_L(0); PG8_MMA(0, 1, At, B1); PG8_BAR;
;             PG8_LDA(At, 1, 1); PG8_STAGE(PG8_SA(1, 0), a3, voffA);
	s_add_u32 s44, s44, s10
	s_addc_u32 s45, s45, s11
	s_add_i32 s4, s4, s54
	v_lshl_add_u64 v[226:227], s[44:45], 0, v[130:131]
	s_mov_b32 m0, s4
	v_lshl_add_u64 v[228:229], s[44:45], 0, v[134:135]
	global_load_lds_dwordx4 v[226:227], off
	s_add_i32 m0, s4, 0x2000
	s_nop 0
	global_load_lds_dwordx4 v[228:229], off
	s_waitcnt vmcnt(6)
	s_barrier
	v_mfma_f32_16x16x32_bf16 v[52:55], v[204:207], v[160:163], 0
	v_mfma_f32_16x16x32_bf16 v[48:51], v[212:215], v[160:163], 0
	v_mfma_f32_16x16x32_bf16 v[36:39], v[204:207], v[174:177], 0
	v_mfma_f32_16x16x32_bf16 v[32:35], v[212:215], v[174:177], 0
	v_mfma_f32_16x16x32_bf16 v[20:23], v[204:207], v[188:191], 0
	v_mfma_f32_16x16x32_bf16 v[16:19], v[212:215], v[188:191], 0
	v_mfma_f32_16x16x32_bf16 v[4:7], v[204:207], v[196:199], 0
	v_mfma_f32_16x16x32_bf16 v[0:3], v[212:215], v[196:199], 0
	v_mfma_f32_16x16x32_bf16 v[52:55], v[208:211], v[170:173], v[52:55]
	v_mfma_f32_16x16x32_bf16 v[48:51], v[216:219], v[170:173], v[48:51]
	v_mfma_f32_16x16x32_bf16 v[36:39], v[208:211], v[178:181], v[36:39]
	v_mfma_f32_16x16x32_bf16 v[32:35], v[216:219], v[178:181], v[32:35]
	v_mfma_f32_16x16x32_bf16 v[20:23], v[208:211], v[192:195], v[20:23]
	v_mfma_f32_16x16x32_bf16 v[16:19], v[216:219], v[192:195], v[16:19]
	v_mfma_f32_16x16x32_bf16 v[4:7], v[208:211], v[200:203], v[4:7]
	v_mfma_f32_16x16x32_bf16 v[0:3], v[216:219], v[200:203], v[0:3]
	s_add_i32 s4, s74, 0x100
	v_add_u32_e32 v156, s4, v150
	s_barrier
	ds_read_b128 v[140:143], v156
	ds_read_b128 v[144:147], v156 offset:1024
	ds_read_b128 v[152:155], v156 offset:2048
	ds_read_b128 v[156:159], v156 offset:3072
	s_add_u32 s42, s42, s10
	s_addc_u32 s43, s43, s11
	s_mov_b32 m0, s57
	v_lshl_add_u64 v[204:205], s[42:43], 0, v[128:129]
	ds_read_b128 v[160:163], v151 offset:32768
	ds_read_b128 v[170:173], v151 offset:33792
	ds_read_b128 v[174:177], v151 offset:34816
	ds_read_b128 v[178:181], v151 offset:35840
	ds_read_b128 v[188:191], v151 offset:36864
	ds_read_b128 v[192:195], v151 offset:37888
	ds_read_b128 v[196:199], v151 offset:38912
	ds_read_b128 v[200:203], v151 offset:39936
	global_load_lds_dwordx4 v[204:205], off
	v_lshl_add_u64 v[204:205], s[42:43], 0, v[132:133]
	s_mov_b32 m0, s58
	s_nop 0
	global_load_lds_dwordx4 v[204:205], off
	s_waitcnt lgkmcnt(8)
	s_barrier
	s_waitcnt lgkmcnt(0)
	s_waitcnt lgkmcnt(0)
	v_mfma_f32_16x16x32_bf16 v[120:123], v[140:143], v[160:163], v[120:123]
	v_mfma_f32_16x16x32_bf16 v[124:127], v[152:155], v[160:163], v[124:127]
	v_mfma_f32_16x16x32_bf16 v[108:111], v[140:143], v[174:177], v[108:111]
	v_mfma_f32_16x16x32_bf16 v[104:107], v[152:155], v[174:177], v[104:107]
	v_mfma_f32_16x16x32_bf16 v[92:95], v[140:143], v[188:191], v[92:95]
	v_mfma_f32_16x16x32_bf16 v[88:91], v[152:155], v[188:191], v[88:91]
	v_mfma_f32_16x16x32_bf16 v[76:79], v[140:143], v[196:199], v[76:79]
	v_mfma_f32_16x16x32_bf16 v[72:75], v[152:155], v[196:199], v[72:75]
	v_mfma_f32_16x16x32_bf16 v[120:123], v[144:147], v[170:173], v[120:123]
	v_mfma_f32_16x16x32_bf16 v[124:127], v[156:159], v[170:173], v[124:127]
	v_mfma_f32_16x16x32_bf16 v[108:111], v[144:147], v[178:181], v[108:111]
	v_mfma_f32_16x16x32_bf16 v[104:107], v[156:159], v[178:181], v[104:107]
	v_mfma_f32_16x16x32_bf16 v[92:95], v[144:147], v[192:195], v[92:95]
	v_mfma_f32_16x16x32_bf16 v[88:91], v[156:159], v[192:195], v[88:91]
	v_mfma_f32_16x16x32_bf16 v[76:79], v[144:147], v[200:203], v[76:79]
	v_mfma_f32_16x16x32_bf16 v[72:75], v[156:159], v[200:203], v[72:75]
	s_barrier
	s_add_i32 s42, s75, 0x100
	s_add_i32 s4, s4, s54
	v_add_u32_e32 v166, s42, v150
	v_lshl_add_u64 v[182:183], v[182:183], 0, s[76:77]
	s_mov_b32 m0, s4
	ds_read_b128 v[204:207], v166
	ds_read_b128 v[208:211], v166 offset:1024
	ds_read_b128 v[212:215], v166 offset:2048
	ds_read_b128 v[216:219], v166 offset:3072
	global_load_lds_dwordx4 v[182:183], off
	v_lshl_add_u64 v[182:183], v[220:221], 0, s[76:77]
	s_add_i32 m0, s4, 0x2000
	s_nop 0
	global_load_lds_dwordx4 v[182:183], off
	s_barrier
	s_waitcnt lgkmcnt(0)
	s_waitcnt lgkmcnt(0)
	v_mfma_f32_16x16x32_bf16 v[116:119], v[204:207], v[160:163], v[116:119]
	v_mfma_f32_16x16x32_bf16 v[112:115], v[212:215], v[160:163], v[112:115]
	v_mfma_f32_16x16x32_bf16 v[100:103], v[204:207], v[174:177], v[100:103]
	v_mfma_f32_16x16x32_bf16 v[96:99], v[212:215], v[174:177], v[96:99]
	v_mfma_f32_16x16x32_bf16 v[84:87], v[204:207], v[188:191], v[84:87]
	v_mfma_f32_16x16x32_bf16 v[80:83], v[212:215], v[188:191], v[80:83]
	v_mfma_f32_16x16x32_bf16 v[68:71], v[204:207], v[196:199], v[68:71]
	v_mfma_f32_16x16x32_bf16 v[64:67], v[212:215], v[196:199], v[64:67]
	v_mfma_f32_16x16x32_bf16 v[116:119], v[208:211], v[170:173], v[116:119]
	v_mfma_f32_16x16x32_bf16 v[112:115], v[216:219], v[170:173], v[112:115]
	v_mfma_f32_16x16x32_bf16 v[100:103], v[208:211], v[178:181], v[100:103]
	v_mfma_f32_16x16x32_bf16 v[96:99], v[216:219], v[178:181], v[96:99]
	v_mfma_f32_16x16x32_bf16 v[84:87], v[208:211], v[192:195], v[84:87]
	v_mfma_f32_16x16x32_bf16 v[80:83], v[216:219], v[192:195], v[80:83]
	v_mfma_f32_16x16x32_bf16 v[68:71], v[208:211], v[200:203], v[68:71]
	v_mfma_f32_16x16x32_bf16 v[64:67], v[216:219], v[200:203], v[64:67]
	s_mov_b32 m0, s61
	v_lshl_add_u64 v[182:183], v[222:223], 0, s[76:77]
	s_barrier
	ds_read_b128 v[160:163], v151 offset:49152
	ds_read_b128 v[170:173], v151 offset:50176
	ds_read_b128 v[174:177], v151 offset:51200
	ds_read_b128 v[178:181], v151 offset:52224
	ds_read_b128 v[188:191], v151 offset:53248
	ds_read_b128 v[192:195], v151 offset:54272
	ds_read_b128 v[196:199], v151 offset:55296
	ds_read_b128 v[200:203], v151 offset:56320
	global_load_lds_dwordx4 v[182:183], off
	v_lshl_add_u64 v[182:183], v[224:225], 0, s[76:77]
	s_mov_b32 m0, s62
	s_nop 0
	global_load_lds_dwordx4 v[182:183], off
	s_barrier
; #define PG8_STAGE(bufoff, gbase, voff) do { _Pragma("unroll") for (int _i = 0; _i < 2; ++_i) \
;         __builtin_amdgcn_global_load_lds((const unsigned*)((const char*)(gbase) + (voff)[_i]), (LAS unsigned*)(lds + (bufoff) + ldsw + _i * 8192), 16, 0, 0); } while (0)
; #define PG8_LDA(dst, b, h) do { _Pragma("unroll") for (int m = 0; m < 4; ++m) _Pragma("unroll") for (int k = 0; k < 2; ++k) dst[m][k] = *(const LAS bf16x8*)(lds + PG8_SA(b, h) + aoff + m * 2048 + k * 1024); } while (0)
; #define PG8_LDB(dst, b, h) do { _Pragma("unroll") for (int n = 0; n < 2; ++n) _Pragma("unroll") for (int k = 0; k < 2; ++k) dst[n][k] = *(const LAS bf16x8*)(lds + PG8_SB(b, h) + boff + n * 2048 + k * 1024); } while (0)
; #define PG8_MMA(ai, bj, At, Bt) do { __builtin_amdgcn_s_setprio(1); _Pragma("unroll") for (int m = 0; m < 4; ++m) _Pragma("unroll") for (int n = 0; n < 2; ++n) _Pragma("unroll") for (int k = 0; k < 2; ++k) \
;         acc[ai][bj][m][n] = __builtin_amdgcn_mfma_f32_16x16x32_bf16(Bt[n][k], At[m][k], acc[ai][bj][m][n], 0, 0, 0); __builtin_amdgcn_s_setprio(0); } while (0)
; #define PG8_WAIT_V(n) asm volatile("s_waitcnt vmcnt(" #n ")" ::: "memory")
; #define PG8_WAIT_L(n) asm volatile("s_waitcnt lgkmcnt(" #n ")" ::: "memory")
; #define PG8_BAR __builtin_amdgcn_s_barrier()
; #define PG8_SCHED __builtin_amdgcn_sched_barrier(0)
; template <class Epi>
; DI void gemm_phase(LAS unsigned char* lds, const Gemm g, const StaticOrder& S, const Epi& E) {
;     ...
;         for (int t = 0; t < nt; t += 2) {
;             const bool last = (t == nt - 2);
;             const char* a1 = cA + (size_t)(t + 1) * kstep;
;             const char* a2 = last ? nA : cA + (size_t)(t + 2) * kstep; const char* b2 = last ? nB : cB + (size_t)(t + 2) * kstep;
;             const char* a3 = a2 + kstep; const char* b3 = b2 + kstep;
;             PG8_LDB(B0, 0, 0); PG8_SCHED; PG8_LDA(At, 0, 0); PG8_STAGE(PG8_SA(1, 1), a1 + hstep, voffA);
;             PG8_WAIT_L(8); PG8_BAR; PG8_WAIT_L(0); PG8_MMA(0, 0, At, B0); PG8_BAR; PG8_SCHED;
;             PG8_LDB(B1, 0, 1); PG8_STAGE(PG8_SB(0, 0), b2, voffB);
;     ...
;             PG8_LDA(At, 1, 1); PG8_STAGE(PG8_SA(1, 0), a3, voffA);
;             PG8_BAR; PG8_WAIT_L(0); PG8_MMA(1, 0, At, B0); PG8_BAR; PG8_SCHED;
;             PG8_STAGE(PG8_SB(1, 1), b3 + hstep, voffB);
;             PG8_WAIT_V(6); PG8_BAR; PG8_MMA(1, 1, At, B1); PG8_BAR;
	s_waitcnt lgkmcnt(0)
	s_waitcnt lgkmcnt(0)
	v_mfma_f32_16x16x32_bf16 v[60:63], v[140:143], v[160:163], v[60:63]
	v_mfma_f32_16x16x32_bf16 v[56:59], v[152:155], v[160:163], v[56:59]
	v_mfma_f32_16x16x32_bf16 v[44:47], v[140:143], v[174:177], v[44:47]
	v_mfma_f32_16x16x32_bf16 v[40:43], v[152:155], v[174:177], v[40:43]
	v_mfma_f32_16x16x32_bf16 v[28:31], v[140:143], v[188:191], v[28:31]
	v_mfma_f32_16x16x32_bf16 v[24:27], v[152:155], v[188:191], v[24:27]
	v_mfma_f32_16x16x32_bf16 v[12:15], v[140:143], v[196:199], v[12:15]
	v_mfma_f32_16x16x32_bf16 v[8:11], v[152:155], v[196:199], v[8:11]
	v_mfma_f32_16x16x32_bf16 v[60:63], v[144:147], v[170:173], v[60:63]
	v_mfma_f32_16x16x32_bf16 v[56:59], v[156:159], v[170:173], v[56:59]
	v_mfma_f32_16x16x32_bf16 v[44:47], v[144:147], v[178:181], v[44:47]
	v_mfma_f32_16x16x32_bf16 v[40:43], v[156:159], v[178:181], v[40:43]
	v_mfma_f32_16x16x32_bf16 v[28:31], v[144:147], v[192:195], v[28:31]
	v_mfma_f32_16x16x32_bf16 v[24:27], v[156:159], v[192:195], v[24:27]
	v_mfma_f32_16x16x32_bf16 v[12:15], v[144:147], v[200:203], v[12:15]
	v_mfma_f32_16x16x32_bf16 v[8:11], v[156:159], v[200:203], v[8:11]
	s_barrier
	s_add_i32 s4, s42, s54
	v_lshl_add_u64 v[140:141], v[226:227], 0, s[76:77]
	s_mov_b32 m0, s4
	s_nop 0
	global_load_lds_dwordx4 v[140:141], off
	v_lshl_add_u64 v[140:141], v[228:229], 0, s[76:77]
	s_add_i32 m0, s4, 0x2000
	s_nop 0
	global_load_lds_dwordx4 v[140:141], off
	s_waitcnt vmcnt(6)
	s_barrier
	v_mfma_f32_16x16x32_bf16 v[52:55], v[204:207], v[160:163], v[52:55]
	v_mfma_f32_16x16x32_bf16 v[48:51], v[212:215], v[160:163], v[48:51]
	v_mfma_f32_16x16x32_bf16 v[36:39], v[204:207], v[174:177], v[36:39]
	v_mfma_f32_16x16x32_bf16 v[32:35], v[212:215], v[174:177], v[32:35]
	v_mfma_f32_16x16x32_bf16 v[20:23], v[204:207], v[188:191], v[20:23]
	v_mfma_f32_16x16x32_bf16 v[16:19], v[212:215], v[188:191], v[16:19]
	v_mfma_f32_16x16x32_bf16 v[4:7], v[204:207], v[196:199], v[4:7]
	v_mfma_f32_16x16x32_bf16 v[0:3], v[212:215], v[196:199], v[0:3]
	v_mfma_f32_16x16x32_bf16 v[52:55], v[208:211], v[170:173], v[52:55]
	v_mfma_f32_16x16x32_bf16 v[48:51], v[216:219], v[170:173], v[48:51]
	v_mfma_f32_16x16x32_bf16 v[36:39], v[208:211], v[178:181], v[36:39]
	v_mfma_f32_16x16x32_bf16 v[32:35], v[216:219], v[178:181], v[32:35]
	v_mfma_f32_16x16x32_bf16 v[20:23], v[208:211], v[192:195], v[20:23]
	v_mfma_f32_16x16x32_bf16 v[16:19], v[216:219], v[192:195], v[16:19]
	v_mfma_f32_16x16x32_bf16 v[4:7], v[208:211], v[200:203], v[4:7]
	v_mfma_f32_16x16x32_bf16 v[0:3], v[216:219], v[200:203], v[0:3]
	s_add_u32 s40, s40, 0x100
	s_addc_u32 s41, s41, 0
	s_add_u32 s0, s0, 0x100
	s_addc_u32 s46, s46, 0
	s_cmp_ge_i32 s5, s33
	s_mov_b32 s4, s5
	s_barrier
	s_cbranch_scc0 .LBB0_645
	s_branch .Lpeel_exit_1
.LBB0_645:
	s_add_i32 s5, s4, 2
	s_add_u32 s42, s40, 0x80
	s_addc_u32 s43, s41, 0
	s_add_i32 s47, s72, 0x100
	v_add_u32_e32 v156, s47, v150
	ds_read_b128 v[140:143], v156
	ds_read_b128 v[144:147], v156 offset:1024
	ds_read_b128 v[152:155], v156 offset:2048
	ds_read_b128 v[156:159], v156 offset:3072
	s_cmp_eq_u32 s63, s4
	s_cselect_b32 s43, s19, s43
	s_cselect_b32 s42, s18, s42
	s_cselect_b32 s45, s37, s46
	s_cselect_b32 s44, s36, s0
	v_lshl_add_u64 v[182:183], s[40:41], 0, v[136:137]
	s_add_i32 m0, s55, 0xc000
	ds_read_b128 v[160:163], v151
	ds_read_b128 v[170:173], v151 offset:1024
	ds_read_b128 v[174:177], v151 offset:2048
	ds_read_b128 v[178:181], v151 offset:3072
	ds_read_b128 v[188:191], v151 offset:4096
	ds_read_b128 v[192:195], v151 offset:5120
	ds_read_b128 v[196:199], v151 offset:6144
	ds_read_b128 v[200:203], v151 offset:7168
	global_load_lds_dwordx4 v[182:183], off
	v_lshl_add_u64 v[182:183], s[40:41], 0, v[138:139]
	s_add_i32 m0, s55, 0xe000
	s_nop 0
	global_load_lds_dwordx4 v[182:183], off
	s_waitcnt lgkmcnt(8)
	s_barrier
	s_waitcnt lgkmcnt(0)
	s_waitcnt lgkmcnt(0)
	v_mfma_f32_16x16x32_bf16 v[120:123], v[140:143], v[160:163], v[120:123]
	v_mfma_f32_16x16x32_bf16 v[124:127], v[152:155], v[160:163], v[124:127]
	v_mfma_f32_16x16x32_bf16 v[108:111], v[140:143], v[174:177], v[108:111]
	v_mfma_f32_16x16x32_bf16 v[104:107], v[152:155], v[174:177], v[104:107]
	v_mfma_f32_16x16x32_bf16 v[92:95], v[140:143], v[188:191], v[92:95]
	v_mfma_f32_16x16x32_bf16 v[88:91], v[152:155], v[188:191], v[88:91]
	v_mfma_f32_16x16x32_bf16 v[76:79], v[140:143], v[196:199], v[76:79]
	v_mfma_f32_16x16x32_bf16 v[72:75], v[152:155], v[196:199], v[72:75]
	v_mfma_f32_16x16x32_bf16 v[120:123], v[144:147], v[170:173], v[120:123]
	v_mfma_f32_16x16x32_bf16 v[124:127], v[156:159], v[170:173], v[124:127]
	v_mfma_f32_16x16x32_bf16 v[108:111], v[144:147], v[178:181], v[108:111]
	v_mfma_f32_16x16x32_bf16 v[104:107], v[156:159], v[178:181], v[104:107]
	v_mfma_f32_16x16x32_bf16 v[92:95], v[144:147], v[192:195], v[92:95]
	v_mfma_f32_16x16x32_bf16 v[88:91], v[156:159], v[192:195], v[88:91]
	v_mfma_f32_16x16x32_bf16 v[76:79], v[144:147], v[200:203], v[76:79]
	v_mfma_f32_16x16x32_bf16 v[72:75], v[156:159], v[200:203], v[72:75]
	s_barrier
	s_add_i32 s4, s73, 0x100
	s_add_i32 s47, s47, s54
	v_add_u32_e32 v166, s4, v150
	v_lshl_add_u64 v[182:183], s[44:45], 0, v[130:131]
	s_mov_b32 m0, s47
	ds_read_b128 v[204:207], v166
	ds_read_b128 v[208:211], v166 offset:1024
	ds_read_b128 v[212:215], v166 offset:2048
	ds_read_b128 v[216:219], v166 offset:3072
	global_load_lds_dwordx4 v[182:183], off
	v_lshl_add_u64 v[220:221], s[44:45], 0, v[134:135]
	s_add_i32 m0, s47, 0x2000
	s_nop 0
	global_load_lds_dwordx4 v[220:221], off
	s_barrier
; #define PG8_STAGE(bufoff, gbase, voff) do { _Pragma("unroll") for (int _i = 0; _i < 2; ++_i) \
;         __builtin_amdgcn_global_load_lds((const unsigned*)((const char*)(gbase) + (voff)[_i]), (LAS unsigned*)(lds + (bufoff) + ldsw + _i * 8192), 16, 0, 0); } while (0)
; #define PG8_LDA(dst, b, h) do { _Pragma("unroll") for (int m = 0; m < 4; ++m) _Pragma("unroll") for (int k = 0; k < 2; ++k) dst[m][k] = *(const LAS bf16x8*)(lds + PG8_SA(b, h) + aoff + m * 2048 + k * 1024); } while (0)
; #define PG8_LDB(dst, b, h) do { _Pragma("unroll") for (int n = 0; n < 2; ++n) _Pragma("unroll") for (int k = 0; k < 2; ++k) dst[n][k] = *(const LAS bf16x8*)(lds + PG8_SB(b, h) + boff + n * 2048 + k * 1024); } while (0)
; #define PG8_MMA(ai, bj, At, Bt) do { __builtin_amdgcn_s_setprio(1); _Pragma("unroll") for (int m = 0; m < 4; ++m) _Pragma("unroll") for (int n = 0; n < 2; ++n) _Pragma("unroll") for (int k = 0; k < 2; ++k) \
;         acc[ai][bj][m][n] = __builtin_amdgcn_mfma_f32_16x16x32_bf16(Bt[n][k], At[m][k], acc[ai][bj][m][n], 0, 0, 0); __builtin_amdgcn_s_setprio(0); } while (0)
; #define PG8_WAIT_V(n) asm volatile("s_waitcnt vmcnt(" #n ")" ::: "memory")
; #define PG8_WAIT_L(n) asm volatile("s_waitcnt lgkmcnt(" #n ")" ::: "memory")
; #define PG8_BAR __builtin_amdgcn_s_barrier()
; #define PG8_SCHED __builtin_amdgcn_sched_barrier(0)
; template <class Epi>
; DI void gemm_phase(LAS unsigned char* lds, const Gemm g, const StaticOrder& S, const Epi& E) {
;     ...
;             PG8_BAR; PG8_WAIT_L(0); PG8_MMA(0, 1, At, B1); PG8_BAR;
;             PG8_LDA(At, 0, 1); PG8_STAGE(PG8_SA(0, 0), a2, voffA);
;             PG8_BAR; PG8_WAIT_L(0); PG8_MMA(1, 0, At, B0); PG8_BAR; PG8_SCHED;
;             PG8_STAGE(PG8_SB(0, 1), b2 + hstep, voffB);
;             PG8_WAIT_V(6); PG8_BAR; PG8_MMA(1, 1, At, B1); PG8_BAR;
;             PG8_LDB(B0, 1, 0); PG8_SCHED; PG8_LDA(At, 1, 0); PG8_STAGE(PG8_SA(0, 1), a2 + hstep, voffA);
;             PG8_WAIT_L(8); PG8_BAR; PG8_WAIT_L(0); PG8_MMA(0, 0, At, B0); PG8_BAR; PG8_SCHED;
	s_waitcnt lgkmcnt(0)
	s_waitcnt lgkmcnt(0)
	v_mfma_f32_16x16x32_bf16 v[116:119], v[204:207], v[160:163], v[116:119]
	v_mfma_f32_16x16x32_bf16 v[112:115], v[212:215], v[160:163], v[112:115]
	v_mfma_f32_16x16x32_bf16 v[100:103], v[204:207], v[174:177], v[100:103]
	v_mfma_f32_16x16x32_bf16 v[96:99], v[212:215], v[174:177], v[96:99]
	v_mfma_f32_16x16x32_bf16 v[84:87], v[204:207], v[188:191], v[84:87]
	v_mfma_f32_16x16x32_bf16 v[80:83], v[212:215], v[188:191], v[80:83]
	v_mfma_f32_16x16x32_bf16 v[68:71], v[204:207], v[196:199], v[68:71]
	v_mfma_f32_16x16x32_bf16 v[64:67], v[212:215], v[196:199], v[64:67]
	v_mfma_f32_16x16x32_bf16 v[116:119], v[208:211], v[170:173], v[116:119]
	v_mfma_f32_16x16x32_bf16 v[112:115], v[216:219], v[170:173], v[112:115]
	v_mfma_f32_16x16x32_bf16 v[100:103], v[208:211], v[178:181], v[100:103]
	v_mfma_f32_16x16x32_bf16 v[96:99], v[216:219], v[178:181], v[96:99]
	v_mfma_f32_16x16x32_bf16 v[84:87], v[208:211], v[192:195], v[84:87]
	v_mfma_f32_16x16x32_bf16 v[80:83], v[216:219], v[192:195], v[80:83]
	v_mfma_f32_16x16x32_bf16 v[68:71], v[208:211], v[200:203], v[68:71]
	v_mfma_f32_16x16x32_bf16 v[64:67], v[216:219], v[200:203], v[64:67]
	s_mov_b32 m0, s55
	v_lshl_add_u64 v[222:223], s[42:43], 0, v[128:129]
	s_barrier
	ds_read_b128 v[160:163], v151 offset:16384
	ds_read_b128 v[170:173], v151 offset:17408
	ds_read_b128 v[174:177], v151 offset:18432
	ds_read_b128 v[178:181], v151 offset:19456
	ds_read_b128 v[188:191], v151 offset:20480
	ds_read_b128 v[192:195], v151 offset:21504
	ds_read_b128 v[196:199], v151 offset:22528
	ds_read_b128 v[200:203], v151 offset:23552
	global_load_lds_dwordx4 v[222:223], off
	v_lshl_add_u64 v[224:225], s[42:43], 0, v[132:133]
	s_mov_b32 m0, s56
	s_nop 0
	global_load_lds_dwordx4 v[224:225], off
	s_barrier
	s_waitcnt lgkmcnt(0)
	s_waitcnt lgkmcnt(0)
	v_mfma_f32_16x16x32_bf16 v[60:63], v[140:143], v[160:163], v[60:63]
	v_mfma_f32_16x16x32_bf16 v[56:59], v[152:155], v[160:163], v[56:59]
	v_mfma_f32_16x16x32_bf16 v[44:47], v[140:143], v[174:177], v[44:47]
	v_mfma_f32_16x16x32_bf16 v[40:43], v[152:155], v[174:177], v[40:43]
	v_mfma_f32_16x16x32_bf16 v[28:31], v[140:143], v[188:191], v[28:31]
	v_mfma_f32_16x16x32_bf16 v[24:27], v[152:155], v[188:191], v[24:27]
	v_mfma_f32_16x16x32_bf16 v[12:15], v[140:143], v[196:199], v[12:15]
	v_mfma_f32_16x16x32_bf16 v[8:11], v[152:155], v[196:199], v[8:11]
	v_mfma_f32_16x16x32_bf16 v[60:63], v[144:147], v[170:173], v[60:63]
	v_mfma_f32_16x16x32_bf16 v[56:59], v[156:159], v[170:173], v[56:59]
	v_mfma_f32_16x16x32_bf16 v[44:47], v[144:147], v[178:181], v[44:47]
	v_mfma_f32_16x16x32_bf16 v[40:43], v[156:159], v[178:181], v[40:43]
	v_mfma_f32_16x16x32_bf16 v[28:31], v[144:147], v[192:195], v[28:31]
	v_mfma_f32_16x16x32_bf16 v[24:27], v[156:159], v[192:195], v[24:27]
	v_mfma_f32_16x16x32_bf16 v[12:15], v[144:147], v[200:203], v[12:15]
	v_mfma_f32_16x16x32_bf16 v[8:11], v[156:159], v[200:203], v[8:11]
	s_barrier
	s_add_u32 s44, s44, s10
	s_addc_u32 s45, s45, s11
	s_add_i32 s4, s4, s54
	v_lshl_add_u64 v[226:227], s[44:45], 0, v[130:131]
	s_mov_b32 m0, s4
	v_lshl_add_u64 v[228:229], s[44:45], 0, v[134:135]
	global_load_lds_dwordx4 v[226:227], off
	s_add_i32 m0, s4, 0x2000
	s_nop 0
	global_load_lds_dwordx4 v[228:229], off
	s_waitcnt vmcnt(6)
	s_barrier
	v_mfma_f32_16x16x32_bf16 v[52:55], v[204:207], v[160:163], v[52:55]
	v_mfma_f32_16x16x32_bf16 v[48:51], v[212:215], v[160:163], v[48:51]
	v_mfma_f32_16x16x32_bf16 v[36:39], v[204:207], v[174:177], v[36:39]
	v_mfma_f32_16x16x32_bf16 v[32:35], v[212:215], v[174:177], v[32:35]
	v_mfma_f32_16x16x32_bf16 v[20:23], v[204:207], v[188:191], v[20:23]
	v_mfma_f32_16x16x32_bf16 v[16:19], v[212:215], v[188:191], v[16:19]
	v_mfma_f32_16x16x32_bf16 v[4:7], v[204:207], v[196:199], v[4:7]
	v_mfma_f32_16x16x32_bf16 v[0:3], v[212:215], v[196:199], v[0:3]
	v_mfma_f32_16x16x32_bf16 v[52:55], v[208:211], v[170:173], v[52:55]
	v_mfma_f32_16x16x32_bf16 v[48:51], v[216:219], v[170:173], v[48:51]
	v_mfma_f32_16x16x32_bf16 v[36:39], v[208:211], v[178:181], v[36:39]
	v_mfma_f32_16x16x32_bf16 v[32:35], v[216:219], v[178:181], v[32:35]
	v_mfma_f32_16x16x32_bf16 v[20:23], v[208:211], v[192:195], v[20:23]
	v_mfma_f32_16x16x32_bf16 v[16:19], v[216:219], v[192:195], v[16:19]
	v_mfma_f32_16x16x32_bf16 v[4:7], v[208:211], v[200:203], v[4:7]
	v_mfma_f32_16x16x32_bf16 v[0:3], v[216:219], v[200:203], v[0:3]
	s_add_i32 s4, s74, 0x100
	v_add_u32_e32 v156, s4, v150
	s_barrier
	ds_read_b128 v[140:143], v156
	ds_read_b128 v[144:147], v156 offset:1024
	ds_read_b128 v[152:155], v156 offset:2048
	ds_read_b128 v[156:159], v156 offset:3072
	s_add_u32 s42, s42, s10
	s_addc_u32 s43, s43, s11
	s_mov_b32 m0, s57
	v_lshl_add_u64 v[204:205], s[42:43], 0, v[128:129]
	ds_read_b128 v[160:163], v151 offset:32768
	ds_read_b128 v[170:173], v151 offset:33792
	ds_read_b128 v[174:177], v151 offset:34816
	ds_read_b128 v[178:181], v151 offset:35840
	ds_read_b128 v[188:191], v151 offset:36864
	ds_read_b128 v[192:195], v151 offset:37888
	ds_read_b128 v[196:199], v151 offset:38912
	ds_read_b128 v[200:203], v151 offset:39936
	global_load_lds_dwordx4 v[204:205], off
	v_lshl_add_u64 v[204:205], s[42:43], 0, v[132:133]
	s_mov_b32 m0, s58
	s_nop 0
	global_load_lds_dwordx4 v[204:205], off
	s_waitcnt lgkmcnt(8)
	s_barrier
; #define PG8_STAGE(bufoff, gbase, voff) do { _Pragma("unroll") for (int _i = 0; _i < 2; ++_i) \
;         __builtin_amdgcn_global_load_lds((const unsigned*)((const char*)(gbase) + (voff)[_i]), (LAS unsigned*)(lds + (bufoff) + ldsw + _i * 8192), 16, 0, 0); } while (0)
; #define PG8_LDA(dst, b, h) do { _Pragma("unroll") for (int m = 0; m < 4; ++m) _Pragma("unroll") for (int k = 0; k < 2; ++k) dst[m][k] = *(const LAS bf16x8*)(lds + PG8_SA(b, h) + aoff + m * 2048 + k * 1024); } while (0)
; #define PG8_LDB(dst, b, h) do { _Pragma("unroll") for (int n = 0; n < 2; ++n) _Pragma("unroll") for (int k = 0; k < 2; ++k) dst[n][k] = *(const LAS bf16x8*)(lds + PG8_SB(b, h) + boff + n * 2048 + k * 1024); } while (0)
; #define PG8_MMA(ai, bj, At, Bt) do { __builtin_amdgcn_s_setprio(1); _Pragma("unroll") for (int m = 0; m < 4; ++m) _Pragma("unroll") for (int n = 0; n < 2; ++n) _Pragma("unroll") for (int k = 0; k < 2; ++k) \
;         acc[ai][bj][m][n] = __builtin_amdgcn_mfma_f32_16x16x32_bf16(Bt[n][k], At[m][k], acc[ai][bj][m][n], 0, 0, 0); __builtin_amdgcn_s_setprio(0); } while (0)
; #define PG8_WAIT_V(n) asm volatile("s_waitcnt vmcnt(" #n ")" ::: "memory")
; #define PG8_WAIT_L(n) asm volatile("s_waitcnt lgkmcnt(" #n ")" ::: "memory")
; #define PG8_BAR __builtin_amdgcn_s_barrier()
; #define PG8_SCHED __builtin_amdgcn_sched_barrier(0)
; template <class Epi>
; DI void gemm_phase(LAS unsigned char* lds, const Gemm g, const StaticOrder& S, const Epi& E) {
;     ...
;             PG8_WAIT_L(8); PG8_BAR; PG8_WAIT_L(0); PG8_MMA(0, 0, At, B0); PG8_BAR; PG8_SCHED;
;             PG8_LDB(B1, 1, 1); PG8_STAGE(PG8_SB(1, 0), b3, voffB);
;             PG8_BAR; PG8_WAIT_L(0); PG8_MMA(0, 1, At, B1); PG8_BAR;
;             PG8_LDA(At, 1, 1); PG8_STAGE(PG8_SA(1, 0), a3, voffA);
;             PG8_BAR; PG8_WAIT_L(0); PG8_MMA(1, 0, At, B0); PG8_BAR; PG8_SCHED;
;             PG8_STAGE(PG8_SB(1, 1), b3 + hstep, voffB);
;             PG8_WAIT_V(6); PG8_BAR; PG8_MMA(1, 1, At, B1); PG8_BAR;
;         }
	s_waitcnt lgkmcnt(0)
	s_waitcnt lgkmcnt(0)
	v_mfma_f32_16x16x32_bf16 v[120:123], v[140:143], v[160:163], v[120:123]
	v_mfma_f32_16x16x32_bf16 v[124:127], v[152:155], v[160:163], v[124:127]
	v_mfma_f32_16x16x32_bf16 v[108:111], v[140:143], v[174:177], v[108:111]
	v_mfma_f32_16x16x32_bf16 v[104:107], v[152:155], v[174:177], v[104:107]
	v_mfma_f32_16x16x32_bf16 v[92:95], v[140:143], v[188:191], v[92:95]
	v_mfma_f32_16x16x32_bf16 v[88:91], v[152:155], v[188:191], v[88:91]
	v_mfma_f32_16x16x32_bf16 v[76:79], v[140:143], v[196:199], v[76:79]
	v_mfma_f32_16x16x32_bf16 v[72:75], v[152:155], v[196:199], v[72:75]
	v_mfma_f32_16x16x32_bf16 v[120:123], v[144:147], v[170:173], v[120:123]
	v_mfma_f32_16x16x32_bf16 v[124:127], v[156:159], v[170:173], v[124:127]
	v_mfma_f32_16x16x32_bf16 v[108:111], v[144:147], v[178:181], v[108:111]
	v_mfma_f32_16x16x32_bf16 v[104:107], v[156:159], v[178:181], v[104:107]
	v_mfma_f32_16x16x32_bf16 v[92:95], v[144:147], v[192:195], v[92:95]
	v_mfma_f32_16x16x32_bf16 v[88:91], v[156:159], v[192:195], v[88:91]
	v_mfma_f32_16x16x32_bf16 v[76:79], v[144:147], v[200:203], v[76:79]
	v_mfma_f32_16x16x32_bf16 v[72:75], v[156:159], v[200:203], v[72:75]
	s_barrier
	s_add_i32 s42, s75, 0x100
	s_add_i32 s4, s4, s54
	v_add_u32_e32 v166, s42, v150
	v_lshl_add_u64 v[182:183], v[182:183], 0, s[76:77]
	s_mov_b32 m0, s4
	ds_read_b128 v[204:207], v166
	ds_read_b128 v[208:211], v166 offset:1024
	ds_read_b128 v[212:215], v166 offset:2048
	ds_read_b128 v[216:219], v166 offset:3072
	global_load_lds_dwordx4 v[182:183], off
	v_lshl_add_u64 v[182:183], v[220:221], 0, s[76:77]
	s_add_i32 m0, s4, 0x2000
	s_nop 0
	global_load_lds_dwordx4 v[182:183], off
	s_barrier
	s_waitcnt lgkmcnt(0)
	s_waitcnt lgkmcnt(0)
	v_mfma_f32_16x16x32_bf16 v[116:119], v[204:207], v[160:163], v[116:119]
	v_mfma_f32_16x16x32_bf16 v[112:115], v[212:215], v[160:163], v[112:115]
	v_mfma_f32_16x16x32_bf16 v[100:103], v[204:207], v[174:177], v[100:103]
	v_mfma_f32_16x16x32_bf16 v[96:99], v[212:215], v[174:177], v[96:99]
	v_mfma_f32_16x16x32_bf16 v[84:87], v[204:207], v[188:191], v[84:87]
	v_mfma_f32_16x16x32_bf16 v[80:83], v[212:215], v[188:191], v[80:83]
	v_mfma_f32_16x16x32_bf16 v[68:71], v[204:207], v[196:199], v[68:71]
	v_mfma_f32_16x16x32_bf16 v[64:67], v[212:215], v[196:199], v[64:67]
	v_mfma_f32_16x16x32_bf16 v[116:119], v[208:211], v[170:173], v[116:119]
	v_mfma_f32_16x16x32_bf16 v[112:115], v[216:219], v[170:173], v[112:115]
	v_mfma_f32_16x16x32_bf16 v[100:103], v[208:211], v[178:181], v[100:103]
	v_mfma_f32_16x16x32_bf16 v[96:99], v[216:219], v[178:181], v[96:99]
	v_mfma_f32_16x16x32_bf16 v[84:87], v[208:211], v[192:195], v[84:87]
	v_mfma_f32_16x16x32_bf16 v[80:83], v[216:219], v[192:195], v[80:83]
	v_mfma_f32_16x16x32_bf16 v[68:71], v[208:211], v[200:203], v[68:71]
	v_mfma_f32_16x16x32_bf16 v[64:67], v[216:219], v[200:203], v[64:67]
	s_mov_b32 m0, s61
	v_lshl_add_u64 v[182:183], v[222:223], 0, s[76:77]
	s_barrier
	ds_read_b128 v[160:163], v151 offset:49152
	ds_read_b128 v[170:173], v151 offset:50176
	ds_read_b128 v[174:177], v151 offset:51200
	ds_read_b128 v[178:181], v151 offset:52224
	ds_read_b128 v[188:191], v151 offset:53248
	ds_read_b128 v[192:195], v151 offset:54272
	ds_read_b128 v[196:199], v151 offset:55296
	ds_read_b128 v[200:203], v151 offset:56320
	global_load_lds_dwordx4 v[182:183], off
	v_lshl_add_u64 v[182:183], v[224:225], 0, s[76:77]
	s_mov_b32 m0, s62
	s_nop 0
	global_load_lds_dwordx4 v[182:183], off
	s_barrier
	s_waitcnt lgkmcnt(0)
	s_waitcnt lgkmcnt(0)
	v_mfma_f32_16x16x32_bf16 v[60:63], v[140:143], v[160:163], v[60:63]
	v_mfma_f32_16x16x32_bf16 v[56:59], v[152:155], v[160:163], v[56:59]
	v_mfma_f32_16x16x32_bf16 v[44:47], v[140:143], v[174:177], v[44:47]
	v_mfma_f32_16x16x32_bf16 v[40:43], v[152:155], v[174:177], v[40:43]
	v_mfma_f32_16x16x32_bf16 v[28:31], v[140:143], v[188:191], v[28:31]
	v_mfma_f32_16x16x32_bf16 v[24:27], v[152:155], v[188:191], v[24:27]
	v_mfma_f32_16x16x32_bf16 v[12:15], v[140:143], v[196:199], v[12:15]
	v_mfma_f32_16x16x32_bf16 v[8:11], v[152:155], v[196:199], v[8:11]
	v_mfma_f32_16x16x32_bf16 v[60:63], v[144:147], v[170:173], v[60:63]
	v_mfma_f32_16x16x32_bf16 v[56:59], v[156:159], v[170:173], v[56:59]
	v_mfma_f32_16x16x32_bf16 v[44:47], v[144:147], v[178:181], v[44:47]
	v_mfma_f32_16x16x32_bf16 v[40:43], v[156:159], v[178:181], v[40:43]
	v_mfma_f32_16x16x32_bf16 v[28:31], v[144:147], v[192:195], v[28:31]
	v_mfma_f32_16x16x32_bf16 v[24:27], v[156:159], v[192:195], v[24:27]
	v_mfma_f32_16x16x32_bf16 v[12:15], v[144:147], v[200:203], v[12:15]
	v_mfma_f32_16x16x32_bf16 v[8:11], v[156:159], v[200:203], v[8:11]
	s_barrier
	s_add_i32 s4, s42, s54
	v_lshl_add_u64 v[140:141], v[226:227], 0, s[76:77]
	s_mov_b32 m0, s4
	s_nop 0
	global_load_lds_dwordx4 v[140:141], off
	v_lshl_add_u64 v[140:141], v[228:229], 0, s[76:77]
	s_add_i32 m0, s4, 0x2000
	s_nop 0
	global_load_lds_dwordx4 v[140:141], off
	s_waitcnt vmcnt(6)
	s_barrier
	v_mfma_f32_16x16x32_bf16 v[52:55], v[204:207], v[160:163], v[52:55]
	v_mfma_f32_16x16x32_bf16 v[48:51], v[212:215], v[160:163], v[48:51]
	v_mfma_f32_16x16x32_bf16 v[36:39], v[204:207], v[174:177], v[36:39]
	v_mfma_f32_16x16x32_bf16 v[32:35], v[212:215], v[174:177], v[32:35]
	v_mfma_f32_16x16x32_bf16 v[20:23], v[204:207], v[188:191], v[20:23]
	v_mfma_f32_16x16x32_bf16 v[16:19], v[212:215], v[188:191], v[16:19]
	v_mfma_f32_16x16x32_bf16 v[4:7], v[204:207], v[196:199], v[4:7]
	v_mfma_f32_16x16x32_bf16 v[0:3], v[212:215], v[196:199], v[0:3]
	v_mfma_f32_16x16x32_bf16 v[52:55], v[208:211], v[170:173], v[52:55]
	v_mfma_f32_16x16x32_bf16 v[48:51], v[216:219], v[170:173], v[48:51]
	v_mfma_f32_16x16x32_bf16 v[36:39], v[208:211], v[178:181], v[36:39]
	v_mfma_f32_16x16x32_bf16 v[32:35], v[216:219], v[178:181], v[32:35]
	v_mfma_f32_16x16x32_bf16 v[20:23], v[208:211], v[192:195], v[20:23]
	v_mfma_f32_16x16x32_bf16 v[16:19], v[216:219], v[192:195], v[16:19]
	v_mfma_f32_16x16x32_bf16 v[4:7], v[208:211], v[200:203], v[4:7]
	v_mfma_f32_16x16x32_bf16 v[0:3], v[216:219], v[200:203], v[0:3]
	s_add_u32 s40, s40, 0x100
	s_addc_u32 s41, s41, 0
	s_add_u32 s0, s0, 0x100
	s_addc_u32 s46, s46, 0
	s_cmp_ge_i32 s5, s33
	s_mov_b32 s4, s5
	s_barrier
	s_cbranch_scc0 .LBB0_645

; #define PG8_WAIT_V(n) asm volatile("s_waitcnt vmcnt(" #n ")" ::: "memory")
; #define PG8_BAR __builtin_amdgcn_s_barrier()
; template <class Epi>
; DI void gemm_phase(LAS unsigned char* lds, const Gemm g, const StaticOrder& S, const Epi& E) {
;     ...
;     PG8_WAIT_V(0);
;     if (wr == 0) PG8_BAR;
;     PG8_BAR;
.LBB0_704:
	v_readlane_b32 s40, v236, 23
	v_readlane_b32 s42, v238, 30
	v_readlane_b32 s44, v236, 29
	v_readlane_b32 s33, v236, 20
	v_readlane_b32 s41, v236, 24
	v_readlane_b32 s43, v238, 31
	v_readlane_b32 s45, v236, 30
	s_barrier
	s_setprio 0

; #define PG8_STAGE(bufoff, gbase, voff) do { _Pragma("unroll") for (int _i = 0; _i < 2; ++_i) \
;         __builtin_amdgcn_global_load_lds((const unsigned*)((const char*)(gbase) + (voff)[_i]), (LAS unsigned*)(lds + (bufoff) + ldsw + _i * 8192), 16, 0, 0); } while (0)
; #define PG8_BAR __builtin_amdgcn_s_barrier()
; template <class Epi>
; DI void gemm_phase(LAS unsigned char* lds, const Gemm g, const StaticOrder& S, const Epi& E) {
;     ...
;     for (int i = 0; i < 2; ++i) { int R, C; stage_rc(tid * 16 + i * 8192, R, C); const int Rb = (R & ~31) + perm32(R & 31);
;         voffA[i] = (unsigned)(R * K + C) * 2u; voffB[i] = (unsigned)(Rb * K + C) * 2u; }
;     const size_t kstep = (size_t)(BK * 2);
;     const size_t hstep = (size_t)HALF * K * 2;
;     const size_t tstep = 2 * hstep;
;     const unsigned ldsw = (unsigned)wid * 1024u;
;     const int aoff = lds_byte(wr * 64 + fr, fq * 8), boff = lds_byte(wc * 32 + fr, fq * 8);
;     ...
;     Unit cur, nxt; int ui = 0;
;     if (!S.next(0, cur)) return;
;     f32x4 acc[2][2][4][2];
; #pragma unroll
;     for (int a = 0; a < 2; ++a)
; #pragma unroll
;         for (int b = 0; b < 2; ++b)
; #pragma unroll
;             for (int m = 0; m < 4; ++m)
; #pragma unroll
;                 for (int n = 0; n < 2; ++n) acc[a][b][m][n] = (f32x4){0.f, 0.f, 0.f, 0.f};
;     bf16x8 At[4][2], B0[2][2], B1[2][2];
;     const char* cA = (const char*)g.A + (size_t)cur.pm * tstep; const char* cB = (const char*)g.Bt + (size_t)cur.pn * tstep;
;     PG8_STAGE(PG8_SB(0, 0), cB, voffB); PG8_STAGE(PG8_SA(0, 0), cA, voffA); PG8_STAGE(PG8_SB(0, 1), cB + hstep, voffB); PG8_STAGE(PG8_SA(0, 1), cA + hstep, voffA);
;     if (wr == 1) PG8_BAR;
.LBB0_1218:
	s_andn2_b64 vcc, exec, s[10:11]
	s_cbranch_vccnz .LBB0_1251
	v_bfe_i32 v2, v18, 27, 1
	v_lshlrev_b32_e32 v0, 4, v18
	v_lshrrev_b32_e32 v2, 22, v2
	v_add_u32_e32 v2, v0, v2
	v_and_b32_e32 v2, 0xfffffc00, v2
	v_ashrrev_i32_e32 v1, 31, v18
	v_sub_u32_e32 v2, v0, v2
	v_lshrrev_b32_e32 v1, 26, v1
	v_lshrrev_b32_e32 v3, 4, v2
	v_add_u32_e32 v1, v18, v1
	v_bitop3_b32 v3, v3, v2, 32 bitop3:0x6c
	v_ashrrev_i32_e32 v2, 31, v2
	v_ashrrev_i32_e32 v1, 6, v1
	v_lshrrev_b32_e32 v2, 26, v2
	v_lshlrev_b32_e32 v4, 3, v1
	v_add_u32_e32 v2, v3, v2
	v_and_b32_e32 v4, -16, v4
	v_ashrrev_i32_e32 v2, 6, v2
	v_lshlrev_b32_e32 v1, 5, v1
	v_add_u32_e32 v4, v2, v4
	v_and_b32_e32 v12, 32, v1
	v_mul_i32_i24_e32 v1, 64, v2
	v_sub_u32_e32 v1, v3, v1
	v_lshlrev_b32_e32 v3, 1, v4
	v_lshrrev_b32_e32 v5, 2, v4
	v_and_b32_e32 v2, 3, v2
	s_mov_b32 s4, 0x7fffffe0
	v_ashrrev_i16_sdwa v1, v169, sext(v1) dst_sel:DWORD dst_unused:UNUSED_PAD src0_sel:DWORD src1_sel:BYTE_0
	v_and_b32_e32 v3, 24, v3
	v_and_b32_e32 v5, 4, v5
	v_and_or_b32 v2, v4, s4, v2
	v_bfe_i32 v13, v1, 0, 16
	v_or3_b32 v2, v2, v5, v3
	v_add_u32_e32 v1, v12, v13
	v_mul_lo_u32 v14, v4, s14
	v_mul_lo_u32 v2, v2, s14
	v_add_u32_e32 v0, 0x2000, v0
	s_waitcnt vmcnt(8)
	v_add_lshl_u32 v128, v1, v14, 1
	v_add_lshl_u32 v166, v2, v1, 1
	v_ashrrev_i32_e32 v1, 31, v0
	v_lshrrev_b32_e32 v1, 22, v1
	v_add_u32_e32 v1, v0, v1
	v_ashrrev_i32_e32 v1, 10, v1
	v_mul_i32_i24_e32 v2, 0x400, v1
	v_sub_u32_e32 v0, v0, v2
	v_readlane_b32 s3, v236, 31
	v_lshrrev_b32_e32 v2, 4, v0
	s_add_u32 s48, s3, 0x750000
	v_readlane_b32 s3, v236, 32
	v_bitop3_b32 v0, v2, v0, 32 bitop3:0x6c
	s_addc_u32 s49, s3, 0
	v_ashrrev_i32_e32 v3, 31, v0
	s_ashr_i32 s15, s14, 31
	v_lshrrev_b32_e32 v3, 26, v3
	s_lshl_b64 s[12:13], s[14:15], 9
	s_ashr_i32 s5, s78, 31
	v_lshlrev_b32_e32 v2, 3, v1
	v_add_u32_e32 v3, v0, v3
	s_mul_i32 s5, s12, s5
	s_mul_hi_u32 s16, s12, s78
	s_ashr_i32 s18, s71, 31
	v_and_b32_e32 v2, -16, v2
	v_ashrrev_i32_e32 v4, 6, v3
	s_add_i32 s5, s16, s5
	s_lshr_b64 s[16:17], s[14:15], 23
	s_mul_i32 s18, s12, s18
	s_mul_hi_u32 s19, s12, s71
	s_ashr_i32 s3, s46, 6
	v_add_u32_e32 v2, v4, v2
	v_lshlrev_b32_e32 v1, 5, v1
	v_and_b32_e32 v4, 3, v4
	s_mul_i32 s17, s16, s78
	s_add_i32 s18, s19, s18
	s_mul_i32 s16, s16, s71
	v_and_b32_e32 v15, 32, v1
	v_and_b32_e32 v1, 0xc0, v3
	v_and_or_b32 v4, v2, s4, v4
	s_ashr_i32 s4, s46, 8
	s_lshl_b64 s[10:11], s[14:15], 8
	s_lshl_b32 s50, s3, 10
	s_add_i32 s5, s5, s17
	s_add_i32 s18, s18, s16
	s_mul_i32 s16, s12, s71
	v_sub_u32_e32 v0, v0, v1
	v_lshlrev_b32_e32 v1, 1, v2
	v_lshrrev_b32_e32 v3, 2, v2
	s_add_u32 s44, s48, s16
	v_ashrrev_i16_sdwa v0, v169, sext(v0) dst_sel:DWORD dst_unused:UNUSED_PAD src0_sel:DWORD src1_sel:BYTE_0
	v_and_b32_e32 v1, 24, v1
	v_and_b32_e32 v3, 4, v3
	s_addc_u32 s45, s49, s18
	s_add_i32 s51, s50, 0x100
	v_bfe_i32 v16, v0, 0, 16
	v_or3_b32 v1, v4, v3, v1
	s_add_i32 m0, s51, 0x10000
	v_readlane_b32 s52, v238, 1
	v_add_u32_e32 v0, v15, v16
	v_mul_lo_u32 v1, v1, s14
	s_mul_i32 s17, s12, s78
	global_load_lds_dwordx4 v166, s[44:45]
	s_add_i32 m0, s51, 0x12000
	v_readlane_b32 s64, v238, 13
	v_add_lshl_u32 v132, v1, v0, 1
	v_readlane_b32 s65, v238, 14
	s_add_u32 s36, s64, s17
	v_mul_lo_u32 v17, v2, s14
	global_load_lds_dwordx4 v132, s[44:45]
	s_addc_u32 s37, s65, s5
	s_mov_b32 m0, s51
	s_add_i32 s79, s51, 0x2000
	v_add_lshl_u32 v130, v0, v17, 1
	global_load_lds_dwordx4 v128, s[36:37]
	s_mov_b32 m0, s79
	s_add_u32 s16, s44, s10
	global_load_lds_dwordx4 v130, s[36:37]
	s_addc_u32 s17, s45, s11
	s_add_i32 m0, s51, 0x14000
	v_mov_b32_e32 v133, v167
	global_load_lds_dwordx4 v166, s[16:17]
	s_add_i32 m0, s51, 0x16000
	v_lshl_add_u64 v[8:9], s[16:17], 0, v[166:167]
	v_lshl_add_u64 v[10:11], s[16:17], 0, v[132:133]
	global_load_lds_dwordx4 v132, s[16:17]
	s_add_u32 s16, s36, s10
	s_addc_u32 s17, s37, s11
	s_add_i32 s88, s51, 0x4000
	s_mov_b32 m0, s88
	s_add_i32 s89, s51, 0x6000
	global_load_lds_dwordx4 v128, s[16:17]
	s_mov_b32 m0, s89
	v_mov_b32_e32 v129, v167
	global_load_lds_dwordx4 v130, s[16:17]
	v_mov_b32_e32 v131, v167
	v_lshl_add_u64 v[0:1], s[44:45], 0, v[166:167]
	v_lshl_add_u64 v[2:3], s[44:45], 0, v[132:133]
	v_lshl_add_u64 v[4:5], s[36:37], 0, v[128:129]
	v_lshl_add_u64 v[6:7], s[36:37], 0, v[130:131]
	s_cmp_lg_u32 s4, 1
	v_readlane_b32 s53, v238, 2
	v_readlane_b32 s54, v238, 3
	v_readlane_b32 s55, v238, 4
	v_readlane_b32 s56, v238, 5
	v_readlane_b32 s57, v238, 6
	v_readlane_b32 s58, v238, 7
	v_readlane_b32 s59, v238, 8
	v_readlane_b32 s60, v238, 9
	v_readlane_b32 s61, v238, 10
	v_readlane_b32 s62, v238, 11
	v_readlane_b32 s63, v238, 12
	v_readlane_b32 s66, v238, 15
	v_readlane_b32 s67, v238, 16
	s_cbranch_scc1 .LBB0_1221
	s_setprio 1
	s_barrier

; #define PG8_STAGE(bufoff, gbase, voff) do { _Pragma("unroll") for (int _i = 0; _i < 2; ++_i) \
;         __builtin_amdgcn_global_load_lds((const unsigned*)((const char*)(gbase) + (voff)[_i]), (LAS unsigned*)(lds + (bufoff) + ldsw + _i * 8192), 16, 0, 0); } while (0)
; #define PG8_LDA(dst, b, h) do { _Pragma("unroll") for (int m = 0; m < 4; ++m) _Pragma("unroll") for (int k = 0; k < 2; ++k) dst[m][k] = *(const LAS bf16x8*)(lds + PG8_SA(b, h) + aoff + m * 2048 + k * 1024); } while (0)
; #define PG8_LDB(dst, b, h) do { _Pragma("unroll") for (int n = 0; n < 2; ++n) _Pragma("unroll") for (int k = 0; k < 2; ++k) dst[n][k] = *(const LAS bf16x8*)(lds + PG8_SB(b, h) + boff + n * 2048 + k * 1024); } while (0)
; #define PG8_MMA(ai, bj, At, Bt) do { __builtin_amdgcn_s_setprio(1); _Pragma("unroll") for (int m = 0; m < 4; ++m) _Pragma("unroll") for (int n = 0; n < 2; ++n) _Pragma("unroll") for (int k = 0; k < 2; ++k) \
;         acc[ai][bj][m][n] = __builtin_amdgcn_mfma_f32_16x16x32_bf16(Bt[n][k], At[m][k], acc[ai][bj][m][n], 0, 0, 0); __builtin_amdgcn_s_setprio(0); } while (0)
; #define PG8_WAIT_V(n) asm volatile("s_waitcnt vmcnt(" #n ")" ::: "memory")
; #define PG8_WAIT_L(n) asm volatile("s_waitcnt lgkmcnt(" #n ")" ::: "memory")
; #define PG8_BAR __builtin_amdgcn_s_barrier()
; template <class Epi>
; DI void gemm_phase(LAS unsigned char* lds, const Gemm g, const StaticOrder& S, const Epi& E) {
;     ...
;         for (int t = 0; t < nt; t += 2) {
;             const bool last = (t == nt - 2);
;             const char* a1 = cA + (size_t)(t + 1) * kstep;
;             const char* a2 = last ? nA : cA + (size_t)(t + 2) * kstep; const char* b2 = last ? nB : cB + (size_t)(t + 2) * kstep;
;             const char* a3 = a2 + kstep; const char* b3 = b2 + kstep;
;             PG8_LDB(B0, 0, 0); PG8_SCHED; PG8_LDA(At, 0, 0); PG8_STAGE(PG8_SA(1, 1), a1 + hstep, voffA);
;             PG8_WAIT_L(8); PG8_BAR; PG8_WAIT_L(0); PG8_MMA(0, 0, At, B0); PG8_BAR; PG8_SCHED;
;             PG8_LDB(B1, 0, 1); PG8_STAGE(PG8_SB(0, 0), b2, voffB);
;             PG8_BAR; PG8_WAIT_L(0); PG8_MMA(0, 1, At, B1); PG8_BAR;
;             PG8_LDA(At, 0, 1); PG8_STAGE(PG8_SA(0, 0), a2, voffA);
;             PG8_BAR; PG8_WAIT_L(0); PG8_MMA(1, 0, At, B0); PG8_BAR; PG8_SCHED;
;             PG8_STAGE(PG8_SB(0, 1), b2 + hstep, voffB);
;             PG8_WAIT_V(6); PG8_BAR; PG8_MMA(1, 1, At, B1); PG8_BAR;
.LBB0_1229:
	s_andn2_b64 vcc, exec, s[14:15]
	s_waitcnt lgkmcnt(0)
	s_cbranch_vccnz .LBB0_1232
	s_add_u32 s36, s36, 0x80
	s_addc_u32 s37, s37, 0
	s_add_u32 s0, s44, 0x100
	s_addc_u32 s44, s45, 0
	s_mov_b32 s4, 0
	s_add_i32 s5, s4, 2
	s_add_u32 s40, s36, 0x80
	s_addc_u32 s41, s37, 0
	s_add_i32 s45, s60, 0x100
	v_add_u32_e32 v154, s45, v144
	ds_read_b128 v[138:141], v154
	ds_read_b128 v[146:149], v154 offset:1024
	ds_read_b128 v[150:153], v154 offset:2048
	ds_read_b128 v[154:157], v154 offset:3072
	s_cmp_eq_u32 s76, s4
	s_cselect_b32 s41, s17, s41
	s_cselect_b32 s40, s16, s40
	s_cselect_b32 s43, s19, s44
	s_cselect_b32 s42, s18, s0
	v_lshl_add_u64 v[162:163], s[36:37], 0, v[134:135]
	s_add_i32 m0, s51, 0xc000
	ds_read_b128 v[158:161], v145
	ds_read_b128 v[170:173], v145 offset:1024
	ds_read_b128 v[174:177], v145 offset:2048
	ds_read_b128 v[178:181], v145 offset:3072
	ds_read_b128 v[188:191], v145 offset:4096
	ds_read_b128 v[192:195], v145 offset:5120
	ds_read_b128 v[196:199], v145 offset:6144
	ds_read_b128 v[200:203], v145 offset:7168
	global_load_lds_dwordx4 v[162:163], off
	v_lshl_add_u64 v[162:163], s[36:37], 0, v[136:137]
	s_add_i32 m0, s51, 0xe000
	s_nop 0
	global_load_lds_dwordx4 v[162:163], off
	s_waitcnt lgkmcnt(8)
	s_barrier
	s_waitcnt lgkmcnt(0)
	s_waitcnt lgkmcnt(0)
	v_mfma_f32_16x16x32_bf16 v[124:127], v[138:141], v[158:161], 0
	v_mfma_f32_16x16x32_bf16 v[120:123], v[150:153], v[158:161], 0
	v_mfma_f32_16x16x32_bf16 v[108:111], v[138:141], v[174:177], 0
	v_mfma_f32_16x16x32_bf16 v[104:107], v[150:153], v[174:177], 0
	v_mfma_f32_16x16x32_bf16 v[92:95], v[138:141], v[188:191], 0
	v_mfma_f32_16x16x32_bf16 v[88:91], v[150:153], v[188:191], 0
	v_mfma_f32_16x16x32_bf16 v[76:79], v[138:141], v[196:199], 0
	v_mfma_f32_16x16x32_bf16 v[72:75], v[150:153], v[196:199], 0
	v_mfma_f32_16x16x32_bf16 v[124:127], v[146:149], v[170:173], v[124:127]
	v_mfma_f32_16x16x32_bf16 v[120:123], v[154:157], v[170:173], v[120:123]
	v_mfma_f32_16x16x32_bf16 v[108:111], v[146:149], v[178:181], v[108:111]
	v_mfma_f32_16x16x32_bf16 v[104:107], v[154:157], v[178:181], v[104:107]
	v_mfma_f32_16x16x32_bf16 v[92:95], v[146:149], v[192:195], v[92:95]
	v_mfma_f32_16x16x32_bf16 v[88:91], v[154:157], v[192:195], v[88:91]
	v_mfma_f32_16x16x32_bf16 v[76:79], v[146:149], v[200:203], v[76:79]
	v_mfma_f32_16x16x32_bf16 v[72:75], v[154:157], v[200:203], v[72:75]
	s_barrier
	s_add_i32 s4, s61, 0x100
	v_add_u32_e32 v162, s4, v144
	s_add_i32 s45, s45, s50
	ds_read_b128 v[204:207], v162
	ds_read_b128 v[208:211], v162 offset:1024
	ds_read_b128 v[212:215], v162 offset:2048
	ds_read_b128 v[216:219], v162 offset:3072
	v_lshl_add_u64 v[162:163], s[42:43], 0, v[166:167]
	s_mov_b32 m0, s45
	v_lshl_add_u64 v[182:183], s[42:43], 0, v[132:133]
	global_load_lds_dwordx4 v[162:163], off
	s_add_i32 m0, s45, 0x2000
	s_nop 0
	global_load_lds_dwordx4 v[182:183], off
	s_barrier
	s_waitcnt lgkmcnt(0)
	s_waitcnt lgkmcnt(0)
	v_mfma_f32_16x16x32_bf16 v[116:119], v[204:207], v[158:161], 0
	v_mfma_f32_16x16x32_bf16 v[112:115], v[212:215], v[158:161], 0
	v_mfma_f32_16x16x32_bf16 v[100:103], v[204:207], v[174:177], 0
	v_mfma_f32_16x16x32_bf16 v[96:99], v[212:215], v[174:177], 0
	v_mfma_f32_16x16x32_bf16 v[84:87], v[204:207], v[188:191], 0
	v_mfma_f32_16x16x32_bf16 v[80:83], v[212:215], v[188:191], 0
	v_mfma_f32_16x16x32_bf16 v[68:71], v[204:207], v[196:199], 0
	v_mfma_f32_16x16x32_bf16 v[64:67], v[212:215], v[196:199], 0
	v_mfma_f32_16x16x32_bf16 v[116:119], v[208:211], v[170:173], v[116:119]
	v_mfma_f32_16x16x32_bf16 v[112:115], v[216:219], v[170:173], v[112:115]
	v_mfma_f32_16x16x32_bf16 v[100:103], v[208:211], v[178:181], v[100:103]
	v_mfma_f32_16x16x32_bf16 v[96:99], v[216:219], v[178:181], v[96:99]
	v_mfma_f32_16x16x32_bf16 v[84:87], v[208:211], v[192:195], v[84:87]
	v_mfma_f32_16x16x32_bf16 v[80:83], v[216:219], v[192:195], v[80:83]
	v_mfma_f32_16x16x32_bf16 v[68:71], v[208:211], v[200:203], v[68:71]
	v_mfma_f32_16x16x32_bf16 v[64:67], v[216:219], v[200:203], v[64:67]
	s_mov_b32 m0, s51
	v_lshl_add_u64 v[220:221], s[40:41], 0, v[128:129]
	s_barrier
	ds_read_b128 v[158:161], v145 offset:16384
	ds_read_b128 v[170:173], v145 offset:17408
	ds_read_b128 v[174:177], v145 offset:18432
	ds_read_b128 v[178:181], v145 offset:19456
	ds_read_b128 v[188:191], v145 offset:20480
	ds_read_b128 v[192:195], v145 offset:21504
	ds_read_b128 v[196:199], v145 offset:22528
	ds_read_b128 v[200:203], v145 offset:23552
	global_load_lds_dwordx4 v[220:221], off
	v_lshl_add_u64 v[222:223], s[40:41], 0, v[130:131]
	s_mov_b32 m0, s79
	s_nop 0
	global_load_lds_dwordx4 v[222:223], off
	s_barrier
	s_waitcnt lgkmcnt(0)
	s_waitcnt lgkmcnt(0)
	v_mfma_f32_16x16x32_bf16 v[60:63], v[138:141], v[158:161], 0
	v_mfma_f32_16x16x32_bf16 v[56:59], v[150:153], v[158:161], 0
	v_mfma_f32_16x16x32_bf16 v[44:47], v[138:141], v[174:177], 0
	v_mfma_f32_16x16x32_bf16 v[40:43], v[150:153], v[174:177], 0
	v_mfma_f32_16x16x32_bf16 v[28:31], v[138:141], v[188:191], 0
	v_mfma_f32_16x16x32_bf16 v[24:27], v[150:153], v[188:191], 0
	v_mfma_f32_16x16x32_bf16 v[12:15], v[138:141], v[196:199], 0
	v_mfma_f32_16x16x32_bf16 v[8:11], v[150:153], v[196:199], 0
	v_mfma_f32_16x16x32_bf16 v[60:63], v[146:149], v[170:173], v[60:63]
	v_mfma_f32_16x16x32_bf16 v[56:59], v[154:157], v[170:173], v[56:59]
	v_mfma_f32_16x16x32_bf16 v[44:47], v[146:149], v[178:181], v[44:47]
	v_mfma_f32_16x16x32_bf16 v[40:43], v[154:157], v[178:181], v[40:43]
	v_mfma_f32_16x16x32_bf16 v[28:31], v[146:149], v[192:195], v[28:31]
	v_mfma_f32_16x16x32_bf16 v[24:27], v[154:157], v[192:195], v[24:27]
	v_mfma_f32_16x16x32_bf16 v[12:15], v[146:149], v[200:203], v[12:15]
	v_mfma_f32_16x16x32_bf16 v[8:11], v[154:157], v[200:203], v[8:11]
	s_barrier
; #define PG8_STAGE(bufoff, gbase, voff) do { _Pragma("unroll") for (int _i = 0; _i < 2; ++_i) \
;         __builtin_amdgcn_global_load_lds((const unsigned*)((const char*)(gbase) + (voff)[_i]), (LAS unsigned*)(lds + (bufoff) + ldsw + _i * 8192), 16, 0, 0); } while (0)
; #define PG8_LDA(dst, b, h) do { _Pragma("unroll") for (int m = 0; m < 4; ++m) _Pragma("unroll") for (int k = 0; k < 2; ++k) dst[m][k] = *(const LAS bf16x8*)(lds + PG8_SA(b, h) + aoff + m * 2048 + k * 1024); } while (0)
; #define PG8_LDB(dst, b, h) do { _Pragma("unroll") for (int n = 0; n < 2; ++n) _Pragma("unroll") for (int k = 0; k < 2; ++k) dst[n][k] = *(const LAS bf16x8*)(lds + PG8_SB(b, h) + boff + n * 2048 + k * 1024); } while (0)
; #define PG8_MMA(ai, bj, At, Bt) do { __builtin_amdgcn_s_setprio(1); _Pragma("unroll") for (int m = 0; m < 4; ++m) _Pragma("unroll") for (int n = 0; n < 2; ++n) _Pragma("unroll") for (int k = 0; k < 2; ++k) \
;         acc[ai][bj][m][n] = __builtin_amdgcn_mfma_f32_16x16x32_bf16(Bt[n][k], At[m][k], acc[ai][bj][m][n], 0, 0, 0); __builtin_amdgcn_s_setprio(0); } while (0)
; #define PG8_WAIT_V(n) asm volatile("s_waitcnt vmcnt(" #n ")" ::: "memory")
; #define PG8_WAIT_L(n) asm volatile("s_waitcnt lgkmcnt(" #n ")" ::: "memory")
; #define PG8_BAR __builtin_amdgcn_s_barrier()
; #define PG8_SCHED __builtin_amdgcn_sched_barrier(0)
; template <class Epi>
; DI void gemm_phase(LAS unsigned char* lds, const Gemm g, const StaticOrder& S, const Epi& E) {
;     ...
;             PG8_WAIT_V(6); PG8_BAR; PG8_MMA(1, 1, At, B1); PG8_BAR;
;             PG8_LDB(B0, 1, 0); PG8_SCHED; PG8_LDA(At, 1, 0); PG8_STAGE(PG8_SA(0, 1), a2 + hstep, voffA);
;             PG8_WAIT_L(8); PG8_BAR; PG8_WAIT_L(0); PG8_MMA(0, 0, At, B0); PG8_BAR; PG8_SCHED;
;             PG8_LDB(B1, 1, 1); PG8_STAGE(PG8_SB(1, 0), b3, voffB);
;             PG8_BAR; PG8_WAIT_L(0); PG8_MMA(0, 1, At, B1); PG8_BAR;
;             PG8_LDA(At, 1, 1); PG8_STAGE(PG8_SA(1, 0), a3, voffA);
;             PG8_BAR; PG8_WAIT_L(0); PG8_MMA(1, 0, At, B0); PG8_BAR; PG8_SCHED;
	s_add_u32 s42, s42, s10
	s_addc_u32 s43, s43, s11
	s_add_i32 s4, s4, s50
	v_lshl_add_u64 v[224:225], s[42:43], 0, v[166:167]
	s_mov_b32 m0, s4
	v_lshl_add_u64 v[226:227], s[42:43], 0, v[132:133]
	global_load_lds_dwordx4 v[224:225], off
	s_add_i32 m0, s4, 0x2000
	s_nop 0
	global_load_lds_dwordx4 v[226:227], off
	s_waitcnt vmcnt(6)
	s_barrier
	v_mfma_f32_16x16x32_bf16 v[52:55], v[204:207], v[158:161], 0
	v_mfma_f32_16x16x32_bf16 v[48:51], v[212:215], v[158:161], 0
	v_mfma_f32_16x16x32_bf16 v[36:39], v[204:207], v[174:177], 0
	v_mfma_f32_16x16x32_bf16 v[32:35], v[212:215], v[174:177], 0
	v_mfma_f32_16x16x32_bf16 v[20:23], v[204:207], v[188:191], 0
	v_mfma_f32_16x16x32_bf16 v[16:19], v[212:215], v[188:191], 0
	v_mfma_f32_16x16x32_bf16 v[4:7], v[204:207], v[196:199], 0
	v_mfma_f32_16x16x32_bf16 v[0:3], v[212:215], v[196:199], 0
	v_mfma_f32_16x16x32_bf16 v[52:55], v[208:211], v[170:173], v[52:55]
	v_mfma_f32_16x16x32_bf16 v[48:51], v[216:219], v[170:173], v[48:51]
	v_mfma_f32_16x16x32_bf16 v[36:39], v[208:211], v[178:181], v[36:39]
	v_mfma_f32_16x16x32_bf16 v[32:35], v[216:219], v[178:181], v[32:35]
	v_mfma_f32_16x16x32_bf16 v[20:23], v[208:211], v[192:195], v[20:23]
	v_mfma_f32_16x16x32_bf16 v[16:19], v[216:219], v[192:195], v[16:19]
	v_mfma_f32_16x16x32_bf16 v[4:7], v[208:211], v[200:203], v[4:7]
	v_mfma_f32_16x16x32_bf16 v[0:3], v[216:219], v[200:203], v[0:3]
	s_add_i32 s4, s62, 0x100
	v_add_u32_e32 v154, s4, v144
	s_barrier
	ds_read_b128 v[138:141], v154
	ds_read_b128 v[146:149], v154 offset:1024
	ds_read_b128 v[150:153], v154 offset:2048
	ds_read_b128 v[154:157], v154 offset:3072
	s_add_u32 s40, s40, s10
	s_addc_u32 s41, s41, s11
	s_mov_b32 m0, s88
	v_lshl_add_u64 v[204:205], s[40:41], 0, v[128:129]
	ds_read_b128 v[158:161], v145 offset:32768
	ds_read_b128 v[170:173], v145 offset:33792
	ds_read_b128 v[174:177], v145 offset:34816
	ds_read_b128 v[178:181], v145 offset:35840
	ds_read_b128 v[188:191], v145 offset:36864
	ds_read_b128 v[192:195], v145 offset:37888
	ds_read_b128 v[196:199], v145 offset:38912
	ds_read_b128 v[200:203], v145 offset:39936
	global_load_lds_dwordx4 v[204:205], off
	v_lshl_add_u64 v[204:205], s[40:41], 0, v[130:131]
	s_mov_b32 m0, s89
	s_nop 0
	global_load_lds_dwordx4 v[204:205], off
	s_waitcnt lgkmcnt(8)
	s_barrier
	s_waitcnt lgkmcnt(0)
	s_waitcnt lgkmcnt(0)
	v_mfma_f32_16x16x32_bf16 v[124:127], v[138:141], v[158:161], v[124:127]
	v_mfma_f32_16x16x32_bf16 v[120:123], v[150:153], v[158:161], v[120:123]
	v_mfma_f32_16x16x32_bf16 v[108:111], v[138:141], v[174:177], v[108:111]
	v_mfma_f32_16x16x32_bf16 v[104:107], v[150:153], v[174:177], v[104:107]
	v_mfma_f32_16x16x32_bf16 v[92:95], v[138:141], v[188:191], v[92:95]
	v_mfma_f32_16x16x32_bf16 v[88:91], v[150:153], v[188:191], v[88:91]
	v_mfma_f32_16x16x32_bf16 v[76:79], v[138:141], v[196:199], v[76:79]
	v_mfma_f32_16x16x32_bf16 v[72:75], v[150:153], v[196:199], v[72:75]
	v_mfma_f32_16x16x32_bf16 v[124:127], v[146:149], v[170:173], v[124:127]
	v_mfma_f32_16x16x32_bf16 v[120:123], v[154:157], v[170:173], v[120:123]
	v_mfma_f32_16x16x32_bf16 v[108:111], v[146:149], v[178:181], v[108:111]
	v_mfma_f32_16x16x32_bf16 v[104:107], v[154:157], v[178:181], v[104:107]
	v_mfma_f32_16x16x32_bf16 v[92:95], v[146:149], v[192:195], v[92:95]
	v_mfma_f32_16x16x32_bf16 v[88:91], v[154:157], v[192:195], v[88:91]
	v_mfma_f32_16x16x32_bf16 v[76:79], v[146:149], v[200:203], v[76:79]
	v_mfma_f32_16x16x32_bf16 v[72:75], v[154:157], v[200:203], v[72:75]
	s_barrier
	s_add_i32 s40, s63, 0x100
	s_add_i32 s4, s4, s50
	v_add_u32_e32 v216, s40, v144
	v_lshl_add_u64 v[162:163], v[162:163], 0, s[66:67]
	s_mov_b32 m0, s4
	ds_read_b128 v[204:207], v216
	ds_read_b128 v[208:211], v216 offset:1024
	ds_read_b128 v[212:215], v216 offset:2048
	ds_read_b128 v[216:219], v216 offset:3072
	global_load_lds_dwordx4 v[162:163], off
	v_lshl_add_u64 v[162:163], v[182:183], 0, s[66:67]
	s_add_i32 m0, s4, 0x2000
	s_nop 0
	global_load_lds_dwordx4 v[162:163], off
	s_barrier
	s_waitcnt lgkmcnt(0)
	s_waitcnt lgkmcnt(0)
	v_mfma_f32_16x16x32_bf16 v[116:119], v[204:207], v[158:161], v[116:119]
	v_mfma_f32_16x16x32_bf16 v[112:115], v[212:215], v[158:161], v[112:115]
	v_mfma_f32_16x16x32_bf16 v[100:103], v[204:207], v[174:177], v[100:103]
	v_mfma_f32_16x16x32_bf16 v[96:99], v[212:215], v[174:177], v[96:99]
	v_mfma_f32_16x16x32_bf16 v[84:87], v[204:207], v[188:191], v[84:87]
	v_mfma_f32_16x16x32_bf16 v[80:83], v[212:215], v[188:191], v[80:83]
	v_mfma_f32_16x16x32_bf16 v[68:71], v[204:207], v[196:199], v[68:71]
	v_mfma_f32_16x16x32_bf16 v[64:67], v[212:215], v[196:199], v[64:67]
	v_mfma_f32_16x16x32_bf16 v[116:119], v[208:211], v[170:173], v[116:119]
	v_mfma_f32_16x16x32_bf16 v[112:115], v[216:219], v[170:173], v[112:115]
	v_mfma_f32_16x16x32_bf16 v[100:103], v[208:211], v[178:181], v[100:103]
	v_mfma_f32_16x16x32_bf16 v[96:99], v[216:219], v[178:181], v[96:99]
	v_mfma_f32_16x16x32_bf16 v[84:87], v[208:211], v[192:195], v[84:87]
	v_mfma_f32_16x16x32_bf16 v[80:83], v[216:219], v[192:195], v[80:83]
	v_mfma_f32_16x16x32_bf16 v[68:71], v[208:211], v[200:203], v[68:71]
	v_mfma_f32_16x16x32_bf16 v[64:67], v[216:219], v[200:203], v[64:67]
	s_mov_b32 m0, s90
	v_lshl_add_u64 v[162:163], v[220:221], 0, s[66:67]
	s_barrier
	ds_read_b128 v[158:161], v145 offset:49152
	ds_read_b128 v[170:173], v145 offset:50176
	ds_read_b128 v[174:177], v145 offset:51200
	ds_read_b128 v[178:181], v145 offset:52224
	ds_read_b128 v[188:191], v145 offset:53248
	ds_read_b128 v[192:195], v145 offset:54272
	ds_read_b128 v[196:199], v145 offset:55296
	ds_read_b128 v[200:203], v145 offset:56320
	global_load_lds_dwordx4 v[162:163], off
	v_lshl_add_u64 v[162:163], v[222:223], 0, s[66:67]
	s_mov_b32 m0, s91
	s_nop 0
	global_load_lds_dwordx4 v[162:163], off
	s_barrier
; #define PG8_STAGE(bufoff, gbase, voff) do { _Pragma("unroll") for (int _i = 0; _i < 2; ++_i) \
;         __builtin_amdgcn_global_load_lds((const unsigned*)((const char*)(gbase) + (voff)[_i]), (LAS unsigned*)(lds + (bufoff) + ldsw + _i * 8192), 16, 0, 0); } while (0)
; #define PG8_LDA(dst, b, h) do { _Pragma("unroll") for (int m = 0; m < 4; ++m) _Pragma("unroll") for (int k = 0; k < 2; ++k) dst[m][k] = *(const LAS bf16x8*)(lds + PG8_SA(b, h) + aoff + m * 2048 + k * 1024); } while (0)
; #define PG8_LDB(dst, b, h) do { _Pragma("unroll") for (int n = 0; n < 2; ++n) _Pragma("unroll") for (int k = 0; k < 2; ++k) dst[n][k] = *(const LAS bf16x8*)(lds + PG8_SB(b, h) + boff + n * 2048 + k * 1024); } while (0)
; #define PG8_WAIT_V(n) asm volatile("s_waitcnt vmcnt(" #n ")" ::: "memory")
; #define PG8_WAIT_L(n) asm volatile("s_waitcnt lgkmcnt(" #n ")" ::: "memory")
; #define PG8_BAR __builtin_amdgcn_s_barrier()
; #define PG8_SCHED __builtin_amdgcn_sched_barrier(0)
; template <class Epi>
; DI void gemm_phase(LAS unsigned char* lds, const Gemm g, const StaticOrder& S, const Epi& E) {
;     ...
;             PG8_LDB(B0, 0, 0); PG8_SCHED; PG8_LDA(At, 0, 0); PG8_STAGE(PG8_SA(1, 1), a1 + hstep, voffA);
;             PG8_WAIT_L(8); PG8_BAR; PG8_WAIT_L(0); PG8_MMA(0, 0, At, B0); PG8_BAR; PG8_SCHED;
;             PG8_LDB(B1, 0, 1); PG8_STAGE(PG8_SB(0, 0), b2, voffB);
;             PG8_BAR; PG8_WAIT_L(0); PG8_MMA(0, 1, At, B1); PG8_BAR;
;             PG8_LDA(At, 0, 1); PG8_STAGE(PG8_SA(0, 0), a2, voffA);
;             PG8_BAR; PG8_WAIT_L(0); PG8_MMA(1, 0, At, B0); PG8_BAR; PG8_SCHED;
;             PG8_STAGE(PG8_SB(0, 1), b2 + hstep, voffB);
;             PG8_WAIT_V(6); PG8_BAR; PG8_MMA(1, 1, At, B1); PG8_BAR;
;             PG8_LDB(B0, 1, 0); PG8_SCHED; PG8_LDA(At, 1, 0); PG8_STAGE(PG8_SA(0, 1), a2 + hstep, voffA);
;             PG8_WAIT_L(8); PG8_BAR; PG8_WAIT_L(0); PG8_MMA(0, 0, At, B0); PG8_BAR; PG8_SCHED;
;             PG8_LDB(B1, 1, 1); PG8_STAGE(PG8_SB(1, 0), b3, voffB);
;             PG8_BAR; PG8_WAIT_L(0); PG8_MMA(0, 1, At, B1); PG8_BAR;
;             PG8_LDA(At, 1, 1); PG8_STAGE(PG8_SA(1, 0), a3, voffA);
;             PG8_BAR; PG8_WAIT_L(0); PG8_MMA(1, 0, At, B0); PG8_BAR; PG8_SCHED;
;             PG8_STAGE(PG8_SB(1, 1), b3 + hstep, voffB);
;             PG8_WAIT_V(6); PG8_BAR; PG8_MMA(1, 1, At, B1); PG8_BAR;
	s_waitcnt lgkmcnt(0)
	s_waitcnt lgkmcnt(0)
	v_mfma_f32_16x16x32_bf16 v[60:63], v[138:141], v[158:161], v[60:63]
	v_mfma_f32_16x16x32_bf16 v[56:59], v[150:153], v[158:161], v[56:59]
	v_mfma_f32_16x16x32_bf16 v[44:47], v[138:141], v[174:177], v[44:47]
	v_mfma_f32_16x16x32_bf16 v[40:43], v[150:153], v[174:177], v[40:43]
	v_mfma_f32_16x16x32_bf16 v[28:31], v[138:141], v[188:191], v[28:31]
	v_mfma_f32_16x16x32_bf16 v[24:27], v[150:153], v[188:191], v[24:27]
	v_mfma_f32_16x16x32_bf16 v[12:15], v[138:141], v[196:199], v[12:15]
	v_mfma_f32_16x16x32_bf16 v[8:11], v[150:153], v[196:199], v[8:11]
	v_mfma_f32_16x16x32_bf16 v[60:63], v[146:149], v[170:173], v[60:63]
	v_mfma_f32_16x16x32_bf16 v[56:59], v[154:157], v[170:173], v[56:59]
	v_mfma_f32_16x16x32_bf16 v[44:47], v[146:149], v[178:181], v[44:47]
	v_mfma_f32_16x16x32_bf16 v[40:43], v[154:157], v[178:181], v[40:43]
	v_mfma_f32_16x16x32_bf16 v[28:31], v[146:149], v[192:195], v[28:31]
	v_mfma_f32_16x16x32_bf16 v[24:27], v[154:157], v[192:195], v[24:27]
	v_mfma_f32_16x16x32_bf16 v[12:15], v[146:149], v[200:203], v[12:15]
	v_mfma_f32_16x16x32_bf16 v[8:11], v[154:157], v[200:203], v[8:11]
	s_barrier
	s_add_i32 s4, s40, s50
	v_lshl_add_u64 v[138:139], v[224:225], 0, s[66:67]
	s_mov_b32 m0, s4
	s_nop 0
	global_load_lds_dwordx4 v[138:139], off
	v_lshl_add_u64 v[138:139], v[226:227], 0, s[66:67]
	s_add_i32 m0, s4, 0x2000
	s_nop 0
	global_load_lds_dwordx4 v[138:139], off
	s_waitcnt vmcnt(6)
	s_barrier
	v_mfma_f32_16x16x32_bf16 v[52:55], v[204:207], v[158:161], v[52:55]
	v_mfma_f32_16x16x32_bf16 v[48:51], v[212:215], v[158:161], v[48:51]
	v_mfma_f32_16x16x32_bf16 v[36:39], v[204:207], v[174:177], v[36:39]
	v_mfma_f32_16x16x32_bf16 v[32:35], v[212:215], v[174:177], v[32:35]
	v_mfma_f32_16x16x32_bf16 v[20:23], v[204:207], v[188:191], v[20:23]
	v_mfma_f32_16x16x32_bf16 v[16:19], v[212:215], v[188:191], v[16:19]
	v_mfma_f32_16x16x32_bf16 v[4:7], v[204:207], v[196:199], v[4:7]
	v_mfma_f32_16x16x32_bf16 v[0:3], v[212:215], v[196:199], v[0:3]
	v_mfma_f32_16x16x32_bf16 v[52:55], v[208:211], v[170:173], v[52:55]
	v_mfma_f32_16x16x32_bf16 v[48:51], v[216:219], v[170:173], v[48:51]
	v_mfma_f32_16x16x32_bf16 v[36:39], v[208:211], v[178:181], v[36:39]
	v_mfma_f32_16x16x32_bf16 v[32:35], v[216:219], v[178:181], v[32:35]
	v_mfma_f32_16x16x32_bf16 v[20:23], v[208:211], v[192:195], v[20:23]
	v_mfma_f32_16x16x32_bf16 v[16:19], v[216:219], v[192:195], v[16:19]
	v_mfma_f32_16x16x32_bf16 v[4:7], v[208:211], v[200:203], v[4:7]
	v_mfma_f32_16x16x32_bf16 v[0:3], v[216:219], v[200:203], v[0:3]
	s_add_u32 s36, s36, 0x100
	s_addc_u32 s37, s37, 0
	s_add_u32 s0, s0, 0x100
	s_addc_u32 s44, s44, 0
	s_cmp_ge_i32 s5, s73
	s_mov_b32 s4, s5
	s_barrier
	s_cbranch_scc0 .LBB0_1231
	s_branch .Lpeel_exit_2
.LBB0_1231:
	s_add_i32 s5, s4, 2
	s_add_u32 s40, s36, 0x80
	s_addc_u32 s41, s37, 0
	s_add_i32 s45, s60, 0x100
	v_add_u32_e32 v154, s45, v144
	ds_read_b128 v[138:141], v154
	ds_read_b128 v[146:149], v154 offset:1024
	ds_read_b128 v[150:153], v154 offset:2048
	ds_read_b128 v[154:157], v154 offset:3072
	s_cmp_eq_u32 s76, s4
	s_cselect_b32 s41, s17, s41
	s_cselect_b32 s40, s16, s40
	s_cselect_b32 s43, s19, s44
	s_cselect_b32 s42, s18, s0
	v_lshl_add_u64 v[162:163], s[36:37], 0, v[134:135]
	s_add_i32 m0, s51, 0xc000
	ds_read_b128 v[158:161], v145
	ds_read_b128 v[170:173], v145 offset:1024
	ds_read_b128 v[174:177], v145 offset:2048
	ds_read_b128 v[178:181], v145 offset:3072
	ds_read_b128 v[188:191], v145 offset:4096
	ds_read_b128 v[192:195], v145 offset:5120
	ds_read_b128 v[196:199], v145 offset:6144
	ds_read_b128 v[200:203], v145 offset:7168
	global_load_lds_dwordx4 v[162:163], off
	v_lshl_add_u64 v[162:163], s[36:37], 0, v[136:137]
	s_add_i32 m0, s51, 0xe000
	s_nop 0
	global_load_lds_dwordx4 v[162:163], off
	s_waitcnt lgkmcnt(8)
	s_barrier
	s_waitcnt lgkmcnt(0)
	s_waitcnt lgkmcnt(0)
	v_mfma_f32_16x16x32_bf16 v[124:127], v[138:141], v[158:161], v[124:127]
	v_mfma_f32_16x16x32_bf16 v[120:123], v[150:153], v[158:161], v[120:123]
	v_mfma_f32_16x16x32_bf16 v[108:111], v[138:141], v[174:177], v[108:111]
	v_mfma_f32_16x16x32_bf16 v[104:107], v[150:153], v[174:177], v[104:107]
	v_mfma_f32_16x16x32_bf16 v[92:95], v[138:141], v[188:191], v[92:95]
	v_mfma_f32_16x16x32_bf16 v[88:91], v[150:153], v[188:191], v[88:91]
	v_mfma_f32_16x16x32_bf16 v[76:79], v[138:141], v[196:199], v[76:79]
	v_mfma_f32_16x16x32_bf16 v[72:75], v[150:153], v[196:199], v[72:75]
	v_mfma_f32_16x16x32_bf16 v[124:127], v[146:149], v[170:173], v[124:127]
	v_mfma_f32_16x16x32_bf16 v[120:123], v[154:157], v[170:173], v[120:123]
	v_mfma_f32_16x16x32_bf16 v[108:111], v[146:149], v[178:181], v[108:111]
	v_mfma_f32_16x16x32_bf16 v[104:107], v[154:157], v[178:181], v[104:107]
	v_mfma_f32_16x16x32_bf16 v[92:95], v[146:149], v[192:195], v[92:95]
	v_mfma_f32_16x16x32_bf16 v[88:91], v[154:157], v[192:195], v[88:91]
	v_mfma_f32_16x16x32_bf16 v[76:79], v[146:149], v[200:203], v[76:79]
	v_mfma_f32_16x16x32_bf16 v[72:75], v[154:157], v[200:203], v[72:75]
	s_barrier
	s_add_i32 s4, s61, 0x100
	v_add_u32_e32 v162, s4, v144
	s_add_i32 s45, s45, s50
	ds_read_b128 v[204:207], v162
	ds_read_b128 v[208:211], v162 offset:1024
	ds_read_b128 v[212:215], v162 offset:2048
	ds_read_b128 v[216:219], v162 offset:3072
	v_lshl_add_u64 v[162:163], s[42:43], 0, v[166:167]
	s_mov_b32 m0, s45
	v_lshl_add_u64 v[182:183], s[42:43], 0, v[132:133]
	global_load_lds_dwordx4 v[162:163], off
	s_add_i32 m0, s45, 0x2000
	s_nop 0
	global_load_lds_dwordx4 v[182:183], off
	s_barrier
; #define PG8_STAGE(bufoff, gbase, voff) do { _Pragma("unroll") for (int _i = 0; _i < 2; ++_i) \
;         __builtin_amdgcn_global_load_lds((const unsigned*)((const char*)(gbase) + (voff)[_i]), (LAS unsigned*)(lds + (bufoff) + ldsw + _i * 8192), 16, 0, 0); } while (0)
; #define PG8_LDA(dst, b, h) do { _Pragma("unroll") for (int m = 0; m < 4; ++m) _Pragma("unroll") for (int k = 0; k < 2; ++k) dst[m][k] = *(const LAS bf16x8*)(lds + PG8_SA(b, h) + aoff + m * 2048 + k * 1024); } while (0)
; #define PG8_LDB(dst, b, h) do { _Pragma("unroll") for (int n = 0; n < 2; ++n) _Pragma("unroll") for (int k = 0; k < 2; ++k) dst[n][k] = *(const LAS bf16x8*)(lds + PG8_SB(b, h) + boff + n * 2048 + k * 1024); } while (0)
; #define PG8_MMA(ai, bj, At, Bt) do { __builtin_amdgcn_s_setprio(1); _Pragma("unroll") for (int m = 0; m < 4; ++m) _Pragma("unroll") for (int n = 0; n < 2; ++n) _Pragma("unroll") for (int k = 0; k < 2; ++k) \
;         acc[ai][bj][m][n] = __builtin_amdgcn_mfma_f32_16x16x32_bf16(Bt[n][k], At[m][k], acc[ai][bj][m][n], 0, 0, 0); __builtin_amdgcn_s_setprio(0); } while (0)
; #define PG8_WAIT_V(n) asm volatile("s_waitcnt vmcnt(" #n ")" ::: "memory")
; #define PG8_WAIT_L(n) asm volatile("s_waitcnt lgkmcnt(" #n ")" ::: "memory")
; #define PG8_BAR __builtin_amdgcn_s_barrier()
; #define PG8_SCHED __builtin_amdgcn_sched_barrier(0)
; template <class Epi>
; DI void gemm_phase(LAS unsigned char* lds, const Gemm g, const StaticOrder& S, const Epi& E) {
;     ...
;             PG8_BAR; PG8_WAIT_L(0); PG8_MMA(0, 1, At, B1); PG8_BAR;
;             PG8_LDA(At, 0, 1); PG8_STAGE(PG8_SA(0, 0), a2, voffA);
;             PG8_BAR; PG8_WAIT_L(0); PG8_MMA(1, 0, At, B0); PG8_BAR; PG8_SCHED;
;             PG8_STAGE(PG8_SB(0, 1), b2 + hstep, voffB);
;             PG8_WAIT_V(6); PG8_BAR; PG8_MMA(1, 1, At, B1); PG8_BAR;
;             PG8_LDB(B0, 1, 0); PG8_SCHED; PG8_LDA(At, 1, 0); PG8_STAGE(PG8_SA(0, 1), a2 + hstep, voffA);
	s_waitcnt lgkmcnt(0)
	s_waitcnt lgkmcnt(0)
	v_mfma_f32_16x16x32_bf16 v[116:119], v[204:207], v[158:161], v[116:119]
	v_mfma_f32_16x16x32_bf16 v[112:115], v[212:215], v[158:161], v[112:115]
	v_mfma_f32_16x16x32_bf16 v[100:103], v[204:207], v[174:177], v[100:103]
	v_mfma_f32_16x16x32_bf16 v[96:99], v[212:215], v[174:177], v[96:99]
	v_mfma_f32_16x16x32_bf16 v[84:87], v[204:207], v[188:191], v[84:87]
	v_mfma_f32_16x16x32_bf16 v[80:83], v[212:215], v[188:191], v[80:83]
	v_mfma_f32_16x16x32_bf16 v[68:71], v[204:207], v[196:199], v[68:71]
	v_mfma_f32_16x16x32_bf16 v[64:67], v[212:215], v[196:199], v[64:67]
	v_mfma_f32_16x16x32_bf16 v[116:119], v[208:211], v[170:173], v[116:119]
	v_mfma_f32_16x16x32_bf16 v[112:115], v[216:219], v[170:173], v[112:115]
	v_mfma_f32_16x16x32_bf16 v[100:103], v[208:211], v[178:181], v[100:103]
	v_mfma_f32_16x16x32_bf16 v[96:99], v[216:219], v[178:181], v[96:99]
	v_mfma_f32_16x16x32_bf16 v[84:87], v[208:211], v[192:195], v[84:87]
	v_mfma_f32_16x16x32_bf16 v[80:83], v[216:219], v[192:195], v[80:83]
	v_mfma_f32_16x16x32_bf16 v[68:71], v[208:211], v[200:203], v[68:71]
	v_mfma_f32_16x16x32_bf16 v[64:67], v[216:219], v[200:203], v[64:67]
	s_mov_b32 m0, s51
	v_lshl_add_u64 v[220:221], s[40:41], 0, v[128:129]
	s_barrier
	ds_read_b128 v[158:161], v145 offset:16384
	ds_read_b128 v[170:173], v145 offset:17408
	ds_read_b128 v[174:177], v145 offset:18432
	ds_read_b128 v[178:181], v145 offset:19456
	ds_read_b128 v[188:191], v145 offset:20480
	ds_read_b128 v[192:195], v145 offset:21504
	ds_read_b128 v[196:199], v145 offset:22528
	ds_read_b128 v[200:203], v145 offset:23552
	global_load_lds_dwordx4 v[220:221], off
	v_lshl_add_u64 v[222:223], s[40:41], 0, v[130:131]
	s_mov_b32 m0, s79
	s_nop 0
	global_load_lds_dwordx4 v[222:223], off
	s_barrier
	s_waitcnt lgkmcnt(0)
	s_waitcnt lgkmcnt(0)
	v_mfma_f32_16x16x32_bf16 v[60:63], v[138:141], v[158:161], v[60:63]
	v_mfma_f32_16x16x32_bf16 v[56:59], v[150:153], v[158:161], v[56:59]
	v_mfma_f32_16x16x32_bf16 v[44:47], v[138:141], v[174:177], v[44:47]
	v_mfma_f32_16x16x32_bf16 v[40:43], v[150:153], v[174:177], v[40:43]
	v_mfma_f32_16x16x32_bf16 v[28:31], v[138:141], v[188:191], v[28:31]
	v_mfma_f32_16x16x32_bf16 v[24:27], v[150:153], v[188:191], v[24:27]
	v_mfma_f32_16x16x32_bf16 v[12:15], v[138:141], v[196:199], v[12:15]
	v_mfma_f32_16x16x32_bf16 v[8:11], v[150:153], v[196:199], v[8:11]
	v_mfma_f32_16x16x32_bf16 v[60:63], v[146:149], v[170:173], v[60:63]
	v_mfma_f32_16x16x32_bf16 v[56:59], v[154:157], v[170:173], v[56:59]
	v_mfma_f32_16x16x32_bf16 v[44:47], v[146:149], v[178:181], v[44:47]
	v_mfma_f32_16x16x32_bf16 v[40:43], v[154:157], v[178:181], v[40:43]
	v_mfma_f32_16x16x32_bf16 v[28:31], v[146:149], v[192:195], v[28:31]
	v_mfma_f32_16x16x32_bf16 v[24:27], v[154:157], v[192:195], v[24:27]
	v_mfma_f32_16x16x32_bf16 v[12:15], v[146:149], v[200:203], v[12:15]
	v_mfma_f32_16x16x32_bf16 v[8:11], v[154:157], v[200:203], v[8:11]
	s_barrier
	s_add_u32 s42, s42, s10
	s_addc_u32 s43, s43, s11
	s_add_i32 s4, s4, s50
	v_lshl_add_u64 v[224:225], s[42:43], 0, v[166:167]
	s_mov_b32 m0, s4
	v_lshl_add_u64 v[226:227], s[42:43], 0, v[132:133]
	global_load_lds_dwordx4 v[224:225], off
	s_add_i32 m0, s4, 0x2000
	s_nop 0
	global_load_lds_dwordx4 v[226:227], off
	s_waitcnt vmcnt(6)
	s_barrier
	v_mfma_f32_16x16x32_bf16 v[52:55], v[204:207], v[158:161], v[52:55]
	v_mfma_f32_16x16x32_bf16 v[48:51], v[212:215], v[158:161], v[48:51]
	v_mfma_f32_16x16x32_bf16 v[36:39], v[204:207], v[174:177], v[36:39]
	v_mfma_f32_16x16x32_bf16 v[32:35], v[212:215], v[174:177], v[32:35]
	v_mfma_f32_16x16x32_bf16 v[20:23], v[204:207], v[188:191], v[20:23]
	v_mfma_f32_16x16x32_bf16 v[16:19], v[212:215], v[188:191], v[16:19]
	v_mfma_f32_16x16x32_bf16 v[4:7], v[204:207], v[196:199], v[4:7]
	v_mfma_f32_16x16x32_bf16 v[0:3], v[212:215], v[196:199], v[0:3]
	v_mfma_f32_16x16x32_bf16 v[52:55], v[208:211], v[170:173], v[52:55]
	v_mfma_f32_16x16x32_bf16 v[48:51], v[216:219], v[170:173], v[48:51]
	v_mfma_f32_16x16x32_bf16 v[36:39], v[208:211], v[178:181], v[36:39]
	v_mfma_f32_16x16x32_bf16 v[32:35], v[216:219], v[178:181], v[32:35]
	v_mfma_f32_16x16x32_bf16 v[20:23], v[208:211], v[192:195], v[20:23]
	v_mfma_f32_16x16x32_bf16 v[16:19], v[216:219], v[192:195], v[16:19]
	v_mfma_f32_16x16x32_bf16 v[4:7], v[208:211], v[200:203], v[4:7]
	v_mfma_f32_16x16x32_bf16 v[0:3], v[216:219], v[200:203], v[0:3]
	s_add_i32 s4, s62, 0x100
	v_add_u32_e32 v154, s4, v144
	s_barrier
	ds_read_b128 v[138:141], v154
	ds_read_b128 v[146:149], v154 offset:1024
	ds_read_b128 v[150:153], v154 offset:2048
	ds_read_b128 v[154:157], v154 offset:3072
	s_add_u32 s40, s40, s10
	s_addc_u32 s41, s41, s11
	s_mov_b32 m0, s88
	v_lshl_add_u64 v[204:205], s[40:41], 0, v[128:129]
	ds_read_b128 v[158:161], v145 offset:32768
	ds_read_b128 v[170:173], v145 offset:33792
	ds_read_b128 v[174:177], v145 offset:34816
	ds_read_b128 v[178:181], v145 offset:35840
	ds_read_b128 v[188:191], v145 offset:36864
	ds_read_b128 v[192:195], v145 offset:37888
	ds_read_b128 v[196:199], v145 offset:38912
	ds_read_b128 v[200:203], v145 offset:39936
	global_load_lds_dwordx4 v[204:205], off
	v_lshl_add_u64 v[204:205], s[40:41], 0, v[130:131]
	s_mov_b32 m0, s89
	s_nop 0
	global_load_lds_dwordx4 v[204:205], off
	s_waitcnt lgkmcnt(8)
	s_barrier
; #define PG8_STAGE(bufoff, gbase, voff) do { _Pragma("unroll") for (int _i = 0; _i < 2; ++_i) \
;         __builtin_amdgcn_global_load_lds((const unsigned*)((const char*)(gbase) + (voff)[_i]), (LAS unsigned*)(lds + (bufoff) + ldsw + _i * 8192), 16, 0, 0); } while (0)
; #define PG8_LDA(dst, b, h) do { _Pragma("unroll") for (int m = 0; m < 4; ++m) _Pragma("unroll") for (int k = 0; k < 2; ++k) dst[m][k] = *(const LAS bf16x8*)(lds + PG8_SA(b, h) + aoff + m * 2048 + k * 1024); } while (0)
; #define PG8_LDB(dst, b, h) do { _Pragma("unroll") for (int n = 0; n < 2; ++n) _Pragma("unroll") for (int k = 0; k < 2; ++k) dst[n][k] = *(const LAS bf16x8*)(lds + PG8_SB(b, h) + boff + n * 2048 + k * 1024); } while (0)
; #define PG8_MMA(ai, bj, At, Bt) do { __builtin_amdgcn_s_setprio(1); _Pragma("unroll") for (int m = 0; m < 4; ++m) _Pragma("unroll") for (int n = 0; n < 2; ++n) _Pragma("unroll") for (int k = 0; k < 2; ++k) \
;         acc[ai][bj][m][n] = __builtin_amdgcn_mfma_f32_16x16x32_bf16(Bt[n][k], At[m][k], acc[ai][bj][m][n], 0, 0, 0); __builtin_amdgcn_s_setprio(0); } while (0)
; #define PG8_WAIT_V(n) asm volatile("s_waitcnt vmcnt(" #n ")" ::: "memory")
; #define PG8_WAIT_L(n) asm volatile("s_waitcnt lgkmcnt(" #n ")" ::: "memory")
; #define PG8_BAR __builtin_amdgcn_s_barrier()
; #define PG8_SCHED __builtin_amdgcn_sched_barrier(0)
; template <class Epi>
; DI void gemm_phase(LAS unsigned char* lds, const Gemm g, const StaticOrder& S, const Epi& E) {
;     ...
;             PG8_WAIT_L(8); PG8_BAR; PG8_WAIT_L(0); PG8_MMA(0, 0, At, B0); PG8_BAR; PG8_SCHED;
;             PG8_LDB(B1, 1, 1); PG8_STAGE(PG8_SB(1, 0), b3, voffB);
;             PG8_BAR; PG8_WAIT_L(0); PG8_MMA(0, 1, At, B1); PG8_BAR;
;             PG8_LDA(At, 1, 1); PG8_STAGE(PG8_SA(1, 0), a3, voffA);
;             PG8_BAR; PG8_WAIT_L(0); PG8_MMA(1, 0, At, B0); PG8_BAR; PG8_SCHED;
;             PG8_STAGE(PG8_SB(1, 1), b3 + hstep, voffB);
;             PG8_WAIT_V(6); PG8_BAR; PG8_MMA(1, 1, At, B1); PG8_BAR;
	s_waitcnt lgkmcnt(0)
	s_waitcnt lgkmcnt(0)
	v_mfma_f32_16x16x32_bf16 v[124:127], v[138:141], v[158:161], v[124:127]
	v_mfma_f32_16x16x32_bf16 v[120:123], v[150:153], v[158:161], v[120:123]
	v_mfma_f32_16x16x32_bf16 v[108:111], v[138:141], v[174:177], v[108:111]
	v_mfma_f32_16x16x32_bf16 v[104:107], v[150:153], v[174:177], v[104:107]
	v_mfma_f32_16x16x32_bf16 v[92:95], v[138:141], v[188:191], v[92:95]
	v_mfma_f32_16x16x32_bf16 v[88:91], v[150:153], v[188:191], v[88:91]
	v_mfma_f32_16x16x32_bf16 v[76:79], v[138:141], v[196:199], v[76:79]
	v_mfma_f32_16x16x32_bf16 v[72:75], v[150:153], v[196:199], v[72:75]
	v_mfma_f32_16x16x32_bf16 v[124:127], v[146:149], v[170:173], v[124:127]
	v_mfma_f32_16x16x32_bf16 v[120:123], v[154:157], v[170:173], v[120:123]
	v_mfma_f32_16x16x32_bf16 v[108:111], v[146:149], v[178:181], v[108:111]
	v_mfma_f32_16x16x32_bf16 v[104:107], v[154:157], v[178:181], v[104:107]
	v_mfma_f32_16x16x32_bf16 v[92:95], v[146:149], v[192:195], v[92:95]
	v_mfma_f32_16x16x32_bf16 v[88:91], v[154:157], v[192:195], v[88:91]
	v_mfma_f32_16x16x32_bf16 v[76:79], v[146:149], v[200:203], v[76:79]
	v_mfma_f32_16x16x32_bf16 v[72:75], v[154:157], v[200:203], v[72:75]
	s_barrier
	s_add_i32 s40, s63, 0x100
	s_add_i32 s4, s4, s50
	v_add_u32_e32 v216, s40, v144
	v_lshl_add_u64 v[162:163], v[162:163], 0, s[66:67]
	s_mov_b32 m0, s4
	ds_read_b128 v[204:207], v216
	ds_read_b128 v[208:211], v216 offset:1024
	ds_read_b128 v[212:215], v216 offset:2048
	ds_read_b128 v[216:219], v216 offset:3072
	global_load_lds_dwordx4 v[162:163], off
	v_lshl_add_u64 v[162:163], v[182:183], 0, s[66:67]
	s_add_i32 m0, s4, 0x2000
	s_nop 0
	global_load_lds_dwordx4 v[162:163], off
	s_barrier
	s_waitcnt lgkmcnt(0)
	s_waitcnt lgkmcnt(0)
	v_mfma_f32_16x16x32_bf16 v[116:119], v[204:207], v[158:161], v[116:119]
	v_mfma_f32_16x16x32_bf16 v[112:115], v[212:215], v[158:161], v[112:115]
	v_mfma_f32_16x16x32_bf16 v[100:103], v[204:207], v[174:177], v[100:103]
	v_mfma_f32_16x16x32_bf16 v[96:99], v[212:215], v[174:177], v[96:99]
	v_mfma_f32_16x16x32_bf16 v[84:87], v[204:207], v[188:191], v[84:87]
	v_mfma_f32_16x16x32_bf16 v[80:83], v[212:215], v[188:191], v[80:83]
	v_mfma_f32_16x16x32_bf16 v[68:71], v[204:207], v[196:199], v[68:71]
	v_mfma_f32_16x16x32_bf16 v[64:67], v[212:215], v[196:199], v[64:67]
	v_mfma_f32_16x16x32_bf16 v[116:119], v[208:211], v[170:173], v[116:119]
	v_mfma_f32_16x16x32_bf16 v[112:115], v[216:219], v[170:173], v[112:115]
	v_mfma_f32_16x16x32_bf16 v[100:103], v[208:211], v[178:181], v[100:103]
	v_mfma_f32_16x16x32_bf16 v[96:99], v[216:219], v[178:181], v[96:99]
	v_mfma_f32_16x16x32_bf16 v[84:87], v[208:211], v[192:195], v[84:87]
	v_mfma_f32_16x16x32_bf16 v[80:83], v[216:219], v[192:195], v[80:83]
	v_mfma_f32_16x16x32_bf16 v[68:71], v[208:211], v[200:203], v[68:71]
	v_mfma_f32_16x16x32_bf16 v[64:67], v[216:219], v[200:203], v[64:67]
	s_mov_b32 m0, s90
	v_lshl_add_u64 v[162:163], v[220:221], 0, s[66:67]
	s_barrier
	ds_read_b128 v[158:161], v145 offset:49152
	ds_read_b128 v[170:173], v145 offset:50176
	ds_read_b128 v[174:177], v145 offset:51200
	ds_read_b128 v[178:181], v145 offset:52224
	ds_read_b128 v[188:191], v145 offset:53248
	ds_read_b128 v[192:195], v145 offset:54272
	ds_read_b128 v[196:199], v145 offset:55296
	ds_read_b128 v[200:203], v145 offset:56320
	global_load_lds_dwordx4 v[162:163], off
	v_lshl_add_u64 v[162:163], v[222:223], 0, s[66:67]
	s_mov_b32 m0, s91
	s_nop 0
	global_load_lds_dwordx4 v[162:163], off
	s_barrier
	s_waitcnt lgkmcnt(0)
	s_waitcnt lgkmcnt(0)
	v_mfma_f32_16x16x32_bf16 v[60:63], v[138:141], v[158:161], v[60:63]
	v_mfma_f32_16x16x32_bf16 v[56:59], v[150:153], v[158:161], v[56:59]
	v_mfma_f32_16x16x32_bf16 v[44:47], v[138:141], v[174:177], v[44:47]
	v_mfma_f32_16x16x32_bf16 v[40:43], v[150:153], v[174:177], v[40:43]
	v_mfma_f32_16x16x32_bf16 v[28:31], v[138:141], v[188:191], v[28:31]
	v_mfma_f32_16x16x32_bf16 v[24:27], v[150:153], v[188:191], v[24:27]
	v_mfma_f32_16x16x32_bf16 v[12:15], v[138:141], v[196:199], v[12:15]
	v_mfma_f32_16x16x32_bf16 v[8:11], v[150:153], v[196:199], v[8:11]
	v_mfma_f32_16x16x32_bf16 v[60:63], v[146:149], v[170:173], v[60:63]
	v_mfma_f32_16x16x32_bf16 v[56:59], v[154:157], v[170:173], v[56:59]
	v_mfma_f32_16x16x32_bf16 v[44:47], v[146:149], v[178:181], v[44:47]
	v_mfma_f32_16x16x32_bf16 v[40:43], v[154:157], v[178:181], v[40:43]
	v_mfma_f32_16x16x32_bf16 v[28:31], v[146:149], v[192:195], v[28:31]
	v_mfma_f32_16x16x32_bf16 v[24:27], v[154:157], v[192:195], v[24:27]
	v_mfma_f32_16x16x32_bf16 v[12:15], v[146:149], v[200:203], v[12:15]
	v_mfma_f32_16x16x32_bf16 v[8:11], v[154:157], v[200:203], v[8:11]
	s_barrier
	s_add_i32 s4, s40, s50
	v_lshl_add_u64 v[138:139], v[224:225], 0, s[66:67]
	s_mov_b32 m0, s4
	s_nop 0
	global_load_lds_dwordx4 v[138:139], off
	v_lshl_add_u64 v[138:139], v[226:227], 0, s[66:67]
	s_add_i32 m0, s4, 0x2000
	s_nop 0
	global_load_lds_dwordx4 v[138:139], off
	s_waitcnt vmcnt(6)
	s_barrier
	v_mfma_f32_16x16x32_bf16 v[52:55], v[204:207], v[158:161], v[52:55]
	v_mfma_f32_16x16x32_bf16 v[48:51], v[212:215], v[158:161], v[48:51]
	v_mfma_f32_16x16x32_bf16 v[36:39], v[204:207], v[174:177], v[36:39]
	v_mfma_f32_16x16x32_bf16 v[32:35], v[212:215], v[174:177], v[32:35]
	v_mfma_f32_16x16x32_bf16 v[20:23], v[204:207], v[188:191], v[20:23]
	v_mfma_f32_16x16x32_bf16 v[16:19], v[212:215], v[188:191], v[16:19]
	v_mfma_f32_16x16x32_bf16 v[4:7], v[204:207], v[196:199], v[4:7]
	v_mfma_f32_16x16x32_bf16 v[0:3], v[212:215], v[196:199], v[0:3]
	v_mfma_f32_16x16x32_bf16 v[52:55], v[208:211], v[170:173], v[52:55]
	v_mfma_f32_16x16x32_bf16 v[48:51], v[216:219], v[170:173], v[48:51]
	v_mfma_f32_16x16x32_bf16 v[36:39], v[208:211], v[178:181], v[36:39]
	v_mfma_f32_16x16x32_bf16 v[32:35], v[216:219], v[178:181], v[32:35]
	v_mfma_f32_16x16x32_bf16 v[20:23], v[208:211], v[192:195], v[20:23]
	v_mfma_f32_16x16x32_bf16 v[16:19], v[216:219], v[192:195], v[16:19]
	v_mfma_f32_16x16x32_bf16 v[4:7], v[208:211], v[200:203], v[4:7]
	v_mfma_f32_16x16x32_bf16 v[0:3], v[216:219], v[200:203], v[0:3]
	s_add_u32 s36, s36, 0x100
	s_addc_u32 s37, s37, 0
	s_add_u32 s0, s0, 0x100
	s_addc_u32 s44, s44, 0
	s_cmp_ge_i32 s5, s73
	s_mov_b32 s4, s5
	s_barrier
	s_cbranch_scc0 .LBB0_1231

; #define PG8_WAIT_V(n) asm volatile("s_waitcnt vmcnt(" #n ")" ::: "memory")
; #define PG8_BAR __builtin_amdgcn_s_barrier()
; template <class Epi>
; DI void gemm_phase(LAS unsigned char* lds, const Gemm g, const StaticOrder& S, const Epi& E) {
;     ...
;     PG8_WAIT_V(0);
;     if (wr == 0) PG8_BAR;
;     PG8_BAR;
.LBB0_1250:
	s_barrier
	s_setprio 0

; #define PG8_STAGE(bufoff, gbase, voff) do { _Pragma("unroll") for (int _i = 0; _i < 2; ++_i) \
;         __builtin_amdgcn_global_load_lds((const unsigned*)((const char*)(gbase) + (voff)[_i]), (LAS unsigned*)(lds + (bufoff) + ldsw + _i * 8192), 16, 0, 0); } while (0)
; #define PG8_BAR __builtin_amdgcn_s_barrier()
;     DI bool next(int i, Unit& u) const {
;         const long L = (long)i * G + c; if (L >= nwg) return false;
;         int wgid = (int)L; { const int q = nwg / NXCD, r = nwg % NXCD, xcd = wgid % NXCD, off = wgid / NXCD; wgid = (xcd < r ? xcd * (q + 1) : r * (q + 1) + (xcd - r) * q) + off; }
;         const int nig = WGM * nN, gid = wgid / nig, fm = gid * WGM, gsz = (nM - fm) < WGM ? (nM - fm) : WGM;
;         u.pm = fm + ((wgid % nig) % gsz); u.pn = (wgid % nig) / gsz; return true;
;     }
; template <class Epi>
; DI void gemm_phase(LAS unsigned char* lds, const Gemm g, const StaticOrder& S, const Epi& E) {
;     ...
;     for (int i = 0; i < 2; ++i) { int R, C; stage_rc(tid * 16 + i * 8192, R, C); const int Rb = (R & ~31) + perm32(R & 31);
;         voffA[i] = (unsigned)(R * K + C) * 2u; voffB[i] = (unsigned)(Rb * K + C) * 2u; }
;     const size_t kstep = (size_t)(BK * 2);
;     const size_t hstep = (size_t)HALF * K * 2;
;     const size_t tstep = 2 * hstep;
;     const unsigned ldsw = (unsigned)wid * 1024u;
;     const int aoff = lds_byte(wr * 64 + fr, fq * 8), boff = lds_byte(wc * 32 + fr, fq * 8);
;     ...
;     Unit cur, nxt; int ui = 0;
;     if (!S.next(0, cur)) return;
;     f32x4 acc[2][2][4][2];
; #pragma unroll
;     for (int a = 0; a < 2; ++a)
; #pragma unroll
;         for (int b = 0; b < 2; ++b)
; #pragma unroll
;             for (int m = 0; m < 4; ++m)
; #pragma unroll
;                 for (int n = 0; n < 2; ++n) acc[a][b][m][n] = (f32x4){0.f, 0.f, 0.f, 0.f};
;     bf16x8 At[4][2], B0[2][2], B1[2][2];
;     const char* cA = (const char*)g.A + (size_t)cur.pm * tstep; const char* cB = (const char*)g.Bt + (size_t)cur.pn * tstep;
;     PG8_STAGE(PG8_SB(0, 0), cB, voffB); PG8_STAGE(PG8_SA(0, 0), cA, voffA); PG8_STAGE(PG8_SB(0, 1), cB + hstep, voffB); PG8_STAGE(PG8_SA(0, 1), cA + hstep, voffA);
;     if (wr == 1) PG8_BAR;
.LBB0_1366:
	s_or_b64 exec, exec, s[2:3]
	s_movk_i32 s0, 0x1000
	s_waitcnt lgkmcnt(0)
	s_barrier
	s_ashr_i32 s2, s0, 31
	s_lshr_b32 s2, s2, 24
	s_add_i32 s0, s0, s2
	s_ashr_i32 s0, s0, 8
	s_movk_i32 s14, 0x400
	s_mov_b32 s33, s52
	v_readlane_b32 s46, v238, 0
	s_mul_i32 s2, s0, 0xc0
	v_mov_b32_e32 v18, v164
	s_cmp_ge_i32 s46, s2
	v_readfirstlane_b32 s47, v18
	s_cbranch_scc1 .LBB0_1383
	v_lshlrev_b32_e32 v0, 4, v18
	v_add_u32_e32 v1, 0x2000, v0
	v_ashrrev_i32_e32 v2, 31, v1
	v_lshrrev_b32_e32 v2, 22, v2
	v_add_u32_e32 v2, v1, v2
	v_ashrrev_i32_e32 v2, 10, v2
	v_mul_i32_i24_e32 v3, 0x400, v2
	v_sub_u32_e32 v1, v1, v3
	v_lshrrev_b32_e32 v3, 4, v1
	v_bitop3_b32 v1, v3, v1, 32 bitop3:0x6c
	v_ashrrev_i32_e32 v3, 31, v1
	v_lshrrev_b32_e32 v3, 26, v3
	v_add_u32_e32 v3, v1, v3
	v_lshlrev_b32_e32 v5, 3, v2
	v_ashrrev_i32_e32 v4, 6, v3
	v_and_b32_e32 v5, -16, v5
	v_lshlrev_b32_e32 v2, 5, v2
	v_add_u32_e32 v5, v4, v5
	v_and_b32_e32 v12, 32, v2
	v_and_b32_e32 v2, 0xc0, v3
	v_and_b32_e32 v4, 3, v4
	s_mov_b32 s5, 0x7fffffe0
	v_lshrrev_b32_e32 v6, 2, v5
	v_lshlrev_b32_e32 v7, 1, v5
	v_sub_u32_e32 v1, v1, v2
	v_and_or_b32 v4, v5, s5, v4
	v_and_b32_e32 v6, 4, v6
	v_and_b32_e32 v7, 24, v7
	v_ashrrev_i16_sdwa v1, v169, sext(v1) dst_sel:DWORD dst_unused:UNUSED_PAD src0_sel:DWORD src1_sel:BYTE_0
	v_or3_b32 v4, v4, v6, v7
	v_bfe_i32 v13, v1, 0, 16
	v_mul_lo_u32 v4, v4, s14
	v_add_u32_e32 v1, v12, v13
	v_mul_lo_u32 v14, v5, s14
	v_add_lshl_u32 v128, v4, v1, 1
	v_add_lshl_u32 v130, v1, v14, 1
	v_bfe_i32 v1, v18, 27, 1
	v_lshrrev_b32_e32 v1, 22, v1
	v_add_u32_e32 v1, v0, v1
	v_and_b32_e32 v1, 0xfffffc00, v1
	v_sub_u32_e32 v0, v0, v1
	v_ashrrev_i32_e32 v2, 31, v18
	v_lshrrev_b32_e32 v1, 4, v0
	v_lshrrev_b32_e32 v2, 26, v2
	v_bitop3_b32 v1, v1, v0, 32 bitop3:0x6c
	v_ashrrev_i32_e32 v0, 31, v0
	v_add_u32_e32 v2, v18, v2
	v_lshrrev_b32_e32 v0, 26, v0
	v_ashrrev_i32_e32 v2, 6, v2
	v_readlane_b32 s3, v236, 31
	v_add_u32_e32 v0, v1, v0
	v_lshlrev_b32_e32 v3, 3, v2
	s_add_u32 s48, s3, 0x950000
	v_readlane_b32 s3, v236, 32
	v_ashrrev_i32_e32 v0, 6, v0
	v_and_b32_e32 v3, -16, v3
	s_addc_u32 s49, s3, 0
	v_add_u32_e32 v3, v0, v3
	v_and_b32_e32 v4, 3, v0
	s_ashr_i32 s52, s46, 31
	v_and_or_b32 v4, v3, s5, v4
	s_lshr_b32 s5, s52, 29
	s_add_i32 s5, s46, s5
	s_ashr_i32 s3, s47, 6
	s_ashr_i32 s15, s14, 31
	s_mul_i32 s51, s0, 24
	s_ashr_i32 s16, s5, 3
	s_and_b32 s5, s5, -8
	s_ashr_i32 s4, s47, 8
	s_lshl_b64 s[10:11], s[14:15], 8
	s_lshl_b64 s[12:13], s[14:15], 9
	s_lshl_b32 s50, s3, 10
	s_sub_i32 s5, s46, s5
	s_or_b32 s53, s51, 1
	s_cmp_lt_i32 s5, 0
	s_cselect_b32 s17, s53, s51
	v_mul_i32_i24_e32 v0, 64, v0
	s_mul_i32 s5, s17, s5
	v_lshrrev_b32_e32 v5, 2, v3
	v_lshlrev_b32_e32 v6, 1, v3
	v_sub_u32_e32 v0, v1, v0
	s_add_i32 s5, s5, s16
	v_and_b32_e32 v5, 4, v5
	v_and_b32_e32 v6, 24, v6
	v_lshlrev_b32_e32 v2, 5, v2
	v_ashrrev_i16_sdwa v0, v169, sext(v0) dst_sel:DWORD dst_unused:UNUSED_PAD src0_sel:DWORD src1_sel:BYTE_0
	s_lshl_b32 s54, s0, 3
	s_ashr_i32 s16, s5, 31
	s_ashr_i32 s55, s0, 31
	v_or3_b32 v4, v4, v5, v6
	v_and_b32_e32 v15, 32, v2
	v_bfe_i32 v16, v0, 0, 16
	s_xor_b32 s0, s16, s55
	s_add_i32 s16, s54, s55
	v_mul_lo_u32 v4, v4, s14
	v_add_u32_e32 v0, v15, v16
	v_mul_lo_u32 v17, v3, s14
	s_xor_b32 s56, s16, s55
	v_add_lshl_u32 v166, v4, v0, 1
	v_add_lshl_u32 v132, v0, v17, 1
	v_cvt_f32_u32_e32 v0, s56
	s_sub_i32 s16, 0, s56
	s_abs_i32 s17, s5
	v_readlane_b32 s80, v238, 1
	v_rcp_iflag_f32_e32 v0, v0
	v_readlane_b32 s92, v238, 13
	v_readlane_b32 s93, v238, 14
	v_mov_b32_e32 v129, v167
	v_mul_f32_e32 v0, 0x4f7ffffe, v0
	v_cvt_u32_f32_e32 v0, v0
	v_mov_b32_e32 v133, v167
	v_mov_b32_e32 v131, v167
	v_readlane_b32 s81, v238, 2
	v_readfirstlane_b32 s57, v0
	s_mul_i32 s16, s16, s57
	s_mul_hi_u32 s16, s57, s16
	s_add_i32 s57, s57, s16
	s_mul_hi_u32 s16, s17, s57
	s_mul_i32 s18, s16, s56
	s_sub_i32 s17, s17, s18
	s_add_i32 s18, s16, 1
	s_sub_i32 s19, s17, s56
	s_cmp_ge_u32 s17, s56
	s_cselect_b32 s16, s18, s16
	s_cselect_b32 s17, s19, s17
	s_add_i32 s18, s16, 1
	s_cmp_ge_u32 s17, s56
	s_cselect_b32 s16, s18, s16
	s_xor_b32 s16, s16, s0
	s_sub_i32 s0, s16, s0
	s_lshl_b32 s16, s0, 3
	s_sub_i32 s17, 0xc0, s16
	s_min_i32 s17, s17, 8
	s_abs_i32 s19, s17
	v_cvt_f32_u32_e32 v0, s19
	s_sub_i32 s36, 0, s19
	s_mul_i32 s0, s0, s54
	s_sub_i32 s5, s5, s0
	v_rcp_iflag_f32_e32 v0, v0
	s_abs_i32 s18, s5
	s_xor_b32 s0, s5, s17
	s_ashr_i32 s0, s0, 31
	v_mul_f32_e32 v0, 0x4f7ffffe, v0
	v_cvt_u32_f32_e32 v0, v0
	v_readlane_b32 s82, v238, 3
	v_readlane_b32 s83, v238, 4
	v_readlane_b32 s84, v238, 5
	v_readfirstlane_b32 s37, v0
	s_mul_i32 s36, s36, s37
	s_mul_hi_u32 s36, s37, s36
	s_add_i32 s37, s37, s36
	s_mul_hi_u32 s36, s18, s37
	s_mul_i32 s37, s36, s19
	s_sub_i32 s18, s18, s37
	s_add_i32 s37, s36, 1
	s_sub_i32 s38, s18, s19
	s_cmp_ge_u32 s18, s19
	s_cselect_b32 s36, s37, s36
	s_cselect_b32 s18, s38, s18
	s_add_i32 s37, s36, 1
	s_cmp_ge_u32 s18, s19
	s_cselect_b32 s18, s37, s36
	s_xor_b32 s18, s18, s0
	s_sub_i32 s0, s18, s0
	s_mul_i32 s17, s0, s17
	s_sub_i32 s5, s5, s17
	s_add_i32 s78, s5, s16
	s_ashr_i32 s5, s78, 31
	s_mul_i32 s5, s12, s5
	s_mul_hi_u32 s16, s12, s78
	s_ashr_i32 s18, s0, 31
	s_add_i32 s5, s16, s5
	s_lshr_b64 s[16:17], s[14:15], 23
	s_mul_i32 s18, s12, s18
	s_mul_hi_u32 s19, s12, s0
	s_mul_i32 s17, s16, s78
	s_add_i32 s18, s19, s18
	s_mul_i32 s16, s16, s0
	s_add_i32 s5, s5, s17
	s_add_i32 s18, s18, s16
	s_mul_i32 s16, s12, s0
	s_add_u32 s44, s48, s16
	s_addc_u32 s45, s49, s18
	s_add_i32 s58, s50, 0x100
	s_add_i32 m0, s58, 0x10000
	s_mul_i32 s17, s12, s78
	global_load_lds_dwordx4 v166, s[44:45]
	s_add_i32 m0, s58, 0x12000
	s_add_u32 s36, s92, s17
	global_load_lds_dwordx4 v128, s[44:45]
	s_addc_u32 s37, s93, s5
	s_mov_b32 m0, s58
	s_add_i32 s59, s58, 0x2000
	global_load_lds_dwordx4 v132, s[36:37]
	s_mov_b32 m0, s59
	s_add_u32 s16, s44, s10
	global_load_lds_dwordx4 v130, s[36:37]
	s_addc_u32 s17, s45, s11
	s_add_i32 m0, s58, 0x14000
	v_lshl_add_u64 v[8:9], s[16:17], 0, v[166:167]
	global_load_lds_dwordx4 v166, s[16:17]
	s_add_i32 m0, s58, 0x16000
	v_lshl_add_u64 v[10:11], s[16:17], 0, v[128:129]
	global_load_lds_dwordx4 v128, s[16:17]
	s_add_u32 s16, s36, s10
	s_addc_u32 s17, s37, s11
	s_add_i32 s76, s58, 0x4000
	s_mov_b32 m0, s76
	s_add_i32 s77, s58, 0x6000
	global_load_lds_dwordx4 v132, s[16:17]
	s_mov_b32 m0, s77
	v_lshl_add_u64 v[0:1], s[44:45], 0, v[166:167]
	global_load_lds_dwordx4 v130, s[16:17]
	v_lshl_add_u64 v[2:3], s[44:45], 0, v[128:129]
	v_lshl_add_u64 v[4:5], s[36:37], 0, v[132:133]
	v_lshl_add_u64 v[6:7], s[36:37], 0, v[130:131]
	s_cmp_lg_u32 s4, 1
	v_readlane_b32 s85, v238, 6
	v_readlane_b32 s86, v238, 7
	v_readlane_b32 s87, v238, 8
	v_readlane_b32 s88, v238, 9
	v_readlane_b32 s89, v238, 10
	v_readlane_b32 s90, v238, 11
	v_readlane_b32 s91, v238, 12
	v_readlane_b32 s94, v238, 15
	v_readlane_b32 s95, v238, 16
	s_cbranch_scc1 .LBB0_1369
	s_setprio 1
	s_barrier

; #define PG8_STAGE(bufoff, gbase, voff) do { _Pragma("unroll") for (int _i = 0; _i < 2; ++_i) \
;         __builtin_amdgcn_global_load_lds((const unsigned*)((const char*)(gbase) + (voff)[_i]), (LAS unsigned*)(lds + (bufoff) + ldsw + _i * 8192), 16, 0, 0); } while (0)
; #define PG8_LDA(dst, b, h) do { _Pragma("unroll") for (int m = 0; m < 4; ++m) _Pragma("unroll") for (int k = 0; k < 2; ++k) dst[m][k] = *(const LAS bf16x8*)(lds + PG8_SA(b, h) + aoff + m * 2048 + k * 1024); } while (0)
; #define PG8_LDB(dst, b, h) do { _Pragma("unroll") for (int n = 0; n < 2; ++n) _Pragma("unroll") for (int k = 0; k < 2; ++k) dst[n][k] = *(const LAS bf16x8*)(lds + PG8_SB(b, h) + boff + n * 2048 + k * 1024); } while (0)
; #define PG8_MMA(ai, bj, At, Bt) do { __builtin_amdgcn_s_setprio(1); _Pragma("unroll") for (int m = 0; m < 4; ++m) _Pragma("unroll") for (int n = 0; n < 2; ++n) _Pragma("unroll") for (int k = 0; k < 2; ++k) \
;         acc[ai][bj][m][n] = __builtin_amdgcn_mfma_f32_16x16x32_bf16(Bt[n][k], At[m][k], acc[ai][bj][m][n], 0, 0, 0); __builtin_amdgcn_s_setprio(0); } while (0)
; #define PG8_WAIT_V(n) asm volatile("s_waitcnt vmcnt(" #n ")" ::: "memory")
; #define PG8_WAIT_L(n) asm volatile("s_waitcnt lgkmcnt(" #n ")" ::: "memory")
; #define PG8_BAR __builtin_amdgcn_s_barrier()
; template <class Epi>
; DI void gemm_phase(LAS unsigned char* lds, const Gemm g, const StaticOrder& S, const Epi& E) {
;     ...
;         for (int t = 0; t < nt; t += 2) {
;             const bool last = (t == nt - 2);
;             const char* a1 = cA + (size_t)(t + 1) * kstep;
;             const char* a2 = last ? nA : cA + (size_t)(t + 2) * kstep; const char* b2 = last ? nB : cB + (size_t)(t + 2) * kstep;
;             const char* a3 = a2 + kstep; const char* b3 = b2 + kstep;
;             PG8_LDB(B0, 0, 0); PG8_SCHED; PG8_LDA(At, 0, 0); PG8_STAGE(PG8_SA(1, 1), a1 + hstep, voffA);
;             PG8_WAIT_L(8); PG8_BAR; PG8_WAIT_L(0); PG8_MMA(0, 0, At, B0); PG8_BAR; PG8_SCHED;
;             PG8_LDB(B1, 0, 1); PG8_STAGE(PG8_SB(0, 0), b2, voffB);
;             PG8_BAR; PG8_WAIT_L(0); PG8_MMA(0, 1, At, B1); PG8_BAR;
;             PG8_LDA(At, 0, 1); PG8_STAGE(PG8_SA(0, 0), a2, voffA);
;             PG8_BAR; PG8_WAIT_L(0); PG8_MMA(1, 0, At, B0); PG8_BAR; PG8_SCHED;
;             PG8_STAGE(PG8_SB(0, 1), b2 + hstep, voffB);
;             PG8_WAIT_V(6); PG8_BAR; PG8_MMA(1, 1, At, B1); PG8_BAR;
.LBB0_1377:
	s_andn2_b64 vcc, exec, s[14:15]
	s_cbranch_vccnz .LBB0_1370
	s_add_u32 s36, s36, 0x80
	s_addc_u32 s37, s37, 0
	s_add_u32 s44, s44, 0x100
	s_addc_u32 s45, s45, 0
	s_mov_b32 s4, 0
	s_add_i32 s5, s4, 2
	s_add_u32 s40, s36, 0x80
	s_addc_u32 s41, s37, 0
	s_add_i32 s79, s60, 0x100
	v_add_u32_e32 v149, s79, v140
	ds_read_b128 v[150:153], v149
	ds_read_b128 v[154:157], v149 offset:1024
	ds_read_b128 v[158:161], v149 offset:2048
	ds_read_b128 v[170:173], v149 offset:3072
	s_cmp_eq_u32 s87, s4
	s_cselect_b32 s41, s17, s41
	s_cselect_b32 s40, s16, s40
	s_cselect_b32 s43, s19, s45
	s_cselect_b32 s42, s18, s44
	v_lshl_add_u64 v[162:163], s[36:37], 0, v[134:135]
	s_add_i32 m0, s58, 0xc000
	ds_read_b128 v[174:177], v141
	ds_read_b128 v[178:181], v141 offset:1024
	ds_read_b128 v[188:191], v141 offset:2048
	ds_read_b128 v[192:195], v141 offset:3072
	ds_read_b128 v[196:199], v141 offset:4096
	ds_read_b128 v[200:203], v141 offset:5120
	ds_read_b128 v[204:207], v141 offset:6144
	ds_read_b128 v[208:211], v141 offset:7168
	global_load_lds_dwordx4 v[162:163], off
	v_lshl_add_u64 v[162:163], s[36:37], 0, v[136:137]
	s_add_i32 m0, s58, 0xe000
	s_nop 0
	global_load_lds_dwordx4 v[162:163], off
	s_waitcnt lgkmcnt(8)
	s_barrier
	s_waitcnt lgkmcnt(0)
	s_waitcnt lgkmcnt(0)
	v_mfma_f32_16x16x32_bf16 v[120:123], v[150:153], v[174:177], 0
	v_mfma_f32_16x16x32_bf16 v[124:127], v[158:161], v[174:177], 0
	v_mfma_f32_16x16x32_bf16 v[108:111], v[150:153], v[188:191], 0
	v_mfma_f32_16x16x32_bf16 v[104:107], v[158:161], v[188:191], 0
	v_mfma_f32_16x16x32_bf16 v[92:95], v[150:153], v[196:199], 0
	v_mfma_f32_16x16x32_bf16 v[88:91], v[158:161], v[196:199], 0
	v_mfma_f32_16x16x32_bf16 v[76:79], v[150:153], v[204:207], 0
	v_mfma_f32_16x16x32_bf16 v[72:75], v[158:161], v[204:207], 0
	v_mfma_f32_16x16x32_bf16 v[120:123], v[154:157], v[178:181], v[120:123]
	v_mfma_f32_16x16x32_bf16 v[124:127], v[170:173], v[178:181], v[124:127]
	v_mfma_f32_16x16x32_bf16 v[108:111], v[154:157], v[192:195], v[108:111]
	v_mfma_f32_16x16x32_bf16 v[104:107], v[170:173], v[192:195], v[104:107]
	v_mfma_f32_16x16x32_bf16 v[92:95], v[154:157], v[200:203], v[92:95]
	v_mfma_f32_16x16x32_bf16 v[88:91], v[170:173], v[200:203], v[88:91]
	v_mfma_f32_16x16x32_bf16 v[76:79], v[154:157], v[208:211], v[76:79]
	v_mfma_f32_16x16x32_bf16 v[72:75], v[170:173], v[208:211], v[72:75]
	s_barrier
	s_add_i32 s4, s61, 0x100
	s_add_i32 s79, s79, s50
	v_add_u32_e32 v149, s4, v140
	v_lshl_add_u64 v[162:163], s[42:43], 0, v[166:167]
	s_mov_b32 m0, s79
	ds_read_b128 v[212:215], v149
	ds_read_b128 v[216:219], v149 offset:1024
	ds_read_b128 v[220:223], v149 offset:2048
	ds_read_b128 v[224:227], v149 offset:3072
	global_load_lds_dwordx4 v[162:163], off
	v_lshl_add_u64 v[182:183], s[42:43], 0, v[128:129]
	s_add_i32 m0, s79, 0x2000
	s_nop 0
	global_load_lds_dwordx4 v[182:183], off
	s_barrier
	s_waitcnt lgkmcnt(0)
	s_waitcnt lgkmcnt(0)
	v_mfma_f32_16x16x32_bf16 v[116:119], v[212:215], v[174:177], 0
	v_mfma_f32_16x16x32_bf16 v[112:115], v[220:223], v[174:177], 0
	v_mfma_f32_16x16x32_bf16 v[100:103], v[212:215], v[188:191], 0
	v_mfma_f32_16x16x32_bf16 v[96:99], v[220:223], v[188:191], 0
	v_mfma_f32_16x16x32_bf16 v[84:87], v[212:215], v[196:199], 0
	v_mfma_f32_16x16x32_bf16 v[80:83], v[220:223], v[196:199], 0
	v_mfma_f32_16x16x32_bf16 v[68:71], v[212:215], v[204:207], 0
	v_mfma_f32_16x16x32_bf16 v[64:67], v[220:223], v[204:207], 0
	v_mfma_f32_16x16x32_bf16 v[116:119], v[216:219], v[178:181], v[116:119]
	v_mfma_f32_16x16x32_bf16 v[112:115], v[224:227], v[178:181], v[112:115]
	v_mfma_f32_16x16x32_bf16 v[100:103], v[216:219], v[192:195], v[100:103]
	v_mfma_f32_16x16x32_bf16 v[96:99], v[224:227], v[192:195], v[96:99]
	v_mfma_f32_16x16x32_bf16 v[84:87], v[216:219], v[200:203], v[84:87]
	v_mfma_f32_16x16x32_bf16 v[80:83], v[224:227], v[200:203], v[80:83]
	v_mfma_f32_16x16x32_bf16 v[68:71], v[216:219], v[208:211], v[68:71]
	v_mfma_f32_16x16x32_bf16 v[64:67], v[224:227], v[208:211], v[64:67]
	s_mov_b32 m0, s58
	v_lshl_add_u64 v[228:229], s[40:41], 0, v[132:133]
	s_barrier
	ds_read_b128 v[174:177], v141 offset:16384
	ds_read_b128 v[178:181], v141 offset:17408
	ds_read_b128 v[188:191], v141 offset:18432
	ds_read_b128 v[192:195], v141 offset:19456
	ds_read_b128 v[196:199], v141 offset:20480
	ds_read_b128 v[200:203], v141 offset:21504
	ds_read_b128 v[204:207], v141 offset:22528
	ds_read_b128 v[208:211], v141 offset:23552
	global_load_lds_dwordx4 v[228:229], off
	v_lshl_add_u64 v[230:231], s[40:41], 0, v[130:131]
	s_mov_b32 m0, s59
	s_nop 0
	global_load_lds_dwordx4 v[230:231], off
	s_barrier
	s_waitcnt lgkmcnt(0)
	s_waitcnt lgkmcnt(0)
	v_mfma_f32_16x16x32_bf16 v[60:63], v[150:153], v[174:177], 0
	v_mfma_f32_16x16x32_bf16 v[56:59], v[158:161], v[174:177], 0
	v_mfma_f32_16x16x32_bf16 v[44:47], v[150:153], v[188:191], 0
	v_mfma_f32_16x16x32_bf16 v[40:43], v[158:161], v[188:191], 0
	v_mfma_f32_16x16x32_bf16 v[28:31], v[150:153], v[196:199], 0
	v_mfma_f32_16x16x32_bf16 v[24:27], v[158:161], v[196:199], 0
	v_mfma_f32_16x16x32_bf16 v[12:15], v[150:153], v[204:207], 0
	v_mfma_f32_16x16x32_bf16 v[8:11], v[158:161], v[204:207], 0
	v_mfma_f32_16x16x32_bf16 v[60:63], v[154:157], v[178:181], v[60:63]
	v_mfma_f32_16x16x32_bf16 v[56:59], v[170:173], v[178:181], v[56:59]
	v_mfma_f32_16x16x32_bf16 v[44:47], v[154:157], v[192:195], v[44:47]
	v_mfma_f32_16x16x32_bf16 v[40:43], v[170:173], v[192:195], v[40:43]
	v_mfma_f32_16x16x32_bf16 v[28:31], v[154:157], v[200:203], v[28:31]
	v_mfma_f32_16x16x32_bf16 v[24:27], v[170:173], v[200:203], v[24:27]
	v_mfma_f32_16x16x32_bf16 v[12:15], v[154:157], v[208:211], v[12:15]
	v_mfma_f32_16x16x32_bf16 v[8:11], v[170:173], v[208:211], v[8:11]
	s_barrier
; #define PG8_STAGE(bufoff, gbase, voff) do { _Pragma("unroll") for (int _i = 0; _i < 2; ++_i) \
;         __builtin_amdgcn_global_load_lds((const unsigned*)((const char*)(gbase) + (voff)[_i]), (LAS unsigned*)(lds + (bufoff) + ldsw + _i * 8192), 16, 0, 0); } while (0)
; #define PG8_LDA(dst, b, h) do { _Pragma("unroll") for (int m = 0; m < 4; ++m) _Pragma("unroll") for (int k = 0; k < 2; ++k) dst[m][k] = *(const LAS bf16x8*)(lds + PG8_SA(b, h) + aoff + m * 2048 + k * 1024); } while (0)
; #define PG8_LDB(dst, b, h) do { _Pragma("unroll") for (int n = 0; n < 2; ++n) _Pragma("unroll") for (int k = 0; k < 2; ++k) dst[n][k] = *(const LAS bf16x8*)(lds + PG8_SB(b, h) + boff + n * 2048 + k * 1024); } while (0)
; #define PG8_MMA(ai, bj, At, Bt) do { __builtin_amdgcn_s_setprio(1); _Pragma("unroll") for (int m = 0; m < 4; ++m) _Pragma("unroll") for (int n = 0; n < 2; ++n) _Pragma("unroll") for (int k = 0; k < 2; ++k) \
;         acc[ai][bj][m][n] = __builtin_amdgcn_mfma_f32_16x16x32_bf16(Bt[n][k], At[m][k], acc[ai][bj][m][n], 0, 0, 0); __builtin_amdgcn_s_setprio(0); } while (0)
; #define PG8_WAIT_V(n) asm volatile("s_waitcnt vmcnt(" #n ")" ::: "memory")
; #define PG8_WAIT_L(n) asm volatile("s_waitcnt lgkmcnt(" #n ")" ::: "memory")
; #define PG8_BAR __builtin_amdgcn_s_barrier()
; #define PG8_SCHED __builtin_amdgcn_sched_barrier(0)
; template <class Epi>
; DI void gemm_phase(LAS unsigned char* lds, const Gemm g, const StaticOrder& S, const Epi& E) {
;     ...
;             PG8_WAIT_V(6); PG8_BAR; PG8_MMA(1, 1, At, B1); PG8_BAR;
;             PG8_LDB(B0, 1, 0); PG8_SCHED; PG8_LDA(At, 1, 0); PG8_STAGE(PG8_SA(0, 1), a2 + hstep, voffA);
;             PG8_WAIT_L(8); PG8_BAR; PG8_WAIT_L(0); PG8_MMA(0, 0, At, B0); PG8_BAR; PG8_SCHED;
;             PG8_LDB(B1, 1, 1); PG8_STAGE(PG8_SB(1, 0), b3, voffB);
;             PG8_BAR; PG8_WAIT_L(0); PG8_MMA(0, 1, At, B1); PG8_BAR;
;             PG8_LDA(At, 1, 1); PG8_STAGE(PG8_SA(1, 0), a3, voffA);
;             PG8_BAR; PG8_WAIT_L(0); PG8_MMA(1, 0, At, B0); PG8_BAR; PG8_SCHED;
	s_add_u32 s42, s42, s10
	s_addc_u32 s43, s43, s11
	s_add_i32 s4, s4, s50
	v_lshl_add_u64 v[232:233], s[42:43], 0, v[166:167]
	s_mov_b32 m0, s4
	v_lshl_add_u64 v[234:235], s[42:43], 0, v[128:129]
	global_load_lds_dwordx4 v[232:233], off
	s_add_i32 m0, s4, 0x2000
	s_nop 0
	global_load_lds_dwordx4 v[234:235], off
	s_waitcnt vmcnt(6)
	s_barrier
	v_mfma_f32_16x16x32_bf16 v[52:55], v[212:215], v[174:177], 0
	v_mfma_f32_16x16x32_bf16 v[48:51], v[220:223], v[174:177], 0
	v_mfma_f32_16x16x32_bf16 v[36:39], v[212:215], v[188:191], 0
	v_mfma_f32_16x16x32_bf16 v[32:35], v[220:223], v[188:191], 0
	v_mfma_f32_16x16x32_bf16 v[20:23], v[212:215], v[196:199], 0
	v_mfma_f32_16x16x32_bf16 v[16:19], v[220:223], v[196:199], 0
	v_mfma_f32_16x16x32_bf16 v[4:7], v[212:215], v[204:207], 0
	v_mfma_f32_16x16x32_bf16 v[0:3], v[220:223], v[204:207], 0
	v_mfma_f32_16x16x32_bf16 v[52:55], v[216:219], v[178:181], v[52:55]
	v_mfma_f32_16x16x32_bf16 v[48:51], v[224:227], v[178:181], v[48:51]
	v_mfma_f32_16x16x32_bf16 v[36:39], v[216:219], v[192:195], v[36:39]
	v_mfma_f32_16x16x32_bf16 v[32:35], v[224:227], v[192:195], v[32:35]
	v_mfma_f32_16x16x32_bf16 v[20:23], v[216:219], v[200:203], v[20:23]
	v_mfma_f32_16x16x32_bf16 v[16:19], v[224:227], v[200:203], v[16:19]
	v_mfma_f32_16x16x32_bf16 v[4:7], v[216:219], v[208:211], v[4:7]
	v_mfma_f32_16x16x32_bf16 v[0:3], v[224:227], v[208:211], v[0:3]
	s_add_i32 s4, s62, 0x100
	v_add_u32_e32 v149, s4, v140
	s_barrier
	ds_read_b128 v[150:153], v149
	ds_read_b128 v[154:157], v149 offset:1024
	ds_read_b128 v[158:161], v149 offset:2048
	ds_read_b128 v[170:173], v149 offset:3072
	s_add_u32 s40, s40, s10
	s_addc_u32 s41, s41, s11
	s_mov_b32 m0, s76
	v_lshl_add_u64 v[212:213], s[40:41], 0, v[132:133]
	ds_read_b128 v[174:177], v141 offset:32768
	ds_read_b128 v[178:181], v141 offset:33792
	ds_read_b128 v[188:191], v141 offset:34816
	ds_read_b128 v[192:195], v141 offset:35840
	ds_read_b128 v[196:199], v141 offset:36864
	ds_read_b128 v[200:203], v141 offset:37888
	ds_read_b128 v[204:207], v141 offset:38912
	ds_read_b128 v[208:211], v141 offset:39936
	global_load_lds_dwordx4 v[212:213], off
	v_lshl_add_u64 v[212:213], s[40:41], 0, v[130:131]
	s_mov_b32 m0, s77
	s_nop 0
	global_load_lds_dwordx4 v[212:213], off
	s_waitcnt lgkmcnt(8)
	s_barrier
	s_waitcnt lgkmcnt(0)
	s_waitcnt lgkmcnt(0)
	v_mfma_f32_16x16x32_bf16 v[120:123], v[150:153], v[174:177], v[120:123]
	v_mfma_f32_16x16x32_bf16 v[124:127], v[158:161], v[174:177], v[124:127]
	v_mfma_f32_16x16x32_bf16 v[108:111], v[150:153], v[188:191], v[108:111]
	v_mfma_f32_16x16x32_bf16 v[104:107], v[158:161], v[188:191], v[104:107]
	v_mfma_f32_16x16x32_bf16 v[92:95], v[150:153], v[196:199], v[92:95]
	v_mfma_f32_16x16x32_bf16 v[88:91], v[158:161], v[196:199], v[88:91]
	v_mfma_f32_16x16x32_bf16 v[76:79], v[150:153], v[204:207], v[76:79]
	v_mfma_f32_16x16x32_bf16 v[72:75], v[158:161], v[204:207], v[72:75]
	v_mfma_f32_16x16x32_bf16 v[120:123], v[154:157], v[178:181], v[120:123]
	v_mfma_f32_16x16x32_bf16 v[124:127], v[170:173], v[178:181], v[124:127]
	v_mfma_f32_16x16x32_bf16 v[108:111], v[154:157], v[192:195], v[108:111]
	v_mfma_f32_16x16x32_bf16 v[104:107], v[170:173], v[192:195], v[104:107]
	v_mfma_f32_16x16x32_bf16 v[92:95], v[154:157], v[200:203], v[92:95]
	v_mfma_f32_16x16x32_bf16 v[88:91], v[170:173], v[200:203], v[88:91]
	v_mfma_f32_16x16x32_bf16 v[76:79], v[154:157], v[208:211], v[76:79]
	v_mfma_f32_16x16x32_bf16 v[72:75], v[170:173], v[208:211], v[72:75]
	s_barrier
	s_add_i32 s40, s63, 0x100
	s_add_i32 s4, s4, s50
	v_add_u32_e32 v149, s40, v140
	v_lshl_add_u64 v[162:163], v[162:163], 0, s[66:67]
	s_mov_b32 m0, s4
	ds_read_b128 v[212:215], v149
	ds_read_b128 v[216:219], v149 offset:1024
	ds_read_b128 v[220:223], v149 offset:2048
	ds_read_b128 v[224:227], v149 offset:3072
	global_load_lds_dwordx4 v[162:163], off
	v_lshl_add_u64 v[162:163], v[182:183], 0, s[66:67]
	s_add_i32 m0, s4, 0x2000
	s_nop 0
	global_load_lds_dwordx4 v[162:163], off
	s_barrier
	s_waitcnt lgkmcnt(0)
	s_waitcnt lgkmcnt(0)
	v_mfma_f32_16x16x32_bf16 v[116:119], v[212:215], v[174:177], v[116:119]
	v_mfma_f32_16x16x32_bf16 v[112:115], v[220:223], v[174:177], v[112:115]
	v_mfma_f32_16x16x32_bf16 v[100:103], v[212:215], v[188:191], v[100:103]
	v_mfma_f32_16x16x32_bf16 v[96:99], v[220:223], v[188:191], v[96:99]
	v_mfma_f32_16x16x32_bf16 v[84:87], v[212:215], v[196:199], v[84:87]
	v_mfma_f32_16x16x32_bf16 v[80:83], v[220:223], v[196:199], v[80:83]
	v_mfma_f32_16x16x32_bf16 v[68:71], v[212:215], v[204:207], v[68:71]
	v_mfma_f32_16x16x32_bf16 v[64:67], v[220:223], v[204:207], v[64:67]
	v_mfma_f32_16x16x32_bf16 v[116:119], v[216:219], v[178:181], v[116:119]
	v_mfma_f32_16x16x32_bf16 v[112:115], v[224:227], v[178:181], v[112:115]
	v_mfma_f32_16x16x32_bf16 v[100:103], v[216:219], v[192:195], v[100:103]
	v_mfma_f32_16x16x32_bf16 v[96:99], v[224:227], v[192:195], v[96:99]
	v_mfma_f32_16x16x32_bf16 v[84:87], v[216:219], v[200:203], v[84:87]
	v_mfma_f32_16x16x32_bf16 v[80:83], v[224:227], v[200:203], v[80:83]
	v_mfma_f32_16x16x32_bf16 v[68:71], v[216:219], v[208:211], v[68:71]
	v_mfma_f32_16x16x32_bf16 v[64:67], v[224:227], v[208:211], v[64:67]
	s_mov_b32 m0, s80
	v_lshl_add_u64 v[162:163], v[228:229], 0, s[66:67]
	s_barrier
	ds_read_b128 v[174:177], v141 offset:49152
	ds_read_b128 v[178:181], v141 offset:50176
	ds_read_b128 v[188:191], v141 offset:51200
	ds_read_b128 v[192:195], v141 offset:52224
	ds_read_b128 v[196:199], v141 offset:53248
	ds_read_b128 v[200:203], v141 offset:54272
	ds_read_b128 v[204:207], v141 offset:55296
	ds_read_b128 v[208:211], v141 offset:56320
	global_load_lds_dwordx4 v[162:163], off
	v_lshl_add_u64 v[162:163], v[230:231], 0, s[66:67]
	s_mov_b32 m0, s81
	s_nop 0
	global_load_lds_dwordx4 v[162:163], off
	s_barrier
; #define PG8_STAGE(bufoff, gbase, voff) do { _Pragma("unroll") for (int _i = 0; _i < 2; ++_i) \
;         __builtin_amdgcn_global_load_lds((const unsigned*)((const char*)(gbase) + (voff)[_i]), (LAS unsigned*)(lds + (bufoff) + ldsw + _i * 8192), 16, 0, 0); } while (0)
; #define PG8_LDA(dst, b, h) do { _Pragma("unroll") for (int m = 0; m < 4; ++m) _Pragma("unroll") for (int k = 0; k < 2; ++k) dst[m][k] = *(const LAS bf16x8*)(lds + PG8_SA(b, h) + aoff + m * 2048 + k * 1024); } while (0)
; #define PG8_LDB(dst, b, h) do { _Pragma("unroll") for (int n = 0; n < 2; ++n) _Pragma("unroll") for (int k = 0; k < 2; ++k) dst[n][k] = *(const LAS bf16x8*)(lds + PG8_SB(b, h) + boff + n * 2048 + k * 1024); } while (0)
; #define PG8_WAIT_V(n) asm volatile("s_waitcnt vmcnt(" #n ")" ::: "memory")
; #define PG8_WAIT_L(n) asm volatile("s_waitcnt lgkmcnt(" #n ")" ::: "memory")
; #define PG8_BAR __builtin_amdgcn_s_barrier()
; #define PG8_SCHED __builtin_amdgcn_sched_barrier(0)
; template <class Epi>
; DI void gemm_phase(LAS unsigned char* lds, const Gemm g, const StaticOrder& S, const Epi& E) {
;     ...
;             PG8_LDB(B0, 0, 0); PG8_SCHED; PG8_LDA(At, 0, 0); PG8_STAGE(PG8_SA(1, 1), a1 + hstep, voffA);
;             PG8_WAIT_L(8); PG8_BAR; PG8_WAIT_L(0); PG8_MMA(0, 0, At, B0); PG8_BAR; PG8_SCHED;
;             PG8_LDB(B1, 0, 1); PG8_STAGE(PG8_SB(0, 0), b2, voffB);
;             PG8_BAR; PG8_WAIT_L(0); PG8_MMA(0, 1, At, B1); PG8_BAR;
;             PG8_LDA(At, 0, 1); PG8_STAGE(PG8_SA(0, 0), a2, voffA);
;             PG8_BAR; PG8_WAIT_L(0); PG8_MMA(1, 0, At, B0); PG8_BAR; PG8_SCHED;
;             PG8_STAGE(PG8_SB(0, 1), b2 + hstep, voffB);
;             PG8_WAIT_V(6); PG8_BAR; PG8_MMA(1, 1, At, B1); PG8_BAR;
;             PG8_LDB(B0, 1, 0); PG8_SCHED; PG8_LDA(At, 1, 0); PG8_STAGE(PG8_SA(0, 1), a2 + hstep, voffA);
;             PG8_WAIT_L(8); PG8_BAR; PG8_WAIT_L(0); PG8_MMA(0, 0, At, B0); PG8_BAR; PG8_SCHED;
;             PG8_LDB(B1, 1, 1); PG8_STAGE(PG8_SB(1, 0), b3, voffB);
;             PG8_BAR; PG8_WAIT_L(0); PG8_MMA(0, 1, At, B1); PG8_BAR;
;             PG8_LDA(At, 1, 1); PG8_STAGE(PG8_SA(1, 0), a3, voffA);
;             PG8_BAR; PG8_WAIT_L(0); PG8_MMA(1, 0, At, B0); PG8_BAR; PG8_SCHED;
;             PG8_STAGE(PG8_SB(1, 1), b3 + hstep, voffB);
;             PG8_WAIT_V(6); PG8_BAR; PG8_MMA(1, 1, At, B1); PG8_BAR;
	s_waitcnt lgkmcnt(0)
	s_waitcnt lgkmcnt(0)
	v_mfma_f32_16x16x32_bf16 v[60:63], v[150:153], v[174:177], v[60:63]
	v_mfma_f32_16x16x32_bf16 v[56:59], v[158:161], v[174:177], v[56:59]
	v_mfma_f32_16x16x32_bf16 v[44:47], v[150:153], v[188:191], v[44:47]
	v_mfma_f32_16x16x32_bf16 v[40:43], v[158:161], v[188:191], v[40:43]
	v_mfma_f32_16x16x32_bf16 v[28:31], v[150:153], v[196:199], v[28:31]
	v_mfma_f32_16x16x32_bf16 v[24:27], v[158:161], v[196:199], v[24:27]
	v_mfma_f32_16x16x32_bf16 v[12:15], v[150:153], v[204:207], v[12:15]
	v_mfma_f32_16x16x32_bf16 v[8:11], v[158:161], v[204:207], v[8:11]
	v_mfma_f32_16x16x32_bf16 v[60:63], v[154:157], v[178:181], v[60:63]
	v_mfma_f32_16x16x32_bf16 v[56:59], v[170:173], v[178:181], v[56:59]
	v_mfma_f32_16x16x32_bf16 v[44:47], v[154:157], v[192:195], v[44:47]
	v_mfma_f32_16x16x32_bf16 v[40:43], v[170:173], v[192:195], v[40:43]
	v_mfma_f32_16x16x32_bf16 v[28:31], v[154:157], v[200:203], v[28:31]
	v_mfma_f32_16x16x32_bf16 v[24:27], v[170:173], v[200:203], v[24:27]
	v_mfma_f32_16x16x32_bf16 v[12:15], v[154:157], v[208:211], v[12:15]
	v_mfma_f32_16x16x32_bf16 v[8:11], v[170:173], v[208:211], v[8:11]
	s_barrier
	s_add_i32 s4, s40, s50
	v_lshl_add_u64 v[150:151], v[232:233], 0, s[66:67]
	s_mov_b32 m0, s4
	s_nop 0
	global_load_lds_dwordx4 v[150:151], off
	v_lshl_add_u64 v[150:151], v[234:235], 0, s[66:67]
	s_add_i32 m0, s4, 0x2000
	s_nop 0
	global_load_lds_dwordx4 v[150:151], off
	s_waitcnt vmcnt(6)
	s_barrier
	v_mfma_f32_16x16x32_bf16 v[52:55], v[212:215], v[174:177], v[52:55]
	v_mfma_f32_16x16x32_bf16 v[48:51], v[220:223], v[174:177], v[48:51]
	v_mfma_f32_16x16x32_bf16 v[36:39], v[212:215], v[188:191], v[36:39]
	v_mfma_f32_16x16x32_bf16 v[32:35], v[220:223], v[188:191], v[32:35]
	v_mfma_f32_16x16x32_bf16 v[20:23], v[212:215], v[196:199], v[20:23]
	v_mfma_f32_16x16x32_bf16 v[16:19], v[220:223], v[196:199], v[16:19]
	v_mfma_f32_16x16x32_bf16 v[4:7], v[212:215], v[204:207], v[4:7]
	v_mfma_f32_16x16x32_bf16 v[0:3], v[220:223], v[204:207], v[0:3]
	v_mfma_f32_16x16x32_bf16 v[52:55], v[216:219], v[178:181], v[52:55]
	v_mfma_f32_16x16x32_bf16 v[48:51], v[224:227], v[178:181], v[48:51]
	v_mfma_f32_16x16x32_bf16 v[36:39], v[216:219], v[192:195], v[36:39]
	v_mfma_f32_16x16x32_bf16 v[32:35], v[224:227], v[192:195], v[32:35]
	v_mfma_f32_16x16x32_bf16 v[20:23], v[216:219], v[200:203], v[20:23]
	v_mfma_f32_16x16x32_bf16 v[16:19], v[224:227], v[200:203], v[16:19]
	v_mfma_f32_16x16x32_bf16 v[4:7], v[216:219], v[208:211], v[4:7]
	v_mfma_f32_16x16x32_bf16 v[0:3], v[224:227], v[208:211], v[0:3]
	s_add_u32 s36, s36, 0x100
	s_addc_u32 s37, s37, 0
	s_add_u32 s44, s44, 0x100
	s_addc_u32 s45, s45, 0
	s_cmp_ge_i32 s5, s84
	s_mov_b32 s4, s5
	s_barrier
	s_cbranch_scc0 .LBB0_1379
	s_branch .Lpeel_exit_3
.LBB0_1379:
	s_add_i32 s5, s4, 2
	s_add_u32 s40, s36, 0x80
	s_addc_u32 s41, s37, 0
	s_add_i32 s79, s60, 0x100
	v_add_u32_e32 v149, s79, v140
	ds_read_b128 v[150:153], v149
	ds_read_b128 v[154:157], v149 offset:1024
	ds_read_b128 v[158:161], v149 offset:2048
	ds_read_b128 v[170:173], v149 offset:3072
	s_cmp_eq_u32 s87, s4
	s_cselect_b32 s41, s17, s41
	s_cselect_b32 s40, s16, s40
	s_cselect_b32 s43, s19, s45
	s_cselect_b32 s42, s18, s44
	v_lshl_add_u64 v[162:163], s[36:37], 0, v[134:135]
	s_add_i32 m0, s58, 0xc000
	ds_read_b128 v[174:177], v141
	ds_read_b128 v[178:181], v141 offset:1024
	ds_read_b128 v[188:191], v141 offset:2048
	ds_read_b128 v[192:195], v141 offset:3072
	ds_read_b128 v[196:199], v141 offset:4096
	ds_read_b128 v[200:203], v141 offset:5120
	ds_read_b128 v[204:207], v141 offset:6144
	ds_read_b128 v[208:211], v141 offset:7168
	global_load_lds_dwordx4 v[162:163], off
	v_lshl_add_u64 v[162:163], s[36:37], 0, v[136:137]
	s_add_i32 m0, s58, 0xe000
	s_nop 0
	global_load_lds_dwordx4 v[162:163], off
	s_waitcnt lgkmcnt(8)
	s_barrier
	s_waitcnt lgkmcnt(0)
	s_waitcnt lgkmcnt(0)
	v_mfma_f32_16x16x32_bf16 v[120:123], v[150:153], v[174:177], v[120:123]
	v_mfma_f32_16x16x32_bf16 v[124:127], v[158:161], v[174:177], v[124:127]
	v_mfma_f32_16x16x32_bf16 v[108:111], v[150:153], v[188:191], v[108:111]
	v_mfma_f32_16x16x32_bf16 v[104:107], v[158:161], v[188:191], v[104:107]
	v_mfma_f32_16x16x32_bf16 v[92:95], v[150:153], v[196:199], v[92:95]
	v_mfma_f32_16x16x32_bf16 v[88:91], v[158:161], v[196:199], v[88:91]
	v_mfma_f32_16x16x32_bf16 v[76:79], v[150:153], v[204:207], v[76:79]
	v_mfma_f32_16x16x32_bf16 v[72:75], v[158:161], v[204:207], v[72:75]
	v_mfma_f32_16x16x32_bf16 v[120:123], v[154:157], v[178:181], v[120:123]
	v_mfma_f32_16x16x32_bf16 v[124:127], v[170:173], v[178:181], v[124:127]
	v_mfma_f32_16x16x32_bf16 v[108:111], v[154:157], v[192:195], v[108:111]
	v_mfma_f32_16x16x32_bf16 v[104:107], v[170:173], v[192:195], v[104:107]
	v_mfma_f32_16x16x32_bf16 v[92:95], v[154:157], v[200:203], v[92:95]
	v_mfma_f32_16x16x32_bf16 v[88:91], v[170:173], v[200:203], v[88:91]
	v_mfma_f32_16x16x32_bf16 v[76:79], v[154:157], v[208:211], v[76:79]
	v_mfma_f32_16x16x32_bf16 v[72:75], v[170:173], v[208:211], v[72:75]
	s_barrier
	s_add_i32 s4, s61, 0x100
	s_add_i32 s79, s79, s50
	v_add_u32_e32 v149, s4, v140
	v_lshl_add_u64 v[162:163], s[42:43], 0, v[166:167]
	s_mov_b32 m0, s79
	ds_read_b128 v[212:215], v149
	ds_read_b128 v[216:219], v149 offset:1024
	ds_read_b128 v[220:223], v149 offset:2048
	ds_read_b128 v[224:227], v149 offset:3072
	global_load_lds_dwordx4 v[162:163], off
	v_lshl_add_u64 v[182:183], s[42:43], 0, v[128:129]
	s_add_i32 m0, s79, 0x2000
	s_nop 0
	global_load_lds_dwordx4 v[182:183], off
	s_barrier
; #define PG8_STAGE(bufoff, gbase, voff) do { _Pragma("unroll") for (int _i = 0; _i < 2; ++_i) \
;         __builtin_amdgcn_global_load_lds((const unsigned*)((const char*)(gbase) + (voff)[_i]), (LAS unsigned*)(lds + (bufoff) + ldsw + _i * 8192), 16, 0, 0); } while (0)
; #define PG8_LDA(dst, b, h) do { _Pragma("unroll") for (int m = 0; m < 4; ++m) _Pragma("unroll") for (int k = 0; k < 2; ++k) dst[m][k] = *(const LAS bf16x8*)(lds + PG8_SA(b, h) + aoff + m * 2048 + k * 1024); } while (0)
; #define PG8_LDB(dst, b, h) do { _Pragma("unroll") for (int n = 0; n < 2; ++n) _Pragma("unroll") for (int k = 0; k < 2; ++k) dst[n][k] = *(const LAS bf16x8*)(lds + PG8_SB(b, h) + boff + n * 2048 + k * 1024); } while (0)
; #define PG8_MMA(ai, bj, At, Bt) do { __builtin_amdgcn_s_setprio(1); _Pragma("unroll") for (int m = 0; m < 4; ++m) _Pragma("unroll") for (int n = 0; n < 2; ++n) _Pragma("unroll") for (int k = 0; k < 2; ++k) \
;         acc[ai][bj][m][n] = __builtin_amdgcn_mfma_f32_16x16x32_bf16(Bt[n][k], At[m][k], acc[ai][bj][m][n], 0, 0, 0); __builtin_amdgcn_s_setprio(0); } while (0)
; #define PG8_WAIT_V(n) asm volatile("s_waitcnt vmcnt(" #n ")" ::: "memory")
; #define PG8_WAIT_L(n) asm volatile("s_waitcnt lgkmcnt(" #n ")" ::: "memory")
; #define PG8_BAR __builtin_amdgcn_s_barrier()
; #define PG8_SCHED __builtin_amdgcn_sched_barrier(0)
; template <class Epi>
; DI void gemm_phase(LAS unsigned char* lds, const Gemm g, const StaticOrder& S, const Epi& E) {
;     ...
;             PG8_BAR; PG8_WAIT_L(0); PG8_MMA(0, 1, At, B1); PG8_BAR;
;             PG8_LDA(At, 0, 1); PG8_STAGE(PG8_SA(0, 0), a2, voffA);
;             PG8_BAR; PG8_WAIT_L(0); PG8_MMA(1, 0, At, B0); PG8_BAR; PG8_SCHED;
;             PG8_STAGE(PG8_SB(0, 1), b2 + hstep, voffB);
;             PG8_WAIT_V(6); PG8_BAR; PG8_MMA(1, 1, At, B1); PG8_BAR;
;             PG8_LDB(B0, 1, 0); PG8_SCHED; PG8_LDA(At, 1, 0); PG8_STAGE(PG8_SA(0, 1), a2 + hstep, voffA);
	s_waitcnt lgkmcnt(0)
	s_waitcnt lgkmcnt(0)
	v_mfma_f32_16x16x32_bf16 v[116:119], v[212:215], v[174:177], v[116:119]
	v_mfma_f32_16x16x32_bf16 v[112:115], v[220:223], v[174:177], v[112:115]
	v_mfma_f32_16x16x32_bf16 v[100:103], v[212:215], v[188:191], v[100:103]
	v_mfma_f32_16x16x32_bf16 v[96:99], v[220:223], v[188:191], v[96:99]
	v_mfma_f32_16x16x32_bf16 v[84:87], v[212:215], v[196:199], v[84:87]
	v_mfma_f32_16x16x32_bf16 v[80:83], v[220:223], v[196:199], v[80:83]
	v_mfma_f32_16x16x32_bf16 v[68:71], v[212:215], v[204:207], v[68:71]
	v_mfma_f32_16x16x32_bf16 v[64:67], v[220:223], v[204:207], v[64:67]
	v_mfma_f32_16x16x32_bf16 v[116:119], v[216:219], v[178:181], v[116:119]
	v_mfma_f32_16x16x32_bf16 v[112:115], v[224:227], v[178:181], v[112:115]
	v_mfma_f32_16x16x32_bf16 v[100:103], v[216:219], v[192:195], v[100:103]
	v_mfma_f32_16x16x32_bf16 v[96:99], v[224:227], v[192:195], v[96:99]
	v_mfma_f32_16x16x32_bf16 v[84:87], v[216:219], v[200:203], v[84:87]
	v_mfma_f32_16x16x32_bf16 v[80:83], v[224:227], v[200:203], v[80:83]
	v_mfma_f32_16x16x32_bf16 v[68:71], v[216:219], v[208:211], v[68:71]
	v_mfma_f32_16x16x32_bf16 v[64:67], v[224:227], v[208:211], v[64:67]
	s_mov_b32 m0, s58
	v_lshl_add_u64 v[228:229], s[40:41], 0, v[132:133]
	s_barrier
	ds_read_b128 v[174:177], v141 offset:16384
	ds_read_b128 v[178:181], v141 offset:17408
	ds_read_b128 v[188:191], v141 offset:18432
	ds_read_b128 v[192:195], v141 offset:19456
	ds_read_b128 v[196:199], v141 offset:20480
	ds_read_b128 v[200:203], v141 offset:21504
	ds_read_b128 v[204:207], v141 offset:22528
	ds_read_b128 v[208:211], v141 offset:23552
	global_load_lds_dwordx4 v[228:229], off
	v_lshl_add_u64 v[230:231], s[40:41], 0, v[130:131]
	s_mov_b32 m0, s59
	s_nop 0
	global_load_lds_dwordx4 v[230:231], off
	s_barrier
	s_waitcnt lgkmcnt(0)
	s_waitcnt lgkmcnt(0)
	v_mfma_f32_16x16x32_bf16 v[60:63], v[150:153], v[174:177], v[60:63]
	v_mfma_f32_16x16x32_bf16 v[56:59], v[158:161], v[174:177], v[56:59]
	v_mfma_f32_16x16x32_bf16 v[44:47], v[150:153], v[188:191], v[44:47]
	v_mfma_f32_16x16x32_bf16 v[40:43], v[158:161], v[188:191], v[40:43]
	v_mfma_f32_16x16x32_bf16 v[28:31], v[150:153], v[196:199], v[28:31]
	v_mfma_f32_16x16x32_bf16 v[24:27], v[158:161], v[196:199], v[24:27]
	v_mfma_f32_16x16x32_bf16 v[12:15], v[150:153], v[204:207], v[12:15]
	v_mfma_f32_16x16x32_bf16 v[8:11], v[158:161], v[204:207], v[8:11]
	v_mfma_f32_16x16x32_bf16 v[60:63], v[154:157], v[178:181], v[60:63]
	v_mfma_f32_16x16x32_bf16 v[56:59], v[170:173], v[178:181], v[56:59]
	v_mfma_f32_16x16x32_bf16 v[44:47], v[154:157], v[192:195], v[44:47]
	v_mfma_f32_16x16x32_bf16 v[40:43], v[170:173], v[192:195], v[40:43]
	v_mfma_f32_16x16x32_bf16 v[28:31], v[154:157], v[200:203], v[28:31]
	v_mfma_f32_16x16x32_bf16 v[24:27], v[170:173], v[200:203], v[24:27]
	v_mfma_f32_16x16x32_bf16 v[12:15], v[154:157], v[208:211], v[12:15]
	v_mfma_f32_16x16x32_bf16 v[8:11], v[170:173], v[208:211], v[8:11]
	s_barrier
	s_add_u32 s42, s42, s10
	s_addc_u32 s43, s43, s11
	s_add_i32 s4, s4, s50
	v_lshl_add_u64 v[232:233], s[42:43], 0, v[166:167]
	s_mov_b32 m0, s4
	v_lshl_add_u64 v[234:235], s[42:43], 0, v[128:129]
	global_load_lds_dwordx4 v[232:233], off
	s_add_i32 m0, s4, 0x2000
	s_nop 0
	global_load_lds_dwordx4 v[234:235], off
	s_waitcnt vmcnt(6)
	s_barrier
	v_mfma_f32_16x16x32_bf16 v[52:55], v[212:215], v[174:177], v[52:55]
	v_mfma_f32_16x16x32_bf16 v[48:51], v[220:223], v[174:177], v[48:51]
	v_mfma_f32_16x16x32_bf16 v[36:39], v[212:215], v[188:191], v[36:39]
	v_mfma_f32_16x16x32_bf16 v[32:35], v[220:223], v[188:191], v[32:35]
	v_mfma_f32_16x16x32_bf16 v[20:23], v[212:215], v[196:199], v[20:23]
	v_mfma_f32_16x16x32_bf16 v[16:19], v[220:223], v[196:199], v[16:19]
	v_mfma_f32_16x16x32_bf16 v[4:7], v[212:215], v[204:207], v[4:7]
	v_mfma_f32_16x16x32_bf16 v[0:3], v[220:223], v[204:207], v[0:3]
	v_mfma_f32_16x16x32_bf16 v[52:55], v[216:219], v[178:181], v[52:55]
	v_mfma_f32_16x16x32_bf16 v[48:51], v[224:227], v[178:181], v[48:51]
	v_mfma_f32_16x16x32_bf16 v[36:39], v[216:219], v[192:195], v[36:39]
	v_mfma_f32_16x16x32_bf16 v[32:35], v[224:227], v[192:195], v[32:35]
	v_mfma_f32_16x16x32_bf16 v[20:23], v[216:219], v[200:203], v[20:23]
	v_mfma_f32_16x16x32_bf16 v[16:19], v[224:227], v[200:203], v[16:19]
	v_mfma_f32_16x16x32_bf16 v[4:7], v[216:219], v[208:211], v[4:7]
	v_mfma_f32_16x16x32_bf16 v[0:3], v[224:227], v[208:211], v[0:3]
	s_add_i32 s4, s62, 0x100
	v_add_u32_e32 v149, s4, v140
	s_barrier
	ds_read_b128 v[150:153], v149
	ds_read_b128 v[154:157], v149 offset:1024
	ds_read_b128 v[158:161], v149 offset:2048
	ds_read_b128 v[170:173], v149 offset:3072
	s_add_u32 s40, s40, s10
	s_addc_u32 s41, s41, s11
	s_mov_b32 m0, s76
	v_lshl_add_u64 v[212:213], s[40:41], 0, v[132:133]
	ds_read_b128 v[174:177], v141 offset:32768
	ds_read_b128 v[178:181], v141 offset:33792
	ds_read_b128 v[188:191], v141 offset:34816
	ds_read_b128 v[192:195], v141 offset:35840
	ds_read_b128 v[196:199], v141 offset:36864
	ds_read_b128 v[200:203], v141 offset:37888
	ds_read_b128 v[204:207], v141 offset:38912
	ds_read_b128 v[208:211], v141 offset:39936
	global_load_lds_dwordx4 v[212:213], off
	v_lshl_add_u64 v[212:213], s[40:41], 0, v[130:131]
	s_mov_b32 m0, s77
	s_nop 0
	global_load_lds_dwordx4 v[212:213], off
	s_waitcnt lgkmcnt(8)
	s_barrier
; #define PG8_STAGE(bufoff, gbase, voff) do { _Pragma("unroll") for (int _i = 0; _i < 2; ++_i) \
;         __builtin_amdgcn_global_load_lds((const unsigned*)((const char*)(gbase) + (voff)[_i]), (LAS unsigned*)(lds + (bufoff) + ldsw + _i * 8192), 16, 0, 0); } while (0)
; #define PG8_LDA(dst, b, h) do { _Pragma("unroll") for (int m = 0; m < 4; ++m) _Pragma("unroll") for (int k = 0; k < 2; ++k) dst[m][k] = *(const LAS bf16x8*)(lds + PG8_SA(b, h) + aoff + m * 2048 + k * 1024); } while (0)
; #define PG8_LDB(dst, b, h) do { _Pragma("unroll") for (int n = 0; n < 2; ++n) _Pragma("unroll") for (int k = 0; k < 2; ++k) dst[n][k] = *(const LAS bf16x8*)(lds + PG8_SB(b, h) + boff + n * 2048 + k * 1024); } while (0)
; #define PG8_MMA(ai, bj, At, Bt) do { __builtin_amdgcn_s_setprio(1); _Pragma("unroll") for (int m = 0; m < 4; ++m) _Pragma("unroll") for (int n = 0; n < 2; ++n) _Pragma("unroll") for (int k = 0; k < 2; ++k) \
;         acc[ai][bj][m][n] = __builtin_amdgcn_mfma_f32_16x16x32_bf16(Bt[n][k], At[m][k], acc[ai][bj][m][n], 0, 0, 0); __builtin_amdgcn_s_setprio(0); } while (0)
; #define PG8_WAIT_V(n) asm volatile("s_waitcnt vmcnt(" #n ")" ::: "memory")
; #define PG8_WAIT_L(n) asm volatile("s_waitcnt lgkmcnt(" #n ")" ::: "memory")
; #define PG8_BAR __builtin_amdgcn_s_barrier()
; #define PG8_SCHED __builtin_amdgcn_sched_barrier(0)
; template <class Epi>
; DI void gemm_phase(LAS unsigned char* lds, const Gemm g, const StaticOrder& S, const Epi& E) {
;     ...
;             PG8_WAIT_L(8); PG8_BAR; PG8_WAIT_L(0); PG8_MMA(0, 0, At, B0); PG8_BAR; PG8_SCHED;
;             PG8_LDB(B1, 1, 1); PG8_STAGE(PG8_SB(1, 0), b3, voffB);
;             PG8_BAR; PG8_WAIT_L(0); PG8_MMA(0, 1, At, B1); PG8_BAR;
;             PG8_LDA(At, 1, 1); PG8_STAGE(PG8_SA(1, 0), a3, voffA);
;             PG8_BAR; PG8_WAIT_L(0); PG8_MMA(1, 0, At, B0); PG8_BAR; PG8_SCHED;
;             PG8_STAGE(PG8_SB(1, 1), b3 + hstep, voffB);
;             PG8_WAIT_V(6); PG8_BAR; PG8_MMA(1, 1, At, B1); PG8_BAR;
	s_waitcnt lgkmcnt(0)
	s_waitcnt lgkmcnt(0)
	v_mfma_f32_16x16x32_bf16 v[120:123], v[150:153], v[174:177], v[120:123]
	v_mfma_f32_16x16x32_bf16 v[124:127], v[158:161], v[174:177], v[124:127]
	v_mfma_f32_16x16x32_bf16 v[108:111], v[150:153], v[188:191], v[108:111]
	v_mfma_f32_16x16x32_bf16 v[104:107], v[158:161], v[188:191], v[104:107]
	v_mfma_f32_16x16x32_bf16 v[92:95], v[150:153], v[196:199], v[92:95]
	v_mfma_f32_16x16x32_bf16 v[88:91], v[158:161], v[196:199], v[88:91]
	v_mfma_f32_16x16x32_bf16 v[76:79], v[150:153], v[204:207], v[76:79]
	v_mfma_f32_16x16x32_bf16 v[72:75], v[158:161], v[204:207], v[72:75]
	v_mfma_f32_16x16x32_bf16 v[120:123], v[154:157], v[178:181], v[120:123]
	v_mfma_f32_16x16x32_bf16 v[124:127], v[170:173], v[178:181], v[124:127]
	v_mfma_f32_16x16x32_bf16 v[108:111], v[154:157], v[192:195], v[108:111]
	v_mfma_f32_16x16x32_bf16 v[104:107], v[170:173], v[192:195], v[104:107]
	v_mfma_f32_16x16x32_bf16 v[92:95], v[154:157], v[200:203], v[92:95]
	v_mfma_f32_16x16x32_bf16 v[88:91], v[170:173], v[200:203], v[88:91]
	v_mfma_f32_16x16x32_bf16 v[76:79], v[154:157], v[208:211], v[76:79]
	v_mfma_f32_16x16x32_bf16 v[72:75], v[170:173], v[208:211], v[72:75]
	s_barrier
	s_add_i32 s40, s63, 0x100
	s_add_i32 s4, s4, s50
	v_add_u32_e32 v149, s40, v140
	v_lshl_add_u64 v[162:163], v[162:163], 0, s[66:67]
	s_mov_b32 m0, s4
	ds_read_b128 v[212:215], v149
	ds_read_b128 v[216:219], v149 offset:1024
	ds_read_b128 v[220:223], v149 offset:2048
	ds_read_b128 v[224:227], v149 offset:3072
	global_load_lds_dwordx4 v[162:163], off
	v_lshl_add_u64 v[162:163], v[182:183], 0, s[66:67]
	s_add_i32 m0, s4, 0x2000
	s_nop 0
	global_load_lds_dwordx4 v[162:163], off
	s_barrier
	s_waitcnt lgkmcnt(0)
	s_waitcnt lgkmcnt(0)
	v_mfma_f32_16x16x32_bf16 v[116:119], v[212:215], v[174:177], v[116:119]
	v_mfma_f32_16x16x32_bf16 v[112:115], v[220:223], v[174:177], v[112:115]
	v_mfma_f32_16x16x32_bf16 v[100:103], v[212:215], v[188:191], v[100:103]
	v_mfma_f32_16x16x32_bf16 v[96:99], v[220:223], v[188:191], v[96:99]
	v_mfma_f32_16x16x32_bf16 v[84:87], v[212:215], v[196:199], v[84:87]
	v_mfma_f32_16x16x32_bf16 v[80:83], v[220:223], v[196:199], v[80:83]
	v_mfma_f32_16x16x32_bf16 v[68:71], v[212:215], v[204:207], v[68:71]
	v_mfma_f32_16x16x32_bf16 v[64:67], v[220:223], v[204:207], v[64:67]
	v_mfma_f32_16x16x32_bf16 v[116:119], v[216:219], v[178:181], v[116:119]
	v_mfma_f32_16x16x32_bf16 v[112:115], v[224:227], v[178:181], v[112:115]
	v_mfma_f32_16x16x32_bf16 v[100:103], v[216:219], v[192:195], v[100:103]
	v_mfma_f32_16x16x32_bf16 v[96:99], v[224:227], v[192:195], v[96:99]
	v_mfma_f32_16x16x32_bf16 v[84:87], v[216:219], v[200:203], v[84:87]
	v_mfma_f32_16x16x32_bf16 v[80:83], v[224:227], v[200:203], v[80:83]
	v_mfma_f32_16x16x32_bf16 v[68:71], v[216:219], v[208:211], v[68:71]
	v_mfma_f32_16x16x32_bf16 v[64:67], v[224:227], v[208:211], v[64:67]
	s_mov_b32 m0, s80
	v_lshl_add_u64 v[162:163], v[228:229], 0, s[66:67]
	s_barrier
	ds_read_b128 v[174:177], v141 offset:49152
	ds_read_b128 v[178:181], v141 offset:50176
	ds_read_b128 v[188:191], v141 offset:51200
	ds_read_b128 v[192:195], v141 offset:52224
	ds_read_b128 v[196:199], v141 offset:53248
	ds_read_b128 v[200:203], v141 offset:54272
	ds_read_b128 v[204:207], v141 offset:55296
	ds_read_b128 v[208:211], v141 offset:56320
	global_load_lds_dwordx4 v[162:163], off
	v_lshl_add_u64 v[162:163], v[230:231], 0, s[66:67]
	s_mov_b32 m0, s81
	s_nop 0
	global_load_lds_dwordx4 v[162:163], off
	s_barrier
	s_waitcnt lgkmcnt(0)
	s_waitcnt lgkmcnt(0)
	v_mfma_f32_16x16x32_bf16 v[60:63], v[150:153], v[174:177], v[60:63]
	v_mfma_f32_16x16x32_bf16 v[56:59], v[158:161], v[174:177], v[56:59]
	v_mfma_f32_16x16x32_bf16 v[44:47], v[150:153], v[188:191], v[44:47]
	v_mfma_f32_16x16x32_bf16 v[40:43], v[158:161], v[188:191], v[40:43]
	v_mfma_f32_16x16x32_bf16 v[28:31], v[150:153], v[196:199], v[28:31]
	v_mfma_f32_16x16x32_bf16 v[24:27], v[158:161], v[196:199], v[24:27]
	v_mfma_f32_16x16x32_bf16 v[12:15], v[150:153], v[204:207], v[12:15]
	v_mfma_f32_16x16x32_bf16 v[8:11], v[158:161], v[204:207], v[8:11]
	v_mfma_f32_16x16x32_bf16 v[60:63], v[154:157], v[178:181], v[60:63]
	v_mfma_f32_16x16x32_bf16 v[56:59], v[170:173], v[178:181], v[56:59]
	v_mfma_f32_16x16x32_bf16 v[44:47], v[154:157], v[192:195], v[44:47]
	v_mfma_f32_16x16x32_bf16 v[40:43], v[170:173], v[192:195], v[40:43]
	v_mfma_f32_16x16x32_bf16 v[28:31], v[154:157], v[200:203], v[28:31]
	v_mfma_f32_16x16x32_bf16 v[24:27], v[170:173], v[200:203], v[24:27]
	v_mfma_f32_16x16x32_bf16 v[12:15], v[154:157], v[208:211], v[12:15]
	v_mfma_f32_16x16x32_bf16 v[8:11], v[170:173], v[208:211], v[8:11]
	s_barrier
	s_add_i32 s4, s40, s50
	v_lshl_add_u64 v[150:151], v[232:233], 0, s[66:67]
	s_mov_b32 m0, s4
	s_nop 0
	global_load_lds_dwordx4 v[150:151], off
	v_lshl_add_u64 v[150:151], v[234:235], 0, s[66:67]
	s_add_i32 m0, s4, 0x2000
	s_nop 0
	global_load_lds_dwordx4 v[150:151], off
	s_waitcnt vmcnt(6)
	s_barrier
	v_mfma_f32_16x16x32_bf16 v[52:55], v[212:215], v[174:177], v[52:55]
	v_mfma_f32_16x16x32_bf16 v[48:51], v[220:223], v[174:177], v[48:51]
	v_mfma_f32_16x16x32_bf16 v[36:39], v[212:215], v[188:191], v[36:39]
	v_mfma_f32_16x16x32_bf16 v[32:35], v[220:223], v[188:191], v[32:35]
	v_mfma_f32_16x16x32_bf16 v[20:23], v[212:215], v[196:199], v[20:23]
	v_mfma_f32_16x16x32_bf16 v[16:19], v[220:223], v[196:199], v[16:19]
	v_mfma_f32_16x16x32_bf16 v[4:7], v[212:215], v[204:207], v[4:7]
	v_mfma_f32_16x16x32_bf16 v[0:3], v[220:223], v[204:207], v[0:3]
	v_mfma_f32_16x16x32_bf16 v[52:55], v[216:219], v[178:181], v[52:55]
	v_mfma_f32_16x16x32_bf16 v[48:51], v[224:227], v[178:181], v[48:51]
	v_mfma_f32_16x16x32_bf16 v[36:39], v[216:219], v[192:195], v[36:39]
	v_mfma_f32_16x16x32_bf16 v[32:35], v[224:227], v[192:195], v[32:35]
	v_mfma_f32_16x16x32_bf16 v[20:23], v[216:219], v[200:203], v[20:23]
	v_mfma_f32_16x16x32_bf16 v[16:19], v[224:227], v[200:203], v[16:19]
	v_mfma_f32_16x16x32_bf16 v[4:7], v[216:219], v[208:211], v[4:7]
	v_mfma_f32_16x16x32_bf16 v[0:3], v[224:227], v[208:211], v[0:3]
	s_add_u32 s36, s36, 0x100
	s_addc_u32 s37, s37, 0
	s_add_u32 s44, s44, 0x100
	s_addc_u32 s45, s45, 0
	s_cmp_ge_i32 s5, s84
	s_mov_b32 s4, s5
	s_barrier
	s_cbranch_scc0 .LBB0_1379

; #define PG8_WAIT_V(n) asm volatile("s_waitcnt vmcnt(" #n ")" ::: "memory")
; #define PG8_BAR __builtin_amdgcn_s_barrier()
; template <class Epi>
; DI void gemm_phase(LAS unsigned char* lds, const Gemm g, const StaticOrder& S, const Epi& E) {
;     ...
;     PG8_WAIT_V(0);
;     if (wr == 0) PG8_BAR;
;     PG8_BAR;
.LBB0_1382:
	v_readlane_b32 s36, v237, 62
	v_readlane_b32 s44, v236, 6
	v_readlane_b32 s45, v236, 7
	v_readlane_b32 s48, v236, 10
	v_readlane_b32 s49, v236, 11
	v_readlane_b32 s44, v236, 25
	v_readlane_b32 s48, v236, 27
	v_readlane_b32 s58, v236, 29
	v_readlane_b32 s52, v237, 60
	v_readlane_b32 s45, v236, 26
	v_readlane_b32 s49, v236, 28
	s_mov_b32 s56, 0xc000
	s_mov_b32 s57, 0xbfff
	v_readlane_b32 s59, v236, 30
	s_barrier
	s_setprio 0
	v_readlane_b32 s53, v237, 61
	v_readlane_b32 s37, v237, 63
	v_readlane_b32 s38, v236, 0
	v_readlane_b32 s39, v236, 1
	v_readlane_b32 s40, v236, 2
	v_readlane_b32 s41, v236, 3
	v_readlane_b32 s42, v236, 4
	v_readlane_b32 s43, v236, 5
	v_readlane_b32 s46, v236, 8
	v_readlane_b32 s47, v236, 9
	v_readlane_b32 s50, v236, 12
	v_readlane_b32 s51, v236, 13

; #define PG8_STAGE(bufoff, gbase, voff) do { _Pragma("unroll") for (int _i = 0; _i < 2; ++_i) \
;         __builtin_amdgcn_global_load_lds((const unsigned*)((const char*)(gbase) + (voff)[_i]), (LAS unsigned*)(lds + (bufoff) + ldsw + _i * 8192), 16, 0, 0); } while (0)
; #define PG8_BAR __builtin_amdgcn_s_barrier()
; template <class Epi>
; DI void gemm_phase(LAS unsigned char* lds, const Gemm g, const StaticOrder& S, const Epi& E) {
;     ...
;     for (int i = 0; i < 2; ++i) { int R, C; stage_rc(tid * 16 + i * 8192, R, C); const int Rb = (R & ~31) + perm32(R & 31);
;         voffA[i] = (unsigned)(R * K + C) * 2u; voffB[i] = (unsigned)(Rb * K + C) * 2u; }
;     const size_t kstep = (size_t)(BK * 2);
;     const size_t hstep = (size_t)HALF * K * 2;
;     const size_t tstep = 2 * hstep;
;     const unsigned ldsw = (unsigned)wid * 1024u;
;     const int aoff = lds_byte(wr * 64 + fr, fq * 8), boff = lds_byte(wc * 32 + fr, fq * 8);
;     ...
;     Unit cur, nxt; int ui = 0;
;     if (!S.next(0, cur)) return;
;     f32x4 acc[2][2][4][2];
; #pragma unroll
;     for (int a = 0; a < 2; ++a)
; #pragma unroll
;         for (int b = 0; b < 2; ++b)
; #pragma unroll
;             for (int m = 0; m < 4; ++m)
; #pragma unroll
;                 for (int n = 0; n < 2; ++n) acc[a][b][m][n] = (f32x4){0.f, 0.f, 0.f, 0.f};
;     bf16x8 At[4][2], B0[2][2], B1[2][2];
;     const char* cA = (const char*)g.A + (size_t)cur.pm * tstep; const char* cB = (const char*)g.Bt + (size_t)cur.pn * tstep;
;     PG8_STAGE(PG8_SB(0, 0), cB, voffB); PG8_STAGE(PG8_SA(0, 0), cA, voffA); PG8_STAGE(PG8_SB(0, 1), cB + hstep, voffB); PG8_STAGE(PG8_SA(0, 1), cA + hstep, voffA);
;     if (wr == 1) PG8_BAR;
.LBB0_1437:
	s_andn2_b64 vcc, exec, s[10:11]
	s_cbranch_vccnz .LBB0_1470
	v_bfe_i32 v2, v18, 27, 1
	v_lshlrev_b32_e32 v0, 4, v18
	v_lshrrev_b32_e32 v2, 22, v2
	v_add_u32_e32 v2, v0, v2
	v_and_b32_e32 v2, 0xfffffc00, v2
	v_ashrrev_i32_e32 v1, 31, v18
	v_sub_u32_e32 v2, v0, v2
	v_lshrrev_b32_e32 v1, 26, v1
	v_lshrrev_b32_e32 v3, 4, v2
	v_add_u32_e32 v1, v18, v1
	v_bitop3_b32 v3, v3, v2, 32 bitop3:0x6c
	v_ashrrev_i32_e32 v2, 31, v2
	v_ashrrev_i32_e32 v1, 6, v1
	v_lshrrev_b32_e32 v2, 26, v2
	v_lshlrev_b32_e32 v4, 3, v1
	v_add_u32_e32 v2, v3, v2
	v_and_b32_e32 v4, -16, v4
	v_ashrrev_i32_e32 v2, 6, v2
	v_lshlrev_b32_e32 v1, 5, v1
	v_add_u32_e32 v4, v2, v4
	v_and_b32_e32 v12, 32, v1
	v_mul_i32_i24_e32 v1, 64, v2
	v_sub_u32_e32 v1, v3, v1
	v_lshlrev_b32_e32 v3, 1, v4
	v_lshrrev_b32_e32 v5, 2, v4
	v_and_b32_e32 v2, 3, v2
	s_mov_b32 s4, 0x7fffffe0
	v_ashrrev_i16_sdwa v1, v169, sext(v1) dst_sel:DWORD dst_unused:UNUSED_PAD src0_sel:DWORD src1_sel:BYTE_0
	v_and_b32_e32 v3, 24, v3
	v_and_b32_e32 v5, 4, v5
	v_and_or_b32 v2, v4, s4, v2
	v_bfe_i32 v13, v1, 0, 16
	v_or3_b32 v2, v2, v5, v3
	v_add_u32_e32 v1, v12, v13
	v_mul_lo_u32 v14, v4, s14
	v_mul_lo_u32 v2, v2, s14
	v_add_u32_e32 v0, 0x2000, v0
	v_add_lshl_u32 v128, v1, v14, 1
	v_add_lshl_u32 v166, v2, v1, 1
	v_ashrrev_i32_e32 v1, 31, v0
	v_lshrrev_b32_e32 v1, 22, v1
	v_add_u32_e32 v1, v0, v1
	v_ashrrev_i32_e32 v1, 10, v1
	v_mul_i32_i24_e32 v2, 0x400, v1
	v_sub_u32_e32 v0, v0, v2
	v_readlane_b32 s3, v236, 31
	v_lshrrev_b32_e32 v2, 4, v0
	s_add_u32 s49, s3, 0x1150000
	v_readlane_b32 s3, v236, 32
	v_bitop3_b32 v0, v2, v0, 32 bitop3:0x6c
	s_addc_u32 s50, s3, 0
	v_ashrrev_i32_e32 v3, 31, v0
	s_ashr_i32 s15, s14, 31
	v_lshrrev_b32_e32 v3, 26, v3
	s_lshl_b64 s[12:13], s[14:15], 9
	s_ashr_i32 s5, s79, 31
	v_lshlrev_b32_e32 v2, 3, v1
	v_add_u32_e32 v3, v0, v3
	s_mul_i32 s5, s12, s5
	s_mul_hi_u32 s16, s12, s79
	s_ashr_i32 s18, s78, 31
	v_and_b32_e32 v2, -16, v2
	v_ashrrev_i32_e32 v4, 6, v3
	s_add_i32 s5, s16, s5
	s_lshr_b64 s[16:17], s[14:15], 23
	s_mul_i32 s18, s12, s18
	s_mul_hi_u32 s19, s12, s78
	s_ashr_i32 s3, s47, 6
	v_add_u32_e32 v2, v4, v2
	v_lshlrev_b32_e32 v1, 5, v1
	v_and_b32_e32 v4, 3, v4
	s_mul_i32 s17, s16, s79
	s_add_i32 s18, s19, s18
	s_mul_i32 s16, s16, s78
	v_and_b32_e32 v15, 32, v1
	v_and_b32_e32 v1, 0xc0, v3
	v_and_or_b32 v4, v2, s4, v4
	s_ashr_i32 s4, s47, 8
	s_lshl_b64 s[10:11], s[14:15], 8
	s_lshl_b32 s51, s3, 10
	s_add_i32 s5, s5, s17
	s_add_i32 s18, s18, s16
	s_mul_i32 s16, s12, s78
	v_sub_u32_e32 v0, v0, v1
	v_lshlrev_b32_e32 v1, 1, v2
	v_lshrrev_b32_e32 v3, 2, v2
	s_add_u32 s44, s49, s16
	v_ashrrev_i16_sdwa v0, v169, sext(v0) dst_sel:DWORD dst_unused:UNUSED_PAD src0_sel:DWORD src1_sel:BYTE_0
	v_and_b32_e32 v1, 24, v1
	v_and_b32_e32 v3, 4, v3
	s_addc_u32 s45, s50, s18
	s_add_i32 s52, s51, 0x100
	v_bfe_i32 v16, v0, 0, 16
	v_or3_b32 v1, v4, v3, v1
	s_add_i32 m0, s52, 0x10000
	v_add_u32_e32 v0, v15, v16
	v_mul_lo_u32 v1, v1, s14
	s_mul_i32 s17, s12, s79
	global_load_lds_dwordx4 v166, s[44:45]
	s_add_i32 m0, s52, 0x12000
	v_readlane_b32 s18, v237, 44
	v_add_lshl_u32 v132, v1, v0, 1
	v_readlane_b32 s19, v237, 45
	s_add_u32 s36, s18, s17
	v_mul_lo_u32 v17, v2, s14
	global_load_lds_dwordx4 v132, s[44:45]
	s_addc_u32 s37, s19, s5
	s_mov_b32 m0, s52
	s_add_i32 s53, s52, 0x2000
	v_add_lshl_u32 v130, v0, v17, 1
	global_load_lds_dwordx4 v128, s[36:37]
	s_mov_b32 m0, s53
	s_add_u32 s16, s44, s10
	global_load_lds_dwordx4 v130, s[36:37]
	s_addc_u32 s17, s45, s11
	s_add_i32 m0, s52, 0x14000
	v_mov_b32_e32 v133, v167
	global_load_lds_dwordx4 v166, s[16:17]
	s_add_i32 m0, s52, 0x16000
	v_lshl_add_u64 v[8:9], s[16:17], 0, v[166:167]
	v_lshl_add_u64 v[10:11], s[16:17], 0, v[132:133]
	global_load_lds_dwordx4 v132, s[16:17]
	s_add_u32 s16, s36, s10
	s_addc_u32 s17, s37, s11
	s_add_i32 s54, s52, 0x4000
	s_mov_b32 m0, s54
	s_add_i32 s55, s52, 0x6000
	global_load_lds_dwordx4 v128, s[16:17]
	s_mov_b32 m0, s55
	v_mov_b32_e32 v129, v167
	global_load_lds_dwordx4 v130, s[16:17]
	v_mov_b32_e32 v131, v167
	v_lshl_add_u64 v[0:1], s[44:45], 0, v[166:167]
	v_lshl_add_u64 v[2:3], s[44:45], 0, v[132:133]
	v_lshl_add_u64 v[4:5], s[36:37], 0, v[128:129]
	v_lshl_add_u64 v[6:7], s[36:37], 0, v[130:131]
	s_cmp_lg_u32 s4, 1
	s_cbranch_scc1 .LBB0_1440
	s_setprio 1
	s_barrier

; #define PG8_STAGE(bufoff, gbase, voff) do { _Pragma("unroll") for (int _i = 0; _i < 2; ++_i) \
;         __builtin_amdgcn_global_load_lds((const unsigned*)((const char*)(gbase) + (voff)[_i]), (LAS unsigned*)(lds + (bufoff) + ldsw + _i * 8192), 16, 0, 0); } while (0)
; #define PG8_LDA(dst, b, h) do { _Pragma("unroll") for (int m = 0; m < 4; ++m) _Pragma("unroll") for (int k = 0; k < 2; ++k) dst[m][k] = *(const LAS bf16x8*)(lds + PG8_SA(b, h) + aoff + m * 2048 + k * 1024); } while (0)
; #define PG8_LDB(dst, b, h) do { _Pragma("unroll") for (int n = 0; n < 2; ++n) _Pragma("unroll") for (int k = 0; k < 2; ++k) dst[n][k] = *(const LAS bf16x8*)(lds + PG8_SB(b, h) + boff + n * 2048 + k * 1024); } while (0)
; #define PG8_MMA(ai, bj, At, Bt) do { __builtin_amdgcn_s_setprio(1); _Pragma("unroll") for (int m = 0; m < 4; ++m) _Pragma("unroll") for (int n = 0; n < 2; ++n) _Pragma("unroll") for (int k = 0; k < 2; ++k) \
;         acc[ai][bj][m][n] = __builtin_amdgcn_mfma_f32_16x16x32_bf16(Bt[n][k], At[m][k], acc[ai][bj][m][n], 0, 0, 0); __builtin_amdgcn_s_setprio(0); } while (0)
; #define PG8_WAIT_V(n) asm volatile("s_waitcnt vmcnt(" #n ")" ::: "memory")
; #define PG8_WAIT_L(n) asm volatile("s_waitcnt lgkmcnt(" #n ")" ::: "memory")
; #define PG8_BAR __builtin_amdgcn_s_barrier()
; template <class Epi>
; DI void gemm_phase(LAS unsigned char* lds, const Gemm g, const StaticOrder& S, const Epi& E) {
;     ...
;         for (int t = 0; t < nt; t += 2) {
;             const bool last = (t == nt - 2);
;             const char* a1 = cA + (size_t)(t + 1) * kstep;
;             const char* a2 = last ? nA : cA + (size_t)(t + 2) * kstep; const char* b2 = last ? nB : cB + (size_t)(t + 2) * kstep;
;             const char* a3 = a2 + kstep; const char* b3 = b2 + kstep;
;             PG8_LDB(B0, 0, 0); PG8_SCHED; PG8_LDA(At, 0, 0); PG8_STAGE(PG8_SA(1, 1), a1 + hstep, voffA);
;             PG8_WAIT_L(8); PG8_BAR; PG8_WAIT_L(0); PG8_MMA(0, 0, At, B0); PG8_BAR; PG8_SCHED;
;             PG8_LDB(B1, 0, 1); PG8_STAGE(PG8_SB(0, 0), b2, voffB);
;             PG8_BAR; PG8_WAIT_L(0); PG8_MMA(0, 1, At, B1); PG8_BAR;
;             PG8_LDA(At, 0, 1); PG8_STAGE(PG8_SA(0, 0), a2, voffA);
;             PG8_BAR; PG8_WAIT_L(0); PG8_MMA(1, 0, At, B0); PG8_BAR; PG8_SCHED;
;             PG8_STAGE(PG8_SB(0, 1), b2 + hstep, voffB);
;             PG8_WAIT_V(6); PG8_BAR; PG8_MMA(1, 1, At, B1); PG8_BAR;
.LBB0_1448:
	s_andn2_b64 vcc, exec, s[14:15]
	s_waitcnt lgkmcnt(0)
	s_cbranch_vccnz .LBB0_1451
	s_add_u32 s36, s36, 0x80
	s_addc_u32 s37, s37, 0
	s_add_u32 s0, s44, 0x100
	s_addc_u32 s44, s45, 0
	s_mov_b32 s4, 0
	s_mov_b32 s72, 0x10000
	s_mov_b32 s73, 0x14000
	s_mov_b32 s74, 0x18000
	s_mov_b32 s75, 0x1c000
	s_mov_b64 s[76:77], 0x80
	s_add_i32 s5, s4, 2
	s_add_u32 s40, s36, 0x80
	s_addc_u32 s41, s37, 0
	s_add_i32 s45, s72, 0x100
	v_add_u32_e32 v153, s45, v151
	ds_read_b128 v[138:141], v153
	ds_read_b128 v[154:157], v153 offset:1024
	ds_read_b128 v[158:161], v153 offset:2048
	ds_read_b128 v[170:173], v153 offset:3072
	s_cmp_eq_u32 s62, s4
	s_cselect_b32 s41, s17, s41
	s_cselect_b32 s40, s16, s40
	s_cselect_b32 s43, s19, s44
	s_cselect_b32 s42, s18, s0
	v_lshl_add_u64 v[162:163], s[36:37], 0, v[134:135]
	s_add_i32 m0, s52, 0xc000
	ds_read_b128 v[174:177], v152
	ds_read_b128 v[178:181], v152 offset:1024
	ds_read_b128 v[188:191], v152 offset:2048
	ds_read_b128 v[192:195], v152 offset:3072
	ds_read_b128 v[196:199], v152 offset:4096
	ds_read_b128 v[200:203], v152 offset:5120
	ds_read_b128 v[204:207], v152 offset:6144
	ds_read_b128 v[208:211], v152 offset:7168
	global_load_lds_dwordx4 v[162:163], off
	v_lshl_add_u64 v[162:163], s[36:37], 0, v[136:137]
	s_add_i32 m0, s52, 0xe000
	s_nop 0
	global_load_lds_dwordx4 v[162:163], off
	s_waitcnt lgkmcnt(8)
	s_barrier
	s_waitcnt lgkmcnt(0)
	s_waitcnt lgkmcnt(0)
	v_mfma_f32_16x16x32_bf16 v[124:127], v[138:141], v[174:177], 0
	v_mfma_f32_16x16x32_bf16 v[120:123], v[158:161], v[174:177], 0
	v_mfma_f32_16x16x32_bf16 v[108:111], v[138:141], v[188:191], 0
	v_mfma_f32_16x16x32_bf16 v[104:107], v[158:161], v[188:191], 0
	v_mfma_f32_16x16x32_bf16 v[92:95], v[138:141], v[196:199], 0
	v_mfma_f32_16x16x32_bf16 v[88:91], v[158:161], v[196:199], 0
	v_mfma_f32_16x16x32_bf16 v[76:79], v[138:141], v[204:207], 0
	v_mfma_f32_16x16x32_bf16 v[72:75], v[158:161], v[204:207], 0
	v_mfma_f32_16x16x32_bf16 v[124:127], v[154:157], v[178:181], v[124:127]
	v_mfma_f32_16x16x32_bf16 v[120:123], v[170:173], v[178:181], v[120:123]
	v_mfma_f32_16x16x32_bf16 v[108:111], v[154:157], v[192:195], v[108:111]
	v_mfma_f32_16x16x32_bf16 v[104:107], v[170:173], v[192:195], v[104:107]
	v_mfma_f32_16x16x32_bf16 v[92:95], v[154:157], v[200:203], v[92:95]
	v_mfma_f32_16x16x32_bf16 v[88:91], v[170:173], v[200:203], v[88:91]
	v_mfma_f32_16x16x32_bf16 v[76:79], v[154:157], v[208:211], v[76:79]
	v_mfma_f32_16x16x32_bf16 v[72:75], v[170:173], v[208:211], v[72:75]
	s_barrier
	s_add_i32 s4, s73, 0x100
	s_add_i32 s45, s45, s51
	v_add_u32_e32 v153, s4, v151
	v_lshl_add_u64 v[162:163], s[42:43], 0, v[166:167]
	s_mov_b32 m0, s45
	ds_read_b128 v[212:215], v153
	ds_read_b128 v[216:219], v153 offset:1024
	ds_read_b128 v[220:223], v153 offset:2048
	ds_read_b128 v[224:227], v153 offset:3072
	global_load_lds_dwordx4 v[162:163], off
	v_lshl_add_u64 v[182:183], s[42:43], 0, v[132:133]
	s_add_i32 m0, s45, 0x2000
	s_nop 0
	global_load_lds_dwordx4 v[182:183], off
	s_barrier
	s_waitcnt lgkmcnt(0)
	s_waitcnt lgkmcnt(0)
	v_mfma_f32_16x16x32_bf16 v[116:119], v[212:215], v[174:177], 0
	v_mfma_f32_16x16x32_bf16 v[112:115], v[220:223], v[174:177], 0
	v_mfma_f32_16x16x32_bf16 v[100:103], v[212:215], v[188:191], 0
	v_mfma_f32_16x16x32_bf16 v[96:99], v[220:223], v[188:191], 0
	v_mfma_f32_16x16x32_bf16 v[84:87], v[212:215], v[196:199], 0
	v_mfma_f32_16x16x32_bf16 v[80:83], v[220:223], v[196:199], 0
	v_mfma_f32_16x16x32_bf16 v[68:71], v[212:215], v[204:207], 0
	v_mfma_f32_16x16x32_bf16 v[64:67], v[220:223], v[204:207], 0
	v_mfma_f32_16x16x32_bf16 v[116:119], v[216:219], v[178:181], v[116:119]
	v_mfma_f32_16x16x32_bf16 v[112:115], v[224:227], v[178:181], v[112:115]
	v_mfma_f32_16x16x32_bf16 v[100:103], v[216:219], v[192:195], v[100:103]
	v_mfma_f32_16x16x32_bf16 v[96:99], v[224:227], v[192:195], v[96:99]
	v_mfma_f32_16x16x32_bf16 v[84:87], v[216:219], v[200:203], v[84:87]
	v_mfma_f32_16x16x32_bf16 v[80:83], v[224:227], v[200:203], v[80:83]
	v_mfma_f32_16x16x32_bf16 v[68:71], v[216:219], v[208:211], v[68:71]
	v_mfma_f32_16x16x32_bf16 v[64:67], v[224:227], v[208:211], v[64:67]
	s_mov_b32 m0, s52
	v_lshl_add_u64 v[228:229], s[40:41], 0, v[128:129]
	s_barrier
	ds_read_b128 v[174:177], v152 offset:16384
	ds_read_b128 v[178:181], v152 offset:17408
	ds_read_b128 v[188:191], v152 offset:18432
	ds_read_b128 v[192:195], v152 offset:19456
	ds_read_b128 v[196:199], v152 offset:20480
	ds_read_b128 v[200:203], v152 offset:21504
	ds_read_b128 v[204:207], v152 offset:22528
	ds_read_b128 v[208:211], v152 offset:23552
	global_load_lds_dwordx4 v[228:229], off
	v_lshl_add_u64 v[230:231], s[40:41], 0, v[130:131]
	s_mov_b32 m0, s53
	s_nop 0
	global_load_lds_dwordx4 v[230:231], off
	s_barrier
	s_waitcnt lgkmcnt(0)
	s_waitcnt lgkmcnt(0)
	v_mfma_f32_16x16x32_bf16 v[60:63], v[138:141], v[174:177], 0
	v_mfma_f32_16x16x32_bf16 v[56:59], v[158:161], v[174:177], 0
	v_mfma_f32_16x16x32_bf16 v[44:47], v[138:141], v[188:191], 0
	v_mfma_f32_16x16x32_bf16 v[40:43], v[158:161], v[188:191], 0
	v_mfma_f32_16x16x32_bf16 v[28:31], v[138:141], v[196:199], 0
	v_mfma_f32_16x16x32_bf16 v[24:27], v[158:161], v[196:199], 0
	v_mfma_f32_16x16x32_bf16 v[12:15], v[138:141], v[204:207], 0
	v_mfma_f32_16x16x32_bf16 v[8:11], v[158:161], v[204:207], 0
	v_mfma_f32_16x16x32_bf16 v[60:63], v[154:157], v[178:181], v[60:63]
	v_mfma_f32_16x16x32_bf16 v[56:59], v[170:173], v[178:181], v[56:59]
	v_mfma_f32_16x16x32_bf16 v[44:47], v[154:157], v[192:195], v[44:47]
	v_mfma_f32_16x16x32_bf16 v[40:43], v[170:173], v[192:195], v[40:43]
	v_mfma_f32_16x16x32_bf16 v[28:31], v[154:157], v[200:203], v[28:31]
	v_mfma_f32_16x16x32_bf16 v[24:27], v[170:173], v[200:203], v[24:27]
	v_mfma_f32_16x16x32_bf16 v[12:15], v[154:157], v[208:211], v[12:15]
	v_mfma_f32_16x16x32_bf16 v[8:11], v[170:173], v[208:211], v[8:11]
	s_barrier
; #define PG8_STAGE(bufoff, gbase, voff) do { _Pragma("unroll") for (int _i = 0; _i < 2; ++_i) \
;         __builtin_amdgcn_global_load_lds((const unsigned*)((const char*)(gbase) + (voff)[_i]), (LAS unsigned*)(lds + (bufoff) + ldsw + _i * 8192), 16, 0, 0); } while (0)
; #define PG8_LDA(dst, b, h) do { _Pragma("unroll") for (int m = 0; m < 4; ++m) _Pragma("unroll") for (int k = 0; k < 2; ++k) dst[m][k] = *(const LAS bf16x8*)(lds + PG8_SA(b, h) + aoff + m * 2048 + k * 1024); } while (0)
; #define PG8_LDB(dst, b, h) do { _Pragma("unroll") for (int n = 0; n < 2; ++n) _Pragma("unroll") for (int k = 0; k < 2; ++k) dst[n][k] = *(const LAS bf16x8*)(lds + PG8_SB(b, h) + boff + n * 2048 + k * 1024); } while (0)
; #define PG8_MMA(ai, bj, At, Bt) do { __builtin_amdgcn_s_setprio(1); _Pragma("unroll") for (int m = 0; m < 4; ++m) _Pragma("unroll") for (int n = 0; n < 2; ++n) _Pragma("unroll") for (int k = 0; k < 2; ++k) \
;         acc[ai][bj][m][n] = __builtin_amdgcn_mfma_f32_16x16x32_bf16(Bt[n][k], At[m][k], acc[ai][bj][m][n], 0, 0, 0); __builtin_amdgcn_s_setprio(0); } while (0)
; #define PG8_WAIT_V(n) asm volatile("s_waitcnt vmcnt(" #n ")" ::: "memory")
; #define PG8_WAIT_L(n) asm volatile("s_waitcnt lgkmcnt(" #n ")" ::: "memory")
; #define PG8_BAR __builtin_amdgcn_s_barrier()
; #define PG8_SCHED __builtin_amdgcn_sched_barrier(0)
; template <class Epi>
; DI void gemm_phase(LAS unsigned char* lds, const Gemm g, const StaticOrder& S, const Epi& E) {
;     ...
;             PG8_WAIT_V(6); PG8_BAR; PG8_MMA(1, 1, At, B1); PG8_BAR;
;             PG8_LDB(B0, 1, 0); PG8_SCHED; PG8_LDA(At, 1, 0); PG8_STAGE(PG8_SA(0, 1), a2 + hstep, voffA);
;             PG8_WAIT_L(8); PG8_BAR; PG8_WAIT_L(0); PG8_MMA(0, 0, At, B0); PG8_BAR; PG8_SCHED;
;             PG8_LDB(B1, 1, 1); PG8_STAGE(PG8_SB(1, 0), b3, voffB);
;             PG8_BAR; PG8_WAIT_L(0); PG8_MMA(0, 1, At, B1); PG8_BAR;
;             PG8_LDA(At, 1, 1); PG8_STAGE(PG8_SA(1, 0), a3, voffA);
;             PG8_BAR; PG8_WAIT_L(0); PG8_MMA(1, 0, At, B0); PG8_BAR; PG8_SCHED;
	s_add_u32 s42, s42, s10
	s_addc_u32 s43, s43, s11
	s_add_i32 s4, s4, s51
	v_lshl_add_u64 v[232:233], s[42:43], 0, v[166:167]
	s_mov_b32 m0, s4
	v_lshl_add_u64 v[234:235], s[42:43], 0, v[132:133]
	global_load_lds_dwordx4 v[232:233], off
	s_add_i32 m0, s4, 0x2000
	s_nop 0
	global_load_lds_dwordx4 v[234:235], off
	s_waitcnt vmcnt(6)
	s_barrier
	v_mfma_f32_16x16x32_bf16 v[52:55], v[212:215], v[174:177], 0
	v_mfma_f32_16x16x32_bf16 v[48:51], v[220:223], v[174:177], 0
	v_mfma_f32_16x16x32_bf16 v[36:39], v[212:215], v[188:191], 0
	v_mfma_f32_16x16x32_bf16 v[32:35], v[220:223], v[188:191], 0
	v_mfma_f32_16x16x32_bf16 v[20:23], v[212:215], v[196:199], 0
	v_mfma_f32_16x16x32_bf16 v[16:19], v[220:223], v[196:199], 0
	v_mfma_f32_16x16x32_bf16 v[4:7], v[212:215], v[204:207], 0
	v_mfma_f32_16x16x32_bf16 v[0:3], v[220:223], v[204:207], 0
	v_mfma_f32_16x16x32_bf16 v[52:55], v[216:219], v[178:181], v[52:55]
	v_mfma_f32_16x16x32_bf16 v[48:51], v[224:227], v[178:181], v[48:51]
	v_mfma_f32_16x16x32_bf16 v[36:39], v[216:219], v[192:195], v[36:39]
	v_mfma_f32_16x16x32_bf16 v[32:35], v[224:227], v[192:195], v[32:35]
	v_mfma_f32_16x16x32_bf16 v[20:23], v[216:219], v[200:203], v[20:23]
	v_mfma_f32_16x16x32_bf16 v[16:19], v[224:227], v[200:203], v[16:19]
	v_mfma_f32_16x16x32_bf16 v[4:7], v[216:219], v[208:211], v[4:7]
	v_mfma_f32_16x16x32_bf16 v[0:3], v[224:227], v[208:211], v[0:3]
	s_add_i32 s4, s74, 0x100
	v_add_u32_e32 v153, s4, v151
	s_barrier
	ds_read_b128 v[138:141], v153
	ds_read_b128 v[154:157], v153 offset:1024
	ds_read_b128 v[158:161], v153 offset:2048
	ds_read_b128 v[170:173], v153 offset:3072
	s_add_u32 s40, s40, s10
	s_addc_u32 s41, s41, s11
	s_mov_b32 m0, s54
	v_lshl_add_u64 v[212:213], s[40:41], 0, v[128:129]
	ds_read_b128 v[174:177], v152 offset:32768
	ds_read_b128 v[178:181], v152 offset:33792
	ds_read_b128 v[188:191], v152 offset:34816
	ds_read_b128 v[192:195], v152 offset:35840
	ds_read_b128 v[196:199], v152 offset:36864
	ds_read_b128 v[200:203], v152 offset:37888
	ds_read_b128 v[204:207], v152 offset:38912
	ds_read_b128 v[208:211], v152 offset:39936
	global_load_lds_dwordx4 v[212:213], off
	v_lshl_add_u64 v[212:213], s[40:41], 0, v[130:131]
	s_mov_b32 m0, s55
	s_nop 0
	global_load_lds_dwordx4 v[212:213], off
	s_waitcnt lgkmcnt(8)
	s_barrier
	s_waitcnt lgkmcnt(0)
	s_waitcnt lgkmcnt(0)
	v_mfma_f32_16x16x32_bf16 v[124:127], v[138:141], v[174:177], v[124:127]
	v_mfma_f32_16x16x32_bf16 v[120:123], v[158:161], v[174:177], v[120:123]
	v_mfma_f32_16x16x32_bf16 v[108:111], v[138:141], v[188:191], v[108:111]
	v_mfma_f32_16x16x32_bf16 v[104:107], v[158:161], v[188:191], v[104:107]
	v_mfma_f32_16x16x32_bf16 v[92:95], v[138:141], v[196:199], v[92:95]
	v_mfma_f32_16x16x32_bf16 v[88:91], v[158:161], v[196:199], v[88:91]
	v_mfma_f32_16x16x32_bf16 v[76:79], v[138:141], v[204:207], v[76:79]
	v_mfma_f32_16x16x32_bf16 v[72:75], v[158:161], v[204:207], v[72:75]
	v_mfma_f32_16x16x32_bf16 v[124:127], v[154:157], v[178:181], v[124:127]
	v_mfma_f32_16x16x32_bf16 v[120:123], v[170:173], v[178:181], v[120:123]
	v_mfma_f32_16x16x32_bf16 v[108:111], v[154:157], v[192:195], v[108:111]
	v_mfma_f32_16x16x32_bf16 v[104:107], v[170:173], v[192:195], v[104:107]
	v_mfma_f32_16x16x32_bf16 v[92:95], v[154:157], v[200:203], v[92:95]
	v_mfma_f32_16x16x32_bf16 v[88:91], v[170:173], v[200:203], v[88:91]
	v_mfma_f32_16x16x32_bf16 v[76:79], v[154:157], v[208:211], v[76:79]
	v_mfma_f32_16x16x32_bf16 v[72:75], v[170:173], v[208:211], v[72:75]
	s_barrier
	s_add_i32 s40, s75, 0x100
	s_add_i32 s4, s4, s51
	v_add_u32_e32 v153, s40, v151
	v_lshl_add_u64 v[162:163], v[162:163], 0, s[76:77]
	s_mov_b32 m0, s4
	ds_read_b128 v[212:215], v153
	ds_read_b128 v[216:219], v153 offset:1024
	ds_read_b128 v[220:223], v153 offset:2048
	ds_read_b128 v[224:227], v153 offset:3072
	global_load_lds_dwordx4 v[162:163], off
	v_lshl_add_u64 v[162:163], v[182:183], 0, s[76:77]
	s_add_i32 m0, s4, 0x2000
	s_nop 0
	global_load_lds_dwordx4 v[162:163], off
	s_barrier
	s_waitcnt lgkmcnt(0)
	s_waitcnt lgkmcnt(0)
	v_mfma_f32_16x16x32_bf16 v[116:119], v[212:215], v[174:177], v[116:119]
	v_mfma_f32_16x16x32_bf16 v[112:115], v[220:223], v[174:177], v[112:115]
	v_mfma_f32_16x16x32_bf16 v[100:103], v[212:215], v[188:191], v[100:103]
	v_mfma_f32_16x16x32_bf16 v[96:99], v[220:223], v[188:191], v[96:99]
	v_mfma_f32_16x16x32_bf16 v[84:87], v[212:215], v[196:199], v[84:87]
	v_mfma_f32_16x16x32_bf16 v[80:83], v[220:223], v[196:199], v[80:83]
	v_mfma_f32_16x16x32_bf16 v[68:71], v[212:215], v[204:207], v[68:71]
	v_mfma_f32_16x16x32_bf16 v[64:67], v[220:223], v[204:207], v[64:67]
	v_mfma_f32_16x16x32_bf16 v[116:119], v[216:219], v[178:181], v[116:119]
	v_mfma_f32_16x16x32_bf16 v[112:115], v[224:227], v[178:181], v[112:115]
	v_mfma_f32_16x16x32_bf16 v[100:103], v[216:219], v[192:195], v[100:103]
	v_mfma_f32_16x16x32_bf16 v[96:99], v[224:227], v[192:195], v[96:99]
	v_mfma_f32_16x16x32_bf16 v[84:87], v[216:219], v[200:203], v[84:87]
	v_mfma_f32_16x16x32_bf16 v[80:83], v[224:227], v[200:203], v[80:83]
	v_mfma_f32_16x16x32_bf16 v[68:71], v[216:219], v[208:211], v[68:71]
	v_mfma_f32_16x16x32_bf16 v[64:67], v[224:227], v[208:211], v[64:67]
	s_mov_b32 m0, s60
	v_lshl_add_u64 v[162:163], v[228:229], 0, s[76:77]
	s_barrier
	ds_read_b128 v[174:177], v152 offset:49152
	ds_read_b128 v[178:181], v152 offset:50176
	ds_read_b128 v[188:191], v152 offset:51200
	ds_read_b128 v[192:195], v152 offset:52224
	ds_read_b128 v[196:199], v152 offset:53248
	ds_read_b128 v[200:203], v152 offset:54272
	ds_read_b128 v[204:207], v152 offset:55296
	ds_read_b128 v[208:211], v152 offset:56320
	global_load_lds_dwordx4 v[162:163], off
	v_lshl_add_u64 v[162:163], v[230:231], 0, s[76:77]
	s_mov_b32 m0, s61
	s_nop 0
	global_load_lds_dwordx4 v[162:163], off
	s_barrier
; #define PG8_STAGE(bufoff, gbase, voff) do { _Pragma("unroll") for (int _i = 0; _i < 2; ++_i) \
;         __builtin_amdgcn_global_load_lds((const unsigned*)((const char*)(gbase) + (voff)[_i]), (LAS unsigned*)(lds + (bufoff) + ldsw + _i * 8192), 16, 0, 0); } while (0)
; #define PG8_LDA(dst, b, h) do { _Pragma("unroll") for (int m = 0; m < 4; ++m) _Pragma("unroll") for (int k = 0; k < 2; ++k) dst[m][k] = *(const LAS bf16x8*)(lds + PG8_SA(b, h) + aoff + m * 2048 + k * 1024); } while (0)
; #define PG8_LDB(dst, b, h) do { _Pragma("unroll") for (int n = 0; n < 2; ++n) _Pragma("unroll") for (int k = 0; k < 2; ++k) dst[n][k] = *(const LAS bf16x8*)(lds + PG8_SB(b, h) + boff + n * 2048 + k * 1024); } while (0)
; #define PG8_WAIT_V(n) asm volatile("s_waitcnt vmcnt(" #n ")" ::: "memory")
; #define PG8_WAIT_L(n) asm volatile("s_waitcnt lgkmcnt(" #n ")" ::: "memory")
; #define PG8_BAR __builtin_amdgcn_s_barrier()
; #define PG8_SCHED __builtin_amdgcn_sched_barrier(0)
; template <class Epi>
; DI void gemm_phase(LAS unsigned char* lds, const Gemm g, const StaticOrder& S, const Epi& E) {
;     ...
;             PG8_LDB(B0, 0, 0); PG8_SCHED; PG8_LDA(At, 0, 0); PG8_STAGE(PG8_SA(1, 1), a1 + hstep, voffA);
;             PG8_WAIT_L(8); PG8_BAR; PG8_WAIT_L(0); PG8_MMA(0, 0, At, B0); PG8_BAR; PG8_SCHED;
;             PG8_LDB(B1, 0, 1); PG8_STAGE(PG8_SB(0, 0), b2, voffB);
;             PG8_BAR; PG8_WAIT_L(0); PG8_MMA(0, 1, At, B1); PG8_BAR;
;             PG8_LDA(At, 0, 1); PG8_STAGE(PG8_SA(0, 0), a2, voffA);
;             PG8_BAR; PG8_WAIT_L(0); PG8_MMA(1, 0, At, B0); PG8_BAR; PG8_SCHED;
;             PG8_STAGE(PG8_SB(0, 1), b2 + hstep, voffB);
;             PG8_WAIT_V(6); PG8_BAR; PG8_MMA(1, 1, At, B1); PG8_BAR;
;             PG8_LDB(B0, 1, 0); PG8_SCHED; PG8_LDA(At, 1, 0); PG8_STAGE(PG8_SA(0, 1), a2 + hstep, voffA);
;             PG8_WAIT_L(8); PG8_BAR; PG8_WAIT_L(0); PG8_MMA(0, 0, At, B0); PG8_BAR; PG8_SCHED;
;             PG8_LDB(B1, 1, 1); PG8_STAGE(PG8_SB(1, 0), b3, voffB);
;             PG8_BAR; PG8_WAIT_L(0); PG8_MMA(0, 1, At, B1); PG8_BAR;
;             PG8_LDA(At, 1, 1); PG8_STAGE(PG8_SA(1, 0), a3, voffA);
;             PG8_BAR; PG8_WAIT_L(0); PG8_MMA(1, 0, At, B0); PG8_BAR; PG8_SCHED;
;             PG8_STAGE(PG8_SB(1, 1), b3 + hstep, voffB);
;             PG8_WAIT_V(6); PG8_BAR; PG8_MMA(1, 1, At, B1); PG8_BAR;
	s_waitcnt lgkmcnt(0)
	s_waitcnt lgkmcnt(0)
	v_mfma_f32_16x16x32_bf16 v[60:63], v[138:141], v[174:177], v[60:63]
	v_mfma_f32_16x16x32_bf16 v[56:59], v[158:161], v[174:177], v[56:59]
	v_mfma_f32_16x16x32_bf16 v[44:47], v[138:141], v[188:191], v[44:47]
	v_mfma_f32_16x16x32_bf16 v[40:43], v[158:161], v[188:191], v[40:43]
	v_mfma_f32_16x16x32_bf16 v[28:31], v[138:141], v[196:199], v[28:31]
	v_mfma_f32_16x16x32_bf16 v[24:27], v[158:161], v[196:199], v[24:27]
	v_mfma_f32_16x16x32_bf16 v[12:15], v[138:141], v[204:207], v[12:15]
	v_mfma_f32_16x16x32_bf16 v[8:11], v[158:161], v[204:207], v[8:11]
	v_mfma_f32_16x16x32_bf16 v[60:63], v[154:157], v[178:181], v[60:63]
	v_mfma_f32_16x16x32_bf16 v[56:59], v[170:173], v[178:181], v[56:59]
	v_mfma_f32_16x16x32_bf16 v[44:47], v[154:157], v[192:195], v[44:47]
	v_mfma_f32_16x16x32_bf16 v[40:43], v[170:173], v[192:195], v[40:43]
	v_mfma_f32_16x16x32_bf16 v[28:31], v[154:157], v[200:203], v[28:31]
	v_mfma_f32_16x16x32_bf16 v[24:27], v[170:173], v[200:203], v[24:27]
	v_mfma_f32_16x16x32_bf16 v[12:15], v[154:157], v[208:211], v[12:15]
	v_mfma_f32_16x16x32_bf16 v[8:11], v[170:173], v[208:211], v[8:11]
	s_barrier
	s_add_i32 s4, s40, s51
	v_lshl_add_u64 v[138:139], v[232:233], 0, s[76:77]
	s_mov_b32 m0, s4
	s_nop 0
	global_load_lds_dwordx4 v[138:139], off
	v_lshl_add_u64 v[138:139], v[234:235], 0, s[76:77]
	s_add_i32 m0, s4, 0x2000
	s_nop 0
	global_load_lds_dwordx4 v[138:139], off
	s_waitcnt vmcnt(6)
	s_barrier
	v_mfma_f32_16x16x32_bf16 v[52:55], v[212:215], v[174:177], v[52:55]
	v_mfma_f32_16x16x32_bf16 v[48:51], v[220:223], v[174:177], v[48:51]
	v_mfma_f32_16x16x32_bf16 v[36:39], v[212:215], v[188:191], v[36:39]
	v_mfma_f32_16x16x32_bf16 v[32:35], v[220:223], v[188:191], v[32:35]
	v_mfma_f32_16x16x32_bf16 v[20:23], v[212:215], v[196:199], v[20:23]
	v_mfma_f32_16x16x32_bf16 v[16:19], v[220:223], v[196:199], v[16:19]
	v_mfma_f32_16x16x32_bf16 v[4:7], v[212:215], v[204:207], v[4:7]
	v_mfma_f32_16x16x32_bf16 v[0:3], v[220:223], v[204:207], v[0:3]
	v_mfma_f32_16x16x32_bf16 v[52:55], v[216:219], v[178:181], v[52:55]
	v_mfma_f32_16x16x32_bf16 v[48:51], v[224:227], v[178:181], v[48:51]
	v_mfma_f32_16x16x32_bf16 v[36:39], v[216:219], v[192:195], v[36:39]
	v_mfma_f32_16x16x32_bf16 v[32:35], v[224:227], v[192:195], v[32:35]
	v_mfma_f32_16x16x32_bf16 v[20:23], v[216:219], v[200:203], v[20:23]
	v_mfma_f32_16x16x32_bf16 v[16:19], v[224:227], v[200:203], v[16:19]
	v_mfma_f32_16x16x32_bf16 v[4:7], v[216:219], v[208:211], v[4:7]
	v_mfma_f32_16x16x32_bf16 v[0:3], v[224:227], v[208:211], v[0:3]
	s_add_u32 s36, s36, 0x100
	s_addc_u32 s37, s37, 0
	s_add_u32 s0, s0, 0x100
	s_addc_u32 s44, s44, 0
	s_cmp_ge_i32 s5, s57
	s_mov_b32 s4, s5
	s_barrier
	s_cbranch_scc0 .LBB0_1450
	s_branch .Lpeel_exit_4
.LBB0_1450:
	s_add_i32 s5, s4, 2
	s_add_u32 s40, s36, 0x80
	s_addc_u32 s41, s37, 0
	s_add_i32 s45, s72, 0x100
	v_add_u32_e32 v153, s45, v151
	ds_read_b128 v[138:141], v153
	ds_read_b128 v[154:157], v153 offset:1024
	ds_read_b128 v[158:161], v153 offset:2048
	ds_read_b128 v[170:173], v153 offset:3072
	s_cmp_eq_u32 s62, s4
	s_cselect_b32 s41, s17, s41
	s_cselect_b32 s40, s16, s40
	s_cselect_b32 s43, s19, s44
	s_cselect_b32 s42, s18, s0
	v_lshl_add_u64 v[162:163], s[36:37], 0, v[134:135]
	s_add_i32 m0, s52, 0xc000
	ds_read_b128 v[174:177], v152
	ds_read_b128 v[178:181], v152 offset:1024
	ds_read_b128 v[188:191], v152 offset:2048
	ds_read_b128 v[192:195], v152 offset:3072
	ds_read_b128 v[196:199], v152 offset:4096
	ds_read_b128 v[200:203], v152 offset:5120
	ds_read_b128 v[204:207], v152 offset:6144
	ds_read_b128 v[208:211], v152 offset:7168
	global_load_lds_dwordx4 v[162:163], off
	v_lshl_add_u64 v[162:163], s[36:37], 0, v[136:137]
	s_add_i32 m0, s52, 0xe000
	s_nop 0
	global_load_lds_dwordx4 v[162:163], off
	s_waitcnt lgkmcnt(8)
	s_barrier
	s_waitcnt lgkmcnt(0)
	s_waitcnt lgkmcnt(0)
	v_mfma_f32_16x16x32_bf16 v[124:127], v[138:141], v[174:177], v[124:127]
	v_mfma_f32_16x16x32_bf16 v[120:123], v[158:161], v[174:177], v[120:123]
	v_mfma_f32_16x16x32_bf16 v[108:111], v[138:141], v[188:191], v[108:111]
	v_mfma_f32_16x16x32_bf16 v[104:107], v[158:161], v[188:191], v[104:107]
	v_mfma_f32_16x16x32_bf16 v[92:95], v[138:141], v[196:199], v[92:95]
	v_mfma_f32_16x16x32_bf16 v[88:91], v[158:161], v[196:199], v[88:91]
	v_mfma_f32_16x16x32_bf16 v[76:79], v[138:141], v[204:207], v[76:79]
	v_mfma_f32_16x16x32_bf16 v[72:75], v[158:161], v[204:207], v[72:75]
	v_mfma_f32_16x16x32_bf16 v[124:127], v[154:157], v[178:181], v[124:127]
	v_mfma_f32_16x16x32_bf16 v[120:123], v[170:173], v[178:181], v[120:123]
	v_mfma_f32_16x16x32_bf16 v[108:111], v[154:157], v[192:195], v[108:111]
	v_mfma_f32_16x16x32_bf16 v[104:107], v[170:173], v[192:195], v[104:107]
	v_mfma_f32_16x16x32_bf16 v[92:95], v[154:157], v[200:203], v[92:95]
	v_mfma_f32_16x16x32_bf16 v[88:91], v[170:173], v[200:203], v[88:91]
	v_mfma_f32_16x16x32_bf16 v[76:79], v[154:157], v[208:211], v[76:79]
	v_mfma_f32_16x16x32_bf16 v[72:75], v[170:173], v[208:211], v[72:75]
	s_barrier
	s_add_i32 s4, s73, 0x100
	s_add_i32 s45, s45, s51
	v_add_u32_e32 v153, s4, v151
	v_lshl_add_u64 v[162:163], s[42:43], 0, v[166:167]
	s_mov_b32 m0, s45
	ds_read_b128 v[212:215], v153
	ds_read_b128 v[216:219], v153 offset:1024
	ds_read_b128 v[220:223], v153 offset:2048
	ds_read_b128 v[224:227], v153 offset:3072
	global_load_lds_dwordx4 v[162:163], off
	v_lshl_add_u64 v[182:183], s[42:43], 0, v[132:133]
	s_add_i32 m0, s45, 0x2000
	s_nop 0
	global_load_lds_dwordx4 v[182:183], off
	s_barrier
; #define PG8_STAGE(bufoff, gbase, voff) do { _Pragma("unroll") for (int _i = 0; _i < 2; ++_i) \
;         __builtin_amdgcn_global_load_lds((const unsigned*)((const char*)(gbase) + (voff)[_i]), (LAS unsigned*)(lds + (bufoff) + ldsw + _i * 8192), 16, 0, 0); } while (0)
; #define PG8_LDA(dst, b, h) do { _Pragma("unroll") for (int m = 0; m < 4; ++m) _Pragma("unroll") for (int k = 0; k < 2; ++k) dst[m][k] = *(const LAS bf16x8*)(lds + PG8_SA(b, h) + aoff + m * 2048 + k * 1024); } while (0)
; #define PG8_LDB(dst, b, h) do { _Pragma("unroll") for (int n = 0; n < 2; ++n) _Pragma("unroll") for (int k = 0; k < 2; ++k) dst[n][k] = *(const LAS bf16x8*)(lds + PG8_SB(b, h) + boff + n * 2048 + k * 1024); } while (0)
; #define PG8_MMA(ai, bj, At, Bt) do { __builtin_amdgcn_s_setprio(1); _Pragma("unroll") for (int m = 0; m < 4; ++m) _Pragma("unroll") for (int n = 0; n < 2; ++n) _Pragma("unroll") for (int k = 0; k < 2; ++k) \
;         acc[ai][bj][m][n] = __builtin_amdgcn_mfma_f32_16x16x32_bf16(Bt[n][k], At[m][k], acc[ai][bj][m][n], 0, 0, 0); __builtin_amdgcn_s_setprio(0); } while (0)
; #define PG8_WAIT_V(n) asm volatile("s_waitcnt vmcnt(" #n ")" ::: "memory")
; #define PG8_WAIT_L(n) asm volatile("s_waitcnt lgkmcnt(" #n ")" ::: "memory")
; #define PG8_BAR __builtin_amdgcn_s_barrier()
; #define PG8_SCHED __builtin_amdgcn_sched_barrier(0)
; template <class Epi>
; DI void gemm_phase(LAS unsigned char* lds, const Gemm g, const StaticOrder& S, const Epi& E) {
;     ...
;             PG8_BAR; PG8_WAIT_L(0); PG8_MMA(0, 1, At, B1); PG8_BAR;
;             PG8_LDA(At, 0, 1); PG8_STAGE(PG8_SA(0, 0), a2, voffA);
;             PG8_BAR; PG8_WAIT_L(0); PG8_MMA(1, 0, At, B0); PG8_BAR; PG8_SCHED;
;             PG8_STAGE(PG8_SB(0, 1), b2 + hstep, voffB);
;             PG8_WAIT_V(6); PG8_BAR; PG8_MMA(1, 1, At, B1); PG8_BAR;
;             PG8_LDB(B0, 1, 0); PG8_SCHED; PG8_LDA(At, 1, 0); PG8_STAGE(PG8_SA(0, 1), a2 + hstep, voffA);
	s_waitcnt lgkmcnt(0)
	s_waitcnt lgkmcnt(0)
	v_mfma_f32_16x16x32_bf16 v[116:119], v[212:215], v[174:177], v[116:119]
	v_mfma_f32_16x16x32_bf16 v[112:115], v[220:223], v[174:177], v[112:115]
	v_mfma_f32_16x16x32_bf16 v[100:103], v[212:215], v[188:191], v[100:103]
	v_mfma_f32_16x16x32_bf16 v[96:99], v[220:223], v[188:191], v[96:99]
	v_mfma_f32_16x16x32_bf16 v[84:87], v[212:215], v[196:199], v[84:87]
	v_mfma_f32_16x16x32_bf16 v[80:83], v[220:223], v[196:199], v[80:83]
	v_mfma_f32_16x16x32_bf16 v[68:71], v[212:215], v[204:207], v[68:71]
	v_mfma_f32_16x16x32_bf16 v[64:67], v[220:223], v[204:207], v[64:67]
	v_mfma_f32_16x16x32_bf16 v[116:119], v[216:219], v[178:181], v[116:119]
	v_mfma_f32_16x16x32_bf16 v[112:115], v[224:227], v[178:181], v[112:115]
	v_mfma_f32_16x16x32_bf16 v[100:103], v[216:219], v[192:195], v[100:103]
	v_mfma_f32_16x16x32_bf16 v[96:99], v[224:227], v[192:195], v[96:99]
	v_mfma_f32_16x16x32_bf16 v[84:87], v[216:219], v[200:203], v[84:87]
	v_mfma_f32_16x16x32_bf16 v[80:83], v[224:227], v[200:203], v[80:83]
	v_mfma_f32_16x16x32_bf16 v[68:71], v[216:219], v[208:211], v[68:71]
	v_mfma_f32_16x16x32_bf16 v[64:67], v[224:227], v[208:211], v[64:67]
	s_mov_b32 m0, s52
	v_lshl_add_u64 v[228:229], s[40:41], 0, v[128:129]
	s_barrier
	ds_read_b128 v[174:177], v152 offset:16384
	ds_read_b128 v[178:181], v152 offset:17408
	ds_read_b128 v[188:191], v152 offset:18432
	ds_read_b128 v[192:195], v152 offset:19456
	ds_read_b128 v[196:199], v152 offset:20480
	ds_read_b128 v[200:203], v152 offset:21504
	ds_read_b128 v[204:207], v152 offset:22528
	ds_read_b128 v[208:211], v152 offset:23552
	global_load_lds_dwordx4 v[228:229], off
	v_lshl_add_u64 v[230:231], s[40:41], 0, v[130:131]
	s_mov_b32 m0, s53
	s_nop 0
	global_load_lds_dwordx4 v[230:231], off
	s_barrier
	s_waitcnt lgkmcnt(0)
	s_waitcnt lgkmcnt(0)
	v_mfma_f32_16x16x32_bf16 v[60:63], v[138:141], v[174:177], v[60:63]
	v_mfma_f32_16x16x32_bf16 v[56:59], v[158:161], v[174:177], v[56:59]
	v_mfma_f32_16x16x32_bf16 v[44:47], v[138:141], v[188:191], v[44:47]
	v_mfma_f32_16x16x32_bf16 v[40:43], v[158:161], v[188:191], v[40:43]
	v_mfma_f32_16x16x32_bf16 v[28:31], v[138:141], v[196:199], v[28:31]
	v_mfma_f32_16x16x32_bf16 v[24:27], v[158:161], v[196:199], v[24:27]
	v_mfma_f32_16x16x32_bf16 v[12:15], v[138:141], v[204:207], v[12:15]
	v_mfma_f32_16x16x32_bf16 v[8:11], v[158:161], v[204:207], v[8:11]
	v_mfma_f32_16x16x32_bf16 v[60:63], v[154:157], v[178:181], v[60:63]
	v_mfma_f32_16x16x32_bf16 v[56:59], v[170:173], v[178:181], v[56:59]
	v_mfma_f32_16x16x32_bf16 v[44:47], v[154:157], v[192:195], v[44:47]
	v_mfma_f32_16x16x32_bf16 v[40:43], v[170:173], v[192:195], v[40:43]
	v_mfma_f32_16x16x32_bf16 v[28:31], v[154:157], v[200:203], v[28:31]
	v_mfma_f32_16x16x32_bf16 v[24:27], v[170:173], v[200:203], v[24:27]
	v_mfma_f32_16x16x32_bf16 v[12:15], v[154:157], v[208:211], v[12:15]
	v_mfma_f32_16x16x32_bf16 v[8:11], v[170:173], v[208:211], v[8:11]
	s_barrier
	s_add_u32 s42, s42, s10
	s_addc_u32 s43, s43, s11
	s_add_i32 s4, s4, s51
	v_lshl_add_u64 v[232:233], s[42:43], 0, v[166:167]
	s_mov_b32 m0, s4
	v_lshl_add_u64 v[234:235], s[42:43], 0, v[132:133]
	global_load_lds_dwordx4 v[232:233], off
	s_add_i32 m0, s4, 0x2000
	s_nop 0
	global_load_lds_dwordx4 v[234:235], off
	s_waitcnt vmcnt(6)
	s_barrier
	v_mfma_f32_16x16x32_bf16 v[52:55], v[212:215], v[174:177], v[52:55]
	v_mfma_f32_16x16x32_bf16 v[48:51], v[220:223], v[174:177], v[48:51]
	v_mfma_f32_16x16x32_bf16 v[36:39], v[212:215], v[188:191], v[36:39]
	v_mfma_f32_16x16x32_bf16 v[32:35], v[220:223], v[188:191], v[32:35]
	v_mfma_f32_16x16x32_bf16 v[20:23], v[212:215], v[196:199], v[20:23]
	v_mfma_f32_16x16x32_bf16 v[16:19], v[220:223], v[196:199], v[16:19]
	v_mfma_f32_16x16x32_bf16 v[4:7], v[212:215], v[204:207], v[4:7]
	v_mfma_f32_16x16x32_bf16 v[0:3], v[220:223], v[204:207], v[0:3]
	v_mfma_f32_16x16x32_bf16 v[52:55], v[216:219], v[178:181], v[52:55]
	v_mfma_f32_16x16x32_bf16 v[48:51], v[224:227], v[178:181], v[48:51]
	v_mfma_f32_16x16x32_bf16 v[36:39], v[216:219], v[192:195], v[36:39]
	v_mfma_f32_16x16x32_bf16 v[32:35], v[224:227], v[192:195], v[32:35]
	v_mfma_f32_16x16x32_bf16 v[20:23], v[216:219], v[200:203], v[20:23]
	v_mfma_f32_16x16x32_bf16 v[16:19], v[224:227], v[200:203], v[16:19]
	v_mfma_f32_16x16x32_bf16 v[4:7], v[216:219], v[208:211], v[4:7]
	v_mfma_f32_16x16x32_bf16 v[0:3], v[224:227], v[208:211], v[0:3]
	s_add_i32 s4, s74, 0x100
	v_add_u32_e32 v153, s4, v151
	s_barrier
	ds_read_b128 v[138:141], v153
	ds_read_b128 v[154:157], v153 offset:1024
	ds_read_b128 v[158:161], v153 offset:2048
	ds_read_b128 v[170:173], v153 offset:3072
	s_add_u32 s40, s40, s10
	s_addc_u32 s41, s41, s11
	s_mov_b32 m0, s54
	v_lshl_add_u64 v[212:213], s[40:41], 0, v[128:129]
	ds_read_b128 v[174:177], v152 offset:32768
	ds_read_b128 v[178:181], v152 offset:33792
	ds_read_b128 v[188:191], v152 offset:34816
	ds_read_b128 v[192:195], v152 offset:35840
	ds_read_b128 v[196:199], v152 offset:36864
	ds_read_b128 v[200:203], v152 offset:37888
	ds_read_b128 v[204:207], v152 offset:38912
	ds_read_b128 v[208:211], v152 offset:39936
	global_load_lds_dwordx4 v[212:213], off
	v_lshl_add_u64 v[212:213], s[40:41], 0, v[130:131]
	s_mov_b32 m0, s55
	s_nop 0
	global_load_lds_dwordx4 v[212:213], off
	s_waitcnt lgkmcnt(8)
	s_barrier
; #define PG8_STAGE(bufoff, gbase, voff) do { _Pragma("unroll") for (int _i = 0; _i < 2; ++_i) \
;         __builtin_amdgcn_global_load_lds((const unsigned*)((const char*)(gbase) + (voff)[_i]), (LAS unsigned*)(lds + (bufoff) + ldsw + _i * 8192), 16, 0, 0); } while (0)
; #define PG8_LDA(dst, b, h) do { _Pragma("unroll") for (int m = 0; m < 4; ++m) _Pragma("unroll") for (int k = 0; k < 2; ++k) dst[m][k] = *(const LAS bf16x8*)(lds + PG8_SA(b, h) + aoff + m * 2048 + k * 1024); } while (0)
; #define PG8_LDB(dst, b, h) do { _Pragma("unroll") for (int n = 0; n < 2; ++n) _Pragma("unroll") for (int k = 0; k < 2; ++k) dst[n][k] = *(const LAS bf16x8*)(lds + PG8_SB(b, h) + boff + n * 2048 + k * 1024); } while (0)
; #define PG8_MMA(ai, bj, At, Bt) do { __builtin_amdgcn_s_setprio(1); _Pragma("unroll") for (int m = 0; m < 4; ++m) _Pragma("unroll") for (int n = 0; n < 2; ++n) _Pragma("unroll") for (int k = 0; k < 2; ++k) \
;         acc[ai][bj][m][n] = __builtin_amdgcn_mfma_f32_16x16x32_bf16(Bt[n][k], At[m][k], acc[ai][bj][m][n], 0, 0, 0); __builtin_amdgcn_s_setprio(0); } while (0)
; #define PG8_WAIT_V(n) asm volatile("s_waitcnt vmcnt(" #n ")" ::: "memory")
; #define PG8_WAIT_L(n) asm volatile("s_waitcnt lgkmcnt(" #n ")" ::: "memory")
; #define PG8_BAR __builtin_amdgcn_s_barrier()
; #define PG8_SCHED __builtin_amdgcn_sched_barrier(0)
; template <class Epi>
; DI void gemm_phase(LAS unsigned char* lds, const Gemm g, const StaticOrder& S, const Epi& E) {
;     ...
;             PG8_WAIT_L(8); PG8_BAR; PG8_WAIT_L(0); PG8_MMA(0, 0, At, B0); PG8_BAR; PG8_SCHED;
;             PG8_LDB(B1, 1, 1); PG8_STAGE(PG8_SB(1, 0), b3, voffB);
;             PG8_BAR; PG8_WAIT_L(0); PG8_MMA(0, 1, At, B1); PG8_BAR;
;             PG8_LDA(At, 1, 1); PG8_STAGE(PG8_SA(1, 0), a3, voffA);
;             PG8_BAR; PG8_WAIT_L(0); PG8_MMA(1, 0, At, B0); PG8_BAR; PG8_SCHED;
;             PG8_STAGE(PG8_SB(1, 1), b3 + hstep, voffB);
;             PG8_WAIT_V(6); PG8_BAR; PG8_MMA(1, 1, At, B1); PG8_BAR;
	s_waitcnt lgkmcnt(0)
	s_waitcnt lgkmcnt(0)
	v_mfma_f32_16x16x32_bf16 v[124:127], v[138:141], v[174:177], v[124:127]
	v_mfma_f32_16x16x32_bf16 v[120:123], v[158:161], v[174:177], v[120:123]
	v_mfma_f32_16x16x32_bf16 v[108:111], v[138:141], v[188:191], v[108:111]
	v_mfma_f32_16x16x32_bf16 v[104:107], v[158:161], v[188:191], v[104:107]
	v_mfma_f32_16x16x32_bf16 v[92:95], v[138:141], v[196:199], v[92:95]
	v_mfma_f32_16x16x32_bf16 v[88:91], v[158:161], v[196:199], v[88:91]
	v_mfma_f32_16x16x32_bf16 v[76:79], v[138:141], v[204:207], v[76:79]
	v_mfma_f32_16x16x32_bf16 v[72:75], v[158:161], v[204:207], v[72:75]
	v_mfma_f32_16x16x32_bf16 v[124:127], v[154:157], v[178:181], v[124:127]
	v_mfma_f32_16x16x32_bf16 v[120:123], v[170:173], v[178:181], v[120:123]
	v_mfma_f32_16x16x32_bf16 v[108:111], v[154:157], v[192:195], v[108:111]
	v_mfma_f32_16x16x32_bf16 v[104:107], v[170:173], v[192:195], v[104:107]
	v_mfma_f32_16x16x32_bf16 v[92:95], v[154:157], v[200:203], v[92:95]
	v_mfma_f32_16x16x32_bf16 v[88:91], v[170:173], v[200:203], v[88:91]
	v_mfma_f32_16x16x32_bf16 v[76:79], v[154:157], v[208:211], v[76:79]
	v_mfma_f32_16x16x32_bf16 v[72:75], v[170:173], v[208:211], v[72:75]
	s_barrier
	s_add_i32 s40, s75, 0x100
	s_add_i32 s4, s4, s51
	v_add_u32_e32 v153, s40, v151
	v_lshl_add_u64 v[162:163], v[162:163], 0, s[76:77]
	s_mov_b32 m0, s4
	ds_read_b128 v[212:215], v153
	ds_read_b128 v[216:219], v153 offset:1024
	ds_read_b128 v[220:223], v153 offset:2048
	ds_read_b128 v[224:227], v153 offset:3072
	global_load_lds_dwordx4 v[162:163], off
	v_lshl_add_u64 v[162:163], v[182:183], 0, s[76:77]
	s_add_i32 m0, s4, 0x2000
	s_nop 0
	global_load_lds_dwordx4 v[162:163], off
	s_barrier
	s_waitcnt lgkmcnt(0)
	s_waitcnt lgkmcnt(0)
	v_mfma_f32_16x16x32_bf16 v[116:119], v[212:215], v[174:177], v[116:119]
	v_mfma_f32_16x16x32_bf16 v[112:115], v[220:223], v[174:177], v[112:115]
	v_mfma_f32_16x16x32_bf16 v[100:103], v[212:215], v[188:191], v[100:103]
	v_mfma_f32_16x16x32_bf16 v[96:99], v[220:223], v[188:191], v[96:99]
	v_mfma_f32_16x16x32_bf16 v[84:87], v[212:215], v[196:199], v[84:87]
	v_mfma_f32_16x16x32_bf16 v[80:83], v[220:223], v[196:199], v[80:83]
	v_mfma_f32_16x16x32_bf16 v[68:71], v[212:215], v[204:207], v[68:71]
	v_mfma_f32_16x16x32_bf16 v[64:67], v[220:223], v[204:207], v[64:67]
	v_mfma_f32_16x16x32_bf16 v[116:119], v[216:219], v[178:181], v[116:119]
	v_mfma_f32_16x16x32_bf16 v[112:115], v[224:227], v[178:181], v[112:115]
	v_mfma_f32_16x16x32_bf16 v[100:103], v[216:219], v[192:195], v[100:103]
	v_mfma_f32_16x16x32_bf16 v[96:99], v[224:227], v[192:195], v[96:99]
	v_mfma_f32_16x16x32_bf16 v[84:87], v[216:219], v[200:203], v[84:87]
	v_mfma_f32_16x16x32_bf16 v[80:83], v[224:227], v[200:203], v[80:83]
	v_mfma_f32_16x16x32_bf16 v[68:71], v[216:219], v[208:211], v[68:71]
	v_mfma_f32_16x16x32_bf16 v[64:67], v[224:227], v[208:211], v[64:67]
	s_mov_b32 m0, s60
	v_lshl_add_u64 v[162:163], v[228:229], 0, s[76:77]
	s_barrier
	ds_read_b128 v[174:177], v152 offset:49152
	ds_read_b128 v[178:181], v152 offset:50176
	ds_read_b128 v[188:191], v152 offset:51200
	ds_read_b128 v[192:195], v152 offset:52224
	ds_read_b128 v[196:199], v152 offset:53248
	ds_read_b128 v[200:203], v152 offset:54272
	ds_read_b128 v[204:207], v152 offset:55296
	ds_read_b128 v[208:211], v152 offset:56320
	global_load_lds_dwordx4 v[162:163], off
	v_lshl_add_u64 v[162:163], v[230:231], 0, s[76:77]
	s_mov_b32 m0, s61
	s_nop 0
	global_load_lds_dwordx4 v[162:163], off
	s_barrier
	s_waitcnt lgkmcnt(0)
	s_waitcnt lgkmcnt(0)
	v_mfma_f32_16x16x32_bf16 v[60:63], v[138:141], v[174:177], v[60:63]
	v_mfma_f32_16x16x32_bf16 v[56:59], v[158:161], v[174:177], v[56:59]
	v_mfma_f32_16x16x32_bf16 v[44:47], v[138:141], v[188:191], v[44:47]
	v_mfma_f32_16x16x32_bf16 v[40:43], v[158:161], v[188:191], v[40:43]
	v_mfma_f32_16x16x32_bf16 v[28:31], v[138:141], v[196:199], v[28:31]
	v_mfma_f32_16x16x32_bf16 v[24:27], v[158:161], v[196:199], v[24:27]
	v_mfma_f32_16x16x32_bf16 v[12:15], v[138:141], v[204:207], v[12:15]
	v_mfma_f32_16x16x32_bf16 v[8:11], v[158:161], v[204:207], v[8:11]
	v_mfma_f32_16x16x32_bf16 v[60:63], v[154:157], v[178:181], v[60:63]
	v_mfma_f32_16x16x32_bf16 v[56:59], v[170:173], v[178:181], v[56:59]
	v_mfma_f32_16x16x32_bf16 v[44:47], v[154:157], v[192:195], v[44:47]
	v_mfma_f32_16x16x32_bf16 v[40:43], v[170:173], v[192:195], v[40:43]
	v_mfma_f32_16x16x32_bf16 v[28:31], v[154:157], v[200:203], v[28:31]
	v_mfma_f32_16x16x32_bf16 v[24:27], v[170:173], v[200:203], v[24:27]
	v_mfma_f32_16x16x32_bf16 v[12:15], v[154:157], v[208:211], v[12:15]
	v_mfma_f32_16x16x32_bf16 v[8:11], v[170:173], v[208:211], v[8:11]
	s_barrier
	s_add_i32 s4, s40, s51
	v_lshl_add_u64 v[138:139], v[232:233], 0, s[76:77]
	s_mov_b32 m0, s4
	s_nop 0
	global_load_lds_dwordx4 v[138:139], off
	v_lshl_add_u64 v[138:139], v[234:235], 0, s[76:77]
	s_add_i32 m0, s4, 0x2000
	s_nop 0
	global_load_lds_dwordx4 v[138:139], off
	s_waitcnt vmcnt(6)
	s_barrier
	v_mfma_f32_16x16x32_bf16 v[52:55], v[212:215], v[174:177], v[52:55]
	v_mfma_f32_16x16x32_bf16 v[48:51], v[220:223], v[174:177], v[48:51]
	v_mfma_f32_16x16x32_bf16 v[36:39], v[212:215], v[188:191], v[36:39]
	v_mfma_f32_16x16x32_bf16 v[32:35], v[220:223], v[188:191], v[32:35]
	v_mfma_f32_16x16x32_bf16 v[20:23], v[212:215], v[196:199], v[20:23]
	v_mfma_f32_16x16x32_bf16 v[16:19], v[220:223], v[196:199], v[16:19]
	v_mfma_f32_16x16x32_bf16 v[4:7], v[212:215], v[204:207], v[4:7]
	v_mfma_f32_16x16x32_bf16 v[0:3], v[220:223], v[204:207], v[0:3]
	v_mfma_f32_16x16x32_bf16 v[52:55], v[216:219], v[178:181], v[52:55]
	v_mfma_f32_16x16x32_bf16 v[48:51], v[224:227], v[178:181], v[48:51]
	v_mfma_f32_16x16x32_bf16 v[36:39], v[216:219], v[192:195], v[36:39]
	v_mfma_f32_16x16x32_bf16 v[32:35], v[224:227], v[192:195], v[32:35]
	v_mfma_f32_16x16x32_bf16 v[20:23], v[216:219], v[200:203], v[20:23]
	v_mfma_f32_16x16x32_bf16 v[16:19], v[224:227], v[200:203], v[16:19]
	v_mfma_f32_16x16x32_bf16 v[4:7], v[216:219], v[208:211], v[4:7]
	v_mfma_f32_16x16x32_bf16 v[0:3], v[224:227], v[208:211], v[0:3]
	s_add_u32 s36, s36, 0x100
	s_addc_u32 s37, s37, 0
	s_add_u32 s0, s0, 0x100
	s_addc_u32 s44, s44, 0
	s_cmp_ge_i32 s5, s57
	s_mov_b32 s4, s5
	s_barrier
	s_cbranch_scc0 .LBB0_1450

; #define PG8_STAGE(bufoff, gbase, voff) do { _Pragma("unroll") for (int _i = 0; _i < 2; ++_i) \
;         __builtin_amdgcn_global_load_lds((const unsigned*)((const char*)(gbase) + (voff)[_i]), (LAS unsigned*)(lds + (bufoff) + ldsw + _i * 8192), 16, 0, 0); } while (0)
; #define PG8_BAR __builtin_amdgcn_s_barrier()
;     DI bool next(int i, Unit& u) const {
;         const long L = (long)i * G + c; if (L >= nwg) return false;
;         int wgid = (int)L; { const int q = nwg / NXCD, r = nwg % NXCD, xcd = wgid % NXCD, off = wgid / NXCD; wgid = (xcd < r ? xcd * (q + 1) : r * (q + 1) + (xcd - r) * q) + off; }
;         const int nig = WGM * nN, gid = wgid / nig, fm = gid * WGM, gsz = (nM - fm) < WGM ? (nM - fm) : WGM;
;         u.pm = fm + ((wgid % nig) % gsz); u.pn = (wgid % nig) / gsz; return true;
;     }
; template <class Epi>
; DI void gemm_phase(LAS unsigned char* lds, const Gemm g, const StaticOrder& S, const Epi& E) {
;     ...
;     for (int i = 0; i < 2; ++i) { int R, C; stage_rc(tid * 16 + i * 8192, R, C); const int Rb = (R & ~31) + perm32(R & 31);
;         voffA[i] = (unsigned)(R * K + C) * 2u; voffB[i] = (unsigned)(Rb * K + C) * 2u; }
;     const size_t kstep = (size_t)(BK * 2);
;     const size_t hstep = (size_t)HALF * K * 2;
;     const size_t tstep = 2 * hstep;
;     const unsigned ldsw = (unsigned)wid * 1024u;
;     const int aoff = lds_byte(wr * 64 + fr, fq * 8), boff = lds_byte(wc * 32 + fr, fq * 8);
;     ...
;     Unit cur, nxt; int ui = 0;
;     if (!S.next(0, cur)) return;
;     f32x4 acc[2][2][4][2];
; #pragma unroll
;     for (int a = 0; a < 2; ++a)
; #pragma unroll
;         for (int b = 0; b < 2; ++b)
; #pragma unroll
;             for (int m = 0; m < 4; ++m)
; #pragma unroll
;                 for (int n = 0; n < 2; ++n) acc[a][b][m][n] = (f32x4){0.f, 0.f, 0.f, 0.f};
;     bf16x8 At[4][2], B0[2][2], B1[2][2];
;     const char* cA = (const char*)g.A + (size_t)cur.pm * tstep; const char* cB = (const char*)g.Bt + (size_t)cur.pn * tstep;
;     PG8_STAGE(PG8_SB(0, 0), cB, voffB); PG8_STAGE(PG8_SA(0, 0), cA, voffA); PG8_STAGE(PG8_SB(0, 1), cB + hstep, voffB); PG8_STAGE(PG8_SA(0, 1), cA + hstep, voffA);
;     if (wr == 1) PG8_BAR;
.LBB0_1585:
	s_or_b64 exec, exec, s[2:3]
	s_movk_i32 s0, 0x400
	s_waitcnt lgkmcnt(0)
	s_barrier
	s_ashr_i32 s2, s0, 31
	s_lshr_b32 s2, s2, 24
	s_add_i32 s0, s0, s2
	s_ashr_i32 s0, s0, 8
	s_movk_i32 s14, 0x400
	s_mov_b32 s33, s68
	v_readlane_b32 s46, v238, 0
	s_mul_i32 s2, s0, 0xc0
	v_mov_b32_e32 v18, v164
	s_cmp_ge_i32 s46, s2
	v_readfirstlane_b32 s47, v18
	s_cbranch_scc1 .LBB0_1603
	v_lshlrev_b32_e32 v0, 4, v18
	v_add_u32_e32 v1, 0x2000, v0
	v_ashrrev_i32_e32 v2, 31, v1
	v_lshrrev_b32_e32 v2, 22, v2
	v_add_u32_e32 v2, v1, v2
	v_ashrrev_i32_e32 v2, 10, v2
	v_mul_i32_i24_e32 v3, 0x400, v2
	v_sub_u32_e32 v1, v1, v3
	v_lshrrev_b32_e32 v3, 4, v1
	v_bitop3_b32 v1, v3, v1, 32 bitop3:0x6c
	v_ashrrev_i32_e32 v3, 31, v1
	v_lshrrev_b32_e32 v3, 26, v3
	v_add_u32_e32 v3, v1, v3
	v_lshlrev_b32_e32 v5, 3, v2
	v_ashrrev_i32_e32 v4, 6, v3
	v_and_b32_e32 v5, -16, v5
	v_lshlrev_b32_e32 v2, 5, v2
	v_add_u32_e32 v5, v4, v5
	v_and_b32_e32 v12, 32, v2
	v_and_b32_e32 v2, 0xc0, v3
	v_and_b32_e32 v4, 3, v4
	s_mov_b32 s5, 0x7fffffe0
	v_lshrrev_b32_e32 v6, 2, v5
	v_lshlrev_b32_e32 v7, 1, v5
	v_sub_u32_e32 v1, v1, v2
	v_and_or_b32 v4, v5, s5, v4
	v_and_b32_e32 v6, 4, v6
	v_and_b32_e32 v7, 24, v7
	v_ashrrev_i16_sdwa v1, v169, sext(v1) dst_sel:DWORD dst_unused:UNUSED_PAD src0_sel:DWORD src1_sel:BYTE_0
	v_or3_b32 v4, v4, v6, v7
	v_bfe_i32 v13, v1, 0, 16
	v_mul_lo_u32 v4, v4, s14
	v_add_u32_e32 v1, v12, v13
	v_mul_lo_u32 v14, v5, s14
	v_add_lshl_u32 v128, v4, v1, 1
	v_add_lshl_u32 v130, v1, v14, 1
	v_bfe_i32 v1, v18, 27, 1
	v_lshrrev_b32_e32 v1, 22, v1
	v_add_u32_e32 v1, v0, v1
	v_and_b32_e32 v1, 0xfffffc00, v1
	v_sub_u32_e32 v0, v0, v1
	v_ashrrev_i32_e32 v2, 31, v18
	v_lshrrev_b32_e32 v1, 4, v0
	v_lshrrev_b32_e32 v2, 26, v2
	v_bitop3_b32 v1, v1, v0, 32 bitop3:0x6c
	v_ashrrev_i32_e32 v0, 31, v0
	v_add_u32_e32 v2, v18, v2
	v_lshrrev_b32_e32 v0, 26, v0
	v_ashrrev_i32_e32 v2, 6, v2
	v_readlane_b32 s3, v236, 31
	v_add_u32_e32 v0, v1, v0
	v_lshlrev_b32_e32 v3, 3, v2
	s_add_u32 s48, s3, 0x1950000
	v_readlane_b32 s3, v236, 32
	v_ashrrev_i32_e32 v0, 6, v0
	v_and_b32_e32 v3, -16, v3
	s_addc_u32 s49, s3, 0
	v_add_u32_e32 v3, v0, v3
	v_and_b32_e32 v4, 3, v0
	s_ashr_i32 s52, s46, 31
	v_and_or_b32 v4, v3, s5, v4
	s_lshr_b32 s5, s52, 29
	s_add_i32 s5, s46, s5
	s_ashr_i32 s3, s47, 6
	s_ashr_i32 s15, s14, 31
	s_mul_i32 s51, s0, 24
	s_ashr_i32 s16, s5, 3
	s_and_b32 s5, s5, -8
	s_ashr_i32 s4, s47, 8
	s_lshl_b64 s[10:11], s[14:15], 8
	s_lshl_b64 s[12:13], s[14:15], 9
	s_lshl_b32 s50, s3, 10
	s_sub_i32 s5, s46, s5
	s_or_b32 s53, s51, 1
	s_cmp_lt_i32 s5, 0
	s_cselect_b32 s17, s53, s51
	v_mul_i32_i24_e32 v0, 64, v0
	s_mul_i32 s5, s17, s5
	v_lshrrev_b32_e32 v5, 2, v3
	v_lshlrev_b32_e32 v6, 1, v3
	v_sub_u32_e32 v0, v1, v0
	s_add_i32 s5, s5, s16
	v_and_b32_e32 v5, 4, v5
	v_and_b32_e32 v6, 24, v6
	v_lshlrev_b32_e32 v2, 5, v2
	v_ashrrev_i16_sdwa v0, v169, sext(v0) dst_sel:DWORD dst_unused:UNUSED_PAD src0_sel:DWORD src1_sel:BYTE_0
	s_lshl_b32 s54, s0, 3
	s_ashr_i32 s16, s5, 31
	s_ashr_i32 s55, s0, 31
	v_or3_b32 v4, v4, v5, v6
	v_and_b32_e32 v15, 32, v2
	v_bfe_i32 v16, v0, 0, 16
	s_xor_b32 s0, s16, s55
	s_add_i32 s16, s54, s55
	v_mul_lo_u32 v4, v4, s14
	v_add_u32_e32 v0, v15, v16
	v_mul_lo_u32 v17, v3, s14
	s_xor_b32 s56, s16, s55
	v_add_lshl_u32 v166, v4, v0, 1
	v_add_lshl_u32 v132, v0, v17, 1
	v_cvt_f32_u32_e32 v0, s56
	s_sub_i32 s16, 0, s56
	s_abs_i32 s17, s5
	v_readlane_b32 s60, v238, 1
	v_rcp_iflag_f32_e32 v0, v0
	v_readlane_b32 s72, v238, 13
	v_readlane_b32 s73, v238, 14
	v_mov_b32_e32 v129, v167
	v_mul_f32_e32 v0, 0x4f7ffffe, v0
	v_cvt_u32_f32_e32 v0, v0
	v_readlane_b32 s61, v238, 2
	v_mov_b32_e32 v133, v167
	v_mov_b32_e32 v131, v167
	v_readfirstlane_b32 s57, v0
	s_mul_i32 s16, s16, s57
	s_mul_hi_u32 s16, s57, s16
	s_add_i32 s57, s57, s16
	s_mul_hi_u32 s16, s17, s57
	s_mul_i32 s18, s16, s56
	s_sub_i32 s17, s17, s18
	s_add_i32 s18, s16, 1
	s_sub_i32 s19, s17, s56
	s_cmp_ge_u32 s17, s56
	s_cselect_b32 s16, s18, s16
	s_cselect_b32 s17, s19, s17
	s_add_i32 s18, s16, 1
	s_cmp_ge_u32 s17, s56
	s_cselect_b32 s16, s18, s16
	s_xor_b32 s16, s16, s0
	s_sub_i32 s0, s16, s0
	s_lshl_b32 s16, s0, 3
	s_sub_i32 s17, 0xc0, s16
	s_min_i32 s17, s17, 8
	s_abs_i32 s19, s17
	v_cvt_f32_u32_e32 v0, s19
	s_sub_i32 s36, 0, s19
	s_mul_i32 s0, s0, s54
	s_sub_i32 s5, s5, s0
	v_rcp_iflag_f32_e32 v0, v0
	s_abs_i32 s18, s5
	s_xor_b32 s0, s5, s17
	s_ashr_i32 s0, s0, 31
	v_mul_f32_e32 v0, 0x4f7ffffe, v0
	v_cvt_u32_f32_e32 v0, v0
	s_mov_b32 s77, 0x18000
	s_mov_b32 s76, 0x10000
	v_readlane_b32 s62, v238, 3
	v_readfirstlane_b32 s37, v0
	s_mul_i32 s36, s36, s37
	s_mul_hi_u32 s36, s37, s36
	s_add_i32 s37, s37, s36
	s_mul_hi_u32 s36, s18, s37
	s_mul_i32 s37, s36, s19
	s_sub_i32 s18, s18, s37
	s_add_i32 s37, s36, 1
	s_sub_i32 s38, s18, s19
	s_cmp_ge_u32 s18, s19
	s_cselect_b32 s36, s37, s36
	s_cselect_b32 s18, s38, s18
	s_add_i32 s37, s36, 1
	s_cmp_ge_u32 s18, s19
	s_cselect_b32 s18, s37, s36
	s_xor_b32 s18, s18, s0
	s_sub_i32 s0, s18, s0
	s_mul_i32 s17, s0, s17
	s_sub_i32 s5, s5, s17
	s_add_i32 s78, s5, s16
	s_ashr_i32 s5, s78, 31
	s_mul_i32 s5, s12, s5
	s_mul_hi_u32 s16, s12, s78
	s_ashr_i32 s18, s0, 31
	s_add_i32 s5, s16, s5
	s_lshr_b64 s[16:17], s[14:15], 23
	s_mul_i32 s18, s12, s18
	s_mul_hi_u32 s19, s12, s0
	s_mul_i32 s17, s16, s78
	s_add_i32 s18, s19, s18
	s_mul_i32 s16, s16, s0
	s_add_i32 s5, s5, s17
	s_add_i32 s18, s18, s16
	s_mul_i32 s16, s12, s0
	s_add_u32 s44, s48, s16
	s_addc_u32 s45, s49, s18
	s_add_i32 s58, s50, 0x100
	s_add_i32 m0, s58, 0x10000
	s_mul_i32 s17, s12, s78
	global_load_lds_dwordx4 v166, s[44:45]
	s_add_i32 m0, s58, 0x12000
	s_add_u32 s36, s72, s17
	global_load_lds_dwordx4 v128, s[44:45]
	s_addc_u32 s37, s73, s5
	s_mov_b32 m0, s58
	s_add_i32 s59, s58, 0x2000
	global_load_lds_dwordx4 v132, s[36:37]
	s_mov_b32 m0, s59
	s_add_u32 s16, s44, s10
	global_load_lds_dwordx4 v130, s[36:37]
	s_addc_u32 s17, s45, s11
	s_add_i32 m0, s58, 0x14000
	v_lshl_add_u64 v[8:9], s[16:17], 0, v[166:167]
	global_load_lds_dwordx4 v166, s[16:17]
	s_add_i32 m0, s58, 0x16000
	v_lshl_add_u64 v[10:11], s[16:17], 0, v[128:129]
	global_load_lds_dwordx4 v128, s[16:17]
	s_add_u32 s16, s36, s10
	s_addc_u32 s17, s37, s11
	s_add_i32 s60, s58, 0x4000
	s_mov_b32 m0, s60
	s_add_i32 s61, s58, 0x6000
	global_load_lds_dwordx4 v132, s[16:17]
	s_mov_b32 m0, s61
	v_lshl_add_u64 v[0:1], s[44:45], 0, v[166:167]
	global_load_lds_dwordx4 v130, s[16:17]
	v_lshl_add_u64 v[2:3], s[44:45], 0, v[128:129]
	v_lshl_add_u64 v[4:5], s[36:37], 0, v[132:133]
	v_lshl_add_u64 v[6:7], s[36:37], 0, v[130:131]
	s_cmp_lg_u32 s4, 1
	v_readlane_b32 s63, v238, 4
	v_readlane_b32 s64, v238, 5
	v_readlane_b32 s65, v238, 6
	v_readlane_b32 s66, v238, 7
	v_readlane_b32 s67, v238, 8
	v_readlane_b32 s68, v238, 9
	v_readlane_b32 s69, v238, 10
	v_readlane_b32 s70, v238, 11
	v_readlane_b32 s71, v238, 12
	v_readlane_b32 s74, v238, 15
	v_readlane_b32 s75, v238, 16
	s_cbranch_scc1 .LBB0_1588
	s_setprio 1
	s_barrier

; #define PG8_STAGE(bufoff, gbase, voff) do { _Pragma("unroll") for (int _i = 0; _i < 2; ++_i) \
;         __builtin_amdgcn_global_load_lds((const unsigned*)((const char*)(gbase) + (voff)[_i]), (LAS unsigned*)(lds + (bufoff) + ldsw + _i * 8192), 16, 0, 0); } while (0)
; #define PG8_LDA(dst, b, h) do { _Pragma("unroll") for (int m = 0; m < 4; ++m) _Pragma("unroll") for (int k = 0; k < 2; ++k) dst[m][k] = *(const LAS bf16x8*)(lds + PG8_SA(b, h) + aoff + m * 2048 + k * 1024); } while (0)
; #define PG8_LDB(dst, b, h) do { _Pragma("unroll") for (int n = 0; n < 2; ++n) _Pragma("unroll") for (int k = 0; k < 2; ++k) dst[n][k] = *(const LAS bf16x8*)(lds + PG8_SB(b, h) + boff + n * 2048 + k * 1024); } while (0)
; #define PG8_MMA(ai, bj, At, Bt) do { __builtin_amdgcn_s_setprio(1); _Pragma("unroll") for (int m = 0; m < 4; ++m) _Pragma("unroll") for (int n = 0; n < 2; ++n) _Pragma("unroll") for (int k = 0; k < 2; ++k) \
;         acc[ai][bj][m][n] = __builtin_amdgcn_mfma_f32_16x16x32_bf16(Bt[n][k], At[m][k], acc[ai][bj][m][n], 0, 0, 0); __builtin_amdgcn_s_setprio(0); } while (0)
; #define PG8_WAIT_V(n) asm volatile("s_waitcnt vmcnt(" #n ")" ::: "memory")
; #define PG8_WAIT_L(n) asm volatile("s_waitcnt lgkmcnt(" #n ")" ::: "memory")
; #define PG8_BAR __builtin_amdgcn_s_barrier()
; template <class Epi>
; DI void gemm_phase(LAS unsigned char* lds, const Gemm g, const StaticOrder& S, const Epi& E) {
;     ...
;         for (int t = 0; t < nt; t += 2) {
;             const bool last = (t == nt - 2);
;             const char* a1 = cA + (size_t)(t + 1) * kstep;
;             const char* a2 = last ? nA : cA + (size_t)(t + 2) * kstep; const char* b2 = last ? nB : cB + (size_t)(t + 2) * kstep;
;             const char* a3 = a2 + kstep; const char* b3 = b2 + kstep;
;             PG8_LDB(B0, 0, 0); PG8_SCHED; PG8_LDA(At, 0, 0); PG8_STAGE(PG8_SA(1, 1), a1 + hstep, voffA);
;             PG8_WAIT_L(8); PG8_BAR; PG8_WAIT_L(0); PG8_MMA(0, 0, At, B0); PG8_BAR; PG8_SCHED;
;             PG8_LDB(B1, 0, 1); PG8_STAGE(PG8_SB(0, 0), b2, voffB);
;             PG8_BAR; PG8_WAIT_L(0); PG8_MMA(0, 1, At, B1); PG8_BAR;
;             PG8_LDA(At, 0, 1); PG8_STAGE(PG8_SA(0, 0), a2, voffA);
;             PG8_BAR; PG8_WAIT_L(0); PG8_MMA(1, 0, At, B0); PG8_BAR; PG8_SCHED;
;             PG8_STAGE(PG8_SB(0, 1), b2 + hstep, voffB);
;             PG8_WAIT_V(6); PG8_BAR; PG8_MMA(1, 1, At, B1); PG8_BAR;
.LBB0_1596:
	s_andn2_b64 vcc, exec, s[14:15]
	s_cbranch_vccnz .LBB0_1589
	s_add_u32 s36, s36, 0x80
	s_addc_u32 s37, s37, 0
	s_add_u32 s44, s44, 0x100
	s_addc_u32 s45, s45, 0
	s_mov_b32 s4, 0
	s_mov_b32 s72, 0x10000
	s_mov_b32 s73, 0x14000
	s_mov_b32 s74, 0x18000
	s_mov_b32 s75, 0x1c000
	s_mov_b64 s[76:77], 0x80
	s_add_i32 s5, s4, 2
	s_add_u32 s40, s36, 0x80
	s_addc_u32 s41, s37, 0
	s_add_i32 s79, s72, 0x100
	v_add_u32_e32 v149, s79, v140
	ds_read_b128 v[150:153], v149
	ds_read_b128 v[154:157], v149 offset:1024
	ds_read_b128 v[158:161], v149 offset:2048
	ds_read_b128 v[170:173], v149 offset:3072
	s_cmp_eq_u32 s67, s4
	s_cselect_b32 s41, s17, s41
	s_cselect_b32 s40, s16, s40
	s_cselect_b32 s43, s19, s45
	s_cselect_b32 s42, s18, s44
	v_lshl_add_u64 v[162:163], s[36:37], 0, v[134:135]
	s_add_i32 m0, s58, 0xc000
	ds_read_b128 v[174:177], v141
	ds_read_b128 v[178:181], v141 offset:1024
	ds_read_b128 v[188:191], v141 offset:2048
	ds_read_b128 v[192:195], v141 offset:3072
	ds_read_b128 v[196:199], v141 offset:4096
	ds_read_b128 v[200:203], v141 offset:5120
	ds_read_b128 v[204:207], v141 offset:6144
	ds_read_b128 v[208:211], v141 offset:7168
	global_load_lds_dwordx4 v[162:163], off
	v_lshl_add_u64 v[162:163], s[36:37], 0, v[136:137]
	s_add_i32 m0, s58, 0xe000
	s_nop 0
	global_load_lds_dwordx4 v[162:163], off
	s_waitcnt lgkmcnt(8)
	s_barrier
	s_waitcnt lgkmcnt(0)
	s_waitcnt lgkmcnt(0)
	v_mfma_f32_16x16x32_bf16 v[124:127], v[150:153], v[174:177], 0
	v_mfma_f32_16x16x32_bf16 v[120:123], v[158:161], v[174:177], 0
	v_mfma_f32_16x16x32_bf16 v[108:111], v[150:153], v[188:191], 0
	v_mfma_f32_16x16x32_bf16 v[104:107], v[158:161], v[188:191], 0
	v_mfma_f32_16x16x32_bf16 v[92:95], v[150:153], v[196:199], 0
	v_mfma_f32_16x16x32_bf16 v[88:91], v[158:161], v[196:199], 0
	v_mfma_f32_16x16x32_bf16 v[76:79], v[150:153], v[204:207], 0
	v_mfma_f32_16x16x32_bf16 v[72:75], v[158:161], v[204:207], 0
	v_mfma_f32_16x16x32_bf16 v[124:127], v[154:157], v[178:181], v[124:127]
	v_mfma_f32_16x16x32_bf16 v[120:123], v[170:173], v[178:181], v[120:123]
	v_mfma_f32_16x16x32_bf16 v[108:111], v[154:157], v[192:195], v[108:111]
	v_mfma_f32_16x16x32_bf16 v[104:107], v[170:173], v[192:195], v[104:107]
	v_mfma_f32_16x16x32_bf16 v[92:95], v[154:157], v[200:203], v[92:95]
	v_mfma_f32_16x16x32_bf16 v[88:91], v[170:173], v[200:203], v[88:91]
	v_mfma_f32_16x16x32_bf16 v[76:79], v[154:157], v[208:211], v[76:79]
	v_mfma_f32_16x16x32_bf16 v[72:75], v[170:173], v[208:211], v[72:75]
	s_barrier
	s_add_i32 s4, s73, 0x100
	s_add_i32 s79, s79, s50
	v_add_u32_e32 v149, s4, v140
	v_lshl_add_u64 v[162:163], s[42:43], 0, v[166:167]
	s_mov_b32 m0, s79
	ds_read_b128 v[212:215], v149
	ds_read_b128 v[216:219], v149 offset:1024
	ds_read_b128 v[220:223], v149 offset:2048
	ds_read_b128 v[224:227], v149 offset:3072
	global_load_lds_dwordx4 v[162:163], off
	v_lshl_add_u64 v[182:183], s[42:43], 0, v[128:129]
	s_add_i32 m0, s79, 0x2000
	s_nop 0
	global_load_lds_dwordx4 v[182:183], off
	s_barrier
	s_waitcnt lgkmcnt(0)
	s_waitcnt lgkmcnt(0)
	v_mfma_f32_16x16x32_bf16 v[116:119], v[212:215], v[174:177], 0
	v_mfma_f32_16x16x32_bf16 v[112:115], v[220:223], v[174:177], 0
	v_mfma_f32_16x16x32_bf16 v[100:103], v[212:215], v[188:191], 0
	v_mfma_f32_16x16x32_bf16 v[96:99], v[220:223], v[188:191], 0
	v_mfma_f32_16x16x32_bf16 v[84:87], v[212:215], v[196:199], 0
	v_mfma_f32_16x16x32_bf16 v[80:83], v[220:223], v[196:199], 0
	v_mfma_f32_16x16x32_bf16 v[68:71], v[212:215], v[204:207], 0
	v_mfma_f32_16x16x32_bf16 v[64:67], v[220:223], v[204:207], 0
	v_mfma_f32_16x16x32_bf16 v[116:119], v[216:219], v[178:181], v[116:119]
	v_mfma_f32_16x16x32_bf16 v[112:115], v[224:227], v[178:181], v[112:115]
	v_mfma_f32_16x16x32_bf16 v[100:103], v[216:219], v[192:195], v[100:103]
	v_mfma_f32_16x16x32_bf16 v[96:99], v[224:227], v[192:195], v[96:99]
	v_mfma_f32_16x16x32_bf16 v[84:87], v[216:219], v[200:203], v[84:87]
	v_mfma_f32_16x16x32_bf16 v[80:83], v[224:227], v[200:203], v[80:83]
	v_mfma_f32_16x16x32_bf16 v[68:71], v[216:219], v[208:211], v[68:71]
	v_mfma_f32_16x16x32_bf16 v[64:67], v[224:227], v[208:211], v[64:67]
	s_mov_b32 m0, s58
	v_lshl_add_u64 v[228:229], s[40:41], 0, v[132:133]
	s_barrier
	ds_read_b128 v[174:177], v141 offset:16384
	ds_read_b128 v[178:181], v141 offset:17408
	ds_read_b128 v[188:191], v141 offset:18432
	ds_read_b128 v[192:195], v141 offset:19456
	ds_read_b128 v[196:199], v141 offset:20480
	ds_read_b128 v[200:203], v141 offset:21504
	ds_read_b128 v[204:207], v141 offset:22528
	ds_read_b128 v[208:211], v141 offset:23552
	global_load_lds_dwordx4 v[228:229], off
	v_lshl_add_u64 v[230:231], s[40:41], 0, v[130:131]
	s_mov_b32 m0, s59
	s_nop 0
	global_load_lds_dwordx4 v[230:231], off
	s_barrier
	s_waitcnt lgkmcnt(0)
	s_waitcnt lgkmcnt(0)
	v_mfma_f32_16x16x32_bf16 v[60:63], v[150:153], v[174:177], 0
	v_mfma_f32_16x16x32_bf16 v[56:59], v[158:161], v[174:177], 0
	v_mfma_f32_16x16x32_bf16 v[44:47], v[150:153], v[188:191], 0
	v_mfma_f32_16x16x32_bf16 v[40:43], v[158:161], v[188:191], 0
	v_mfma_f32_16x16x32_bf16 v[28:31], v[150:153], v[196:199], 0
	v_mfma_f32_16x16x32_bf16 v[24:27], v[158:161], v[196:199], 0
	v_mfma_f32_16x16x32_bf16 v[12:15], v[150:153], v[204:207], 0
	v_mfma_f32_16x16x32_bf16 v[8:11], v[158:161], v[204:207], 0
	v_mfma_f32_16x16x32_bf16 v[60:63], v[154:157], v[178:181], v[60:63]
	v_mfma_f32_16x16x32_bf16 v[56:59], v[170:173], v[178:181], v[56:59]
	v_mfma_f32_16x16x32_bf16 v[44:47], v[154:157], v[192:195], v[44:47]
	v_mfma_f32_16x16x32_bf16 v[40:43], v[170:173], v[192:195], v[40:43]
	v_mfma_f32_16x16x32_bf16 v[28:31], v[154:157], v[200:203], v[28:31]
	v_mfma_f32_16x16x32_bf16 v[24:27], v[170:173], v[200:203], v[24:27]
	v_mfma_f32_16x16x32_bf16 v[12:15], v[154:157], v[208:211], v[12:15]
	v_mfma_f32_16x16x32_bf16 v[8:11], v[170:173], v[208:211], v[8:11]
	s_barrier
; #define PG8_STAGE(bufoff, gbase, voff) do { _Pragma("unroll") for (int _i = 0; _i < 2; ++_i) \
;         __builtin_amdgcn_global_load_lds((const unsigned*)((const char*)(gbase) + (voff)[_i]), (LAS unsigned*)(lds + (bufoff) + ldsw + _i * 8192), 16, 0, 0); } while (0)
; #define PG8_LDA(dst, b, h) do { _Pragma("unroll") for (int m = 0; m < 4; ++m) _Pragma("unroll") for (int k = 0; k < 2; ++k) dst[m][k] = *(const LAS bf16x8*)(lds + PG8_SA(b, h) + aoff + m * 2048 + k * 1024); } while (0)
; #define PG8_LDB(dst, b, h) do { _Pragma("unroll") for (int n = 0; n < 2; ++n) _Pragma("unroll") for (int k = 0; k < 2; ++k) dst[n][k] = *(const LAS bf16x8*)(lds + PG8_SB(b, h) + boff + n * 2048 + k * 1024); } while (0)
; #define PG8_MMA(ai, bj, At, Bt) do { __builtin_amdgcn_s_setprio(1); _Pragma("unroll") for (int m = 0; m < 4; ++m) _Pragma("unroll") for (int n = 0; n < 2; ++n) _Pragma("unroll") for (int k = 0; k < 2; ++k) \
;         acc[ai][bj][m][n] = __builtin_amdgcn_mfma_f32_16x16x32_bf16(Bt[n][k], At[m][k], acc[ai][bj][m][n], 0, 0, 0); __builtin_amdgcn_s_setprio(0); } while (0)
; #define PG8_WAIT_V(n) asm volatile("s_waitcnt vmcnt(" #n ")" ::: "memory")
; #define PG8_WAIT_L(n) asm volatile("s_waitcnt lgkmcnt(" #n ")" ::: "memory")
; #define PG8_BAR __builtin_amdgcn_s_barrier()
; #define PG8_SCHED __builtin_amdgcn_sched_barrier(0)
; template <class Epi>
; DI void gemm_phase(LAS unsigned char* lds, const Gemm g, const StaticOrder& S, const Epi& E) {
;     ...
;             PG8_WAIT_V(6); PG8_BAR; PG8_MMA(1, 1, At, B1); PG8_BAR;
;             PG8_LDB(B0, 1, 0); PG8_SCHED; PG8_LDA(At, 1, 0); PG8_STAGE(PG8_SA(0, 1), a2 + hstep, voffA);
;             PG8_WAIT_L(8); PG8_BAR; PG8_WAIT_L(0); PG8_MMA(0, 0, At, B0); PG8_BAR; PG8_SCHED;
;             PG8_LDB(B1, 1, 1); PG8_STAGE(PG8_SB(1, 0), b3, voffB);
;             PG8_BAR; PG8_WAIT_L(0); PG8_MMA(0, 1, At, B1); PG8_BAR;
;             PG8_LDA(At, 1, 1); PG8_STAGE(PG8_SA(1, 0), a3, voffA);
;             PG8_BAR; PG8_WAIT_L(0); PG8_MMA(1, 0, At, B0); PG8_BAR; PG8_SCHED;
	s_add_u32 s42, s42, s10
	s_addc_u32 s43, s43, s11
	s_add_i32 s4, s4, s50
	v_lshl_add_u64 v[232:233], s[42:43], 0, v[166:167]
	s_mov_b32 m0, s4
	v_lshl_add_u64 v[234:235], s[42:43], 0, v[128:129]
	global_load_lds_dwordx4 v[232:233], off
	s_add_i32 m0, s4, 0x2000
	s_nop 0
	global_load_lds_dwordx4 v[234:235], off
	s_waitcnt vmcnt(6)
	s_barrier
	v_mfma_f32_16x16x32_bf16 v[52:55], v[212:215], v[174:177], 0
	v_mfma_f32_16x16x32_bf16 v[48:51], v[220:223], v[174:177], 0
	v_mfma_f32_16x16x32_bf16 v[36:39], v[212:215], v[188:191], 0
	v_mfma_f32_16x16x32_bf16 v[32:35], v[220:223], v[188:191], 0
	v_mfma_f32_16x16x32_bf16 v[20:23], v[212:215], v[196:199], 0
	v_mfma_f32_16x16x32_bf16 v[16:19], v[220:223], v[196:199], 0
	v_mfma_f32_16x16x32_bf16 v[4:7], v[212:215], v[204:207], 0
	v_mfma_f32_16x16x32_bf16 v[0:3], v[220:223], v[204:207], 0
	v_mfma_f32_16x16x32_bf16 v[52:55], v[216:219], v[178:181], v[52:55]
	v_mfma_f32_16x16x32_bf16 v[48:51], v[224:227], v[178:181], v[48:51]
	v_mfma_f32_16x16x32_bf16 v[36:39], v[216:219], v[192:195], v[36:39]
	v_mfma_f32_16x16x32_bf16 v[32:35], v[224:227], v[192:195], v[32:35]
	v_mfma_f32_16x16x32_bf16 v[20:23], v[216:219], v[200:203], v[20:23]
	v_mfma_f32_16x16x32_bf16 v[16:19], v[224:227], v[200:203], v[16:19]
	v_mfma_f32_16x16x32_bf16 v[4:7], v[216:219], v[208:211], v[4:7]
	v_mfma_f32_16x16x32_bf16 v[0:3], v[224:227], v[208:211], v[0:3]
	s_add_i32 s4, s74, 0x100
	v_add_u32_e32 v149, s4, v140
	s_barrier
	ds_read_b128 v[150:153], v149
	ds_read_b128 v[154:157], v149 offset:1024
	ds_read_b128 v[158:161], v149 offset:2048
	ds_read_b128 v[170:173], v149 offset:3072
	s_add_u32 s40, s40, s10
	s_addc_u32 s41, s41, s11
	s_mov_b32 m0, s60
	v_lshl_add_u64 v[212:213], s[40:41], 0, v[132:133]
	ds_read_b128 v[174:177], v141 offset:32768
	ds_read_b128 v[178:181], v141 offset:33792
	ds_read_b128 v[188:191], v141 offset:34816
	ds_read_b128 v[192:195], v141 offset:35840
	ds_read_b128 v[196:199], v141 offset:36864
	ds_read_b128 v[200:203], v141 offset:37888
	ds_read_b128 v[204:207], v141 offset:38912
	ds_read_b128 v[208:211], v141 offset:39936
	global_load_lds_dwordx4 v[212:213], off
	v_lshl_add_u64 v[212:213], s[40:41], 0, v[130:131]
	s_mov_b32 m0, s61
	s_nop 0
	global_load_lds_dwordx4 v[212:213], off
	s_waitcnt lgkmcnt(8)
	s_barrier
	s_waitcnt lgkmcnt(0)
	s_waitcnt lgkmcnt(0)
	v_mfma_f32_16x16x32_bf16 v[124:127], v[150:153], v[174:177], v[124:127]
	v_mfma_f32_16x16x32_bf16 v[120:123], v[158:161], v[174:177], v[120:123]
	v_mfma_f32_16x16x32_bf16 v[108:111], v[150:153], v[188:191], v[108:111]
	v_mfma_f32_16x16x32_bf16 v[104:107], v[158:161], v[188:191], v[104:107]
	v_mfma_f32_16x16x32_bf16 v[92:95], v[150:153], v[196:199], v[92:95]
	v_mfma_f32_16x16x32_bf16 v[88:91], v[158:161], v[196:199], v[88:91]
	v_mfma_f32_16x16x32_bf16 v[76:79], v[150:153], v[204:207], v[76:79]
	v_mfma_f32_16x16x32_bf16 v[72:75], v[158:161], v[204:207], v[72:75]
	v_mfma_f32_16x16x32_bf16 v[124:127], v[154:157], v[178:181], v[124:127]
	v_mfma_f32_16x16x32_bf16 v[120:123], v[170:173], v[178:181], v[120:123]
	v_mfma_f32_16x16x32_bf16 v[108:111], v[154:157], v[192:195], v[108:111]
	v_mfma_f32_16x16x32_bf16 v[104:107], v[170:173], v[192:195], v[104:107]
	v_mfma_f32_16x16x32_bf16 v[92:95], v[154:157], v[200:203], v[92:95]
	v_mfma_f32_16x16x32_bf16 v[88:91], v[170:173], v[200:203], v[88:91]
	v_mfma_f32_16x16x32_bf16 v[76:79], v[154:157], v[208:211], v[76:79]
	v_mfma_f32_16x16x32_bf16 v[72:75], v[170:173], v[208:211], v[72:75]
	s_barrier
	s_add_i32 s40, s75, 0x100
	s_add_i32 s4, s4, s50
	v_add_u32_e32 v149, s40, v140
	v_lshl_add_u64 v[162:163], v[162:163], 0, s[76:77]
	s_mov_b32 m0, s4
	ds_read_b128 v[212:215], v149
	ds_read_b128 v[216:219], v149 offset:1024
	ds_read_b128 v[220:223], v149 offset:2048
	ds_read_b128 v[224:227], v149 offset:3072
	global_load_lds_dwordx4 v[162:163], off
	v_lshl_add_u64 v[162:163], v[182:183], 0, s[76:77]
	s_add_i32 m0, s4, 0x2000
	s_nop 0
	global_load_lds_dwordx4 v[162:163], off
	s_barrier
	s_waitcnt lgkmcnt(0)
	s_waitcnt lgkmcnt(0)
	v_mfma_f32_16x16x32_bf16 v[116:119], v[212:215], v[174:177], v[116:119]
	v_mfma_f32_16x16x32_bf16 v[112:115], v[220:223], v[174:177], v[112:115]
	v_mfma_f32_16x16x32_bf16 v[100:103], v[212:215], v[188:191], v[100:103]
	v_mfma_f32_16x16x32_bf16 v[96:99], v[220:223], v[188:191], v[96:99]
	v_mfma_f32_16x16x32_bf16 v[84:87], v[212:215], v[196:199], v[84:87]
	v_mfma_f32_16x16x32_bf16 v[80:83], v[220:223], v[196:199], v[80:83]
	v_mfma_f32_16x16x32_bf16 v[68:71], v[212:215], v[204:207], v[68:71]
	v_mfma_f32_16x16x32_bf16 v[64:67], v[220:223], v[204:207], v[64:67]
	v_mfma_f32_16x16x32_bf16 v[116:119], v[216:219], v[178:181], v[116:119]
	v_mfma_f32_16x16x32_bf16 v[112:115], v[224:227], v[178:181], v[112:115]
	v_mfma_f32_16x16x32_bf16 v[100:103], v[216:219], v[192:195], v[100:103]
	v_mfma_f32_16x16x32_bf16 v[96:99], v[224:227], v[192:195], v[96:99]
	v_mfma_f32_16x16x32_bf16 v[84:87], v[216:219], v[200:203], v[84:87]
	v_mfma_f32_16x16x32_bf16 v[80:83], v[224:227], v[200:203], v[80:83]
	v_mfma_f32_16x16x32_bf16 v[68:71], v[216:219], v[208:211], v[68:71]
	v_mfma_f32_16x16x32_bf16 v[64:67], v[224:227], v[208:211], v[64:67]
	s_mov_b32 m0, s65
	v_lshl_add_u64 v[162:163], v[228:229], 0, s[76:77]
	s_barrier
	ds_read_b128 v[174:177], v141 offset:49152
	ds_read_b128 v[178:181], v141 offset:50176
	ds_read_b128 v[188:191], v141 offset:51200
	ds_read_b128 v[192:195], v141 offset:52224
	ds_read_b128 v[196:199], v141 offset:53248
	ds_read_b128 v[200:203], v141 offset:54272
	ds_read_b128 v[204:207], v141 offset:55296
	ds_read_b128 v[208:211], v141 offset:56320
	global_load_lds_dwordx4 v[162:163], off
	v_lshl_add_u64 v[162:163], v[230:231], 0, s[76:77]
	s_mov_b32 m0, s66
	s_nop 0
	global_load_lds_dwordx4 v[162:163], off
	s_barrier
; #define PG8_STAGE(bufoff, gbase, voff) do { _Pragma("unroll") for (int _i = 0; _i < 2; ++_i) \
;         __builtin_amdgcn_global_load_lds((const unsigned*)((const char*)(gbase) + (voff)[_i]), (LAS unsigned*)(lds + (bufoff) + ldsw + _i * 8192), 16, 0, 0); } while (0)
; #define PG8_LDA(dst, b, h) do { _Pragma("unroll") for (int m = 0; m < 4; ++m) _Pragma("unroll") for (int k = 0; k < 2; ++k) dst[m][k] = *(const LAS bf16x8*)(lds + PG8_SA(b, h) + aoff + m * 2048 + k * 1024); } while (0)
; #define PG8_LDB(dst, b, h) do { _Pragma("unroll") for (int n = 0; n < 2; ++n) _Pragma("unroll") for (int k = 0; k < 2; ++k) dst[n][k] = *(const LAS bf16x8*)(lds + PG8_SB(b, h) + boff + n * 2048 + k * 1024); } while (0)
; #define PG8_WAIT_V(n) asm volatile("s_waitcnt vmcnt(" #n ")" ::: "memory")
; #define PG8_WAIT_L(n) asm volatile("s_waitcnt lgkmcnt(" #n ")" ::: "memory")
; #define PG8_BAR __builtin_amdgcn_s_barrier()
; #define PG8_SCHED __builtin_amdgcn_sched_barrier(0)
; template <class Epi>
; DI void gemm_phase(LAS unsigned char* lds, const Gemm g, const StaticOrder& S, const Epi& E) {
;     ...
;             PG8_LDB(B0, 0, 0); PG8_SCHED; PG8_LDA(At, 0, 0); PG8_STAGE(PG8_SA(1, 1), a1 + hstep, voffA);
;             PG8_WAIT_L(8); PG8_BAR; PG8_WAIT_L(0); PG8_MMA(0, 0, At, B0); PG8_BAR; PG8_SCHED;
;             PG8_LDB(B1, 0, 1); PG8_STAGE(PG8_SB(0, 0), b2, voffB);
;             PG8_BAR; PG8_WAIT_L(0); PG8_MMA(0, 1, At, B1); PG8_BAR;
;             PG8_LDA(At, 0, 1); PG8_STAGE(PG8_SA(0, 0), a2, voffA);
;             PG8_BAR; PG8_WAIT_L(0); PG8_MMA(1, 0, At, B0); PG8_BAR; PG8_SCHED;
;             PG8_STAGE(PG8_SB(0, 1), b2 + hstep, voffB);
;             PG8_WAIT_V(6); PG8_BAR; PG8_MMA(1, 1, At, B1); PG8_BAR;
;             PG8_LDB(B0, 1, 0); PG8_SCHED; PG8_LDA(At, 1, 0); PG8_STAGE(PG8_SA(0, 1), a2 + hstep, voffA);
;             PG8_WAIT_L(8); PG8_BAR; PG8_WAIT_L(0); PG8_MMA(0, 0, At, B0); PG8_BAR; PG8_SCHED;
;             PG8_LDB(B1, 1, 1); PG8_STAGE(PG8_SB(1, 0), b3, voffB);
;             PG8_BAR; PG8_WAIT_L(0); PG8_MMA(0, 1, At, B1); PG8_BAR;
;             PG8_LDA(At, 1, 1); PG8_STAGE(PG8_SA(1, 0), a3, voffA);
;             PG8_BAR; PG8_WAIT_L(0); PG8_MMA(1, 0, At, B0); PG8_BAR; PG8_SCHED;
;             PG8_STAGE(PG8_SB(1, 1), b3 + hstep, voffB);
;             PG8_WAIT_V(6); PG8_BAR; PG8_MMA(1, 1, At, B1); PG8_BAR;
	s_waitcnt lgkmcnt(0)
	s_waitcnt lgkmcnt(0)
	v_mfma_f32_16x16x32_bf16 v[60:63], v[150:153], v[174:177], v[60:63]
	v_mfma_f32_16x16x32_bf16 v[56:59], v[158:161], v[174:177], v[56:59]
	v_mfma_f32_16x16x32_bf16 v[44:47], v[150:153], v[188:191], v[44:47]
	v_mfma_f32_16x16x32_bf16 v[40:43], v[158:161], v[188:191], v[40:43]
	v_mfma_f32_16x16x32_bf16 v[28:31], v[150:153], v[196:199], v[28:31]
	v_mfma_f32_16x16x32_bf16 v[24:27], v[158:161], v[196:199], v[24:27]
	v_mfma_f32_16x16x32_bf16 v[12:15], v[150:153], v[204:207], v[12:15]
	v_mfma_f32_16x16x32_bf16 v[8:11], v[158:161], v[204:207], v[8:11]
	v_mfma_f32_16x16x32_bf16 v[60:63], v[154:157], v[178:181], v[60:63]
	v_mfma_f32_16x16x32_bf16 v[56:59], v[170:173], v[178:181], v[56:59]
	v_mfma_f32_16x16x32_bf16 v[44:47], v[154:157], v[192:195], v[44:47]
	v_mfma_f32_16x16x32_bf16 v[40:43], v[170:173], v[192:195], v[40:43]
	v_mfma_f32_16x16x32_bf16 v[28:31], v[154:157], v[200:203], v[28:31]
	v_mfma_f32_16x16x32_bf16 v[24:27], v[170:173], v[200:203], v[24:27]
	v_mfma_f32_16x16x32_bf16 v[12:15], v[154:157], v[208:211], v[12:15]
	v_mfma_f32_16x16x32_bf16 v[8:11], v[170:173], v[208:211], v[8:11]
	s_barrier
	s_add_i32 s4, s40, s50
	v_lshl_add_u64 v[150:151], v[232:233], 0, s[76:77]
	s_mov_b32 m0, s4
	s_nop 0
	global_load_lds_dwordx4 v[150:151], off
	v_lshl_add_u64 v[150:151], v[234:235], 0, s[76:77]
	s_add_i32 m0, s4, 0x2000
	s_nop 0
	global_load_lds_dwordx4 v[150:151], off
	s_waitcnt vmcnt(6)
	s_barrier
	v_mfma_f32_16x16x32_bf16 v[52:55], v[212:215], v[174:177], v[52:55]
	v_mfma_f32_16x16x32_bf16 v[48:51], v[220:223], v[174:177], v[48:51]
	v_mfma_f32_16x16x32_bf16 v[36:39], v[212:215], v[188:191], v[36:39]
	v_mfma_f32_16x16x32_bf16 v[32:35], v[220:223], v[188:191], v[32:35]
	v_mfma_f32_16x16x32_bf16 v[20:23], v[212:215], v[196:199], v[20:23]
	v_mfma_f32_16x16x32_bf16 v[16:19], v[220:223], v[196:199], v[16:19]
	v_mfma_f32_16x16x32_bf16 v[4:7], v[212:215], v[204:207], v[4:7]
	v_mfma_f32_16x16x32_bf16 v[0:3], v[220:223], v[204:207], v[0:3]
	v_mfma_f32_16x16x32_bf16 v[52:55], v[216:219], v[178:181], v[52:55]
	v_mfma_f32_16x16x32_bf16 v[48:51], v[224:227], v[178:181], v[48:51]
	v_mfma_f32_16x16x32_bf16 v[36:39], v[216:219], v[192:195], v[36:39]
	v_mfma_f32_16x16x32_bf16 v[32:35], v[224:227], v[192:195], v[32:35]
	v_mfma_f32_16x16x32_bf16 v[20:23], v[216:219], v[200:203], v[20:23]
	v_mfma_f32_16x16x32_bf16 v[16:19], v[224:227], v[200:203], v[16:19]
	v_mfma_f32_16x16x32_bf16 v[4:7], v[216:219], v[208:211], v[4:7]
	v_mfma_f32_16x16x32_bf16 v[0:3], v[224:227], v[208:211], v[0:3]
	s_add_u32 s36, s36, 0x100
	s_addc_u32 s37, s37, 0
	s_add_u32 s44, s44, 0x100
	s_addc_u32 s45, s45, 0
	s_cmp_ge_i32 s5, s62
	s_mov_b32 s4, s5
	s_barrier
	s_cbranch_scc0 .LBB0_1598
	s_branch .Lpeel_exit_5
.LBB0_1598:
	s_add_i32 s5, s4, 2
	s_add_u32 s40, s36, 0x80
	s_addc_u32 s41, s37, 0
	s_add_i32 s79, s72, 0x100
	v_add_u32_e32 v149, s79, v140
	ds_read_b128 v[150:153], v149
	ds_read_b128 v[154:157], v149 offset:1024
	ds_read_b128 v[158:161], v149 offset:2048
	ds_read_b128 v[170:173], v149 offset:3072
	s_cmp_eq_u32 s67, s4
	s_cselect_b32 s41, s17, s41
	s_cselect_b32 s40, s16, s40
	s_cselect_b32 s43, s19, s45
	s_cselect_b32 s42, s18, s44
	v_lshl_add_u64 v[162:163], s[36:37], 0, v[134:135]
	s_add_i32 m0, s58, 0xc000
	ds_read_b128 v[174:177], v141
	ds_read_b128 v[178:181], v141 offset:1024
	ds_read_b128 v[188:191], v141 offset:2048
	ds_read_b128 v[192:195], v141 offset:3072
	ds_read_b128 v[196:199], v141 offset:4096
	ds_read_b128 v[200:203], v141 offset:5120
	ds_read_b128 v[204:207], v141 offset:6144
	ds_read_b128 v[208:211], v141 offset:7168
	global_load_lds_dwordx4 v[162:163], off
	v_lshl_add_u64 v[162:163], s[36:37], 0, v[136:137]
	s_add_i32 m0, s58, 0xe000
	s_nop 0
	global_load_lds_dwordx4 v[162:163], off
	s_waitcnt lgkmcnt(8)
	s_barrier
	s_waitcnt lgkmcnt(0)
	s_waitcnt lgkmcnt(0)
	v_mfma_f32_16x16x32_bf16 v[124:127], v[150:153], v[174:177], v[124:127]
	v_mfma_f32_16x16x32_bf16 v[120:123], v[158:161], v[174:177], v[120:123]
	v_mfma_f32_16x16x32_bf16 v[108:111], v[150:153], v[188:191], v[108:111]
	v_mfma_f32_16x16x32_bf16 v[104:107], v[158:161], v[188:191], v[104:107]
	v_mfma_f32_16x16x32_bf16 v[92:95], v[150:153], v[196:199], v[92:95]
	v_mfma_f32_16x16x32_bf16 v[88:91], v[158:161], v[196:199], v[88:91]
	v_mfma_f32_16x16x32_bf16 v[76:79], v[150:153], v[204:207], v[76:79]
	v_mfma_f32_16x16x32_bf16 v[72:75], v[158:161], v[204:207], v[72:75]
	v_mfma_f32_16x16x32_bf16 v[124:127], v[154:157], v[178:181], v[124:127]
	v_mfma_f32_16x16x32_bf16 v[120:123], v[170:173], v[178:181], v[120:123]
	v_mfma_f32_16x16x32_bf16 v[108:111], v[154:157], v[192:195], v[108:111]
	v_mfma_f32_16x16x32_bf16 v[104:107], v[170:173], v[192:195], v[104:107]
	v_mfma_f32_16x16x32_bf16 v[92:95], v[154:157], v[200:203], v[92:95]
	v_mfma_f32_16x16x32_bf16 v[88:91], v[170:173], v[200:203], v[88:91]
	v_mfma_f32_16x16x32_bf16 v[76:79], v[154:157], v[208:211], v[76:79]
	v_mfma_f32_16x16x32_bf16 v[72:75], v[170:173], v[208:211], v[72:75]
	s_barrier
	s_add_i32 s4, s73, 0x100
	s_add_i32 s79, s79, s50
	v_add_u32_e32 v149, s4, v140
	v_lshl_add_u64 v[162:163], s[42:43], 0, v[166:167]
	s_mov_b32 m0, s79
	ds_read_b128 v[212:215], v149
	ds_read_b128 v[216:219], v149 offset:1024
	ds_read_b128 v[220:223], v149 offset:2048
	ds_read_b128 v[224:227], v149 offset:3072
	global_load_lds_dwordx4 v[162:163], off
	v_lshl_add_u64 v[182:183], s[42:43], 0, v[128:129]
	s_add_i32 m0, s79, 0x2000
	s_nop 0
	global_load_lds_dwordx4 v[182:183], off
	s_barrier
; #define PG8_STAGE(bufoff, gbase, voff) do { _Pragma("unroll") for (int _i = 0; _i < 2; ++_i) \
;         __builtin_amdgcn_global_load_lds((const unsigned*)((const char*)(gbase) + (voff)[_i]), (LAS unsigned*)(lds + (bufoff) + ldsw + _i * 8192), 16, 0, 0); } while (0)
; #define PG8_LDA(dst, b, h) do { _Pragma("unroll") for (int m = 0; m < 4; ++m) _Pragma("unroll") for (int k = 0; k < 2; ++k) dst[m][k] = *(const LAS bf16x8*)(lds + PG8_SA(b, h) + aoff + m * 2048 + k * 1024); } while (0)
; #define PG8_LDB(dst, b, h) do { _Pragma("unroll") for (int n = 0; n < 2; ++n) _Pragma("unroll") for (int k = 0; k < 2; ++k) dst[n][k] = *(const LAS bf16x8*)(lds + PG8_SB(b, h) + boff + n * 2048 + k * 1024); } while (0)
; #define PG8_WAIT_V(n) asm volatile("s_waitcnt vmcnt(" #n ")" ::: "memory")
; #define PG8_WAIT_L(n) asm volatile("s_waitcnt lgkmcnt(" #n ")" ::: "memory")
; #define PG8_BAR __builtin_amdgcn_s_barrier()
; #define PG8_SCHED __builtin_amdgcn_sched_barrier(0)
; template <class Epi>
; DI void gemm_phase(LAS unsigned char* lds, const Gemm g, const StaticOrder& S, const Epi& E) {
;     ...
;             PG8_LDB(B0, 0, 0); PG8_SCHED; PG8_LDA(At, 0, 0); PG8_STAGE(PG8_SA(1, 1), a1 + hstep, voffA);
;             PG8_WAIT_L(8); PG8_BAR; PG8_WAIT_L(0); PG8_MMA(0, 0, At, B0); PG8_BAR; PG8_SCHED;
;             PG8_LDB(B1, 0, 1); PG8_STAGE(PG8_SB(0, 0), b2, voffB);
;             PG8_BAR; PG8_WAIT_L(0); PG8_MMA(0, 1, At, B1); PG8_BAR;
;             PG8_LDA(At, 0, 1); PG8_STAGE(PG8_SA(0, 0), a2, voffA);
;             PG8_BAR; PG8_WAIT_L(0); PG8_MMA(1, 0, At, B0); PG8_BAR; PG8_SCHED;
;             PG8_STAGE(PG8_SB(0, 1), b2 + hstep, voffB);
;             PG8_WAIT_V(6); PG8_BAR; PG8_MMA(1, 1, At, B1); PG8_BAR;
;             PG8_LDB(B0, 1, 0); PG8_SCHED; PG8_LDA(At, 1, 0); PG8_STAGE(PG8_SA(0, 1), a2 + hstep, voffA);
;             PG8_WAIT_L(8); PG8_BAR; PG8_WAIT_L(0); PG8_MMA(0, 0, At, B0); PG8_BAR; PG8_SCHED;
;             PG8_LDB(B1, 1, 1); PG8_STAGE(PG8_SB(1, 0), b3, voffB);
;             PG8_BAR; PG8_WAIT_L(0); PG8_MMA(0, 1, At, B1); PG8_BAR;
;             PG8_LDA(At, 1, 1); PG8_STAGE(PG8_SA(1, 0), a3, voffA);
;             PG8_BAR; PG8_WAIT_L(0); PG8_MMA(1, 0, At, B0); PG8_BAR; PG8_SCHED;
;             PG8_STAGE(PG8_SB(1, 1), b3 + hstep, voffB);
;             PG8_WAIT_V(6); PG8_BAR; PG8_MMA(1, 1, At, B1); PG8_BAR;
	s_waitcnt lgkmcnt(0)
	s_waitcnt lgkmcnt(0)
	v_mfma_f32_16x16x32_bf16 v[116:119], v[212:215], v[174:177], v[116:119]
	v_mfma_f32_16x16x32_bf16 v[112:115], v[220:223], v[174:177], v[112:115]
	v_mfma_f32_16x16x32_bf16 v[100:103], v[212:215], v[188:191], v[100:103]
	v_mfma_f32_16x16x32_bf16 v[96:99], v[220:223], v[188:191], v[96:99]
	v_mfma_f32_16x16x32_bf16 v[84:87], v[212:215], v[196:199], v[84:87]
	v_mfma_f32_16x16x32_bf16 v[80:83], v[220:223], v[196:199], v[80:83]
	v_mfma_f32_16x16x32_bf16 v[68:71], v[212:215], v[204:207], v[68:71]
	v_mfma_f32_16x16x32_bf16 v[64:67], v[220:223], v[204:207], v[64:67]
	v_mfma_f32_16x16x32_bf16 v[116:119], v[216:219], v[178:181], v[116:119]
	v_mfma_f32_16x16x32_bf16 v[112:115], v[224:227], v[178:181], v[112:115]
	v_mfma_f32_16x16x32_bf16 v[100:103], v[216:219], v[192:195], v[100:103]
	v_mfma_f32_16x16x32_bf16 v[96:99], v[224:227], v[192:195], v[96:99]
	v_mfma_f32_16x16x32_bf16 v[84:87], v[216:219], v[200:203], v[84:87]
	v_mfma_f32_16x16x32_bf16 v[80:83], v[224:227], v[200:203], v[80:83]
	v_mfma_f32_16x16x32_bf16 v[68:71], v[216:219], v[208:211], v[68:71]
	v_mfma_f32_16x16x32_bf16 v[64:67], v[224:227], v[208:211], v[64:67]
	s_mov_b32 m0, s58
	v_lshl_add_u64 v[228:229], s[40:41], 0, v[132:133]
	s_barrier
	ds_read_b128 v[174:177], v141 offset:16384
	ds_read_b128 v[178:181], v141 offset:17408
	ds_read_b128 v[188:191], v141 offset:18432
	ds_read_b128 v[192:195], v141 offset:19456
	ds_read_b128 v[196:199], v141 offset:20480
	ds_read_b128 v[200:203], v141 offset:21504
	ds_read_b128 v[204:207], v141 offset:22528
	ds_read_b128 v[208:211], v141 offset:23552
	global_load_lds_dwordx4 v[228:229], off
	v_lshl_add_u64 v[230:231], s[40:41], 0, v[130:131]
	s_mov_b32 m0, s59
	s_nop 0
	global_load_lds_dwordx4 v[230:231], off
	s_barrier
	s_waitcnt lgkmcnt(0)
	s_waitcnt lgkmcnt(0)
	v_mfma_f32_16x16x32_bf16 v[60:63], v[150:153], v[174:177], v[60:63]
	v_mfma_f32_16x16x32_bf16 v[56:59], v[158:161], v[174:177], v[56:59]
	v_mfma_f32_16x16x32_bf16 v[44:47], v[150:153], v[188:191], v[44:47]
	v_mfma_f32_16x16x32_bf16 v[40:43], v[158:161], v[188:191], v[40:43]
	v_mfma_f32_16x16x32_bf16 v[28:31], v[150:153], v[196:199], v[28:31]
	v_mfma_f32_16x16x32_bf16 v[24:27], v[158:161], v[196:199], v[24:27]
	v_mfma_f32_16x16x32_bf16 v[12:15], v[150:153], v[204:207], v[12:15]
	v_mfma_f32_16x16x32_bf16 v[8:11], v[158:161], v[204:207], v[8:11]
	v_mfma_f32_16x16x32_bf16 v[60:63], v[154:157], v[178:181], v[60:63]
	v_mfma_f32_16x16x32_bf16 v[56:59], v[170:173], v[178:181], v[56:59]
	v_mfma_f32_16x16x32_bf16 v[44:47], v[154:157], v[192:195], v[44:47]
	v_mfma_f32_16x16x32_bf16 v[40:43], v[170:173], v[192:195], v[40:43]
	v_mfma_f32_16x16x32_bf16 v[28:31], v[154:157], v[200:203], v[28:31]
	v_mfma_f32_16x16x32_bf16 v[24:27], v[170:173], v[200:203], v[24:27]
	v_mfma_f32_16x16x32_bf16 v[12:15], v[154:157], v[208:211], v[12:15]
	v_mfma_f32_16x16x32_bf16 v[8:11], v[170:173], v[208:211], v[8:11]
	s_barrier
	s_add_u32 s42, s42, s10
	s_addc_u32 s43, s43, s11
	s_add_i32 s4, s4, s50
	v_lshl_add_u64 v[232:233], s[42:43], 0, v[166:167]
	s_mov_b32 m0, s4
	v_lshl_add_u64 v[234:235], s[42:43], 0, v[128:129]
	global_load_lds_dwordx4 v[232:233], off
	s_add_i32 m0, s4, 0x2000
	s_nop 0
	global_load_lds_dwordx4 v[234:235], off
	s_waitcnt vmcnt(6)
	s_barrier
	v_mfma_f32_16x16x32_bf16 v[52:55], v[212:215], v[174:177], v[52:55]
	v_mfma_f32_16x16x32_bf16 v[48:51], v[220:223], v[174:177], v[48:51]
	v_mfma_f32_16x16x32_bf16 v[36:39], v[212:215], v[188:191], v[36:39]
	v_mfma_f32_16x16x32_bf16 v[32:35], v[220:223], v[188:191], v[32:35]
	v_mfma_f32_16x16x32_bf16 v[20:23], v[212:215], v[196:199], v[20:23]
	v_mfma_f32_16x16x32_bf16 v[16:19], v[220:223], v[196:199], v[16:19]
	v_mfma_f32_16x16x32_bf16 v[4:7], v[212:215], v[204:207], v[4:7]
	v_mfma_f32_16x16x32_bf16 v[0:3], v[220:223], v[204:207], v[0:3]
	v_mfma_f32_16x16x32_bf16 v[52:55], v[216:219], v[178:181], v[52:55]
	v_mfma_f32_16x16x32_bf16 v[48:51], v[224:227], v[178:181], v[48:51]
	v_mfma_f32_16x16x32_bf16 v[36:39], v[216:219], v[192:195], v[36:39]
	v_mfma_f32_16x16x32_bf16 v[32:35], v[224:227], v[192:195], v[32:35]
	v_mfma_f32_16x16x32_bf16 v[20:23], v[216:219], v[200:203], v[20:23]
	v_mfma_f32_16x16x32_bf16 v[16:19], v[224:227], v[200:203], v[16:19]
	v_mfma_f32_16x16x32_bf16 v[4:7], v[216:219], v[208:211], v[4:7]
	v_mfma_f32_16x16x32_bf16 v[0:3], v[224:227], v[208:211], v[0:3]
	s_add_i32 s4, s74, 0x100
	v_add_u32_e32 v149, s4, v140
	s_barrier
	ds_read_b128 v[150:153], v149
	ds_read_b128 v[154:157], v149 offset:1024
	ds_read_b128 v[158:161], v149 offset:2048
	ds_read_b128 v[170:173], v149 offset:3072
	s_add_u32 s40, s40, s10
	s_addc_u32 s41, s41, s11
	s_mov_b32 m0, s60
	v_lshl_add_u64 v[212:213], s[40:41], 0, v[132:133]
	ds_read_b128 v[174:177], v141 offset:32768
	ds_read_b128 v[178:181], v141 offset:33792
	ds_read_b128 v[188:191], v141 offset:34816
	ds_read_b128 v[192:195], v141 offset:35840
	ds_read_b128 v[196:199], v141 offset:36864
	ds_read_b128 v[200:203], v141 offset:37888
	ds_read_b128 v[204:207], v141 offset:38912
	ds_read_b128 v[208:211], v141 offset:39936
	global_load_lds_dwordx4 v[212:213], off
	v_lshl_add_u64 v[212:213], s[40:41], 0, v[130:131]
	s_mov_b32 m0, s61
	s_nop 0
	global_load_lds_dwordx4 v[212:213], off
	s_waitcnt lgkmcnt(8)
	s_barrier
; #define PG8_STAGE(bufoff, gbase, voff) do { _Pragma("unroll") for (int _i = 0; _i < 2; ++_i) \
;         __builtin_amdgcn_global_load_lds((const unsigned*)((const char*)(gbase) + (voff)[_i]), (LAS unsigned*)(lds + (bufoff) + ldsw + _i * 8192), 16, 0, 0); } while (0)
; #define PG8_LDA(dst, b, h) do { _Pragma("unroll") for (int m = 0; m < 4; ++m) _Pragma("unroll") for (int k = 0; k < 2; ++k) dst[m][k] = *(const LAS bf16x8*)(lds + PG8_SA(b, h) + aoff + m * 2048 + k * 1024); } while (0)
; #define PG8_LDB(dst, b, h) do { _Pragma("unroll") for (int n = 0; n < 2; ++n) _Pragma("unroll") for (int k = 0; k < 2; ++k) dst[n][k] = *(const LAS bf16x8*)(lds + PG8_SB(b, h) + boff + n * 2048 + k * 1024); } while (0)
; #define PG8_WAIT_V(n) asm volatile("s_waitcnt vmcnt(" #n ")" ::: "memory")
; #define PG8_WAIT_L(n) asm volatile("s_waitcnt lgkmcnt(" #n ")" ::: "memory")
; #define PG8_BAR __builtin_amdgcn_s_barrier()
; #define PG8_SCHED __builtin_amdgcn_sched_barrier(0)
; template <class Epi>
; DI void gemm_phase(LAS unsigned char* lds, const Gemm g, const StaticOrder& S, const Epi& E) {
;     ...
;             PG8_LDB(B0, 0, 0); PG8_SCHED; PG8_LDA(At, 0, 0); PG8_STAGE(PG8_SA(1, 1), a1 + hstep, voffA);
;             PG8_WAIT_L(8); PG8_BAR; PG8_WAIT_L(0); PG8_MMA(0, 0, At, B0); PG8_BAR; PG8_SCHED;
;             PG8_LDB(B1, 0, 1); PG8_STAGE(PG8_SB(0, 0), b2, voffB);
;             PG8_BAR; PG8_WAIT_L(0); PG8_MMA(0, 1, At, B1); PG8_BAR;
;             PG8_LDA(At, 0, 1); PG8_STAGE(PG8_SA(0, 0), a2, voffA);
;             PG8_BAR; PG8_WAIT_L(0); PG8_MMA(1, 0, At, B0); PG8_BAR; PG8_SCHED;
;             PG8_STAGE(PG8_SB(0, 1), b2 + hstep, voffB);
;             PG8_WAIT_V(6); PG8_BAR; PG8_MMA(1, 1, At, B1); PG8_BAR;
;             PG8_LDB(B0, 1, 0); PG8_SCHED; PG8_LDA(At, 1, 0); PG8_STAGE(PG8_SA(0, 1), a2 + hstep, voffA);
;             PG8_WAIT_L(8); PG8_BAR; PG8_WAIT_L(0); PG8_MMA(0, 0, At, B0); PG8_BAR; PG8_SCHED;
;             PG8_LDB(B1, 1, 1); PG8_STAGE(PG8_SB(1, 0), b3, voffB);
;             PG8_BAR; PG8_WAIT_L(0); PG8_MMA(0, 1, At, B1); PG8_BAR;
;             PG8_LDA(At, 1, 1); PG8_STAGE(PG8_SA(1, 0), a3, voffA);
;             PG8_BAR; PG8_WAIT_L(0); PG8_MMA(1, 0, At, B0); PG8_BAR; PG8_SCHED;
;             PG8_STAGE(PG8_SB(1, 1), b3 + hstep, voffB);
;             PG8_WAIT_V(6); PG8_BAR; PG8_MMA(1, 1, At, B1); PG8_BAR;
	s_waitcnt lgkmcnt(0)
	s_waitcnt lgkmcnt(0)
	v_mfma_f32_16x16x32_bf16 v[124:127], v[150:153], v[174:177], v[124:127]
	v_mfma_f32_16x16x32_bf16 v[120:123], v[158:161], v[174:177], v[120:123]
	v_mfma_f32_16x16x32_bf16 v[108:111], v[150:153], v[188:191], v[108:111]
	v_mfma_f32_16x16x32_bf16 v[104:107], v[158:161], v[188:191], v[104:107]
	v_mfma_f32_16x16x32_bf16 v[92:95], v[150:153], v[196:199], v[92:95]
	v_mfma_f32_16x16x32_bf16 v[88:91], v[158:161], v[196:199], v[88:91]
	v_mfma_f32_16x16x32_bf16 v[76:79], v[150:153], v[204:207], v[76:79]
	v_mfma_f32_16x16x32_bf16 v[72:75], v[158:161], v[204:207], v[72:75]
	v_mfma_f32_16x16x32_bf16 v[124:127], v[154:157], v[178:181], v[124:127]
	v_mfma_f32_16x16x32_bf16 v[120:123], v[170:173], v[178:181], v[120:123]
	v_mfma_f32_16x16x32_bf16 v[108:111], v[154:157], v[192:195], v[108:111]
	v_mfma_f32_16x16x32_bf16 v[104:107], v[170:173], v[192:195], v[104:107]
	v_mfma_f32_16x16x32_bf16 v[92:95], v[154:157], v[200:203], v[92:95]
	v_mfma_f32_16x16x32_bf16 v[88:91], v[170:173], v[200:203], v[88:91]
	v_mfma_f32_16x16x32_bf16 v[76:79], v[154:157], v[208:211], v[76:79]
	v_mfma_f32_16x16x32_bf16 v[72:75], v[170:173], v[208:211], v[72:75]
	s_barrier
	s_add_i32 s40, s75, 0x100
	s_add_i32 s4, s4, s50
	v_add_u32_e32 v149, s40, v140
	v_lshl_add_u64 v[162:163], v[162:163], 0, s[76:77]
	s_mov_b32 m0, s4
	ds_read_b128 v[212:215], v149
	ds_read_b128 v[216:219], v149 offset:1024
	ds_read_b128 v[220:223], v149 offset:2048
	ds_read_b128 v[224:227], v149 offset:3072
	global_load_lds_dwordx4 v[162:163], off
	v_lshl_add_u64 v[162:163], v[182:183], 0, s[76:77]
	s_add_i32 m0, s4, 0x2000
	s_nop 0
	global_load_lds_dwordx4 v[162:163], off
	s_barrier
	s_waitcnt lgkmcnt(0)
	s_waitcnt lgkmcnt(0)
	v_mfma_f32_16x16x32_bf16 v[116:119], v[212:215], v[174:177], v[116:119]
	v_mfma_f32_16x16x32_bf16 v[112:115], v[220:223], v[174:177], v[112:115]
	v_mfma_f32_16x16x32_bf16 v[100:103], v[212:215], v[188:191], v[100:103]
	v_mfma_f32_16x16x32_bf16 v[96:99], v[220:223], v[188:191], v[96:99]
	v_mfma_f32_16x16x32_bf16 v[84:87], v[212:215], v[196:199], v[84:87]
	v_mfma_f32_16x16x32_bf16 v[80:83], v[220:223], v[196:199], v[80:83]
	v_mfma_f32_16x16x32_bf16 v[68:71], v[212:215], v[204:207], v[68:71]
	v_mfma_f32_16x16x32_bf16 v[64:67], v[220:223], v[204:207], v[64:67]
	v_mfma_f32_16x16x32_bf16 v[116:119], v[216:219], v[178:181], v[116:119]
	v_mfma_f32_16x16x32_bf16 v[112:115], v[224:227], v[178:181], v[112:115]
	v_mfma_f32_16x16x32_bf16 v[100:103], v[216:219], v[192:195], v[100:103]
	v_mfma_f32_16x16x32_bf16 v[96:99], v[224:227], v[192:195], v[96:99]
	v_mfma_f32_16x16x32_bf16 v[84:87], v[216:219], v[200:203], v[84:87]
	v_mfma_f32_16x16x32_bf16 v[80:83], v[224:227], v[200:203], v[80:83]
	v_mfma_f32_16x16x32_bf16 v[68:71], v[216:219], v[208:211], v[68:71]
	v_mfma_f32_16x16x32_bf16 v[64:67], v[224:227], v[208:211], v[64:67]
	s_mov_b32 m0, s65
	v_lshl_add_u64 v[162:163], v[228:229], 0, s[76:77]
	s_barrier
	ds_read_b128 v[174:177], v141 offset:49152
	ds_read_b128 v[178:181], v141 offset:50176
	ds_read_b128 v[188:191], v141 offset:51200
	ds_read_b128 v[192:195], v141 offset:52224
	ds_read_b128 v[196:199], v141 offset:53248
	ds_read_b128 v[200:203], v141 offset:54272
	ds_read_b128 v[204:207], v141 offset:55296
	ds_read_b128 v[208:211], v141 offset:56320
	global_load_lds_dwordx4 v[162:163], off
	v_lshl_add_u64 v[162:163], v[230:231], 0, s[76:77]
	s_mov_b32 m0, s66
	s_nop 0
	global_load_lds_dwordx4 v[162:163], off
	s_barrier
	s_waitcnt lgkmcnt(0)
	s_waitcnt lgkmcnt(0)
	v_mfma_f32_16x16x32_bf16 v[60:63], v[150:153], v[174:177], v[60:63]
	v_mfma_f32_16x16x32_bf16 v[56:59], v[158:161], v[174:177], v[56:59]
	v_mfma_f32_16x16x32_bf16 v[44:47], v[150:153], v[188:191], v[44:47]
	v_mfma_f32_16x16x32_bf16 v[40:43], v[158:161], v[188:191], v[40:43]
	v_mfma_f32_16x16x32_bf16 v[28:31], v[150:153], v[196:199], v[28:31]
	v_mfma_f32_16x16x32_bf16 v[24:27], v[158:161], v[196:199], v[24:27]
	v_mfma_f32_16x16x32_bf16 v[12:15], v[150:153], v[204:207], v[12:15]
	v_mfma_f32_16x16x32_bf16 v[8:11], v[158:161], v[204:207], v[8:11]
	v_mfma_f32_16x16x32_bf16 v[60:63], v[154:157], v[178:181], v[60:63]
	v_mfma_f32_16x16x32_bf16 v[56:59], v[170:173], v[178:181], v[56:59]
	v_mfma_f32_16x16x32_bf16 v[44:47], v[154:157], v[192:195], v[44:47]
	v_mfma_f32_16x16x32_bf16 v[40:43], v[170:173], v[192:195], v[40:43]
	v_mfma_f32_16x16x32_bf16 v[28:31], v[154:157], v[200:203], v[28:31]
	v_mfma_f32_16x16x32_bf16 v[24:27], v[170:173], v[200:203], v[24:27]
	v_mfma_f32_16x16x32_bf16 v[12:15], v[154:157], v[208:211], v[12:15]
	v_mfma_f32_16x16x32_bf16 v[8:11], v[170:173], v[208:211], v[8:11]
	s_barrier
	s_add_i32 s4, s40, s50
	v_lshl_add_u64 v[150:151], v[232:233], 0, s[76:77]
	s_mov_b32 m0, s4
	s_nop 0
	global_load_lds_dwordx4 v[150:151], off
	v_lshl_add_u64 v[150:151], v[234:235], 0, s[76:77]
	s_add_i32 m0, s4, 0x2000
	s_nop 0
	global_load_lds_dwordx4 v[150:151], off
	s_waitcnt vmcnt(6)
	s_barrier
	v_mfma_f32_16x16x32_bf16 v[52:55], v[212:215], v[174:177], v[52:55]
	v_mfma_f32_16x16x32_bf16 v[48:51], v[220:223], v[174:177], v[48:51]
	v_mfma_f32_16x16x32_bf16 v[36:39], v[212:215], v[188:191], v[36:39]
	v_mfma_f32_16x16x32_bf16 v[32:35], v[220:223], v[188:191], v[32:35]
	v_mfma_f32_16x16x32_bf16 v[20:23], v[212:215], v[196:199], v[20:23]
	v_mfma_f32_16x16x32_bf16 v[16:19], v[220:223], v[196:199], v[16:19]
	v_mfma_f32_16x16x32_bf16 v[4:7], v[212:215], v[204:207], v[4:7]
	v_mfma_f32_16x16x32_bf16 v[0:3], v[220:223], v[204:207], v[0:3]
	v_mfma_f32_16x16x32_bf16 v[52:55], v[216:219], v[178:181], v[52:55]
	v_mfma_f32_16x16x32_bf16 v[48:51], v[224:227], v[178:181], v[48:51]
	v_mfma_f32_16x16x32_bf16 v[36:39], v[216:219], v[192:195], v[36:39]
	v_mfma_f32_16x16x32_bf16 v[32:35], v[224:227], v[192:195], v[32:35]
	v_mfma_f32_16x16x32_bf16 v[20:23], v[216:219], v[200:203], v[20:23]
	v_mfma_f32_16x16x32_bf16 v[16:19], v[224:227], v[200:203], v[16:19]
	v_mfma_f32_16x16x32_bf16 v[4:7], v[216:219], v[208:211], v[4:7]
	v_mfma_f32_16x16x32_bf16 v[0:3], v[224:227], v[208:211], v[0:3]
	s_add_u32 s36, s36, 0x100
	s_addc_u32 s37, s37, 0
	s_add_u32 s44, s44, 0x100
	s_addc_u32 s45, s45, 0
	s_cmp_ge_i32 s5, s62
	s_mov_b32 s4, s5
	s_barrier
	s_cbranch_scc0 .LBB0_1598

; #define PG8_WAIT_V(n) asm volatile("s_waitcnt vmcnt(" #n ")" ::: "memory")
; #define PG8_BAR __builtin_amdgcn_s_barrier()
; template <class Epi>
; DI void gemm_phase(LAS unsigned char* lds, const Gemm g, const StaticOrder& S, const Epi& E) {
;     ...
;     PG8_WAIT_V(0);
;     if (wr == 0) PG8_BAR;
;     PG8_BAR;
.LBB0_1602:
	v_readlane_b32 s48, v236, 25
	v_readlane_b32 s70, v236, 21
	v_readlane_b32 s68, v237, 60
	v_readlane_b32 s49, v236, 26
	v_readlane_b32 s71, v236, 22
	s_barrier
	s_setprio 0
	v_readlane_b32 s69, v237, 61

; #define PG8_STAGE(bufoff, gbase, voff) do { _Pragma("unroll") for (int _i = 0; _i < 2; ++_i) \
;         __builtin_amdgcn_global_load_lds((const unsigned*)((const char*)(gbase) + (voff)[_i]), (LAS unsigned*)(lds + (bufoff) + ldsw + _i * 8192), 16, 0, 0); } while (0)
; #define PG8_BAR __builtin_amdgcn_s_barrier()
; template <class Epi>
; DI void gemm_phase(LAS unsigned char* lds, const Gemm g, const StaticOrder& S, const Epi& E) {
;     ...
;     for (int i = 0; i < 2; ++i) { int R, C; stage_rc(tid * 16 + i * 8192, R, C); const int Rb = (R & ~31) + perm32(R & 31);
;         voffA[i] = (unsigned)(R * K + C) * 2u; voffB[i] = (unsigned)(Rb * K + C) * 2u; }
;     const size_t kstep = (size_t)(BK * 2);
;     const size_t hstep = (size_t)HALF * K * 2;
;     const size_t tstep = 2 * hstep;
;     const unsigned ldsw = (unsigned)wid * 1024u;
;     const int aoff = lds_byte(wr * 64 + fr, fq * 8), boff = lds_byte(wc * 32 + fr, fq * 8);
;     ...
;     Unit cur, nxt; int ui = 0;
;     if (!S.next(0, cur)) return;
;     f32x4 acc[2][2][4][2];
; #pragma unroll
;     for (int a = 0; a < 2; ++a)
; #pragma unroll
;         for (int b = 0; b < 2; ++b)
; #pragma unroll
;             for (int m = 0; m < 4; ++m)
; #pragma unroll
;                 for (int n = 0; n < 2; ++n) acc[a][b][m][n] = (f32x4){0.f, 0.f, 0.f, 0.f};
;     bf16x8 At[4][2], B0[2][2], B1[2][2];
;     const char* cA = (const char*)g.A + (size_t)cur.pm * tstep; const char* cB = (const char*)g.Bt + (size_t)cur.pn * tstep;
;     PG8_STAGE(PG8_SB(0, 0), cB, voffB); PG8_STAGE(PG8_SA(0, 0), cA, voffA); PG8_STAGE(PG8_SB(0, 1), cB + hstep, voffB); PG8_STAGE(PG8_SA(0, 1), cA + hstep, voffA);
;     if (wr == 1) PG8_BAR;
.LBB0_1657:
	v_readlane_b32 s2, v236, 35
	v_readlane_b32 s3, v236, 36
	s_and_b64 s[2:3], s[2:3], exec
	v_readlane_b32 s52, v238, 1
	v_readlane_b32 s54, v238, 3
	v_readlane_b32 s55, v238, 4
	v_readlane_b32 s2, v237, 48
	v_readlane_b32 s64, v238, 13
	v_readlane_b32 s65, v238, 14
	v_readlane_b32 s66, v238, 15
	v_readlane_b32 s67, v238, 16
	v_readlane_b32 s3, v237, 49
	v_readlane_b32 s54, v236, 29
	s_cselect_b32 s3, s3, s65
	s_cselect_b32 s2, s2, s64
	s_andn2_b64 vcc, exec, s[12:13]
	s_mov_b32 s64, 0x18000
	s_mov_b64 s[66:67], 0x80
	v_readlane_b32 s55, v236, 30
	v_readlane_b32 s53, v238, 2
	v_readlane_b32 s56, v238, 5
	v_readlane_b32 s57, v238, 6
	v_readlane_b32 s58, v238, 7
	v_readlane_b32 s59, v238, 8
	v_readlane_b32 s60, v238, 9
	v_readlane_b32 s61, v238, 10
	v_readlane_b32 s62, v238, 11
	v_readlane_b32 s63, v238, 12
	s_cbranch_vccnz .LBB0_1690
	v_bfe_i32 v2, v18, 27, 1
	v_lshlrev_b32_e32 v0, 4, v18
	v_lshrrev_b32_e32 v2, 22, v2
	v_add_u32_e32 v2, v0, v2
	v_and_b32_e32 v2, 0xfffffc00, v2
	v_ashrrev_i32_e32 v1, 31, v18
	v_sub_u32_e32 v2, v0, v2
	v_lshrrev_b32_e32 v1, 26, v1
	v_lshrrev_b32_e32 v3, 4, v2
	v_add_u32_e32 v1, v18, v1
	v_bitop3_b32 v3, v3, v2, 32 bitop3:0x6c
	v_ashrrev_i32_e32 v2, 31, v2
	v_ashrrev_i32_e32 v1, 6, v1
	v_lshrrev_b32_e32 v2, 26, v2
	v_lshlrev_b32_e32 v4, 3, v1
	v_add_u32_e32 v2, v3, v2
	v_and_b32_e32 v4, -16, v4
	v_ashrrev_i32_e32 v2, 6, v2
	v_lshlrev_b32_e32 v1, 5, v1
	v_add_u32_e32 v4, v2, v4
	v_and_b32_e32 v12, 32, v1
	v_mul_i32_i24_e32 v1, 64, v2
	v_sub_u32_e32 v1, v3, v1
	v_lshlrev_b32_e32 v3, 1, v4
	v_lshrrev_b32_e32 v5, 2, v4
	v_and_b32_e32 v2, 3, v2
	s_mov_b32 s5, 0x7fffffe0
	v_ashrrev_i16_sdwa v1, v169, sext(v1) dst_sel:DWORD dst_unused:UNUSED_PAD src0_sel:DWORD src1_sel:BYTE_0
	v_and_b32_e32 v3, 24, v3
	v_and_b32_e32 v5, 4, v5
	v_and_or_b32 v2, v4, s5, v2
	v_bfe_i32 v13, v1, 0, 16
	v_or3_b32 v2, v2, v5, v3
	v_add_u32_e32 v1, v12, v13
	v_mul_lo_u32 v14, v4, s16
	v_mul_lo_u32 v2, v2, s16
	v_add_u32_e32 v0, 0x2000, v0
	v_add_lshl_u32 v128, v1, v14, 1
	v_add_lshl_u32 v166, v2, v1, 1
	v_ashrrev_i32_e32 v1, 31, v0
	v_lshrrev_b32_e32 v1, 22, v1
	v_add_u32_e32 v1, v0, v1
	v_ashrrev_i32_e32 v1, 10, v1
	v_mul_i32_i24_e32 v2, 0x400, v1
	v_sub_u32_e32 v0, v0, v2
	v_readlane_b32 s4, v236, 31
	v_lshrrev_b32_e32 v2, 4, v0
	s_add_u32 s33, s4, 0x1b50000
	v_readlane_b32 s4, v236, 32
	v_bitop3_b32 v0, v2, v0, 32 bitop3:0x6c
	s_addc_u32 s52, s4, 0
	v_ashrrev_i32_e32 v3, 31, v0
	s_ashr_i32 s17, s16, 31
	v_lshrrev_b32_e32 v3, 26, v3
	s_lshl_b64 s[14:15], s[16:17], 9
	s_ashr_i32 s11, s89, 31
	v_lshlrev_b32_e32 v2, 3, v1
	v_add_u32_e32 v3, v0, v3
	s_mul_i32 s11, s14, s11
	s_mul_hi_u32 s18, s14, s89
	s_ashr_i32 s36, s88, 31
	v_and_b32_e32 v2, -16, v2
	v_ashrrev_i32_e32 v4, 6, v3
	s_add_i32 s11, s18, s11
	s_lshr_b64 s[18:19], s[16:17], 23
	s_mul_i32 s36, s14, s36
	s_mul_hi_u32 s37, s14, s88
	s_ashr_i32 s4, s50, 6
	v_add_u32_e32 v2, v4, v2
	v_lshlrev_b32_e32 v1, 5, v1
	v_and_b32_e32 v4, 3, v4
	s_mul_i32 s19, s18, s89
	s_add_i32 s36, s37, s36
	s_mul_i32 s18, s18, s88
	v_and_b32_e32 v15, 32, v1
	v_and_b32_e32 v1, 0xc0, v3
	v_and_or_b32 v4, v2, s5, v4
	s_ashr_i32 s5, s50, 8
	s_lshl_b64 s[12:13], s[16:17], 8
	s_lshl_b32 s53, s4, 10
	s_add_i32 s11, s11, s19
	s_add_i32 s36, s36, s18
	s_mul_i32 s18, s14, s88
	v_sub_u32_e32 v0, v0, v1
	v_lshlrev_b32_e32 v1, 1, v2
	v_lshrrev_b32_e32 v3, 2, v2
	s_add_u32 s44, s33, s18
	v_ashrrev_i16_sdwa v0, v169, sext(v0) dst_sel:DWORD dst_unused:UNUSED_PAD src0_sel:DWORD src1_sel:BYTE_0
	v_and_b32_e32 v1, 24, v1
	v_and_b32_e32 v3, 4, v3
	s_addc_u32 s45, s52, s36
	s_add_i32 s54, s53, 0x100
	v_bfe_i32 v16, v0, 0, 16
	v_or3_b32 v1, v4, v3, v1
	s_add_i32 m0, s54, 0x10000
	v_add_u32_e32 v0, v15, v16
	v_mul_lo_u32 v1, v1, s16
	s_mul_i32 s19, s14, s89
	global_load_lds_dwordx4 v166, s[44:45]
	s_add_i32 m0, s54, 0x12000
	v_readlane_b32 s36, v237, 53
	v_add_lshl_u32 v132, v1, v0, 1
	v_readlane_b32 s37, v237, 54
	s_add_u32 s46, s36, s19
	v_mul_lo_u32 v17, v2, s16
	global_load_lds_dwordx4 v132, s[44:45]
	s_addc_u32 s47, s37, s11
	s_mov_b32 m0, s54
	s_add_i32 s55, s54, 0x2000
	v_add_lshl_u32 v130, v0, v17, 1
	global_load_lds_dwordx4 v128, s[46:47]
	s_mov_b32 m0, s55
	s_add_u32 s18, s44, s12
	global_load_lds_dwordx4 v130, s[46:47]
	s_addc_u32 s19, s45, s13
	s_add_i32 m0, s54, 0x14000
	v_mov_b32_e32 v133, v167
	global_load_lds_dwordx4 v166, s[18:19]
	s_add_i32 m0, s54, 0x16000
	v_lshl_add_u64 v[8:9], s[18:19], 0, v[166:167]
	v_lshl_add_u64 v[10:11], s[18:19], 0, v[132:133]
	global_load_lds_dwordx4 v132, s[18:19]
	s_add_u32 s18, s46, s12
	s_addc_u32 s19, s47, s13
	s_add_i32 s56, s54, 0x4000
	s_mov_b32 m0, s56
	s_add_i32 s57, s54, 0x6000
	global_load_lds_dwordx4 v128, s[18:19]
	s_mov_b32 m0, s57
	v_mov_b32_e32 v129, v167
	global_load_lds_dwordx4 v130, s[18:19]
	v_mov_b32_e32 v131, v167
	v_lshl_add_u64 v[0:1], s[44:45], 0, v[166:167]
	v_lshl_add_u64 v[2:3], s[44:45], 0, v[132:133]
	v_lshl_add_u64 v[4:5], s[46:47], 0, v[128:129]
	v_lshl_add_u64 v[6:7], s[46:47], 0, v[130:131]
	s_cmp_lg_u32 s5, 1
	s_cbranch_scc1 .LBB0_1660
	s_setprio 1
	s_barrier

; #define PG8_STAGE(bufoff, gbase, voff) do { _Pragma("unroll") for (int _i = 0; _i < 2; ++_i) \
;         __builtin_amdgcn_global_load_lds((const unsigned*)((const char*)(gbase) + (voff)[_i]), (LAS unsigned*)(lds + (bufoff) + ldsw + _i * 8192), 16, 0, 0); } while (0)
; #define PG8_LDA(dst, b, h) do { _Pragma("unroll") for (int m = 0; m < 4; ++m) _Pragma("unroll") for (int k = 0; k < 2; ++k) dst[m][k] = *(const LAS bf16x8*)(lds + PG8_SA(b, h) + aoff + m * 2048 + k * 1024); } while (0)
; #define PG8_LDB(dst, b, h) do { _Pragma("unroll") for (int n = 0; n < 2; ++n) _Pragma("unroll") for (int k = 0; k < 2; ++k) dst[n][k] = *(const LAS bf16x8*)(lds + PG8_SB(b, h) + boff + n * 2048 + k * 1024); } while (0)
; #define PG8_WAIT_V(n) asm volatile("s_waitcnt vmcnt(" #n ")" ::: "memory")
; #define PG8_WAIT_L(n) asm volatile("s_waitcnt lgkmcnt(" #n ")" ::: "memory")
; template <class Epi>
; DI void gemm_phase(LAS unsigned char* lds, const Gemm g, const StaticOrder& S, const Epi& E) {
;     ...
;     for (;;) {
;         const bool has_next = S.next(ui + 1, nxt);
;         const char* nA = has_next ? (const char*)g.A + (size_t)nxt.pm * tstep : cA; const char* nB = has_next ? (const char*)g.Bt + (size_t)nxt.pn * tstep : cB;
;         for (int t = 0; t < nt; t += 2) {
;             const bool last = (t == nt - 2);
;             const char* a1 = cA + (size_t)(t + 1) * kstep;
;             const char* a2 = last ? nA : cA + (size_t)(t + 2) * kstep; const char* b2 = last ? nB : cB + (size_t)(t + 2) * kstep;
;             const char* a3 = a2 + kstep; const char* b3 = b2 + kstep;
;             PG8_LDB(B0, 0, 0); PG8_SCHED; PG8_LDA(At, 0, 0); PG8_STAGE(PG8_SA(1, 1), a1 + hstep, voffA);
;             PG8_WAIT_L(8); PG8_BAR; PG8_WAIT_L(0); PG8_MMA(0, 0, At, B0); PG8_BAR; PG8_SCHED;
;             PG8_LDB(B1, 0, 1); PG8_STAGE(PG8_SB(0, 0), b2, voffB);
;             PG8_BAR; PG8_WAIT_L(0); PG8_MMA(0, 1, At, B1); PG8_BAR;
;             PG8_LDA(At, 0, 1); PG8_STAGE(PG8_SA(0, 0), a2, voffA);
;             PG8_BAR; PG8_WAIT_L(0); PG8_MMA(1, 0, At, B0); PG8_BAR; PG8_SCHED;
;             PG8_STAGE(PG8_SB(0, 1), b2 + hstep, voffB);
;             PG8_WAIT_V(6); PG8_BAR; PG8_MMA(1, 1, At, B1); PG8_BAR;
;             PG8_LDB(B0, 1, 0); PG8_SCHED; PG8_LDA(At, 1, 0); PG8_STAGE(PG8_SA(0, 1), a2 + hstep, voffA);
;             PG8_WAIT_L(8); PG8_BAR; PG8_WAIT_L(0); PG8_MMA(0, 0, At, B0); PG8_BAR; PG8_SCHED;
.LBB0_1668:
	s_andn2_b64 vcc, exec, s[16:17]
	s_cbranch_vccnz .LBB0_1671
	s_add_u32 s40, s46, 0x80
	s_addc_u32 s41, s47, 0
	s_add_u32 s0, s44, 0x100
	s_addc_u32 s46, s45, 0
	s_mov_b32 s4, 0
	s_mov_b32 s72, 0x10000
	s_mov_b32 s73, 0x14000
	s_mov_b32 s74, 0x18000
	s_mov_b32 s75, 0x1c000
	s_mov_b64 s[76:77], 0x80
	s_add_i32 s5, s4, 2
	s_add_u32 s42, s40, 0x80
	s_addc_u32 s43, s41, 0
	s_add_i32 s47, s72, 0x100
	v_add_u32_e32 v153, s47, v151
	ds_read_b128 v[138:141], v153
	ds_read_b128 v[154:157], v153 offset:1024
	ds_read_b128 v[158:161], v153 offset:2048
	ds_read_b128 v[170:173], v153 offset:3072
	s_cmp_eq_u32 s64, s4
	s_cselect_b32 s43, s19, s43
	s_cselect_b32 s42, s18, s42
	s_cselect_b32 s45, s37, s46
	s_cselect_b32 s44, s36, s0
	v_lshl_add_u64 v[162:163], s[40:41], 0, v[134:135]
	s_add_i32 m0, s54, 0xc000
	ds_read_b128 v[174:177], v152
	ds_read_b128 v[178:181], v152 offset:1024
	ds_read_b128 v[188:191], v152 offset:2048
	ds_read_b128 v[192:195], v152 offset:3072
	ds_read_b128 v[196:199], v152 offset:4096
	ds_read_b128 v[200:203], v152 offset:5120
	ds_read_b128 v[204:207], v152 offset:6144
	ds_read_b128 v[208:211], v152 offset:7168
	global_load_lds_dwordx4 v[162:163], off
	v_lshl_add_u64 v[162:163], s[40:41], 0, v[136:137]
	s_add_i32 m0, s54, 0xe000
	s_nop 0
	global_load_lds_dwordx4 v[162:163], off
	s_waitcnt lgkmcnt(8)
	s_barrier
	s_waitcnt lgkmcnt(0)
	s_waitcnt lgkmcnt(0)
	v_mfma_f32_16x16x32_bf16 v[124:127], v[138:141], v[174:177], 0
	v_mfma_f32_16x16x32_bf16 v[120:123], v[158:161], v[174:177], 0
	v_mfma_f32_16x16x32_bf16 v[108:111], v[138:141], v[188:191], 0
	v_mfma_f32_16x16x32_bf16 v[104:107], v[158:161], v[188:191], 0
	v_mfma_f32_16x16x32_bf16 v[92:95], v[138:141], v[196:199], 0
	v_mfma_f32_16x16x32_bf16 v[88:91], v[158:161], v[196:199], 0
	v_mfma_f32_16x16x32_bf16 v[76:79], v[138:141], v[204:207], 0
	v_mfma_f32_16x16x32_bf16 v[72:75], v[158:161], v[204:207], 0
	v_mfma_f32_16x16x32_bf16 v[124:127], v[154:157], v[178:181], v[124:127]
	v_mfma_f32_16x16x32_bf16 v[120:123], v[170:173], v[178:181], v[120:123]
	v_mfma_f32_16x16x32_bf16 v[108:111], v[154:157], v[192:195], v[108:111]
	v_mfma_f32_16x16x32_bf16 v[104:107], v[170:173], v[192:195], v[104:107]
	v_mfma_f32_16x16x32_bf16 v[92:95], v[154:157], v[200:203], v[92:95]
	v_mfma_f32_16x16x32_bf16 v[88:91], v[170:173], v[200:203], v[88:91]
	v_mfma_f32_16x16x32_bf16 v[76:79], v[154:157], v[208:211], v[76:79]
	v_mfma_f32_16x16x32_bf16 v[72:75], v[170:173], v[208:211], v[72:75]
	s_barrier
	s_add_i32 s4, s73, 0x100
	s_add_i32 s47, s47, s53
	v_add_u32_e32 v153, s4, v151
	v_lshl_add_u64 v[162:163], s[44:45], 0, v[166:167]
	s_mov_b32 m0, s47
	ds_read_b128 v[212:215], v153
	ds_read_b128 v[216:219], v153 offset:1024
	ds_read_b128 v[220:223], v153 offset:2048
	ds_read_b128 v[224:227], v153 offset:3072
	global_load_lds_dwordx4 v[162:163], off
	v_lshl_add_u64 v[182:183], s[44:45], 0, v[132:133]
	s_add_i32 m0, s47, 0x2000
	s_nop 0
	global_load_lds_dwordx4 v[182:183], off
	s_barrier
	s_waitcnt lgkmcnt(0)
	s_waitcnt lgkmcnt(0)
	v_mfma_f32_16x16x32_bf16 v[116:119], v[212:215], v[174:177], 0
	v_mfma_f32_16x16x32_bf16 v[112:115], v[220:223], v[174:177], 0
	v_mfma_f32_16x16x32_bf16 v[100:103], v[212:215], v[188:191], 0
	v_mfma_f32_16x16x32_bf16 v[96:99], v[220:223], v[188:191], 0
	v_mfma_f32_16x16x32_bf16 v[84:87], v[212:215], v[196:199], 0
	v_mfma_f32_16x16x32_bf16 v[80:83], v[220:223], v[196:199], 0
	v_mfma_f32_16x16x32_bf16 v[68:71], v[212:215], v[204:207], 0
	v_mfma_f32_16x16x32_bf16 v[64:67], v[220:223], v[204:207], 0
	v_mfma_f32_16x16x32_bf16 v[116:119], v[216:219], v[178:181], v[116:119]
	v_mfma_f32_16x16x32_bf16 v[112:115], v[224:227], v[178:181], v[112:115]
	v_mfma_f32_16x16x32_bf16 v[100:103], v[216:219], v[192:195], v[100:103]
	v_mfma_f32_16x16x32_bf16 v[96:99], v[224:227], v[192:195], v[96:99]
	v_mfma_f32_16x16x32_bf16 v[84:87], v[216:219], v[200:203], v[84:87]
	v_mfma_f32_16x16x32_bf16 v[80:83], v[224:227], v[200:203], v[80:83]
	v_mfma_f32_16x16x32_bf16 v[68:71], v[216:219], v[208:211], v[68:71]
	v_mfma_f32_16x16x32_bf16 v[64:67], v[224:227], v[208:211], v[64:67]
	s_mov_b32 m0, s54
	v_lshl_add_u64 v[228:229], s[42:43], 0, v[128:129]
	s_barrier
	ds_read_b128 v[174:177], v152 offset:16384
	ds_read_b128 v[178:181], v152 offset:17408
	ds_read_b128 v[188:191], v152 offset:18432
	ds_read_b128 v[192:195], v152 offset:19456
	ds_read_b128 v[196:199], v152 offset:20480
	ds_read_b128 v[200:203], v152 offset:21504
	ds_read_b128 v[204:207], v152 offset:22528
	ds_read_b128 v[208:211], v152 offset:23552
	global_load_lds_dwordx4 v[228:229], off
	v_lshl_add_u64 v[230:231], s[42:43], 0, v[130:131]
	s_mov_b32 m0, s55
	s_nop 0
	global_load_lds_dwordx4 v[230:231], off
	s_barrier
	s_waitcnt lgkmcnt(0)
	s_waitcnt lgkmcnt(0)
	v_mfma_f32_16x16x32_bf16 v[60:63], v[138:141], v[174:177], 0
	v_mfma_f32_16x16x32_bf16 v[56:59], v[158:161], v[174:177], 0
	v_mfma_f32_16x16x32_bf16 v[44:47], v[138:141], v[188:191], 0
	v_mfma_f32_16x16x32_bf16 v[40:43], v[158:161], v[188:191], 0
	v_mfma_f32_16x16x32_bf16 v[28:31], v[138:141], v[196:199], 0
	v_mfma_f32_16x16x32_bf16 v[24:27], v[158:161], v[196:199], 0
	v_mfma_f32_16x16x32_bf16 v[12:15], v[138:141], v[204:207], 0
	v_mfma_f32_16x16x32_bf16 v[8:11], v[158:161], v[204:207], 0
	v_mfma_f32_16x16x32_bf16 v[60:63], v[154:157], v[178:181], v[60:63]
	v_mfma_f32_16x16x32_bf16 v[56:59], v[170:173], v[178:181], v[56:59]
	v_mfma_f32_16x16x32_bf16 v[44:47], v[154:157], v[192:195], v[44:47]
	v_mfma_f32_16x16x32_bf16 v[40:43], v[170:173], v[192:195], v[40:43]
	v_mfma_f32_16x16x32_bf16 v[28:31], v[154:157], v[200:203], v[28:31]
	v_mfma_f32_16x16x32_bf16 v[24:27], v[170:173], v[200:203], v[24:27]
	v_mfma_f32_16x16x32_bf16 v[12:15], v[154:157], v[208:211], v[12:15]
	v_mfma_f32_16x16x32_bf16 v[8:11], v[170:173], v[208:211], v[8:11]
	s_barrier
; #define PG8_STAGE(bufoff, gbase, voff) do { _Pragma("unroll") for (int _i = 0; _i < 2; ++_i) \
;         __builtin_amdgcn_global_load_lds((const unsigned*)((const char*)(gbase) + (voff)[_i]), (LAS unsigned*)(lds + (bufoff) + ldsw + _i * 8192), 16, 0, 0); } while (0)
; #define PG8_LDA(dst, b, h) do { _Pragma("unroll") for (int m = 0; m < 4; ++m) _Pragma("unroll") for (int k = 0; k < 2; ++k) dst[m][k] = *(const LAS bf16x8*)(lds + PG8_SA(b, h) + aoff + m * 2048 + k * 1024); } while (0)
; #define PG8_LDB(dst, b, h) do { _Pragma("unroll") for (int n = 0; n < 2; ++n) _Pragma("unroll") for (int k = 0; k < 2; ++k) dst[n][k] = *(const LAS bf16x8*)(lds + PG8_SB(b, h) + boff + n * 2048 + k * 1024); } while (0)
; #define PG8_MMA(ai, bj, At, Bt) do { __builtin_amdgcn_s_setprio(1); _Pragma("unroll") for (int m = 0; m < 4; ++m) _Pragma("unroll") for (int n = 0; n < 2; ++n) _Pragma("unroll") for (int k = 0; k < 2; ++k) \
;         acc[ai][bj][m][n] = __builtin_amdgcn_mfma_f32_16x16x32_bf16(Bt[n][k], At[m][k], acc[ai][bj][m][n], 0, 0, 0); __builtin_amdgcn_s_setprio(0); } while (0)
; #define PG8_WAIT_V(n) asm volatile("s_waitcnt vmcnt(" #n ")" ::: "memory")
; #define PG8_WAIT_L(n) asm volatile("s_waitcnt lgkmcnt(" #n ")" ::: "memory")
; #define PG8_BAR __builtin_amdgcn_s_barrier()
; #define PG8_SCHED __builtin_amdgcn_sched_barrier(0)
; template <class Epi>
; DI void gemm_phase(LAS unsigned char* lds, const Gemm g, const StaticOrder& S, const Epi& E) {
;     ...
;             PG8_LDA(At, 0, 1); PG8_STAGE(PG8_SA(0, 0), a2, voffA);
;             PG8_BAR; PG8_WAIT_L(0); PG8_MMA(1, 0, At, B0); PG8_BAR; PG8_SCHED;
;             PG8_STAGE(PG8_SB(0, 1), b2 + hstep, voffB);
;             PG8_WAIT_V(6); PG8_BAR; PG8_MMA(1, 1, At, B1); PG8_BAR;
;             PG8_LDB(B0, 1, 0); PG8_SCHED; PG8_LDA(At, 1, 0); PG8_STAGE(PG8_SA(0, 1), a2 + hstep, voffA);
;             PG8_WAIT_L(8); PG8_BAR; PG8_WAIT_L(0); PG8_MMA(0, 0, At, B0); PG8_BAR; PG8_SCHED;
;             PG8_LDB(B1, 1, 1); PG8_STAGE(PG8_SB(1, 0), b3, voffB);
;             PG8_BAR; PG8_WAIT_L(0); PG8_MMA(0, 1, At, B1); PG8_BAR;
;             PG8_LDA(At, 1, 1); PG8_STAGE(PG8_SA(1, 0), a3, voffA);
;             PG8_BAR; PG8_WAIT_L(0); PG8_MMA(1, 0, At, B0); PG8_BAR; PG8_SCHED;
;             PG8_STAGE(PG8_SB(1, 1), b3 + hstep, voffB);
;             PG8_WAIT_V(6); PG8_BAR; PG8_MMA(1, 1, At, B1); PG8_BAR;
	s_add_u32 s44, s44, s12
	s_addc_u32 s45, s45, s13
	s_add_i32 s4, s4, s53
	v_lshl_add_u64 v[232:233], s[44:45], 0, v[166:167]
	s_mov_b32 m0, s4
	v_lshl_add_u64 v[234:235], s[44:45], 0, v[132:133]
	global_load_lds_dwordx4 v[232:233], off
	s_add_i32 m0, s4, 0x2000
	s_nop 0
	global_load_lds_dwordx4 v[234:235], off
	s_waitcnt vmcnt(6)
	s_barrier
	v_mfma_f32_16x16x32_bf16 v[52:55], v[212:215], v[174:177], 0
	v_mfma_f32_16x16x32_bf16 v[48:51], v[220:223], v[174:177], 0
	v_mfma_f32_16x16x32_bf16 v[36:39], v[212:215], v[188:191], 0
	v_mfma_f32_16x16x32_bf16 v[32:35], v[220:223], v[188:191], 0
	v_mfma_f32_16x16x32_bf16 v[20:23], v[212:215], v[196:199], 0
	v_mfma_f32_16x16x32_bf16 v[16:19], v[220:223], v[196:199], 0
	v_mfma_f32_16x16x32_bf16 v[4:7], v[212:215], v[204:207], 0
	v_mfma_f32_16x16x32_bf16 v[0:3], v[220:223], v[204:207], 0
	v_mfma_f32_16x16x32_bf16 v[52:55], v[216:219], v[178:181], v[52:55]
	v_mfma_f32_16x16x32_bf16 v[48:51], v[224:227], v[178:181], v[48:51]
	v_mfma_f32_16x16x32_bf16 v[36:39], v[216:219], v[192:195], v[36:39]
	v_mfma_f32_16x16x32_bf16 v[32:35], v[224:227], v[192:195], v[32:35]
	v_mfma_f32_16x16x32_bf16 v[20:23], v[216:219], v[200:203], v[20:23]
	v_mfma_f32_16x16x32_bf16 v[16:19], v[224:227], v[200:203], v[16:19]
	v_mfma_f32_16x16x32_bf16 v[4:7], v[216:219], v[208:211], v[4:7]
	v_mfma_f32_16x16x32_bf16 v[0:3], v[224:227], v[208:211], v[0:3]
	s_add_i32 s4, s74, 0x100
	v_add_u32_e32 v153, s4, v151
	s_barrier
	ds_read_b128 v[138:141], v153
	ds_read_b128 v[154:157], v153 offset:1024
	ds_read_b128 v[158:161], v153 offset:2048
	ds_read_b128 v[170:173], v153 offset:3072
	s_add_u32 s42, s42, s12
	s_addc_u32 s43, s43, s13
	s_mov_b32 m0, s56
	v_lshl_add_u64 v[212:213], s[42:43], 0, v[128:129]
	ds_read_b128 v[174:177], v152 offset:32768
	ds_read_b128 v[178:181], v152 offset:33792
	ds_read_b128 v[188:191], v152 offset:34816
	ds_read_b128 v[192:195], v152 offset:35840
	ds_read_b128 v[196:199], v152 offset:36864
	ds_read_b128 v[200:203], v152 offset:37888
	ds_read_b128 v[204:207], v152 offset:38912
	ds_read_b128 v[208:211], v152 offset:39936
	global_load_lds_dwordx4 v[212:213], off
	v_lshl_add_u64 v[212:213], s[42:43], 0, v[130:131]
	s_mov_b32 m0, s57
	s_nop 0
	global_load_lds_dwordx4 v[212:213], off
	s_waitcnt lgkmcnt(8)
	s_barrier
	s_waitcnt lgkmcnt(0)
	s_waitcnt lgkmcnt(0)
	v_mfma_f32_16x16x32_bf16 v[124:127], v[138:141], v[174:177], v[124:127]
	v_mfma_f32_16x16x32_bf16 v[120:123], v[158:161], v[174:177], v[120:123]
	v_mfma_f32_16x16x32_bf16 v[108:111], v[138:141], v[188:191], v[108:111]
	v_mfma_f32_16x16x32_bf16 v[104:107], v[158:161], v[188:191], v[104:107]
	v_mfma_f32_16x16x32_bf16 v[92:95], v[138:141], v[196:199], v[92:95]
	v_mfma_f32_16x16x32_bf16 v[88:91], v[158:161], v[196:199], v[88:91]
	v_mfma_f32_16x16x32_bf16 v[76:79], v[138:141], v[204:207], v[76:79]
	v_mfma_f32_16x16x32_bf16 v[72:75], v[158:161], v[204:207], v[72:75]
	v_mfma_f32_16x16x32_bf16 v[124:127], v[154:157], v[178:181], v[124:127]
	v_mfma_f32_16x16x32_bf16 v[120:123], v[170:173], v[178:181], v[120:123]
	v_mfma_f32_16x16x32_bf16 v[108:111], v[154:157], v[192:195], v[108:111]
	v_mfma_f32_16x16x32_bf16 v[104:107], v[170:173], v[192:195], v[104:107]
	v_mfma_f32_16x16x32_bf16 v[92:95], v[154:157], v[200:203], v[92:95]
	v_mfma_f32_16x16x32_bf16 v[88:91], v[170:173], v[200:203], v[88:91]
	v_mfma_f32_16x16x32_bf16 v[76:79], v[154:157], v[208:211], v[76:79]
	v_mfma_f32_16x16x32_bf16 v[72:75], v[170:173], v[208:211], v[72:75]
	s_barrier
	s_add_i32 s42, s75, 0x100
	s_add_i32 s4, s4, s53
	v_add_u32_e32 v153, s42, v151
	v_lshl_add_u64 v[162:163], v[162:163], 0, s[76:77]
	s_mov_b32 m0, s4
	ds_read_b128 v[212:215], v153
	ds_read_b128 v[216:219], v153 offset:1024
	ds_read_b128 v[220:223], v153 offset:2048
	ds_read_b128 v[224:227], v153 offset:3072
	global_load_lds_dwordx4 v[162:163], off
	v_lshl_add_u64 v[162:163], v[182:183], 0, s[76:77]
	s_add_i32 m0, s4, 0x2000
	s_nop 0
	global_load_lds_dwordx4 v[162:163], off
	s_barrier
	s_waitcnt lgkmcnt(0)
	s_waitcnt lgkmcnt(0)
	v_mfma_f32_16x16x32_bf16 v[116:119], v[212:215], v[174:177], v[116:119]
	v_mfma_f32_16x16x32_bf16 v[112:115], v[220:223], v[174:177], v[112:115]
	v_mfma_f32_16x16x32_bf16 v[100:103], v[212:215], v[188:191], v[100:103]
	v_mfma_f32_16x16x32_bf16 v[96:99], v[220:223], v[188:191], v[96:99]
	v_mfma_f32_16x16x32_bf16 v[84:87], v[212:215], v[196:199], v[84:87]
	v_mfma_f32_16x16x32_bf16 v[80:83], v[220:223], v[196:199], v[80:83]
	v_mfma_f32_16x16x32_bf16 v[68:71], v[212:215], v[204:207], v[68:71]
	v_mfma_f32_16x16x32_bf16 v[64:67], v[220:223], v[204:207], v[64:67]
	v_mfma_f32_16x16x32_bf16 v[116:119], v[216:219], v[178:181], v[116:119]
	v_mfma_f32_16x16x32_bf16 v[112:115], v[224:227], v[178:181], v[112:115]
	v_mfma_f32_16x16x32_bf16 v[100:103], v[216:219], v[192:195], v[100:103]
	v_mfma_f32_16x16x32_bf16 v[96:99], v[224:227], v[192:195], v[96:99]
	v_mfma_f32_16x16x32_bf16 v[84:87], v[216:219], v[200:203], v[84:87]
	v_mfma_f32_16x16x32_bf16 v[80:83], v[224:227], v[200:203], v[80:83]
	v_mfma_f32_16x16x32_bf16 v[68:71], v[216:219], v[208:211], v[68:71]
	v_mfma_f32_16x16x32_bf16 v[64:67], v[224:227], v[208:211], v[64:67]
	s_mov_b32 m0, s62
	v_lshl_add_u64 v[162:163], v[228:229], 0, s[76:77]
	s_barrier
	ds_read_b128 v[174:177], v152 offset:49152
	ds_read_b128 v[178:181], v152 offset:50176
	ds_read_b128 v[188:191], v152 offset:51200
	ds_read_b128 v[192:195], v152 offset:52224
	ds_read_b128 v[196:199], v152 offset:53248
	ds_read_b128 v[200:203], v152 offset:54272
	ds_read_b128 v[204:207], v152 offset:55296
	ds_read_b128 v[208:211], v152 offset:56320
	global_load_lds_dwordx4 v[162:163], off
	v_lshl_add_u64 v[162:163], v[230:231], 0, s[76:77]
	s_mov_b32 m0, s63
	s_nop 0
	global_load_lds_dwordx4 v[162:163], off
	s_barrier
	s_waitcnt lgkmcnt(0)
	s_waitcnt lgkmcnt(0)
	v_mfma_f32_16x16x32_bf16 v[60:63], v[138:141], v[174:177], v[60:63]
	v_mfma_f32_16x16x32_bf16 v[56:59], v[158:161], v[174:177], v[56:59]
	v_mfma_f32_16x16x32_bf16 v[44:47], v[138:141], v[188:191], v[44:47]
	v_mfma_f32_16x16x32_bf16 v[40:43], v[158:161], v[188:191], v[40:43]
	v_mfma_f32_16x16x32_bf16 v[28:31], v[138:141], v[196:199], v[28:31]
	v_mfma_f32_16x16x32_bf16 v[24:27], v[158:161], v[196:199], v[24:27]
	v_mfma_f32_16x16x32_bf16 v[12:15], v[138:141], v[204:207], v[12:15]
	v_mfma_f32_16x16x32_bf16 v[8:11], v[158:161], v[204:207], v[8:11]
	v_mfma_f32_16x16x32_bf16 v[60:63], v[154:157], v[178:181], v[60:63]
	v_mfma_f32_16x16x32_bf16 v[56:59], v[170:173], v[178:181], v[56:59]
	v_mfma_f32_16x16x32_bf16 v[44:47], v[154:157], v[192:195], v[44:47]
	v_mfma_f32_16x16x32_bf16 v[40:43], v[170:173], v[192:195], v[40:43]
	v_mfma_f32_16x16x32_bf16 v[28:31], v[154:157], v[200:203], v[28:31]
	v_mfma_f32_16x16x32_bf16 v[24:27], v[170:173], v[200:203], v[24:27]
	v_mfma_f32_16x16x32_bf16 v[12:15], v[154:157], v[208:211], v[12:15]
	v_mfma_f32_16x16x32_bf16 v[8:11], v[170:173], v[208:211], v[8:11]
	s_barrier
	s_add_i32 s4, s42, s53
	v_lshl_add_u64 v[138:139], v[232:233], 0, s[76:77]
	s_mov_b32 m0, s4
	s_nop 0
	global_load_lds_dwordx4 v[138:139], off
	v_lshl_add_u64 v[138:139], v[234:235], 0, s[76:77]
	s_add_i32 m0, s4, 0x2000
	s_nop 0
	global_load_lds_dwordx4 v[138:139], off
	s_waitcnt vmcnt(6)
	s_barrier
	v_mfma_f32_16x16x32_bf16 v[52:55], v[212:215], v[174:177], v[52:55]
	v_mfma_f32_16x16x32_bf16 v[48:51], v[220:223], v[174:177], v[48:51]
	v_mfma_f32_16x16x32_bf16 v[36:39], v[212:215], v[188:191], v[36:39]
	v_mfma_f32_16x16x32_bf16 v[32:35], v[220:223], v[188:191], v[32:35]
	v_mfma_f32_16x16x32_bf16 v[20:23], v[212:215], v[196:199], v[20:23]
	v_mfma_f32_16x16x32_bf16 v[16:19], v[220:223], v[196:199], v[16:19]
	v_mfma_f32_16x16x32_bf16 v[4:7], v[212:215], v[204:207], v[4:7]
	v_mfma_f32_16x16x32_bf16 v[0:3], v[220:223], v[204:207], v[0:3]
	v_mfma_f32_16x16x32_bf16 v[52:55], v[216:219], v[178:181], v[52:55]
	v_mfma_f32_16x16x32_bf16 v[48:51], v[224:227], v[178:181], v[48:51]
	v_mfma_f32_16x16x32_bf16 v[36:39], v[216:219], v[192:195], v[36:39]
	v_mfma_f32_16x16x32_bf16 v[32:35], v[224:227], v[192:195], v[32:35]
	v_mfma_f32_16x16x32_bf16 v[20:23], v[216:219], v[200:203], v[20:23]
	v_mfma_f32_16x16x32_bf16 v[16:19], v[224:227], v[200:203], v[16:19]
	v_mfma_f32_16x16x32_bf16 v[4:7], v[216:219], v[208:211], v[4:7]
	v_mfma_f32_16x16x32_bf16 v[0:3], v[224:227], v[208:211], v[0:3]
	s_add_u32 s40, s40, 0x100
	s_addc_u32 s41, s41, 0
	s_add_u32 s0, s0, 0x100
	s_addc_u32 s46, s46, 0
	s_cmp_ge_i32 s5, s59
	s_mov_b32 s4, s5
	s_barrier
	s_cbranch_scc0 .LBB0_1670
	s_branch .Lpeel_exit_6
.LBB0_1670:
	s_add_i32 s5, s4, 2
	s_add_u32 s42, s40, 0x80
	s_addc_u32 s43, s41, 0
	s_add_i32 s47, s72, 0x100
	v_add_u32_e32 v153, s47, v151
	ds_read_b128 v[138:141], v153
	ds_read_b128 v[154:157], v153 offset:1024
	ds_read_b128 v[158:161], v153 offset:2048
	ds_read_b128 v[170:173], v153 offset:3072
	s_cmp_eq_u32 s64, s4
	s_cselect_b32 s43, s19, s43
	s_cselect_b32 s42, s18, s42
	s_cselect_b32 s45, s37, s46
	s_cselect_b32 s44, s36, s0
	v_lshl_add_u64 v[162:163], s[40:41], 0, v[134:135]
	s_add_i32 m0, s54, 0xc000
	ds_read_b128 v[174:177], v152
	ds_read_b128 v[178:181], v152 offset:1024
	ds_read_b128 v[188:191], v152 offset:2048
	ds_read_b128 v[192:195], v152 offset:3072
	ds_read_b128 v[196:199], v152 offset:4096
	ds_read_b128 v[200:203], v152 offset:5120
	ds_read_b128 v[204:207], v152 offset:6144
	ds_read_b128 v[208:211], v152 offset:7168
	global_load_lds_dwordx4 v[162:163], off
	v_lshl_add_u64 v[162:163], s[40:41], 0, v[136:137]
	s_add_i32 m0, s54, 0xe000
	s_nop 0
	global_load_lds_dwordx4 v[162:163], off
	s_waitcnt lgkmcnt(8)
	s_barrier
	s_waitcnt lgkmcnt(0)
	s_waitcnt lgkmcnt(0)
	v_mfma_f32_16x16x32_bf16 v[124:127], v[138:141], v[174:177], v[124:127]
	v_mfma_f32_16x16x32_bf16 v[120:123], v[158:161], v[174:177], v[120:123]
	v_mfma_f32_16x16x32_bf16 v[108:111], v[138:141], v[188:191], v[108:111]
	v_mfma_f32_16x16x32_bf16 v[104:107], v[158:161], v[188:191], v[104:107]
	v_mfma_f32_16x16x32_bf16 v[92:95], v[138:141], v[196:199], v[92:95]
	v_mfma_f32_16x16x32_bf16 v[88:91], v[158:161], v[196:199], v[88:91]
	v_mfma_f32_16x16x32_bf16 v[76:79], v[138:141], v[204:207], v[76:79]
	v_mfma_f32_16x16x32_bf16 v[72:75], v[158:161], v[204:207], v[72:75]
	v_mfma_f32_16x16x32_bf16 v[124:127], v[154:157], v[178:181], v[124:127]
	v_mfma_f32_16x16x32_bf16 v[120:123], v[170:173], v[178:181], v[120:123]
	v_mfma_f32_16x16x32_bf16 v[108:111], v[154:157], v[192:195], v[108:111]
	v_mfma_f32_16x16x32_bf16 v[104:107], v[170:173], v[192:195], v[104:107]
	v_mfma_f32_16x16x32_bf16 v[92:95], v[154:157], v[200:203], v[92:95]
	v_mfma_f32_16x16x32_bf16 v[88:91], v[170:173], v[200:203], v[88:91]
	v_mfma_f32_16x16x32_bf16 v[76:79], v[154:157], v[208:211], v[76:79]
	v_mfma_f32_16x16x32_bf16 v[72:75], v[170:173], v[208:211], v[72:75]
	s_barrier
	s_add_i32 s4, s73, 0x100
	s_add_i32 s47, s47, s53
	v_add_u32_e32 v153, s4, v151
	v_lshl_add_u64 v[162:163], s[44:45], 0, v[166:167]
	s_mov_b32 m0, s47
	ds_read_b128 v[212:215], v153
	ds_read_b128 v[216:219], v153 offset:1024
	ds_read_b128 v[220:223], v153 offset:2048
	ds_read_b128 v[224:227], v153 offset:3072
	global_load_lds_dwordx4 v[162:163], off
	v_lshl_add_u64 v[182:183], s[44:45], 0, v[132:133]
	s_add_i32 m0, s47, 0x2000
	s_nop 0
	global_load_lds_dwordx4 v[182:183], off
	s_barrier
; #define PG8_STAGE(bufoff, gbase, voff) do { _Pragma("unroll") for (int _i = 0; _i < 2; ++_i) \
;         __builtin_amdgcn_global_load_lds((const unsigned*)((const char*)(gbase) + (voff)[_i]), (LAS unsigned*)(lds + (bufoff) + ldsw + _i * 8192), 16, 0, 0); } while (0)
; #define PG8_LDA(dst, b, h) do { _Pragma("unroll") for (int m = 0; m < 4; ++m) _Pragma("unroll") for (int k = 0; k < 2; ++k) dst[m][k] = *(const LAS bf16x8*)(lds + PG8_SA(b, h) + aoff + m * 2048 + k * 1024); } while (0)
; #define PG8_LDB(dst, b, h) do { _Pragma("unroll") for (int n = 0; n < 2; ++n) _Pragma("unroll") for (int k = 0; k < 2; ++k) dst[n][k] = *(const LAS bf16x8*)(lds + PG8_SB(b, h) + boff + n * 2048 + k * 1024); } while (0)
; #define PG8_MMA(ai, bj, At, Bt) do { __builtin_amdgcn_s_setprio(1); _Pragma("unroll") for (int m = 0; m < 4; ++m) _Pragma("unroll") for (int n = 0; n < 2; ++n) _Pragma("unroll") for (int k = 0; k < 2; ++k) \
;         acc[ai][bj][m][n] = __builtin_amdgcn_mfma_f32_16x16x32_bf16(Bt[n][k], At[m][k], acc[ai][bj][m][n], 0, 0, 0); __builtin_amdgcn_s_setprio(0); } while (0)
; #define PG8_WAIT_V(n) asm volatile("s_waitcnt vmcnt(" #n ")" ::: "memory")
; #define PG8_WAIT_L(n) asm volatile("s_waitcnt lgkmcnt(" #n ")" ::: "memory")
; #define PG8_BAR __builtin_amdgcn_s_barrier()
; #define PG8_SCHED __builtin_amdgcn_sched_barrier(0)
; template <class Epi>
; DI void gemm_phase(LAS unsigned char* lds, const Gemm g, const StaticOrder& S, const Epi& E) {
;     ...
;             PG8_LDB(B1, 0, 1); PG8_STAGE(PG8_SB(0, 0), b2, voffB);
;             PG8_BAR; PG8_WAIT_L(0); PG8_MMA(0, 1, At, B1); PG8_BAR;
;             PG8_LDA(At, 0, 1); PG8_STAGE(PG8_SA(0, 0), a2, voffA);
;             PG8_BAR; PG8_WAIT_L(0); PG8_MMA(1, 0, At, B0); PG8_BAR; PG8_SCHED;
;             PG8_STAGE(PG8_SB(0, 1), b2 + hstep, voffB);
;             PG8_WAIT_V(6); PG8_BAR; PG8_MMA(1, 1, At, B1); PG8_BAR;
;             PG8_LDB(B0, 1, 0); PG8_SCHED; PG8_LDA(At, 1, 0); PG8_STAGE(PG8_SA(0, 1), a2 + hstep, voffA);
;             PG8_WAIT_L(8); PG8_BAR; PG8_WAIT_L(0); PG8_MMA(0, 0, At, B0); PG8_BAR; PG8_SCHED;
;             PG8_LDB(B1, 1, 1); PG8_STAGE(PG8_SB(1, 0), b3, voffB);
;             PG8_BAR; PG8_WAIT_L(0); PG8_MMA(0, 1, At, B1); PG8_BAR;
;             PG8_LDA(At, 1, 1); PG8_STAGE(PG8_SA(1, 0), a3, voffA);
	s_waitcnt lgkmcnt(0)
	s_waitcnt lgkmcnt(0)
	v_mfma_f32_16x16x32_bf16 v[116:119], v[212:215], v[174:177], v[116:119]
	v_mfma_f32_16x16x32_bf16 v[112:115], v[220:223], v[174:177], v[112:115]
	v_mfma_f32_16x16x32_bf16 v[100:103], v[212:215], v[188:191], v[100:103]
	v_mfma_f32_16x16x32_bf16 v[96:99], v[220:223], v[188:191], v[96:99]
	v_mfma_f32_16x16x32_bf16 v[84:87], v[212:215], v[196:199], v[84:87]
	v_mfma_f32_16x16x32_bf16 v[80:83], v[220:223], v[196:199], v[80:83]
	v_mfma_f32_16x16x32_bf16 v[68:71], v[212:215], v[204:207], v[68:71]
	v_mfma_f32_16x16x32_bf16 v[64:67], v[220:223], v[204:207], v[64:67]
	v_mfma_f32_16x16x32_bf16 v[116:119], v[216:219], v[178:181], v[116:119]
	v_mfma_f32_16x16x32_bf16 v[112:115], v[224:227], v[178:181], v[112:115]
	v_mfma_f32_16x16x32_bf16 v[100:103], v[216:219], v[192:195], v[100:103]
	v_mfma_f32_16x16x32_bf16 v[96:99], v[224:227], v[192:195], v[96:99]
	v_mfma_f32_16x16x32_bf16 v[84:87], v[216:219], v[200:203], v[84:87]
	v_mfma_f32_16x16x32_bf16 v[80:83], v[224:227], v[200:203], v[80:83]
	v_mfma_f32_16x16x32_bf16 v[68:71], v[216:219], v[208:211], v[68:71]
	v_mfma_f32_16x16x32_bf16 v[64:67], v[224:227], v[208:211], v[64:67]
	s_mov_b32 m0, s54
	v_lshl_add_u64 v[228:229], s[42:43], 0, v[128:129]
	s_barrier
	ds_read_b128 v[174:177], v152 offset:16384
	ds_read_b128 v[178:181], v152 offset:17408
	ds_read_b128 v[188:191], v152 offset:18432
	ds_read_b128 v[192:195], v152 offset:19456
	ds_read_b128 v[196:199], v152 offset:20480
	ds_read_b128 v[200:203], v152 offset:21504
	ds_read_b128 v[204:207], v152 offset:22528
	ds_read_b128 v[208:211], v152 offset:23552
	global_load_lds_dwordx4 v[228:229], off
	v_lshl_add_u64 v[230:231], s[42:43], 0, v[130:131]
	s_mov_b32 m0, s55
	s_nop 0
	global_load_lds_dwordx4 v[230:231], off
	s_barrier
	s_waitcnt lgkmcnt(0)
	s_waitcnt lgkmcnt(0)
	v_mfma_f32_16x16x32_bf16 v[60:63], v[138:141], v[174:177], v[60:63]
	v_mfma_f32_16x16x32_bf16 v[56:59], v[158:161], v[174:177], v[56:59]
	v_mfma_f32_16x16x32_bf16 v[44:47], v[138:141], v[188:191], v[44:47]
	v_mfma_f32_16x16x32_bf16 v[40:43], v[158:161], v[188:191], v[40:43]
	v_mfma_f32_16x16x32_bf16 v[28:31], v[138:141], v[196:199], v[28:31]
	v_mfma_f32_16x16x32_bf16 v[24:27], v[158:161], v[196:199], v[24:27]
	v_mfma_f32_16x16x32_bf16 v[12:15], v[138:141], v[204:207], v[12:15]
	v_mfma_f32_16x16x32_bf16 v[8:11], v[158:161], v[204:207], v[8:11]
	v_mfma_f32_16x16x32_bf16 v[60:63], v[154:157], v[178:181], v[60:63]
	v_mfma_f32_16x16x32_bf16 v[56:59], v[170:173], v[178:181], v[56:59]
	v_mfma_f32_16x16x32_bf16 v[44:47], v[154:157], v[192:195], v[44:47]
	v_mfma_f32_16x16x32_bf16 v[40:43], v[170:173], v[192:195], v[40:43]
	v_mfma_f32_16x16x32_bf16 v[28:31], v[154:157], v[200:203], v[28:31]
	v_mfma_f32_16x16x32_bf16 v[24:27], v[170:173], v[200:203], v[24:27]
	v_mfma_f32_16x16x32_bf16 v[12:15], v[154:157], v[208:211], v[12:15]
	v_mfma_f32_16x16x32_bf16 v[8:11], v[170:173], v[208:211], v[8:11]
	s_barrier
	s_add_u32 s44, s44, s12
	s_addc_u32 s45, s45, s13
	s_add_i32 s4, s4, s53
	v_lshl_add_u64 v[232:233], s[44:45], 0, v[166:167]
	s_mov_b32 m0, s4
	v_lshl_add_u64 v[234:235], s[44:45], 0, v[132:133]
	global_load_lds_dwordx4 v[232:233], off
	s_add_i32 m0, s4, 0x2000
	s_nop 0
	global_load_lds_dwordx4 v[234:235], off
	s_waitcnt vmcnt(6)
	s_barrier
	v_mfma_f32_16x16x32_bf16 v[52:55], v[212:215], v[174:177], v[52:55]
	v_mfma_f32_16x16x32_bf16 v[48:51], v[220:223], v[174:177], v[48:51]
	v_mfma_f32_16x16x32_bf16 v[36:39], v[212:215], v[188:191], v[36:39]
	v_mfma_f32_16x16x32_bf16 v[32:35], v[220:223], v[188:191], v[32:35]
	v_mfma_f32_16x16x32_bf16 v[20:23], v[212:215], v[196:199], v[20:23]
	v_mfma_f32_16x16x32_bf16 v[16:19], v[220:223], v[196:199], v[16:19]
	v_mfma_f32_16x16x32_bf16 v[4:7], v[212:215], v[204:207], v[4:7]
	v_mfma_f32_16x16x32_bf16 v[0:3], v[220:223], v[204:207], v[0:3]
	v_mfma_f32_16x16x32_bf16 v[52:55], v[216:219], v[178:181], v[52:55]
	v_mfma_f32_16x16x32_bf16 v[48:51], v[224:227], v[178:181], v[48:51]
	v_mfma_f32_16x16x32_bf16 v[36:39], v[216:219], v[192:195], v[36:39]
	v_mfma_f32_16x16x32_bf16 v[32:35], v[224:227], v[192:195], v[32:35]
	v_mfma_f32_16x16x32_bf16 v[20:23], v[216:219], v[200:203], v[20:23]
	v_mfma_f32_16x16x32_bf16 v[16:19], v[224:227], v[200:203], v[16:19]
	v_mfma_f32_16x16x32_bf16 v[4:7], v[216:219], v[208:211], v[4:7]
	v_mfma_f32_16x16x32_bf16 v[0:3], v[224:227], v[208:211], v[0:3]
	s_add_i32 s4, s74, 0x100
	v_add_u32_e32 v153, s4, v151
	s_barrier
	ds_read_b128 v[138:141], v153
	ds_read_b128 v[154:157], v153 offset:1024
	ds_read_b128 v[158:161], v153 offset:2048
	ds_read_b128 v[170:173], v153 offset:3072
	s_add_u32 s42, s42, s12
	s_addc_u32 s43, s43, s13
	s_mov_b32 m0, s56
	v_lshl_add_u64 v[212:213], s[42:43], 0, v[128:129]
	ds_read_b128 v[174:177], v152 offset:32768
	ds_read_b128 v[178:181], v152 offset:33792
	ds_read_b128 v[188:191], v152 offset:34816
	ds_read_b128 v[192:195], v152 offset:35840
	ds_read_b128 v[196:199], v152 offset:36864
	ds_read_b128 v[200:203], v152 offset:37888
	ds_read_b128 v[204:207], v152 offset:38912
	ds_read_b128 v[208:211], v152 offset:39936
	global_load_lds_dwordx4 v[212:213], off
	v_lshl_add_u64 v[212:213], s[42:43], 0, v[130:131]
	s_mov_b32 m0, s57
	s_nop 0
	global_load_lds_dwordx4 v[212:213], off
	s_waitcnt lgkmcnt(8)
	s_barrier
; #define PG8_STAGE(bufoff, gbase, voff) do { _Pragma("unroll") for (int _i = 0; _i < 2; ++_i) \
;         __builtin_amdgcn_global_load_lds((const unsigned*)((const char*)(gbase) + (voff)[_i]), (LAS unsigned*)(lds + (bufoff) + ldsw + _i * 8192), 16, 0, 0); } while (0)
; #define PG8_LDA(dst, b, h) do { _Pragma("unroll") for (int m = 0; m < 4; ++m) _Pragma("unroll") for (int k = 0; k < 2; ++k) dst[m][k] = *(const LAS bf16x8*)(lds + PG8_SA(b, h) + aoff + m * 2048 + k * 1024); } while (0)
; #define PG8_LDB(dst, b, h) do { _Pragma("unroll") for (int n = 0; n < 2; ++n) _Pragma("unroll") for (int k = 0; k < 2; ++k) dst[n][k] = *(const LAS bf16x8*)(lds + PG8_SB(b, h) + boff + n * 2048 + k * 1024); } while (0)
; #define PG8_MMA(ai, bj, At, Bt) do { __builtin_amdgcn_s_setprio(1); _Pragma("unroll") for (int m = 0; m < 4; ++m) _Pragma("unroll") for (int n = 0; n < 2; ++n) _Pragma("unroll") for (int k = 0; k < 2; ++k) \
;         acc[ai][bj][m][n] = __builtin_amdgcn_mfma_f32_16x16x32_bf16(Bt[n][k], At[m][k], acc[ai][bj][m][n], 0, 0, 0); __builtin_amdgcn_s_setprio(0); } while (0)
; #define PG8_WAIT_V(n) asm volatile("s_waitcnt vmcnt(" #n ")" ::: "memory")
; #define PG8_WAIT_L(n) asm volatile("s_waitcnt lgkmcnt(" #n ")" ::: "memory")
; #define PG8_BAR __builtin_amdgcn_s_barrier()
; #define PG8_SCHED __builtin_amdgcn_sched_barrier(0)
; template <class Epi>
; DI void gemm_phase(LAS unsigned char* lds, const Gemm g, const StaticOrder& S, const Epi& E) {
;     ...
;             PG8_WAIT_L(8); PG8_BAR; PG8_WAIT_L(0); PG8_MMA(0, 0, At, B0); PG8_BAR; PG8_SCHED;
;             PG8_LDB(B1, 1, 1); PG8_STAGE(PG8_SB(1, 0), b3, voffB);
;             PG8_BAR; PG8_WAIT_L(0); PG8_MMA(0, 1, At, B1); PG8_BAR;
;             PG8_LDA(At, 1, 1); PG8_STAGE(PG8_SA(1, 0), a3, voffA);
;             PG8_BAR; PG8_WAIT_L(0); PG8_MMA(1, 0, At, B0); PG8_BAR; PG8_SCHED;
;             PG8_STAGE(PG8_SB(1, 1), b3 + hstep, voffB);
;             PG8_WAIT_V(6); PG8_BAR; PG8_MMA(1, 1, At, B1); PG8_BAR;
	s_waitcnt lgkmcnt(0)
	s_waitcnt lgkmcnt(0)
	v_mfma_f32_16x16x32_bf16 v[124:127], v[138:141], v[174:177], v[124:127]
	v_mfma_f32_16x16x32_bf16 v[120:123], v[158:161], v[174:177], v[120:123]
	v_mfma_f32_16x16x32_bf16 v[108:111], v[138:141], v[188:191], v[108:111]
	v_mfma_f32_16x16x32_bf16 v[104:107], v[158:161], v[188:191], v[104:107]
	v_mfma_f32_16x16x32_bf16 v[92:95], v[138:141], v[196:199], v[92:95]
	v_mfma_f32_16x16x32_bf16 v[88:91], v[158:161], v[196:199], v[88:91]
	v_mfma_f32_16x16x32_bf16 v[76:79], v[138:141], v[204:207], v[76:79]
	v_mfma_f32_16x16x32_bf16 v[72:75], v[158:161], v[204:207], v[72:75]
	v_mfma_f32_16x16x32_bf16 v[124:127], v[154:157], v[178:181], v[124:127]
	v_mfma_f32_16x16x32_bf16 v[120:123], v[170:173], v[178:181], v[120:123]
	v_mfma_f32_16x16x32_bf16 v[108:111], v[154:157], v[192:195], v[108:111]
	v_mfma_f32_16x16x32_bf16 v[104:107], v[170:173], v[192:195], v[104:107]
	v_mfma_f32_16x16x32_bf16 v[92:95], v[154:157], v[200:203], v[92:95]
	v_mfma_f32_16x16x32_bf16 v[88:91], v[170:173], v[200:203], v[88:91]
	v_mfma_f32_16x16x32_bf16 v[76:79], v[154:157], v[208:211], v[76:79]
	v_mfma_f32_16x16x32_bf16 v[72:75], v[170:173], v[208:211], v[72:75]
	s_barrier
	s_add_i32 s42, s75, 0x100
	s_add_i32 s4, s4, s53
	v_add_u32_e32 v153, s42, v151
	v_lshl_add_u64 v[162:163], v[162:163], 0, s[76:77]
	s_mov_b32 m0, s4
	ds_read_b128 v[212:215], v153
	ds_read_b128 v[216:219], v153 offset:1024
	ds_read_b128 v[220:223], v153 offset:2048
	ds_read_b128 v[224:227], v153 offset:3072
	global_load_lds_dwordx4 v[162:163], off
	v_lshl_add_u64 v[162:163], v[182:183], 0, s[76:77]
	s_add_i32 m0, s4, 0x2000
	s_nop 0
	global_load_lds_dwordx4 v[162:163], off
	s_barrier
	s_waitcnt lgkmcnt(0)
	s_waitcnt lgkmcnt(0)
	v_mfma_f32_16x16x32_bf16 v[116:119], v[212:215], v[174:177], v[116:119]
	v_mfma_f32_16x16x32_bf16 v[112:115], v[220:223], v[174:177], v[112:115]
	v_mfma_f32_16x16x32_bf16 v[100:103], v[212:215], v[188:191], v[100:103]
	v_mfma_f32_16x16x32_bf16 v[96:99], v[220:223], v[188:191], v[96:99]
	v_mfma_f32_16x16x32_bf16 v[84:87], v[212:215], v[196:199], v[84:87]
	v_mfma_f32_16x16x32_bf16 v[80:83], v[220:223], v[196:199], v[80:83]
	v_mfma_f32_16x16x32_bf16 v[68:71], v[212:215], v[204:207], v[68:71]
	v_mfma_f32_16x16x32_bf16 v[64:67], v[220:223], v[204:207], v[64:67]
	v_mfma_f32_16x16x32_bf16 v[116:119], v[216:219], v[178:181], v[116:119]
	v_mfma_f32_16x16x32_bf16 v[112:115], v[224:227], v[178:181], v[112:115]
	v_mfma_f32_16x16x32_bf16 v[100:103], v[216:219], v[192:195], v[100:103]
	v_mfma_f32_16x16x32_bf16 v[96:99], v[224:227], v[192:195], v[96:99]
	v_mfma_f32_16x16x32_bf16 v[84:87], v[216:219], v[200:203], v[84:87]
	v_mfma_f32_16x16x32_bf16 v[80:83], v[224:227], v[200:203], v[80:83]
	v_mfma_f32_16x16x32_bf16 v[68:71], v[216:219], v[208:211], v[68:71]
	v_mfma_f32_16x16x32_bf16 v[64:67], v[224:227], v[208:211], v[64:67]
	s_mov_b32 m0, s62
	v_lshl_add_u64 v[162:163], v[228:229], 0, s[76:77]
	s_barrier
	ds_read_b128 v[174:177], v152 offset:49152
	ds_read_b128 v[178:181], v152 offset:50176
	ds_read_b128 v[188:191], v152 offset:51200
	ds_read_b128 v[192:195], v152 offset:52224
	ds_read_b128 v[196:199], v152 offset:53248
	ds_read_b128 v[200:203], v152 offset:54272
	ds_read_b128 v[204:207], v152 offset:55296
	ds_read_b128 v[208:211], v152 offset:56320
	global_load_lds_dwordx4 v[162:163], off
	v_lshl_add_u64 v[162:163], v[230:231], 0, s[76:77]
	s_mov_b32 m0, s63
	s_nop 0
	global_load_lds_dwordx4 v[162:163], off
	s_barrier
	s_waitcnt lgkmcnt(0)
	s_waitcnt lgkmcnt(0)
	v_mfma_f32_16x16x32_bf16 v[60:63], v[138:141], v[174:177], v[60:63]
	v_mfma_f32_16x16x32_bf16 v[56:59], v[158:161], v[174:177], v[56:59]
	v_mfma_f32_16x16x32_bf16 v[44:47], v[138:141], v[188:191], v[44:47]
	v_mfma_f32_16x16x32_bf16 v[40:43], v[158:161], v[188:191], v[40:43]
	v_mfma_f32_16x16x32_bf16 v[28:31], v[138:141], v[196:199], v[28:31]
	v_mfma_f32_16x16x32_bf16 v[24:27], v[158:161], v[196:199], v[24:27]
	v_mfma_f32_16x16x32_bf16 v[12:15], v[138:141], v[204:207], v[12:15]
	v_mfma_f32_16x16x32_bf16 v[8:11], v[158:161], v[204:207], v[8:11]
	v_mfma_f32_16x16x32_bf16 v[60:63], v[154:157], v[178:181], v[60:63]
	v_mfma_f32_16x16x32_bf16 v[56:59], v[170:173], v[178:181], v[56:59]
	v_mfma_f32_16x16x32_bf16 v[44:47], v[154:157], v[192:195], v[44:47]
	v_mfma_f32_16x16x32_bf16 v[40:43], v[170:173], v[192:195], v[40:43]
	v_mfma_f32_16x16x32_bf16 v[28:31], v[154:157], v[200:203], v[28:31]
	v_mfma_f32_16x16x32_bf16 v[24:27], v[170:173], v[200:203], v[24:27]
	v_mfma_f32_16x16x32_bf16 v[12:15], v[154:157], v[208:211], v[12:15]
	v_mfma_f32_16x16x32_bf16 v[8:11], v[170:173], v[208:211], v[8:11]
	s_barrier
	s_add_i32 s4, s42, s53
	v_lshl_add_u64 v[138:139], v[232:233], 0, s[76:77]
	s_mov_b32 m0, s4
	s_nop 0
	global_load_lds_dwordx4 v[138:139], off
	v_lshl_add_u64 v[138:139], v[234:235], 0, s[76:77]
	s_add_i32 m0, s4, 0x2000
	s_nop 0
	global_load_lds_dwordx4 v[138:139], off
	s_waitcnt vmcnt(6)
	s_barrier
	v_mfma_f32_16x16x32_bf16 v[52:55], v[212:215], v[174:177], v[52:55]
	v_mfma_f32_16x16x32_bf16 v[48:51], v[220:223], v[174:177], v[48:51]
	v_mfma_f32_16x16x32_bf16 v[36:39], v[212:215], v[188:191], v[36:39]
	v_mfma_f32_16x16x32_bf16 v[32:35], v[220:223], v[188:191], v[32:35]
	v_mfma_f32_16x16x32_bf16 v[20:23], v[212:215], v[196:199], v[20:23]
	v_mfma_f32_16x16x32_bf16 v[16:19], v[220:223], v[196:199], v[16:19]
	v_mfma_f32_16x16x32_bf16 v[4:7], v[212:215], v[204:207], v[4:7]
	v_mfma_f32_16x16x32_bf16 v[0:3], v[220:223], v[204:207], v[0:3]
	v_mfma_f32_16x16x32_bf16 v[52:55], v[216:219], v[178:181], v[52:55]
	v_mfma_f32_16x16x32_bf16 v[48:51], v[224:227], v[178:181], v[48:51]
	v_mfma_f32_16x16x32_bf16 v[36:39], v[216:219], v[192:195], v[36:39]
	v_mfma_f32_16x16x32_bf16 v[32:35], v[224:227], v[192:195], v[32:35]
	v_mfma_f32_16x16x32_bf16 v[20:23], v[216:219], v[200:203], v[20:23]
	v_mfma_f32_16x16x32_bf16 v[16:19], v[224:227], v[200:203], v[16:19]
	v_mfma_f32_16x16x32_bf16 v[4:7], v[216:219], v[208:211], v[4:7]
	v_mfma_f32_16x16x32_bf16 v[0:3], v[224:227], v[208:211], v[0:3]
	s_add_u32 s40, s40, 0x100
	s_addc_u32 s41, s41, 0
	s_add_u32 s0, s0, 0x100
	s_addc_u32 s46, s46, 0
	s_cmp_ge_i32 s5, s59
	s_mov_b32 s4, s5
	s_barrier
	s_cbranch_scc0 .LBB0_1670

; #define PG8_WAIT_V(n) asm volatile("s_waitcnt vmcnt(" #n ")" ::: "memory")
; #define PG8_BAR __builtin_amdgcn_s_barrier()
; template <class Epi>
; DI void gemm_phase(LAS unsigned char* lds, const Gemm g, const StaticOrder& S, const Epi& E) {
;     ...
;     PG8_WAIT_V(0);
;     if (wr == 0) PG8_BAR;
;     PG8_BAR;
.LBB0_1689:
	s_mov_b64 s[66:67], 0x80
	s_barrier
	s_setprio 0
